# stack: off-diagonal stick-breaking body + trailing-half unit-restart barrier deferred past the unit header and accumulator clears (8 GEMM phases) + s_setprio hoisted over the pre-MFMA barrier and its
# baseline (speedup 1.0000x reference)
; #define LAS __attribute__((address_space(3)))
; __device__ __forceinline__ unsigned xb_add(unsigned* p, unsigned v) { return __hip_atomic_fetch_add(p, v, __ATOMIC_RELAXED, __HIP_MEMORY_SCOPE_AGENT); }
; __device__ __forceinline__ unsigned xb_xcc_id() { return (unsigned)__builtin_amdgcn_s_getreg((3 << 11) | 20) & 0xFu; }
; __device__ __forceinline__ XcdBarrier xcd_barrier_post(unsigned* bar, volatile LAS unsigned* st) {
;     XcdBarrier b; b.bar = bar; b.x = xb_xcc_id(); b.st = st;
;     if (threadIdx.x == 0) (void)xb_add(&bar[XB_XCNT(b.x)], 1u);
;     return b;
; }
; __global__ void __launch_bounds__(NWAVES * 64, 2) fwd_mega(Args args) {
;     extern __shared__ __attribute__((aligned(16))) unsigned char lds[];
;     LAS unsigned char* lds3 = (LAS unsigned char*)lds;
;     volatile LAS unsigned* MISC = (volatile LAS unsigned*)(lds3 + MISC_OFF);
;     const int G = gridDim.x, NGW = G * NWAVES, NT = G * NWAVES * 64;
;     ...
;     unsigned char* ws = args.ws;
;     gu32* ctl = (gu32*)(ws + WS_CTL);
;     for (int u = threadIdx.x; u < (LDS_BYTES - LDSCTL_OFF) / 4; u += NWAVES * 64) ((LAS unsigned*)(lds3 + LDSCTL_OFF))[u] = 0u;
;     __syncthreads();
;     XcdBarrier bar = xcd_barrier_post((unsigned*)(ctl + CW_BAR), MISC + 8);
_Z8fwd_mega4Args:
	s_mov_b32 s98, 0
	v_writelane_b32 v253, s2, 0
	s_nop 1
	v_writelane_b32 v253, s3, 1
	s_load_dwordx2 s[2:3], s[0:1], 0x160
	s_waitcnt lgkmcnt(0)
	v_writelane_b32 v253, s2, 2
	s_nop 1
	v_writelane_b32 v253, s3, 3
	s_add_u32 s2, s0, 0x168
	v_writelane_b32 v253, s0, 4
	s_addc_u32 s3, s1, 0
	s_nop 0
	v_writelane_b32 v253, s1, 5
	s_movk_i32 s0, 0x100
	v_writelane_b32 v253, s2, 6
	v_cmp_gt_u32_e32 vcc, s0, v0
	s_nop 0
	v_writelane_b32 v253, s3, 7
	s_and_saveexec_b64 s[4:5], vcc
	v_lshl_add_u32 v1, v0, 2, 0
	v_add_u32_e32 v1, 0x23c00, v1
	v_mov_b32_e32 v2, 0
	ds_write_b32 v1, v2
	s_or_b64 exec, exec, s[4:5]
	v_readlane_b32 s0, v253, 4
	v_readlane_b32 s1, v253, 5
	s_load_dword s0, s[0:1], 0x168
	s_waitcnt lgkmcnt(0)
	s_barrier
	v_writelane_b32 v253, s0, 8
	s_nop 0
	v_readlane_b32 s0, v253, 2
	v_readlane_b32 s1, v253, 3
	s_add_u32 s0, s0, 0x4000
	s_addc_u32 s1, s1, 0
	v_writelane_b32 v253, s0, 9
	s_nop 1
	v_writelane_b32 v253, s1, 10
	s_getreg_b32 s0, hwreg(HW_REG_XCC_ID, 0, 4)
	s_and_b32 s0, s0, 15
	v_writelane_b32 v253, s0, 11
	v_cmp_eq_u32_e64 s[0:1], 0, v0
	s_mov_b64 s[6:7], exec
	s_nop 0
	v_writelane_b32 v253, s0, 12
	s_nop 1
	v_writelane_b32 v253, s1, 13
	s_and_b64 s[0:1], s[6:7], s[0:1]
	s_mov_b64 exec, s[0:1]
	s_cbranch_execz .LBB0_5
	s_mov_b64 s[8:9], exec
	v_mbcnt_lo_u32_b32 v1, s8, 0
	v_mbcnt_hi_u32_b32 v1, s9, v1
	v_cmp_eq_u32_e32 vcc, 0, v1
	s_and_b64 s[0:1], exec, vcc
	s_mov_b64 exec, s[0:1]
	s_cbranch_execz .LBB0_5
	v_readlane_b32 s0, v253, 11
	s_lshl_b32 s0, s0, 8
	s_bcnt1_i32_b64 s1, s[8:9]
	v_mov_b32_e32 v1, s0
	v_mov_b32_e32 v2, s1
	v_readlane_b32 s0, v253, 9
	v_readlane_b32 s1, v253, 10
	s_nop 4
	global_atomic_add v1, v2, s[0:1] offset:1024

; #define PG8_STAGE(bufoff, gbase, voff) do { _Pragma("unroll") for (int _i = 0; _i < 2; ++_i) \
;         __builtin_amdgcn_global_load_lds((const unsigned*)((const char*)(gbase) + (voff)[_i]), (PG8_LAS unsigned*)(lds + (bufoff) + ldsw + _i * 8192), 16, 0, 0); } while (0)
; #define PG8_LDA(dst, b, h) do { _Pragma("unroll") for (int m = 0; m < 4; ++m) _Pragma("unroll") for (int k = 0; k < 2; ++k) dst[m][k] = *(const PG8_LAS bf16x8*)(lds + PG8_SA(b, h) + aoff + m * 2048 + k * 1024); } while (0)
; #define PG8_LDB(dst, b, h) do { _Pragma("unroll") for (int n = 0; n < 2; ++n) _Pragma("unroll") for (int k = 0; k < 2; ++k) dst[n][k] = *(const PG8_LAS bf16x8*)(lds + PG8_SB(b, h) + boff + n * 2048 + k * 1024); } while (0)
; #define PG8_MMA(ai, bj, At, Bt) do { __builtin_amdgcn_s_setprio(1); _Pragma("unroll") for (int m = 0; m < 4; ++m) _Pragma("unroll") for (int n = 0; n < 2; ++n) _Pragma("unroll") for (int k = 0; k < 2; ++k) \
;         acc[ai][bj][m][n] = __builtin_amdgcn_mfma_f32_16x16x32_bf16(Bt[n][k], At[m][k], acc[ai][bj][m][n], 0, 0, 0); __builtin_amdgcn_s_setprio(0); } while (0)
; #define PG8_WAIT_V(n) asm volatile("s_waitcnt vmcnt(" #n ")" ::: "memory")
; #define PG8_WAIT_L(n) asm volatile("s_waitcnt lgkmcnt(" #n ")" ::: "memory")
; #define PG8_BAR __builtin_amdgcn_s_barrier()
; #define PG8_SCHED __builtin_amdgcn_sched_barrier(0)
; template <class Epi, class Sched, bool ALIGN_EPI = false, bool SP2 = false>
; __device__ __forceinline__ void gemm_phase(PG8_LAS unsigned char* lds, const Gemm g, const Sched& S, const Epi& E) {
;     ...
;             PG8_LDB(B0, 0, 0); PG8_LDB(B1, 0, 1); PG8_SCHED; PG8_LDA(At, 0, 0); PG8_STAGE(PG8_SA(1, 1), a1 + hstepA, voffA);
;             PG8_WAIT_V(8); PG8_WAIT_L(0); PG8_BAR; PG8_MMA(0, 0, At, B0); PG8_MMA(0, 1, At, B1); PG8_BAR; PG8_SCHED;
;     ...
;         for (int a = 0; a < 2; ++a)
; #pragma unroll
;             for (int b = 0; b < 2; ++b)
; #pragma unroll
;                 for (int m = 0; m < 4; ++m)
; #pragma unroll
;                     for (int n = 0; n < 2; ++n) acc[a][b][m][n] = (f32x4){0.f, 0.f, 0.f, 0.f};
;         cur = nxt; cA = nA; cB = nB; ++ui;
;         if constexpr (ALIGN_EPI) { if (wr == 1) PG8_BAR; }
.LBB0_144:
	s_ashr_i32 s21, s20, 31
	s_lshl_b64 s[0:1], s[20:21], 19
	v_readlane_b32 s22, v253, 23
	v_readlane_b32 s23, v253, 24
	s_add_u32 s22, s22, s0
	s_addc_u32 s23, s23, s1
	s_and_b64 s[0:1], s[6:7], exec
	s_cselect_b32 s5, s23, s29
	s_cselect_b32 s21, s22, s28
	s_ashr_i32 s19, s18, 31
	s_lshl_b64 s[0:1], s[18:19], 19
	s_add_u32 s24, s8, s0
	s_addc_u32 s25, s9, s1
	s_and_b64 s[0:1], s[6:7], exec
	s_cselect_b32 s19, s25, s31
	s_cselect_b32 s48, s24, s30
	s_add_u32 s28, s28, 0x40080
	s_addc_u32 s29, s29, 0
	s_add_u32 s49, s30, 0x100
	v_mov_b32_e32 v2, 0
	s_addc_u32 s50, s31, 0
	s_mov_b32 s51, -2
	v_mov_b32_e32 v3, v2
	v_mov_b32_e32 v4, v2
	v_mov_b32_e32 v5, v2
	v_mov_b32_e32 v6, v2
	v_mov_b32_e32 v7, v2
	v_mov_b32_e32 v8, v2
	v_mov_b32_e32 v9, v2
	v_mov_b32_e32 v10, v2
	v_mov_b32_e32 v11, v2
	v_mov_b32_e32 v12, v2
	v_mov_b32_e32 v13, v2
	v_mov_b32_e32 v18, v2
	v_mov_b32_e32 v19, v2
	v_mov_b32_e32 v20, v2
	v_mov_b32_e32 v21, v2
	v_mov_b32_e32 v26, v2
	v_mov_b32_e32 v27, v2
	v_mov_b32_e32 v28, v2
	v_mov_b32_e32 v29, v2
	v_mov_b32_e32 v34, v2
	v_mov_b32_e32 v35, v2
	v_mov_b32_e32 v36, v2
	v_mov_b32_e32 v37, v2
	v_mov_b32_e32 v42, v2
	v_mov_b32_e32 v43, v2
	v_mov_b32_e32 v44, v2
	v_mov_b32_e32 v45, v2
	v_mov_b32_e32 v50, v2
	v_mov_b32_e32 v51, v2
	v_mov_b32_e32 v52, v2
	v_mov_b32_e32 v53, v2
	v_mov_b32_e32 v14, v2
	v_mov_b32_e32 v15, v2
	v_mov_b32_e32 v16, v2
	v_mov_b32_e32 v17, v2
	v_mov_b32_e32 v22, v2
	v_mov_b32_e32 v23, v2
	v_mov_b32_e32 v24, v2
	v_mov_b32_e32 v25, v2
	v_mov_b32_e32 v30, v2
	v_mov_b32_e32 v31, v2
	v_mov_b32_e32 v32, v2
	v_mov_b32_e32 v33, v2
	v_mov_b32_e32 v38, v2
	v_mov_b32_e32 v39, v2
	v_mov_b32_e32 v40, v2
	v_mov_b32_e32 v41, v2
	v_mov_b32_e32 v46, v2
	v_mov_b32_e32 v47, v2
	v_mov_b32_e32 v48, v2
	v_mov_b32_e32 v49, v2
	v_mov_b32_e32 v54, v2
	v_mov_b32_e32 v55, v2
	v_mov_b32_e32 v56, v2
	v_mov_b32_e32 v57, v2
	v_mov_b32_e32 v58, v2
	v_mov_b32_e32 v59, v2
	v_mov_b32_e32 v60, v2
	v_mov_b32_e32 v61, v2
	v_mov_b32_e32 v62, v2
	v_mov_b32_e32 v63, v2
	v_mov_b32_e32 v64, v2
	v_mov_b32_e32 v65, v2
	v_mov_b32_e32 v66, v2
	v_mov_b32_e32 v67, v2
	v_mov_b32_e32 v68, v2
	v_mov_b32_e32 v69, v2
	v_mov_b32_e32 v70, v2
	v_mov_b32_e32 v71, v2
	v_mov_b32_e32 v72, v2
	v_mov_b32_e32 v73, v2
	v_mov_b32_e32 v74, v2
	v_mov_b32_e32 v75, v2
	v_mov_b32_e32 v76, v2
	v_mov_b32_e32 v77, v2
	v_mov_b32_e32 v82, v2
	v_mov_b32_e32 v83, v2
	v_mov_b32_e32 v84, v2
	v_mov_b32_e32 v85, v2
	v_mov_b32_e32 v90, v2
	v_mov_b32_e32 v91, v2
	v_mov_b32_e32 v92, v2
	v_mov_b32_e32 v93, v2
	v_mov_b32_e32 v98, v2
	v_mov_b32_e32 v99, v2
	v_mov_b32_e32 v100, v2
	v_mov_b32_e32 v101, v2
	v_mov_b32_e32 v106, v2
	v_mov_b32_e32 v107, v2
	v_mov_b32_e32 v108, v2
	v_mov_b32_e32 v109, v2
	v_mov_b32_e32 v114, v2
	v_mov_b32_e32 v115, v2
	v_mov_b32_e32 v116, v2
	v_mov_b32_e32 v117, v2
	v_mov_b32_e32 v78, v2
	v_mov_b32_e32 v79, v2
	v_mov_b32_e32 v80, v2
	v_mov_b32_e32 v81, v2
	v_mov_b32_e32 v86, v2
	v_mov_b32_e32 v87, v2
	v_mov_b32_e32 v88, v2
	v_mov_b32_e32 v89, v2
	v_mov_b32_e32 v94, v2
	v_mov_b32_e32 v95, v2
	v_mov_b32_e32 v96, v2
	v_mov_b32_e32 v97, v2
	v_mov_b32_e32 v102, v2
	v_mov_b32_e32 v103, v2
	v_mov_b32_e32 v104, v2
	v_mov_b32_e32 v105, v2
	v_mov_b32_e32 v110, v2
	v_mov_b32_e32 v111, v2
	v_mov_b32_e32 v112, v2
	v_mov_b32_e32 v113, v2
	v_mov_b32_e32 v118, v2
	v_mov_b32_e32 v119, v2
	v_mov_b32_e32 v120, v2
	v_mov_b32_e32 v121, v2
	v_mov_b32_e32 v122, v2
	v_mov_b32_e32 v123, v2
	v_mov_b32_e32 v124, v2
	v_mov_b32_e32 v125, v2
	v_mov_b32_e32 v126, v2
	v_mov_b32_e32 v127, v2
	v_mov_b32_e32 v128, v2
	v_mov_b32_e32 v129, v2
	s_cmp_eq_u32 s98, 1
	s_cbranch_scc0 .Ldefer_0
	s_barrier
	s_mov_b32 s98, 0
.Ldefer_0:
.LBB0_145:
	ds_read_b128 v[146:149], v151
	ds_read_b128 v[156:159], v151 offset:1024
	ds_read_b128 v[160:163], v151 offset:2048
	ds_read_b128 v[164:167], v151 offset:3072
	ds_read_b128 v[168:171], v152
	ds_read_b128 v[172:175], v152 offset:1024
	ds_read_b128 v[176:179], v152 offset:2048
	ds_read_b128 v[180:183], v152 offset:3072
	s_add_u32 s0, s28, 0xfffc0080
	s_addc_u32 s1, s29, -1
	s_cmp_eq_u32 s51, 12
	s_cselect_b32 s35, s5, s1
	s_cselect_b32 s34, s21, s0
	s_cselect_b32 s31, s19, s50
	s_cselect_b32 s30, s48, s49
	v_lshl_add_u64 v[216:217], s[28:29], 0, v[138:139]
	s_add_i32 m0, s27, 0xc000
	ds_read_b128 v[184:187], v153
	ds_read_b128 v[188:191], v153 offset:1024
	ds_read_b128 v[192:195], v153 offset:2048
	ds_read_b128 v[196:199], v153 offset:3072
	ds_read_b128 v[200:203], v153 offset:4096
	ds_read_b128 v[204:207], v153 offset:5120
	ds_read_b128 v[208:211], v153 offset:6144
	ds_read_b128 v[212:215], v153 offset:7168
	global_load_lds_dwordx4 v[216:217], off
	v_lshl_add_u64 v[216:217], s[28:29], 0, v[140:141]
	s_add_i32 m0, s27, 0xe000
	s_nop 0
	global_load_lds_dwordx4 v[216:217], off
	s_waitcnt vmcnt(8)
	s_waitcnt lgkmcnt(0)
	s_setprio 1
	s_barrier
; #define PG8_STAGE(bufoff, gbase, voff) do { _Pragma("unroll") for (int _i = 0; _i < 2; ++_i) \
;         __builtin_amdgcn_global_load_lds((const unsigned*)((const char*)(gbase) + (voff)[_i]), (PG8_LAS unsigned*)(lds + (bufoff) + ldsw + _i * 8192), 16, 0, 0); } while (0)
; #define PG8_LDA(dst, b, h) do { _Pragma("unroll") for (int m = 0; m < 4; ++m) _Pragma("unroll") for (int k = 0; k < 2; ++k) dst[m][k] = *(const PG8_LAS bf16x8*)(lds + PG8_SA(b, h) + aoff + m * 2048 + k * 1024); } while (0)
; #define PG8_LDB(dst, b, h) do { _Pragma("unroll") for (int n = 0; n < 2; ++n) _Pragma("unroll") for (int k = 0; k < 2; ++k) dst[n][k] = *(const PG8_LAS bf16x8*)(lds + PG8_SB(b, h) + boff + n * 2048 + k * 1024); } while (0)
; #define PG8_MMA(ai, bj, At, Bt) do { __builtin_amdgcn_s_setprio(1); _Pragma("unroll") for (int m = 0; m < 4; ++m) _Pragma("unroll") for (int n = 0; n < 2; ++n) _Pragma("unroll") for (int k = 0; k < 2; ++k) \
;         acc[ai][bj][m][n] = __builtin_amdgcn_mfma_f32_16x16x32_bf16(Bt[n][k], At[m][k], acc[ai][bj][m][n], 0, 0, 0); __builtin_amdgcn_s_setprio(0); } while (0)
; #define PG8_WAIT_V(n) asm volatile("s_waitcnt vmcnt(" #n ")" ::: "memory")
; #define PG8_WAIT_L(n) asm volatile("s_waitcnt lgkmcnt(" #n ")" ::: "memory")
; #define PG8_BAR __builtin_amdgcn_s_barrier()
; #define PG8_SCHED __builtin_amdgcn_sched_barrier(0)
; template <class Epi, class Sched, bool ALIGN_EPI = false, bool SP2 = false>
; __device__ __forceinline__ void gemm_phase(PG8_LAS unsigned char* lds, const Gemm g, const Sched& S, const Epi& E) {
;     ...
;             PG8_LDB(B0, 0, 0); PG8_LDB(B1, 0, 1); PG8_SCHED; PG8_LDA(At, 0, 0); PG8_STAGE(PG8_SA(1, 1), a1 + hstepA, voffA);
;             PG8_WAIT_V(8); PG8_WAIT_L(0); PG8_BAR; PG8_MMA(0, 0, At, B0); PG8_MMA(0, 1, At, B1); PG8_BAR; PG8_SCHED;
;             PG8_LDA(At, 0, 1); PG8_STAGE(PG8_SB(0, 0), b2, voffB); PG8_STAGE(PG8_SB(0, 1), b2 + hstepB, voffB); PG8_STAGE(PG8_SA(0, 0), a2, voffA);
;             PG8_WAIT_V(8); PG8_WAIT_L(0); PG8_BAR; PG8_MMA(1, 0, At, B0); PG8_MMA(1, 1, At, B1); PG8_BAR; PG8_SCHED;
	v_mfma_f32_16x16x32_bf16 v[126:129], v[146:149], v[184:187], v[126:129]
	v_mfma_f32_16x16x32_bf16 v[122:125], v[160:163], v[184:187], v[122:125]
	v_mfma_f32_16x16x32_bf16 v[118:121], v[146:149], v[192:195], v[118:121]
	v_mfma_f32_16x16x32_bf16 v[110:113], v[160:163], v[192:195], v[110:113]
	v_mfma_f32_16x16x32_bf16 v[102:105], v[146:149], v[200:203], v[102:105]
	v_mfma_f32_16x16x32_bf16 v[94:97], v[160:163], v[200:203], v[94:97]
	v_mfma_f32_16x16x32_bf16 v[86:89], v[146:149], v[208:211], v[86:89]
	v_mfma_f32_16x16x32_bf16 v[78:81], v[160:163], v[208:211], v[78:81]
	v_mfma_f32_16x16x32_bf16 v[126:129], v[156:159], v[188:191], v[126:129]
	v_mfma_f32_16x16x32_bf16 v[122:125], v[164:167], v[188:191], v[122:125]
	v_mfma_f32_16x16x32_bf16 v[118:121], v[156:159], v[196:199], v[118:121]
	v_mfma_f32_16x16x32_bf16 v[110:113], v[164:167], v[196:199], v[110:113]
	v_mfma_f32_16x16x32_bf16 v[102:105], v[156:159], v[204:207], v[102:105]
	v_mfma_f32_16x16x32_bf16 v[94:97], v[164:167], v[204:207], v[94:97]
	v_mfma_f32_16x16x32_bf16 v[86:89], v[156:159], v[212:215], v[86:89]
	v_mfma_f32_16x16x32_bf16 v[78:81], v[164:167], v[212:215], v[78:81]
	s_setprio 0
	s_setprio 1
	v_mfma_f32_16x16x32_bf16 v[114:117], v[168:171], v[184:187], v[114:117]
	v_mfma_f32_16x16x32_bf16 v[106:109], v[176:179], v[184:187], v[106:109]
	v_mfma_f32_16x16x32_bf16 v[98:101], v[168:171], v[192:195], v[98:101]
	v_mfma_f32_16x16x32_bf16 v[90:93], v[176:179], v[192:195], v[90:93]
	v_mfma_f32_16x16x32_bf16 v[82:85], v[168:171], v[200:203], v[82:85]
	v_mfma_f32_16x16x32_bf16 v[74:77], v[176:179], v[200:203], v[74:77]
	v_mfma_f32_16x16x32_bf16 v[70:73], v[168:171], v[208:211], v[70:73]
	v_mfma_f32_16x16x32_bf16 v[66:69], v[176:179], v[208:211], v[66:69]
	v_mfma_f32_16x16x32_bf16 v[114:117], v[172:175], v[188:191], v[114:117]
	v_mfma_f32_16x16x32_bf16 v[106:109], v[180:183], v[188:191], v[106:109]
	v_mfma_f32_16x16x32_bf16 v[98:101], v[172:175], v[196:199], v[98:101]
	v_mfma_f32_16x16x32_bf16 v[90:93], v[180:183], v[196:199], v[90:93]
	v_mfma_f32_16x16x32_bf16 v[82:85], v[172:175], v[204:207], v[82:85]
	v_mfma_f32_16x16x32_bf16 v[74:77], v[180:183], v[204:207], v[74:77]
	v_mfma_f32_16x16x32_bf16 v[70:73], v[172:175], v[212:215], v[70:73]
	v_mfma_f32_16x16x32_bf16 v[66:69], v[180:183], v[212:215], v[66:69]
	s_setprio 0
	s_barrier
	s_add_i32 s0, s43, s3
	v_lshl_add_u64 v[216:217], s[30:31], 0, v[134:135]
	s_mov_b32 m0, s0
	ds_read_b128 v[184:187], v153 offset:16384
	ds_read_b128 v[188:191], v153 offset:17408
	ds_read_b128 v[192:195], v153 offset:18432
	ds_read_b128 v[196:199], v153 offset:19456
	ds_read_b128 v[200:203], v153 offset:20480
	ds_read_b128 v[204:207], v153 offset:21504
	ds_read_b128 v[208:211], v153 offset:22528
	ds_read_b128 v[212:215], v153 offset:23552
	global_load_lds_dwordx4 v[216:217], off
	s_add_i32 m0, s0, 0x2000
	s_add_u32 s0, s30, 0x40000
	v_lshl_add_u64 v[218:219], s[30:31], 0, v[130:131]
	s_addc_u32 s1, s31, 0
	s_add_i32 s2, s44, s3
	global_load_lds_dwordx4 v[218:219], off
	v_lshl_add_u64 v[220:221], s[0:1], 0, v[134:135]
	s_mov_b32 m0, s2
	v_lshl_add_u64 v[222:223], s[34:35], 0, v[132:133]
	global_load_lds_dwordx4 v[220:221], off
	v_lshl_add_u64 v[220:221], s[0:1], 0, v[130:131]
	s_add_i32 m0, s2, 0x2000
	s_nop 0
	global_load_lds_dwordx4 v[220:221], off
	v_lshl_add_u64 v[220:221], s[34:35], 0, v[136:137]
	s_mov_b32 m0, s27
	s_nop 0
	global_load_lds_dwordx4 v[220:221], off
	s_mov_b32 m0, s36
	s_nop 0
	global_load_lds_dwordx4 v[222:223], off
	s_waitcnt vmcnt(8)
	s_waitcnt lgkmcnt(0)
	s_setprio 1
	s_barrier
	v_mfma_f32_16x16x32_bf16 v[62:65], v[146:149], v[184:187], v[62:65]
	v_mfma_f32_16x16x32_bf16 v[58:61], v[160:163], v[184:187], v[58:61]
	v_mfma_f32_16x16x32_bf16 v[54:57], v[146:149], v[192:195], v[54:57]
	v_mfma_f32_16x16x32_bf16 v[46:49], v[160:163], v[192:195], v[46:49]
	v_mfma_f32_16x16x32_bf16 v[38:41], v[146:149], v[200:203], v[38:41]
	v_mfma_f32_16x16x32_bf16 v[30:33], v[160:163], v[200:203], v[30:33]
	v_mfma_f32_16x16x32_bf16 v[22:25], v[146:149], v[208:211], v[22:25]
	v_mfma_f32_16x16x32_bf16 v[14:17], v[160:163], v[208:211], v[14:17]
	v_mfma_f32_16x16x32_bf16 v[62:65], v[156:159], v[188:191], v[62:65]
	v_mfma_f32_16x16x32_bf16 v[58:61], v[164:167], v[188:191], v[58:61]
	v_mfma_f32_16x16x32_bf16 v[54:57], v[156:159], v[196:199], v[54:57]
	v_mfma_f32_16x16x32_bf16 v[46:49], v[164:167], v[196:199], v[46:49]
	v_mfma_f32_16x16x32_bf16 v[38:41], v[156:159], v[204:207], v[38:41]
	v_mfma_f32_16x16x32_bf16 v[30:33], v[164:167], v[204:207], v[30:33]
	v_mfma_f32_16x16x32_bf16 v[22:25], v[156:159], v[212:215], v[22:25]
	v_mfma_f32_16x16x32_bf16 v[14:17], v[164:167], v[212:215], v[14:17]
	s_setprio 0
	s_setprio 1
	v_mfma_f32_16x16x32_bf16 v[50:53], v[168:171], v[184:187], v[50:53]
	v_mfma_f32_16x16x32_bf16 v[42:45], v[176:179], v[184:187], v[42:45]
	v_mfma_f32_16x16x32_bf16 v[34:37], v[168:171], v[192:195], v[34:37]
	v_mfma_f32_16x16x32_bf16 v[26:29], v[176:179], v[192:195], v[26:29]
	v_mfma_f32_16x16x32_bf16 v[18:21], v[168:171], v[200:203], v[18:21]
	v_mfma_f32_16x16x32_bf16 v[10:13], v[176:179], v[200:203], v[10:13]
	v_mfma_f32_16x16x32_bf16 v[6:9], v[168:171], v[208:211], v[6:9]
	v_mfma_f32_16x16x32_bf16 v[2:5], v[176:179], v[208:211], v[2:5]
	v_mfma_f32_16x16x32_bf16 v[50:53], v[172:175], v[188:191], v[50:53]
	v_mfma_f32_16x16x32_bf16 v[42:45], v[180:183], v[188:191], v[42:45]
	v_mfma_f32_16x16x32_bf16 v[34:37], v[172:175], v[196:199], v[34:37]
	v_mfma_f32_16x16x32_bf16 v[26:29], v[180:183], v[196:199], v[26:29]
	v_mfma_f32_16x16x32_bf16 v[18:21], v[172:175], v[204:207], v[18:21]
	v_mfma_f32_16x16x32_bf16 v[10:13], v[180:183], v[204:207], v[10:13]
	v_mfma_f32_16x16x32_bf16 v[6:9], v[172:175], v[212:215], v[6:9]
	v_mfma_f32_16x16x32_bf16 v[2:5], v[180:183], v[212:215], v[2:5]
	s_setprio 0
	s_barrier
; #define PG8_STAGE(bufoff, gbase, voff) do { _Pragma("unroll") for (int _i = 0; _i < 2; ++_i) \
;         __builtin_amdgcn_global_load_lds((const unsigned*)((const char*)(gbase) + (voff)[_i]), (PG8_LAS unsigned*)(lds + (bufoff) + ldsw + _i * 8192), 16, 0, 0); } while (0)
; #define PG8_LDA(dst, b, h) do { _Pragma("unroll") for (int m = 0; m < 4; ++m) _Pragma("unroll") for (int k = 0; k < 2; ++k) dst[m][k] = *(const PG8_LAS bf16x8*)(lds + PG8_SA(b, h) + aoff + m * 2048 + k * 1024); } while (0)
; #define PG8_LDB(dst, b, h) do { _Pragma("unroll") for (int n = 0; n < 2; ++n) _Pragma("unroll") for (int k = 0; k < 2; ++k) dst[n][k] = *(const PG8_LAS bf16x8*)(lds + PG8_SB(b, h) + boff + n * 2048 + k * 1024); } while (0)
; #define PG8_MMA(ai, bj, At, Bt) do { __builtin_amdgcn_s_setprio(1); _Pragma("unroll") for (int m = 0; m < 4; ++m) _Pragma("unroll") for (int n = 0; n < 2; ++n) _Pragma("unroll") for (int k = 0; k < 2; ++k) \
;         acc[ai][bj][m][n] = __builtin_amdgcn_mfma_f32_16x16x32_bf16(Bt[n][k], At[m][k], acc[ai][bj][m][n], 0, 0, 0); __builtin_amdgcn_s_setprio(0); } while (0)
; #define PG8_WAIT_V(n) asm volatile("s_waitcnt vmcnt(" #n ")" ::: "memory")
; #define PG8_WAIT_L(n) asm volatile("s_waitcnt lgkmcnt(" #n ")" ::: "memory")
; #define PG8_BAR __builtin_amdgcn_s_barrier()
; #define PG8_SCHED __builtin_amdgcn_sched_barrier(0)
; template <class Epi, class Sched, bool ALIGN_EPI = false, bool SP2 = false>
; __device__ __forceinline__ void gemm_phase(PG8_LAS unsigned char* lds, const Gemm g, const Sched& S, const Epi& E) {
;     ...
;             PG8_LDB(B0, 1, 0); PG8_LDB(B1, 1, 1); PG8_SCHED; PG8_LDA(At, 1, 0); PG8_STAGE(PG8_SA(0, 1), a2 + hstepA, voffA);
;             PG8_WAIT_V(8); PG8_WAIT_L(0); PG8_BAR; PG8_MMA(0, 0, At, B0); PG8_MMA(0, 1, At, B1); PG8_BAR; PG8_SCHED;
;             PG8_LDA(At, 1, 1); PG8_STAGE(PG8_SB(1, 0), b3, voffB); PG8_STAGE(PG8_SB(1, 1), b3 + hstepB, voffB); PG8_STAGE(PG8_SA(1, 0), a3, voffA);
;             PG8_WAIT_V(8); PG8_WAIT_L(0); PG8_BAR; PG8_MMA(1, 0, At, B0); PG8_MMA(1, 1, At, B1); PG8_BAR; PG8_SCHED;
;     ...
;         if constexpr (ALIGN_EPI) { if (wr == 0) PG8_BAR; }
	ds_read_b128 v[146:149], v154
	ds_read_b128 v[156:159], v154 offset:1024
	ds_read_b128 v[160:163], v154 offset:2048
	ds_read_b128 v[164:167], v154 offset:3072
	ds_read_b128 v[168:171], v155
	ds_read_b128 v[172:175], v155 offset:1024
	ds_read_b128 v[176:179], v155 offset:2048
	ds_read_b128 v[180:183], v155 offset:3072
	s_add_u32 s0, s34, 0x40000
	s_addc_u32 s1, s35, 0
	s_mov_b32 m0, s37
	v_lshl_add_u64 v[224:225], s[0:1], 0, v[136:137]
	ds_read_b128 v[184:187], v153 offset:32768
	ds_read_b128 v[188:191], v153 offset:33792
	ds_read_b128 v[192:195], v153 offset:34816
	ds_read_b128 v[196:199], v153 offset:35840
	ds_read_b128 v[200:203], v153 offset:36864
	ds_read_b128 v[204:207], v153 offset:37888
	ds_read_b128 v[208:211], v153 offset:38912
	ds_read_b128 v[212:215], v153 offset:39936
	global_load_lds_dwordx4 v[224:225], off
	v_lshl_add_u64 v[224:225], s[0:1], 0, v[132:133]
	s_mov_b32 m0, s38
	s_nop 0
	global_load_lds_dwordx4 v[224:225], off
	s_waitcnt vmcnt(8)
	s_waitcnt lgkmcnt(0)
	s_setprio 1
	s_barrier
	v_mfma_f32_16x16x32_bf16 v[126:129], v[146:149], v[184:187], v[126:129]
	v_mfma_f32_16x16x32_bf16 v[122:125], v[160:163], v[184:187], v[122:125]
	v_mfma_f32_16x16x32_bf16 v[118:121], v[146:149], v[192:195], v[118:121]
	v_mfma_f32_16x16x32_bf16 v[110:113], v[160:163], v[192:195], v[110:113]
	v_mfma_f32_16x16x32_bf16 v[102:105], v[146:149], v[200:203], v[102:105]
	v_mfma_f32_16x16x32_bf16 v[94:97], v[160:163], v[200:203], v[94:97]
	v_mfma_f32_16x16x32_bf16 v[86:89], v[146:149], v[208:211], v[86:89]
	v_mfma_f32_16x16x32_bf16 v[78:81], v[160:163], v[208:211], v[78:81]
	v_mfma_f32_16x16x32_bf16 v[126:129], v[156:159], v[188:191], v[126:129]
	v_mfma_f32_16x16x32_bf16 v[122:125], v[164:167], v[188:191], v[122:125]
	v_mfma_f32_16x16x32_bf16 v[118:121], v[156:159], v[196:199], v[118:121]
	v_mfma_f32_16x16x32_bf16 v[110:113], v[164:167], v[196:199], v[110:113]
	v_mfma_f32_16x16x32_bf16 v[102:105], v[156:159], v[204:207], v[102:105]
	v_mfma_f32_16x16x32_bf16 v[94:97], v[164:167], v[204:207], v[94:97]
	v_mfma_f32_16x16x32_bf16 v[86:89], v[156:159], v[212:215], v[86:89]
	v_mfma_f32_16x16x32_bf16 v[78:81], v[164:167], v[212:215], v[78:81]
	s_setprio 0
	s_setprio 1
	v_mfma_f32_16x16x32_bf16 v[114:117], v[168:171], v[184:187], v[114:117]
	v_mfma_f32_16x16x32_bf16 v[106:109], v[176:179], v[184:187], v[106:109]
	v_mfma_f32_16x16x32_bf16 v[98:101], v[168:171], v[192:195], v[98:101]
	v_mfma_f32_16x16x32_bf16 v[90:93], v[176:179], v[192:195], v[90:93]
	v_mfma_f32_16x16x32_bf16 v[82:85], v[168:171], v[200:203], v[82:85]
	v_mfma_f32_16x16x32_bf16 v[74:77], v[176:179], v[200:203], v[74:77]
	v_mfma_f32_16x16x32_bf16 v[70:73], v[168:171], v[208:211], v[70:73]
	v_mfma_f32_16x16x32_bf16 v[66:69], v[176:179], v[208:211], v[66:69]
	v_mfma_f32_16x16x32_bf16 v[114:117], v[172:175], v[188:191], v[114:117]
	v_mfma_f32_16x16x32_bf16 v[106:109], v[180:183], v[188:191], v[106:109]
	v_mfma_f32_16x16x32_bf16 v[98:101], v[172:175], v[196:199], v[98:101]
	v_mfma_f32_16x16x32_bf16 v[90:93], v[180:183], v[196:199], v[90:93]
	v_mfma_f32_16x16x32_bf16 v[82:85], v[172:175], v[204:207], v[82:85]
	v_mfma_f32_16x16x32_bf16 v[74:77], v[180:183], v[204:207], v[74:77]
	v_mfma_f32_16x16x32_bf16 v[70:73], v[172:175], v[212:215], v[70:73]
	v_mfma_f32_16x16x32_bf16 v[66:69], v[180:183], v[212:215], v[66:69]
	s_setprio 0
	s_barrier
	s_add_i32 s0, s45, s3
	v_lshl_add_u64 v[216:217], v[216:217], 0, s[10:11]
	s_mov_b32 m0, s0
	ds_read_b128 v[184:187], v153 offset:49152
	ds_read_b128 v[188:191], v153 offset:50176
	ds_read_b128 v[192:195], v153 offset:51200
	ds_read_b128 v[196:199], v153 offset:52224
	ds_read_b128 v[200:203], v153 offset:53248
	ds_read_b128 v[204:207], v153 offset:54272
	ds_read_b128 v[208:211], v153 offset:55296
	ds_read_b128 v[212:215], v153 offset:56320
	global_load_lds_dwordx4 v[216:217], off
	s_add_i32 m0, s0, 0x2000
	s_add_u32 s0, s30, 0x40080
	v_lshl_add_u64 v[216:217], v[218:219], 0, s[10:11]
	s_addc_u32 s1, s31, 0
	s_add_i32 s2, s46, s3
	global_load_lds_dwordx4 v[216:217], off
	v_lshl_add_u64 v[216:217], s[0:1], 0, v[134:135]
	s_mov_b32 m0, s2
	s_nop 0
	global_load_lds_dwordx4 v[216:217], off
	v_lshl_add_u64 v[216:217], s[0:1], 0, v[130:131]
	s_add_i32 m0, s2, 0x2000
	s_nop 0
	global_load_lds_dwordx4 v[216:217], off
	v_lshl_add_u64 v[216:217], v[220:221], 0, s[10:11]
	s_mov_b32 m0, s39
	s_nop 0
	global_load_lds_dwordx4 v[216:217], off
	v_lshl_add_u64 v[216:217], v[222:223], 0, s[10:11]
	s_mov_b32 m0, s40
	s_nop 0
	global_load_lds_dwordx4 v[216:217], off
	s_waitcnt vmcnt(8)
	s_waitcnt lgkmcnt(0)
	s_setprio 1
	s_barrier
	v_mfma_f32_16x16x32_bf16 v[62:65], v[146:149], v[184:187], v[62:65]
	v_mfma_f32_16x16x32_bf16 v[58:61], v[160:163], v[184:187], v[58:61]
	v_mfma_f32_16x16x32_bf16 v[54:57], v[146:149], v[192:195], v[54:57]
	v_mfma_f32_16x16x32_bf16 v[46:49], v[160:163], v[192:195], v[46:49]
	v_mfma_f32_16x16x32_bf16 v[38:41], v[146:149], v[200:203], v[38:41]
	v_mfma_f32_16x16x32_bf16 v[30:33], v[160:163], v[200:203], v[30:33]
	v_mfma_f32_16x16x32_bf16 v[22:25], v[146:149], v[208:211], v[22:25]
	v_mfma_f32_16x16x32_bf16 v[14:17], v[160:163], v[208:211], v[14:17]
	v_mfma_f32_16x16x32_bf16 v[62:65], v[156:159], v[188:191], v[62:65]
	v_mfma_f32_16x16x32_bf16 v[58:61], v[164:167], v[188:191], v[58:61]
	v_mfma_f32_16x16x32_bf16 v[54:57], v[156:159], v[196:199], v[54:57]
	v_mfma_f32_16x16x32_bf16 v[46:49], v[164:167], v[196:199], v[46:49]
	v_mfma_f32_16x16x32_bf16 v[38:41], v[156:159], v[204:207], v[38:41]
	v_mfma_f32_16x16x32_bf16 v[30:33], v[164:167], v[204:207], v[30:33]
	v_mfma_f32_16x16x32_bf16 v[22:25], v[156:159], v[212:215], v[22:25]
	v_mfma_f32_16x16x32_bf16 v[14:17], v[164:167], v[212:215], v[14:17]
	s_setprio 0
	s_setprio 1
	v_mfma_f32_16x16x32_bf16 v[50:53], v[168:171], v[184:187], v[50:53]
	v_mfma_f32_16x16x32_bf16 v[42:45], v[176:179], v[184:187], v[42:45]
	v_mfma_f32_16x16x32_bf16 v[34:37], v[168:171], v[192:195], v[34:37]
	v_mfma_f32_16x16x32_bf16 v[26:29], v[176:179], v[192:195], v[26:29]
	v_mfma_f32_16x16x32_bf16 v[18:21], v[168:171], v[200:203], v[18:21]
	v_mfma_f32_16x16x32_bf16 v[10:13], v[176:179], v[200:203], v[10:13]
	v_mfma_f32_16x16x32_bf16 v[6:9], v[168:171], v[208:211], v[6:9]
	v_mfma_f32_16x16x32_bf16 v[2:5], v[176:179], v[208:211], v[2:5]
	v_mfma_f32_16x16x32_bf16 v[50:53], v[172:175], v[188:191], v[50:53]
	v_mfma_f32_16x16x32_bf16 v[42:45], v[180:183], v[188:191], v[42:45]
	v_mfma_f32_16x16x32_bf16 v[34:37], v[172:175], v[196:199], v[34:37]
	v_mfma_f32_16x16x32_bf16 v[26:29], v[180:183], v[196:199], v[26:29]
	v_mfma_f32_16x16x32_bf16 v[18:21], v[172:175], v[204:207], v[18:21]
	v_mfma_f32_16x16x32_bf16 v[10:13], v[180:183], v[204:207], v[10:13]
	v_mfma_f32_16x16x32_bf16 v[6:9], v[172:175], v[212:215], v[6:9]
	v_mfma_f32_16x16x32_bf16 v[2:5], v[180:183], v[212:215], v[2:5]
	s_setprio 0
	s_barrier
	s_add_i32 s51, s51, 2
	s_add_u32 s28, s28, 0x100
	s_addc_u32 s29, s29, 0
	s_add_u32 s49, s49, 0x100
	s_addc_u32 s50, s50, 0
	s_cmp_gt_u32 s51, 13
	s_cbranch_scc0 .LBB0_145
	s_and_b64 vcc, exec, s[16:17]
	s_cbranch_vccz .LBB0_148
	s_barrier
; __device__ __forceinline__ unsigned cvt_pk_bf16(float lo, float hi) { unsigned r; asm volatile("v_cvt_pk_bf16_f32 %0, %1, %2" : "=v"(r) : "v"(lo), "v"(hi)); return r; }
; #define PG8_BAR __builtin_amdgcn_s_barrier()
;     __device__ __forceinline__ void operator()(const f32x4 (&acc)[2][2][4][2], const Unit& u, int wr, int wc, int fr, int fq) const {
;         const int row0 = u.pm * BM + wr * 64 + fr, col0 = u.pn * BM + wc * 32 + 8 * fq;
;         float scv[2][4];
; #pragma unroll
;         for (int ai = 0; ai < 2; ++ai)
; #pragma unroll
;             for (int m = 0; m < 4; ++m) scv[ai][m] = rowscale ? rowscale[(size_t)(row0 + ai * HALF + m * 16) * rs_stride] : 1.f;
; #pragma unroll
;         for (int ai = 0; ai < 2; ++ai)
; #pragma unroll
;             for (int m = 0; m < 4; ++m) { const int row = row0 + ai * HALF + m * 16; const float sc = scv[ai][m];
;                 bf16_t* rowp = O + (size_t)row * ldc + col0;
; #pragma unroll
;                 for (int bj = 0; bj < 2; ++bj) { const f32x4 v0 = acc[ai][bj][m][0] * sc, v1 = acc[ai][bj][m][1] * sc;
;                     u32x4 w; w.x = cvt_pk_bf16(v0[0], v0[1]); w.y = cvt_pk_bf16(v0[2], v0[3]); w.z = cvt_pk_bf16(v1[0], v1[1]); w.w = cvt_pk_bf16(v1[2], v1[3]);
;                     *(u32x4*)(rowp + bj * HALF) = w; } }
;     }
; template <class Epi, class Sched, bool ALIGN_EPI = false, bool SP2 = false>
; __device__ __forceinline__ void gemm_phase(PG8_LAS unsigned char* lds, const Gemm g, const Sched& S, const Epi& E) {
;     ...
;         if (!has_next) break;
; #pragma unroll
;         for (int a = 0; a < 2; ++a)
; #pragma unroll
;             for (int b = 0; b < 2; ++b)
; #pragma unroll
;                 for (int m = 0; m < 4; ++m)
; #pragma unroll
;                     for (int n = 0; n < 2; ++n) acc[a][b][m][n] = (f32x4){0.f, 0.f, 0.f, 0.f};
;         cur = nxt; cA = nA; cB = nB; ++ui;
;         if constexpr (ALIGN_EPI) { if (wr == 1) PG8_BAR; }
.LBB0_148:
	v_readlane_b32 s0, v253, 25
	v_lshl_or_b32 v148, s4, 8, v150
	v_readlane_b32 s1, v253, 26
	v_lshl_add_u32 v158, s26, 8, v1
	v_ashrrev_i32_e32 v149, 31, v148
	v_mov_b64_e32 v[146:147], s[0:1]
	v_mad_i64_i32 v[156:157], s[0:1], v158, s47, v[146:147]
	v_lshlrev_b64 v[148:149], 1, v[148:149]
	v_lshl_add_u64 v[156:157], v[156:157], 0, v[148:149]
	v_cvt_pk_bf16_f32 v126, v126, v127
	v_cvt_pk_bf16_f32 v127, v128, v129
	v_cvt_pk_bf16_f32 v128, v122, v123
	v_cvt_pk_bf16_f32 v129, v124, v125
	global_store_dwordx4 v[156:157], v[126:129], off
	v_cvt_pk_bf16_f32 v114, v114, v115
	v_cvt_pk_bf16_f32 v115, v116, v117
	v_cvt_pk_bf16_f32 v116, v106, v107
	v_or_b32_e32 v106, 16, v158
	v_mad_i64_i32 v[106:107], s[0:1], v106, s47, v[146:147]
	v_cvt_pk_bf16_f32 v117, v108, v109
	global_store_dwordx4 v[156:157], v[114:117], off offset:256
	v_add_u32_e32 v159, 0x80, v158
	v_add_u32_e32 v160, 0xb0, v158
	v_lshl_add_u64 v[114:115], v[106:107], 0, v[148:149]
	v_cvt_pk_bf16_f32 v106, v118, v119
	v_cvt_pk_bf16_f32 v107, v120, v121
	v_cvt_pk_bf16_f32 v108, v110, v111
	v_cvt_pk_bf16_f32 v109, v112, v113
	global_store_dwordx4 v[114:115], v[106:109], off
	v_cvt_pk_bf16_f32 v98, v98, v99
	v_cvt_pk_bf16_f32 v99, v100, v101
	v_cvt_pk_bf16_f32 v100, v90, v91
	v_or_b32_e32 v90, 32, v158
	v_mad_i64_i32 v[90:91], s[0:1], v90, s47, v[146:147]
	v_cvt_pk_bf16_f32 v101, v92, v93
	global_store_dwordx4 v[114:115], v[98:101], off offset:256
	s_andn2_b64 vcc, exec, s[6:7]
	s_mov_b64 s[6:7], -1
	v_lshl_add_u64 v[98:99], v[90:91], 0, v[148:149]
	v_cvt_pk_bf16_f32 v90, v102, v103
	v_cvt_pk_bf16_f32 v91, v104, v105
	v_cvt_pk_bf16_f32 v92, v94, v95
	v_cvt_pk_bf16_f32 v93, v96, v97
	global_store_dwordx4 v[98:99], v[90:93], off
	v_cvt_pk_bf16_f32 v82, v82, v83
	v_cvt_pk_bf16_f32 v83, v84, v85
	v_cvt_pk_bf16_f32 v84, v74, v75
	v_or_b32_e32 v74, 48, v158
	v_mad_i64_i32 v[74:75], s[0:1], v74, s47, v[146:147]
	v_cvt_pk_bf16_f32 v85, v76, v77
	global_store_dwordx4 v[98:99], v[82:85], off offset:256
	s_nop 1
	v_lshl_add_u64 v[82:83], v[74:75], 0, v[148:149]
	v_cvt_pk_bf16_f32 v74, v86, v87
	v_cvt_pk_bf16_f32 v75, v88, v89
	v_cvt_pk_bf16_f32 v76, v78, v79
	v_cvt_pk_bf16_f32 v77, v80, v81
	global_store_dwordx4 v[82:83], v[74:77], off
	v_cvt_pk_bf16_f32 v70, v70, v71
	v_cvt_pk_bf16_f32 v71, v72, v73
	v_cvt_pk_bf16_f32 v72, v66, v67
	v_mad_i64_i32 v[66:67], s[0:1], v159, s47, v[146:147]
	v_lshl_add_u64 v[66:67], v[66:67], 0, v[148:149]
	v_cvt_pk_bf16_f32 v73, v68, v69
	global_store_dwordx4 v[82:83], v[70:73], off offset:256
	v_cvt_pk_bf16_f32 v62, v62, v63
	v_cvt_pk_bf16_f32 v63, v64, v65
	v_cvt_pk_bf16_f32 v64, v58, v59
	v_cvt_pk_bf16_f32 v65, v60, v61
	global_store_dwordx4 v[66:67], v[62:65], off
	v_cvt_pk_bf16_f32 v50, v50, v51
	v_cvt_pk_bf16_f32 v51, v52, v53
	v_cvt_pk_bf16_f32 v52, v42, v43
	v_add_u32_e32 v42, 0x90, v158
	v_mad_i64_i32 v[42:43], s[0:1], v42, s47, v[146:147]
	v_cvt_pk_bf16_f32 v53, v44, v45
	global_store_dwordx4 v[66:67], v[50:53], off offset:256
	s_nop 1
	v_lshl_add_u64 v[50:51], v[42:43], 0, v[148:149]
	v_cvt_pk_bf16_f32 v42, v54, v55
	v_cvt_pk_bf16_f32 v43, v56, v57
	v_cvt_pk_bf16_f32 v44, v46, v47
	v_cvt_pk_bf16_f32 v45, v48, v49
	global_store_dwordx4 v[50:51], v[42:45], off
	v_cvt_pk_bf16_f32 v34, v34, v35
	v_cvt_pk_bf16_f32 v35, v36, v37
	v_cvt_pk_bf16_f32 v36, v26, v27
	v_add_u32_e32 v26, 0xa0, v158
	v_mad_i64_i32 v[26:27], s[0:1], v26, s47, v[146:147]
	v_cvt_pk_bf16_f32 v37, v28, v29
	global_store_dwordx4 v[50:51], v[34:37], off offset:256
	s_nop 1
	v_lshl_add_u64 v[34:35], v[26:27], 0, v[148:149]
	v_cvt_pk_bf16_f32 v26, v38, v39
	v_cvt_pk_bf16_f32 v27, v40, v41
	v_cvt_pk_bf16_f32 v28, v30, v31
	v_cvt_pk_bf16_f32 v29, v32, v33
	global_store_dwordx4 v[34:35], v[26:29], off
	v_cvt_pk_bf16_f32 v18, v18, v19
	v_cvt_pk_bf16_f32 v19, v20, v21
	v_cvt_pk_bf16_f32 v20, v10, v11
	v_mad_i64_i32 v[10:11], s[0:1], v160, s47, v[146:147]
	v_cvt_pk_bf16_f32 v21, v12, v13
	global_store_dwordx4 v[34:35], v[18:21], off offset:256
	s_nop 1
	v_lshl_add_u64 v[18:19], v[10:11], 0, v[148:149]
	v_cvt_pk_bf16_f32 v10, v22, v23
	v_cvt_pk_bf16_f32 v11, v24, v25
	v_cvt_pk_bf16_f32 v12, v14, v15
	v_cvt_pk_bf16_f32 v13, v16, v17
	global_store_dwordx4 v[18:19], v[10:13], off
	v_cvt_pk_bf16_f32 v6, v6, v7
	v_cvt_pk_bf16_f32 v7, v8, v9
	v_cvt_pk_bf16_f32 v8, v2, v3
	v_cvt_pk_bf16_f32 v9, v4, v5
	global_store_dwordx4 v[18:19], v[6:9], off offset:256
	s_cbranch_vccnz .LBB0_141
	s_andn2_b64 vcc, exec, s[14:15]
	s_cbranch_vccnz .LBB0_140
	s_mov_b32 s98, 1
	s_branch .LBB0_140

; #define PG8_STAGE(bufoff, gbase, voff) do { _Pragma("unroll") for (int _i = 0; _i < 2; ++_i) \
;         __builtin_amdgcn_global_load_lds((const unsigned*)((const char*)(gbase) + (voff)[_i]), (PG8_LAS unsigned*)(lds + (bufoff) + ldsw + _i * 8192), 16, 0, 0); } while (0)
; #define PG8_LDA(dst, b, h) do { _Pragma("unroll") for (int m = 0; m < 4; ++m) _Pragma("unroll") for (int k = 0; k < 2; ++k) dst[m][k] = *(const PG8_LAS bf16x8*)(lds + PG8_SA(b, h) + aoff + m * 2048 + k * 1024); } while (0)
; #define PG8_LDB(dst, b, h) do { _Pragma("unroll") for (int n = 0; n < 2; ++n) _Pragma("unroll") for (int k = 0; k < 2; ++k) dst[n][k] = *(const PG8_LAS bf16x8*)(lds + PG8_SB(b, h) + boff + n * 2048 + k * 1024); } while (0)
; #define PG8_MMA(ai, bj, At, Bt) do { __builtin_amdgcn_s_setprio(1); _Pragma("unroll") for (int m = 0; m < 4; ++m) _Pragma("unroll") for (int n = 0; n < 2; ++n) _Pragma("unroll") for (int k = 0; k < 2; ++k) \
;         acc[ai][bj][m][n] = __builtin_amdgcn_mfma_f32_16x16x32_bf16(Bt[n][k], At[m][k], acc[ai][bj][m][n], 0, 0, 0); __builtin_amdgcn_s_setprio(0); } while (0)
; #define PG8_WAIT_V(n) asm volatile("s_waitcnt vmcnt(" #n ")" ::: "memory")
; #define PG8_WAIT_L(n) asm volatile("s_waitcnt lgkmcnt(" #n ")" ::: "memory")
; #define PG8_BAR __builtin_amdgcn_s_barrier()
; #define PG8_SCHED __builtin_amdgcn_sched_barrier(0)
; template <class Epi, class Sched, bool ALIGN_EPI = false, bool SP2 = false>
; __device__ __forceinline__ void gemm_phase(PG8_LAS unsigned char* lds, const Gemm g, const Sched& S, const Epi& E) {
;     ...
;             PG8_LDB(B0, 0, 0); PG8_LDB(B1, 0, 1); PG8_SCHED; PG8_LDA(At, 0, 0); PG8_STAGE(PG8_SA(1, 1), a1 + hstepA, voffA);
;             PG8_WAIT_V(8); PG8_WAIT_L(0); PG8_BAR; PG8_MMA(0, 0, At, B0); PG8_MMA(0, 1, At, B1); PG8_BAR; PG8_SCHED;
;     ...
;         for (int a = 0; a < 2; ++a)
; #pragma unroll
;             for (int b = 0; b < 2; ++b)
; #pragma unroll
;                 for (int m = 0; m < 4; ++m)
; #pragma unroll
;                     for (int n = 0; n < 2; ++n) acc[a][b][m][n] = (f32x4){0.f, 0.f, 0.f, 0.f};
;         cur = nxt; cA = nA; cB = nB; ++ui;
;         if constexpr (ALIGN_EPI) { if (wr == 1) PG8_BAR; }
.LBB0_610:
	s_ashr_i32 s21, s20, 31
	s_lshl_b64 s[0:1], s[20:21], 19
	v_readlane_b32 s22, v253, 29
	v_readlane_b32 s23, v253, 30
	s_add_u32 s22, s22, s0
	s_addc_u32 s23, s23, s1
	s_and_b64 s[0:1], s[6:7], exec
	s_cselect_b32 s5, s23, s29
	s_cselect_b32 s21, s22, s28
	s_ashr_i32 s19, s18, 31
	s_lshl_b64 s[0:1], s[18:19], 19
	v_readlane_b32 s24, v253, 16
	v_readlane_b32 s25, v253, 17
	s_add_u32 s24, s24, s0
	s_addc_u32 s25, s25, s1
	s_and_b64 s[0:1], s[6:7], exec
	s_cselect_b32 s19, s25, s31
	s_cselect_b32 s49, s24, s30
	s_add_u32 s28, s28, 0x40080
	s_addc_u32 s29, s29, 0
	s_add_u32 s50, s30, 0x100
	v_mov_b32_e32 v2, 0
	s_addc_u32 s51, s31, 0
	s_mov_b32 s67, -2
	v_mov_b32_e32 v3, v2
	v_mov_b32_e32 v4, v2
	v_mov_b32_e32 v5, v2
	v_mov_b32_e32 v6, v2
	v_mov_b32_e32 v7, v2
	v_mov_b32_e32 v8, v2
	v_mov_b32_e32 v9, v2
	v_mov_b32_e32 v14, v2
	v_mov_b32_e32 v15, v2
	v_mov_b32_e32 v16, v2
	v_mov_b32_e32 v17, v2
	v_mov_b32_e32 v22, v2
	v_mov_b32_e32 v23, v2
	v_mov_b32_e32 v24, v2
	v_mov_b32_e32 v25, v2
	s_waitcnt vmcnt(0)
	v_mov_b32_e32 v30, v2
	v_mov_b32_e32 v31, v2
	v_mov_b32_e32 v32, v2
	v_mov_b32_e32 v33, v2
	v_mov_b32_e32 v38, v2
	v_mov_b32_e32 v39, v2
	v_mov_b32_e32 v40, v2
	v_mov_b32_e32 v41, v2
	v_mov_b32_e32 v42, v2
	v_mov_b32_e32 v43, v2
	v_mov_b32_e32 v44, v2
	v_mov_b32_e32 v45, v2
	v_mov_b32_e32 v46, v2
	v_mov_b32_e32 v47, v2
	v_mov_b32_e32 v48, v2
	v_mov_b32_e32 v49, v2
	v_mov_b32_e32 v10, v2
	v_mov_b32_e32 v11, v2
	v_mov_b32_e32 v12, v2
	v_mov_b32_e32 v13, v2
	v_mov_b32_e32 v18, v2
	v_mov_b32_e32 v19, v2
	v_mov_b32_e32 v20, v2
	v_mov_b32_e32 v21, v2
	v_mov_b32_e32 v26, v2
	v_mov_b32_e32 v27, v2
	v_mov_b32_e32 v28, v2
	v_mov_b32_e32 v29, v2
	v_mov_b32_e32 v34, v2
	v_mov_b32_e32 v35, v2
	v_mov_b32_e32 v36, v2
	v_mov_b32_e32 v37, v2
	v_mov_b32_e32 v50, v2
	v_mov_b32_e32 v51, v2
	v_mov_b32_e32 v52, v2
	v_mov_b32_e32 v53, v2
	v_mov_b32_e32 v54, v2
	v_mov_b32_e32 v55, v2
	v_mov_b32_e32 v56, v2
	v_mov_b32_e32 v57, v2
	v_mov_b32_e32 v58, v2
	v_mov_b32_e32 v59, v2
	v_mov_b32_e32 v60, v2
	v_mov_b32_e32 v61, v2
	v_mov_b32_e32 v62, v2
	v_mov_b32_e32 v63, v2
	v_mov_b32_e32 v64, v2
	v_mov_b32_e32 v65, v2
	v_mov_b32_e32 v66, v2
	v_mov_b32_e32 v67, v2
	v_mov_b32_e32 v68, v2
	v_mov_b32_e32 v69, v2
	v_mov_b32_e32 v70, v2
	v_mov_b32_e32 v71, v2
	v_mov_b32_e32 v72, v2
	v_mov_b32_e32 v73, v2
	v_mov_b32_e32 v78, v2
	v_mov_b32_e32 v79, v2
	v_mov_b32_e32 v80, v2
	v_mov_b32_e32 v81, v2
	v_mov_b32_e32 v86, v2
	v_mov_b32_e32 v87, v2
	v_mov_b32_e32 v88, v2
	v_mov_b32_e32 v89, v2
	v_mov_b32_e32 v90, v2
	v_mov_b32_e32 v91, v2
	v_mov_b32_e32 v92, v2
	v_mov_b32_e32 v93, v2
	v_mov_b32_e32 v94, v2
	v_mov_b32_e32 v95, v2
	v_mov_b32_e32 v96, v2
	v_mov_b32_e32 v97, v2
	v_mov_b32_e32 v98, v2
	v_mov_b32_e32 v99, v2
	v_mov_b32_e32 v100, v2
	v_mov_b32_e32 v101, v2
	v_mov_b32_e32 v106, v2
	v_mov_b32_e32 v107, v2
	v_mov_b32_e32 v108, v2
	v_mov_b32_e32 v109, v2
	v_mov_b32_e32 v74, v2
	v_mov_b32_e32 v75, v2
	v_mov_b32_e32 v76, v2
	v_mov_b32_e32 v77, v2
	v_mov_b32_e32 v82, v2
	v_mov_b32_e32 v83, v2
	v_mov_b32_e32 v84, v2
	v_mov_b32_e32 v85, v2
	v_mov_b32_e32 v102, v2
	v_mov_b32_e32 v103, v2
	v_mov_b32_e32 v104, v2
	v_mov_b32_e32 v105, v2
	v_mov_b32_e32 v110, v2
	v_mov_b32_e32 v111, v2
	v_mov_b32_e32 v112, v2
	v_mov_b32_e32 v113, v2
	v_mov_b32_e32 v114, v2
	v_mov_b32_e32 v115, v2
	v_mov_b32_e32 v116, v2
	v_mov_b32_e32 v117, v2
	v_mov_b32_e32 v118, v2
	v_mov_b32_e32 v119, v2
	v_mov_b32_e32 v120, v2
	v_mov_b32_e32 v121, v2
	v_mov_b32_e32 v122, v2
	v_mov_b32_e32 v123, v2
	v_mov_b32_e32 v124, v2
	v_mov_b32_e32 v125, v2
	v_mov_b32_e32 v126, v2
	v_mov_b32_e32 v127, v2
	v_mov_b32_e32 v128, v2
	v_mov_b32_e32 v129, v2
	s_cmp_eq_u32 s98, 1
	s_cbranch_scc0 .Ldefer_1
	s_barrier
	s_mov_b32 s98, 0
.Ldefer_1:
.LBB0_611:
	ds_read_b128 v[130:133], v161
	ds_read_b128 v[134:137], v161 offset:1024
	ds_read_b128 v[154:157], v161 offset:2048
	ds_read_b128 v[166:169], v161 offset:3072
	ds_read_b128 v[170:173], v162
	ds_read_b128 v[174:177], v162 offset:1024
	ds_read_b128 v[178:181], v162 offset:2048
	ds_read_b128 v[182:185], v162 offset:3072
	s_add_u32 s0, s28, 0xfffc0080
	s_addc_u32 s1, s29, -1
	s_cmp_eq_u32 s67, 12
	s_cselect_b32 s35, s5, s1
	s_cselect_b32 s34, s21, s0
	s_cselect_b32 s31, s19, s51
	s_cselect_b32 s30, s49, s50
	v_lshl_add_u64 v[158:159], s[28:29], 0, v[146:147]
	s_add_i32 m0, s27, 0xc000
	ds_read_b128 v[186:189], v163
	ds_read_b128 v[190:193], v163 offset:1024
	ds_read_b128 v[194:197], v163 offset:2048
	ds_read_b128 v[198:201], v163 offset:3072
	ds_read_b128 v[202:205], v163 offset:4096
	ds_read_b128 v[206:209], v163 offset:5120
	ds_read_b128 v[210:213], v163 offset:6144
	ds_read_b128 v[214:217], v163 offset:7168
	global_load_lds_dwordx4 v[158:159], off
	v_lshl_add_u64 v[158:159], s[28:29], 0, v[148:149]
	s_add_i32 m0, s27, 0xe000
	s_nop 0
	global_load_lds_dwordx4 v[158:159], off
	s_waitcnt vmcnt(8)
	s_waitcnt lgkmcnt(0)
	s_setprio 1
	s_barrier
; #define PG8_STAGE(bufoff, gbase, voff) do { _Pragma("unroll") for (int _i = 0; _i < 2; ++_i) \
;         __builtin_amdgcn_global_load_lds((const unsigned*)((const char*)(gbase) + (voff)[_i]), (PG8_LAS unsigned*)(lds + (bufoff) + ldsw + _i * 8192), 16, 0, 0); } while (0)
; #define PG8_LDA(dst, b, h) do { _Pragma("unroll") for (int m = 0; m < 4; ++m) _Pragma("unroll") for (int k = 0; k < 2; ++k) dst[m][k] = *(const PG8_LAS bf16x8*)(lds + PG8_SA(b, h) + aoff + m * 2048 + k * 1024); } while (0)
; #define PG8_LDB(dst, b, h) do { _Pragma("unroll") for (int n = 0; n < 2; ++n) _Pragma("unroll") for (int k = 0; k < 2; ++k) dst[n][k] = *(const PG8_LAS bf16x8*)(lds + PG8_SB(b, h) + boff + n * 2048 + k * 1024); } while (0)
; #define PG8_MMA(ai, bj, At, Bt) do { __builtin_amdgcn_s_setprio(1); _Pragma("unroll") for (int m = 0; m < 4; ++m) _Pragma("unroll") for (int n = 0; n < 2; ++n) _Pragma("unroll") for (int k = 0; k < 2; ++k) \
;         acc[ai][bj][m][n] = __builtin_amdgcn_mfma_f32_16x16x32_bf16(Bt[n][k], At[m][k], acc[ai][bj][m][n], 0, 0, 0); __builtin_amdgcn_s_setprio(0); } while (0)
; #define PG8_WAIT_V(n) asm volatile("s_waitcnt vmcnt(" #n ")" ::: "memory")
; #define PG8_WAIT_L(n) asm volatile("s_waitcnt lgkmcnt(" #n ")" ::: "memory")
; #define PG8_BAR __builtin_amdgcn_s_barrier()
; #define PG8_SCHED __builtin_amdgcn_sched_barrier(0)
; template <class Epi, class Sched, bool ALIGN_EPI = false, bool SP2 = false>
; __device__ __forceinline__ void gemm_phase(PG8_LAS unsigned char* lds, const Gemm g, const Sched& S, const Epi& E) {
;     ...
;             PG8_LDB(B0, 0, 0); PG8_LDB(B1, 0, 1); PG8_SCHED; PG8_LDA(At, 0, 0); PG8_STAGE(PG8_SA(1, 1), a1 + hstepA, voffA);
;             PG8_WAIT_V(8); PG8_WAIT_L(0); PG8_BAR; PG8_MMA(0, 0, At, B0); PG8_MMA(0, 1, At, B1); PG8_BAR; PG8_SCHED;
;             PG8_LDA(At, 0, 1); PG8_STAGE(PG8_SB(0, 0), b2, voffB); PG8_STAGE(PG8_SB(0, 1), b2 + hstepB, voffB); PG8_STAGE(PG8_SA(0, 0), a2, voffA);
;             PG8_WAIT_V(8); PG8_WAIT_L(0); PG8_BAR; PG8_MMA(1, 0, At, B0); PG8_MMA(1, 1, At, B1); PG8_BAR; PG8_SCHED;
	v_mfma_f32_16x16x32_bf16 v[126:129], v[130:133], v[186:189], v[126:129]
	v_mfma_f32_16x16x32_bf16 v[122:125], v[154:157], v[186:189], v[122:125]
	v_mfma_f32_16x16x32_bf16 v[118:121], v[130:133], v[194:197], v[118:121]
	v_mfma_f32_16x16x32_bf16 v[114:117], v[154:157], v[194:197], v[114:117]
	v_mfma_f32_16x16x32_bf16 v[110:113], v[130:133], v[202:205], v[110:113]
	v_mfma_f32_16x16x32_bf16 v[102:105], v[154:157], v[202:205], v[102:105]
	v_mfma_f32_16x16x32_bf16 v[82:85], v[130:133], v[210:213], v[82:85]
	v_mfma_f32_16x16x32_bf16 v[74:77], v[154:157], v[210:213], v[74:77]
	v_mfma_f32_16x16x32_bf16 v[126:129], v[134:137], v[190:193], v[126:129]
	v_mfma_f32_16x16x32_bf16 v[122:125], v[166:169], v[190:193], v[122:125]
	v_mfma_f32_16x16x32_bf16 v[118:121], v[134:137], v[198:201], v[118:121]
	v_mfma_f32_16x16x32_bf16 v[114:117], v[166:169], v[198:201], v[114:117]
	v_mfma_f32_16x16x32_bf16 v[110:113], v[134:137], v[206:209], v[110:113]
	v_mfma_f32_16x16x32_bf16 v[102:105], v[166:169], v[206:209], v[102:105]
	v_mfma_f32_16x16x32_bf16 v[82:85], v[134:137], v[214:217], v[82:85]
	v_mfma_f32_16x16x32_bf16 v[74:77], v[166:169], v[214:217], v[74:77]
	s_setprio 0
	s_setprio 1
	v_mfma_f32_16x16x32_bf16 v[106:109], v[170:173], v[186:189], v[106:109]
	v_mfma_f32_16x16x32_bf16 v[98:101], v[178:181], v[186:189], v[98:101]
	v_mfma_f32_16x16x32_bf16 v[94:97], v[170:173], v[194:197], v[94:97]
	v_mfma_f32_16x16x32_bf16 v[90:93], v[178:181], v[194:197], v[90:93]
	v_mfma_f32_16x16x32_bf16 v[86:89], v[170:173], v[202:205], v[86:89]
	v_mfma_f32_16x16x32_bf16 v[78:81], v[178:181], v[202:205], v[78:81]
	v_mfma_f32_16x16x32_bf16 v[70:73], v[170:173], v[210:213], v[70:73]
	v_mfma_f32_16x16x32_bf16 v[66:69], v[178:181], v[210:213], v[66:69]
	v_mfma_f32_16x16x32_bf16 v[106:109], v[174:177], v[190:193], v[106:109]
	v_mfma_f32_16x16x32_bf16 v[98:101], v[182:185], v[190:193], v[98:101]
	v_mfma_f32_16x16x32_bf16 v[94:97], v[174:177], v[198:201], v[94:97]
	v_mfma_f32_16x16x32_bf16 v[90:93], v[182:185], v[198:201], v[90:93]
	v_mfma_f32_16x16x32_bf16 v[86:89], v[174:177], v[206:209], v[86:89]
	v_mfma_f32_16x16x32_bf16 v[78:81], v[182:185], v[206:209], v[78:81]
	v_mfma_f32_16x16x32_bf16 v[70:73], v[174:177], v[214:217], v[70:73]
	v_mfma_f32_16x16x32_bf16 v[66:69], v[182:185], v[214:217], v[66:69]
	s_setprio 0
	s_barrier
	s_add_i32 s0, s45, s17
	v_lshl_add_u64 v[158:159], s[30:31], 0, v[140:141]
	s_mov_b32 m0, s0
	ds_read_b128 v[186:189], v163 offset:16384
	ds_read_b128 v[190:193], v163 offset:17408
	ds_read_b128 v[194:197], v163 offset:18432
	ds_read_b128 v[198:201], v163 offset:19456
	ds_read_b128 v[202:205], v163 offset:20480
	ds_read_b128 v[206:209], v163 offset:21504
	ds_read_b128 v[210:213], v163 offset:22528
	ds_read_b128 v[214:217], v163 offset:23552
	global_load_lds_dwordx4 v[158:159], off
	s_add_i32 m0, s0, 0x2000
	s_add_u32 s0, s30, 0x40000
	v_lshl_add_u64 v[218:219], s[30:31], 0, v[144:145]
	s_addc_u32 s1, s31, 0
	s_add_i32 s2, s46, s17
	global_load_lds_dwordx4 v[218:219], off
	v_lshl_add_u64 v[220:221], s[0:1], 0, v[140:141]
	s_mov_b32 m0, s2
	v_lshl_add_u64 v[222:223], s[34:35], 0, v[142:143]
	global_load_lds_dwordx4 v[220:221], off
	v_lshl_add_u64 v[220:221], s[0:1], 0, v[144:145]
	s_add_i32 m0, s2, 0x2000
	s_nop 0
	global_load_lds_dwordx4 v[220:221], off
	v_lshl_add_u64 v[220:221], s[34:35], 0, v[138:139]
	s_mov_b32 m0, s27
	s_nop 0
	global_load_lds_dwordx4 v[220:221], off
	s_mov_b32 m0, s38
	s_nop 0
	global_load_lds_dwordx4 v[222:223], off
	s_waitcnt vmcnt(8)
	s_waitcnt lgkmcnt(0)
	s_setprio 1
	s_barrier
	v_mfma_f32_16x16x32_bf16 v[62:65], v[130:133], v[186:189], v[62:65]
	v_mfma_f32_16x16x32_bf16 v[58:61], v[154:157], v[186:189], v[58:61]
	v_mfma_f32_16x16x32_bf16 v[54:57], v[130:133], v[194:197], v[54:57]
	v_mfma_f32_16x16x32_bf16 v[50:53], v[154:157], v[194:197], v[50:53]
	v_mfma_f32_16x16x32_bf16 v[34:37], v[130:133], v[202:205], v[34:37]
	v_mfma_f32_16x16x32_bf16 v[26:29], v[154:157], v[202:205], v[26:29]
	v_mfma_f32_16x16x32_bf16 v[18:21], v[130:133], v[210:213], v[18:21]
	v_mfma_f32_16x16x32_bf16 v[10:13], v[154:157], v[210:213], v[10:13]
	v_mfma_f32_16x16x32_bf16 v[62:65], v[134:137], v[190:193], v[62:65]
	v_mfma_f32_16x16x32_bf16 v[58:61], v[166:169], v[190:193], v[58:61]
	v_mfma_f32_16x16x32_bf16 v[54:57], v[134:137], v[198:201], v[54:57]
	v_mfma_f32_16x16x32_bf16 v[50:53], v[166:169], v[198:201], v[50:53]
	v_mfma_f32_16x16x32_bf16 v[34:37], v[134:137], v[206:209], v[34:37]
	v_mfma_f32_16x16x32_bf16 v[26:29], v[166:169], v[206:209], v[26:29]
	v_mfma_f32_16x16x32_bf16 v[18:21], v[134:137], v[214:217], v[18:21]
	v_mfma_f32_16x16x32_bf16 v[10:13], v[166:169], v[214:217], v[10:13]
	s_setprio 0
	s_setprio 1
	v_mfma_f32_16x16x32_bf16 v[46:49], v[170:173], v[186:189], v[46:49]
	v_mfma_f32_16x16x32_bf16 v[42:45], v[178:181], v[186:189], v[42:45]
	v_mfma_f32_16x16x32_bf16 v[38:41], v[170:173], v[194:197], v[38:41]
	v_mfma_f32_16x16x32_bf16 v[30:33], v[178:181], v[194:197], v[30:33]
	v_mfma_f32_16x16x32_bf16 v[22:25], v[170:173], v[202:205], v[22:25]
	v_mfma_f32_16x16x32_bf16 v[14:17], v[178:181], v[202:205], v[14:17]
	v_mfma_f32_16x16x32_bf16 v[6:9], v[170:173], v[210:213], v[6:9]
	v_mfma_f32_16x16x32_bf16 v[2:5], v[178:181], v[210:213], v[2:5]
	v_mfma_f32_16x16x32_bf16 v[46:49], v[174:177], v[190:193], v[46:49]
	v_mfma_f32_16x16x32_bf16 v[42:45], v[182:185], v[190:193], v[42:45]
	v_mfma_f32_16x16x32_bf16 v[38:41], v[174:177], v[198:201], v[38:41]
	v_mfma_f32_16x16x32_bf16 v[30:33], v[182:185], v[198:201], v[30:33]
	v_mfma_f32_16x16x32_bf16 v[22:25], v[174:177], v[206:209], v[22:25]
	v_mfma_f32_16x16x32_bf16 v[14:17], v[182:185], v[206:209], v[14:17]
	v_mfma_f32_16x16x32_bf16 v[6:9], v[174:177], v[214:217], v[6:9]
	v_mfma_f32_16x16x32_bf16 v[2:5], v[182:185], v[214:217], v[2:5]
	s_setprio 0
	s_barrier
; #define PG8_STAGE(bufoff, gbase, voff) do { _Pragma("unroll") for (int _i = 0; _i < 2; ++_i) \
;         __builtin_amdgcn_global_load_lds((const unsigned*)((const char*)(gbase) + (voff)[_i]), (PG8_LAS unsigned*)(lds + (bufoff) + ldsw + _i * 8192), 16, 0, 0); } while (0)
; #define PG8_LDA(dst, b, h) do { _Pragma("unroll") for (int m = 0; m < 4; ++m) _Pragma("unroll") for (int k = 0; k < 2; ++k) dst[m][k] = *(const PG8_LAS bf16x8*)(lds + PG8_SA(b, h) + aoff + m * 2048 + k * 1024); } while (0)
; #define PG8_LDB(dst, b, h) do { _Pragma("unroll") for (int n = 0; n < 2; ++n) _Pragma("unroll") for (int k = 0; k < 2; ++k) dst[n][k] = *(const PG8_LAS bf16x8*)(lds + PG8_SB(b, h) + boff + n * 2048 + k * 1024); } while (0)
; #define PG8_MMA(ai, bj, At, Bt) do { __builtin_amdgcn_s_setprio(1); _Pragma("unroll") for (int m = 0; m < 4; ++m) _Pragma("unroll") for (int n = 0; n < 2; ++n) _Pragma("unroll") for (int k = 0; k < 2; ++k) \
;         acc[ai][bj][m][n] = __builtin_amdgcn_mfma_f32_16x16x32_bf16(Bt[n][k], At[m][k], acc[ai][bj][m][n], 0, 0, 0); __builtin_amdgcn_s_setprio(0); } while (0)
; #define PG8_WAIT_V(n) asm volatile("s_waitcnt vmcnt(" #n ")" ::: "memory")
; #define PG8_WAIT_L(n) asm volatile("s_waitcnt lgkmcnt(" #n ")" ::: "memory")
; #define PG8_BAR __builtin_amdgcn_s_barrier()
; #define PG8_SCHED __builtin_amdgcn_sched_barrier(0)
; template <class Epi, class Sched, bool ALIGN_EPI = false, bool SP2 = false>
; __device__ __forceinline__ void gemm_phase(PG8_LAS unsigned char* lds, const Gemm g, const Sched& S, const Epi& E) {
;     ...
;             PG8_LDB(B0, 1, 0); PG8_LDB(B1, 1, 1); PG8_SCHED; PG8_LDA(At, 1, 0); PG8_STAGE(PG8_SA(0, 1), a2 + hstepA, voffA);
;             PG8_WAIT_V(8); PG8_WAIT_L(0); PG8_BAR; PG8_MMA(0, 0, At, B0); PG8_MMA(0, 1, At, B1); PG8_BAR; PG8_SCHED;
;             PG8_LDA(At, 1, 1); PG8_STAGE(PG8_SB(1, 0), b3, voffB); PG8_STAGE(PG8_SB(1, 1), b3 + hstepB, voffB); PG8_STAGE(PG8_SA(1, 0), a3, voffA);
;             PG8_WAIT_V(8); PG8_WAIT_L(0); PG8_BAR; PG8_MMA(1, 0, At, B0); PG8_MMA(1, 1, At, B1); PG8_BAR; PG8_SCHED;
;     ...
;         if constexpr (ALIGN_EPI) { if (wr == 0) PG8_BAR; }
	ds_read_b128 v[130:133], v164
	ds_read_b128 v[134:137], v164 offset:1024
	ds_read_b128 v[154:157], v164 offset:2048
	ds_read_b128 v[166:169], v164 offset:3072
	ds_read_b128 v[170:173], v165
	ds_read_b128 v[174:177], v165 offset:1024
	ds_read_b128 v[178:181], v165 offset:2048
	ds_read_b128 v[182:185], v165 offset:3072
	s_add_u32 s0, s34, 0x40000
	s_addc_u32 s1, s35, 0
	s_mov_b32 m0, s39
	v_lshl_add_u64 v[224:225], s[0:1], 0, v[138:139]
	ds_read_b128 v[186:189], v163 offset:32768
	ds_read_b128 v[190:193], v163 offset:33792
	ds_read_b128 v[194:197], v163 offset:34816
	ds_read_b128 v[198:201], v163 offset:35840
	ds_read_b128 v[202:205], v163 offset:36864
	ds_read_b128 v[206:209], v163 offset:37888
	ds_read_b128 v[210:213], v163 offset:38912
	ds_read_b128 v[214:217], v163 offset:39936
	global_load_lds_dwordx4 v[224:225], off
	v_lshl_add_u64 v[224:225], s[0:1], 0, v[142:143]
	s_mov_b32 m0, s40
	s_nop 0
	global_load_lds_dwordx4 v[224:225], off
	s_waitcnt vmcnt(8)
	s_waitcnt lgkmcnt(0)
	s_setprio 1
	s_barrier
	v_mfma_f32_16x16x32_bf16 v[126:129], v[130:133], v[186:189], v[126:129]
	v_mfma_f32_16x16x32_bf16 v[122:125], v[154:157], v[186:189], v[122:125]
	v_mfma_f32_16x16x32_bf16 v[118:121], v[130:133], v[194:197], v[118:121]
	v_mfma_f32_16x16x32_bf16 v[114:117], v[154:157], v[194:197], v[114:117]
	v_mfma_f32_16x16x32_bf16 v[110:113], v[130:133], v[202:205], v[110:113]
	v_mfma_f32_16x16x32_bf16 v[102:105], v[154:157], v[202:205], v[102:105]
	v_mfma_f32_16x16x32_bf16 v[82:85], v[130:133], v[210:213], v[82:85]
	v_mfma_f32_16x16x32_bf16 v[74:77], v[154:157], v[210:213], v[74:77]
	v_mfma_f32_16x16x32_bf16 v[126:129], v[134:137], v[190:193], v[126:129]
	v_mfma_f32_16x16x32_bf16 v[122:125], v[166:169], v[190:193], v[122:125]
	v_mfma_f32_16x16x32_bf16 v[118:121], v[134:137], v[198:201], v[118:121]
	v_mfma_f32_16x16x32_bf16 v[114:117], v[166:169], v[198:201], v[114:117]
	v_mfma_f32_16x16x32_bf16 v[110:113], v[134:137], v[206:209], v[110:113]
	v_mfma_f32_16x16x32_bf16 v[102:105], v[166:169], v[206:209], v[102:105]
	v_mfma_f32_16x16x32_bf16 v[82:85], v[134:137], v[214:217], v[82:85]
	v_mfma_f32_16x16x32_bf16 v[74:77], v[166:169], v[214:217], v[74:77]
	s_setprio 0
	s_setprio 1
	v_mfma_f32_16x16x32_bf16 v[106:109], v[170:173], v[186:189], v[106:109]
	v_mfma_f32_16x16x32_bf16 v[98:101], v[178:181], v[186:189], v[98:101]
	v_mfma_f32_16x16x32_bf16 v[94:97], v[170:173], v[194:197], v[94:97]
	v_mfma_f32_16x16x32_bf16 v[90:93], v[178:181], v[194:197], v[90:93]
	v_mfma_f32_16x16x32_bf16 v[86:89], v[170:173], v[202:205], v[86:89]
	v_mfma_f32_16x16x32_bf16 v[78:81], v[178:181], v[202:205], v[78:81]
	v_mfma_f32_16x16x32_bf16 v[70:73], v[170:173], v[210:213], v[70:73]
	v_mfma_f32_16x16x32_bf16 v[66:69], v[178:181], v[210:213], v[66:69]
	v_mfma_f32_16x16x32_bf16 v[106:109], v[174:177], v[190:193], v[106:109]
	v_mfma_f32_16x16x32_bf16 v[98:101], v[182:185], v[190:193], v[98:101]
	v_mfma_f32_16x16x32_bf16 v[94:97], v[174:177], v[198:201], v[94:97]
	v_mfma_f32_16x16x32_bf16 v[90:93], v[182:185], v[198:201], v[90:93]
	v_mfma_f32_16x16x32_bf16 v[86:89], v[174:177], v[206:209], v[86:89]
	v_mfma_f32_16x16x32_bf16 v[78:81], v[182:185], v[206:209], v[78:81]
	v_mfma_f32_16x16x32_bf16 v[70:73], v[174:177], v[214:217], v[70:73]
	v_mfma_f32_16x16x32_bf16 v[66:69], v[182:185], v[214:217], v[66:69]
	s_setprio 0
	s_barrier
	s_add_i32 s0, s47, s17
	v_lshl_add_u64 v[158:159], v[158:159], 0, s[8:9]
	s_mov_b32 m0, s0
	ds_read_b128 v[186:189], v163 offset:49152
	ds_read_b128 v[190:193], v163 offset:50176
	ds_read_b128 v[194:197], v163 offset:51200
	ds_read_b128 v[198:201], v163 offset:52224
	ds_read_b128 v[202:205], v163 offset:53248
	ds_read_b128 v[206:209], v163 offset:54272
	ds_read_b128 v[210:213], v163 offset:55296
	ds_read_b128 v[214:217], v163 offset:56320
	global_load_lds_dwordx4 v[158:159], off
	s_add_i32 m0, s0, 0x2000
	s_add_u32 s0, s30, 0x40080
	v_lshl_add_u64 v[158:159], v[218:219], 0, s[8:9]
	s_addc_u32 s1, s31, 0
	s_add_i32 s2, s48, s17
	global_load_lds_dwordx4 v[158:159], off
	v_lshl_add_u64 v[158:159], s[0:1], 0, v[140:141]
	s_mov_b32 m0, s2
	s_nop 0
	global_load_lds_dwordx4 v[158:159], off
	v_lshl_add_u64 v[158:159], s[0:1], 0, v[144:145]
	s_add_i32 m0, s2, 0x2000
	s_nop 0
	global_load_lds_dwordx4 v[158:159], off
	v_lshl_add_u64 v[158:159], v[220:221], 0, s[8:9]
	s_mov_b32 m0, s41
	s_nop 0
	global_load_lds_dwordx4 v[158:159], off
	v_lshl_add_u64 v[158:159], v[222:223], 0, s[8:9]
	s_mov_b32 m0, s42
	s_nop 0
	global_load_lds_dwordx4 v[158:159], off
	s_waitcnt vmcnt(8)
	s_waitcnt lgkmcnt(0)
	s_setprio 1
	s_barrier
	v_mfma_f32_16x16x32_bf16 v[62:65], v[130:133], v[186:189], v[62:65]
	v_mfma_f32_16x16x32_bf16 v[58:61], v[154:157], v[186:189], v[58:61]
	v_mfma_f32_16x16x32_bf16 v[54:57], v[130:133], v[194:197], v[54:57]
	v_mfma_f32_16x16x32_bf16 v[50:53], v[154:157], v[194:197], v[50:53]
	v_mfma_f32_16x16x32_bf16 v[34:37], v[130:133], v[202:205], v[34:37]
	v_mfma_f32_16x16x32_bf16 v[26:29], v[154:157], v[202:205], v[26:29]
	v_mfma_f32_16x16x32_bf16 v[18:21], v[130:133], v[210:213], v[18:21]
	v_mfma_f32_16x16x32_bf16 v[10:13], v[154:157], v[210:213], v[10:13]
	v_mfma_f32_16x16x32_bf16 v[62:65], v[134:137], v[190:193], v[62:65]
	v_mfma_f32_16x16x32_bf16 v[58:61], v[166:169], v[190:193], v[58:61]
	v_mfma_f32_16x16x32_bf16 v[54:57], v[134:137], v[198:201], v[54:57]
	v_mfma_f32_16x16x32_bf16 v[50:53], v[166:169], v[198:201], v[50:53]
	v_mfma_f32_16x16x32_bf16 v[34:37], v[134:137], v[206:209], v[34:37]
	v_mfma_f32_16x16x32_bf16 v[26:29], v[166:169], v[206:209], v[26:29]
	v_mfma_f32_16x16x32_bf16 v[18:21], v[134:137], v[214:217], v[18:21]
	v_mfma_f32_16x16x32_bf16 v[10:13], v[166:169], v[214:217], v[10:13]
	s_setprio 0
	s_setprio 1
	v_mfma_f32_16x16x32_bf16 v[46:49], v[170:173], v[186:189], v[46:49]
	v_mfma_f32_16x16x32_bf16 v[42:45], v[178:181], v[186:189], v[42:45]
	v_mfma_f32_16x16x32_bf16 v[38:41], v[170:173], v[194:197], v[38:41]
	v_mfma_f32_16x16x32_bf16 v[30:33], v[178:181], v[194:197], v[30:33]
	v_mfma_f32_16x16x32_bf16 v[22:25], v[170:173], v[202:205], v[22:25]
	v_mfma_f32_16x16x32_bf16 v[14:17], v[178:181], v[202:205], v[14:17]
	v_mfma_f32_16x16x32_bf16 v[6:9], v[170:173], v[210:213], v[6:9]
	v_mfma_f32_16x16x32_bf16 v[2:5], v[178:181], v[210:213], v[2:5]
	v_mfma_f32_16x16x32_bf16 v[46:49], v[174:177], v[190:193], v[46:49]
	v_mfma_f32_16x16x32_bf16 v[42:45], v[182:185], v[190:193], v[42:45]
	v_mfma_f32_16x16x32_bf16 v[38:41], v[174:177], v[198:201], v[38:41]
	v_mfma_f32_16x16x32_bf16 v[30:33], v[182:185], v[198:201], v[30:33]
	v_mfma_f32_16x16x32_bf16 v[22:25], v[174:177], v[206:209], v[22:25]
	v_mfma_f32_16x16x32_bf16 v[14:17], v[182:185], v[206:209], v[14:17]
	v_mfma_f32_16x16x32_bf16 v[6:9], v[174:177], v[214:217], v[6:9]
	v_mfma_f32_16x16x32_bf16 v[2:5], v[182:185], v[214:217], v[2:5]
	s_setprio 0
	s_barrier
	s_add_i32 s67, s67, 2
	s_add_u32 s28, s28, 0x100
	s_addc_u32 s29, s29, 0
	s_add_u32 s50, s50, 0x100
	s_addc_u32 s51, s51, 0
	s_cmp_gt_u32 s67, 13
	s_cbranch_scc0 .LBB0_611
	s_and_b64 vcc, exec, s[14:15]
	s_cbranch_vccz .LBB0_614
	s_barrier
; __device__ __forceinline__ unsigned cvt_pk_bf16(float lo, float hi) { unsigned r; asm volatile("v_cvt_pk_bf16_f32 %0, %1, %2" : "=v"(r) : "v"(lo), "v"(hi)); return r; }
;     __device__ __forceinline__ void operator()(const f32x4 (&acc)[2][2][4][2], const Unit& u, int wr, int wc, int fr, int fq) const {
;         const int row0 = u.pm * BM + wr * 64 + fr, col0 = u.pn * BM + wc * 32 + 8 * fq;
; #pragma unroll
;         for (int ai = 0; ai < 2; ++ai) {
;             f32x4 h0[4][2], h1[4][2];
; #pragma unroll
;             for (int m = 0; m < 4; ++m)
; #pragma unroll
;                 for (int bj = 0; bj < 2; ++bj) { const size_t i = (size_t)(row0 + ai * HALF + m * 16) * 1024 + col0 + bj * HALF; h0[m][bj] = *(const f32x4*)(hin + i); h1[m][bj] = *(const f32x4*)(hin + i + 4); }
; #pragma unroll
;             for (int m = 0; m < 4; ++m)
; #pragma unroll
;                 for (int bj = 0; bj < 2; ++bj) { const size_t i = (size_t)(row0 + ai * HALF + m * 16) * 1024 + col0 + bj * HALF;
;                     const f32x4 o0 = h0[m][bj] * alpha + acc[ai][bj][m][0], o1 = h1[m][bj] * alpha + acc[ai][bj][m][1];
;                     u32x4 w; w.x = cvt_pk_bf16(o0[0], o0[1]); w.y = cvt_pk_bf16(o0[2], o0[3]); w.z = cvt_pk_bf16(o1[0], o1[1]); w.w = cvt_pk_bf16(o1[2], o1[3]);
;                     *(u32x4*)(hout + i) = w; }
;         }
;     }
.LBB0_614:
	v_lshl_add_u32 v158, s26, 8, v1
	v_lshl_or_b32 v154, s4, 8, v160
	v_ashrrev_i32_e32 v155, 31, v154
	v_ashrrev_i32_e32 v159, 31, v158
	v_lshl_add_u64 v[156:157], v[154:155], 2, s[10:11]
	v_lshlrev_b64 v[130:131], 12, v[158:159]
	v_or_b32_e32 v222, 16, v158
	v_lshl_add_u64 v[130:131], v[156:157], 0, v[130:131]
	v_ashrrev_i32_e32 v223, 31, v222
	global_load_dwordx4 v[166:169], v[130:131], off
	global_load_dwordx4 v[170:173], v[130:131], off offset:16
	global_load_dwordx4 v[174:177], v[130:131], off offset:512
	global_load_dwordx4 v[178:181], v[130:131], off offset:528
	v_lshlrev_b64 v[130:131], 12, v[222:223]
	v_or_b32_e32 v224, 32, v158
	v_lshl_add_u64 v[130:131], v[156:157], 0, v[130:131]
	v_ashrrev_i32_e32 v225, 31, v224
	global_load_dwordx4 v[182:185], v[130:131], off
	global_load_dwordx4 v[186:189], v[130:131], off offset:16
	global_load_dwordx4 v[190:193], v[130:131], off offset:528
	global_load_dwordx4 v[194:197], v[130:131], off offset:512
	v_lshlrev_b64 v[130:131], 12, v[224:225]
	v_lshl_add_u64 v[130:131], v[156:157], 0, v[130:131]
	global_load_dwordx4 v[198:201], v[130:131], off
	global_load_dwordx4 v[202:205], v[130:131], off offset:16
	global_load_dwordx4 v[206:209], v[130:131], off offset:512
	global_load_dwordx4 v[210:213], v[130:131], off offset:528
	v_or_b32_e32 v226, 48, v158
	v_ashrrev_i32_e32 v227, 31, v226
	v_lshlrev_b64 v[130:131], 12, v[226:227]
	v_lshl_add_u64 v[130:131], v[156:157], 0, v[130:131]
	global_load_dwordx4 v[214:217], v[130:131], off
	global_load_dwordx4 v[218:221], v[130:131], off offset:16
	global_load_dwordx4 v[134:137], v[130:131], off offset:512
	s_nop 0
	global_load_dwordx4 v[130:133], v[130:131], off offset:528
	v_readlane_b32 s0, v253, 21
	v_lshlrev_b64 v[228:229], 11, v[158:159]
	v_readlane_b32 s1, v253, 22
	v_lshlrev_b64 v[154:155], 1, v[154:155]
	v_lshlrev_b64 v[222:223], 11, v[222:223]
	v_lshl_add_u64 v[228:229], s[0:1], 0, v[228:229]
	v_lshl_add_u64 v[228:229], v[228:229], 0, v[154:155]
	v_lshl_add_u64 v[222:223], s[0:1], 0, v[222:223]
	v_lshlrev_b64 v[224:225], 11, v[224:225]
	v_lshl_add_u64 v[222:223], v[222:223], 0, v[154:155]
	v_lshl_add_u64 v[224:225], s[0:1], 0, v[224:225]
	v_lshl_add_u64 v[224:225], v[224:225], 0, v[154:155]
	s_andn2_b64 vcc, exec, s[6:7]
	s_mov_b64 s[6:7], -1
	s_waitcnt vmcnt(0)
	v_pk_fma_f32 v[128:129], v[168:169], s[16:17], v[128:129] op_sel_hi:[1,0,1]
	v_pk_fma_f32 v[124:125], v[172:173], s[16:17], v[124:125] op_sel_hi:[1,0,1]
	v_pk_fma_f32 v[126:127], v[166:167], s[16:17], v[126:127] op_sel_hi:[1,0,1]
	v_pk_fma_f32 v[122:123], v[170:171], s[16:17], v[122:123] op_sel_hi:[1,0,1]
	v_pk_fma_f32 v[108:109], v[176:177], s[16:17], v[108:109] op_sel_hi:[1,0,1]
	v_pk_fma_f32 v[106:107], v[174:175], s[16:17], v[106:107] op_sel_hi:[1,0,1]
	v_pk_fma_f32 v[166:167], v[180:181], s[16:17], v[100:101] op_sel_hi:[1,0,1]
	v_pk_fma_f32 v[168:169], v[178:179], s[16:17], v[98:99] op_sel_hi:[1,0,1]
	v_cvt_pk_bf16_f32 v98, v126, v127
	v_cvt_pk_bf16_f32 v99, v128, v129
	v_cvt_pk_bf16_f32 v100, v122, v123
	v_cvt_pk_bf16_f32 v101, v124, v125
	v_pk_fma_f32 v[124:125], v[208:209], s[16:17], v[88:89] op_sel_hi:[1,0,1]
	global_store_dwordx4 v[228:229], v[98:101], off
	v_cvt_pk_bf16_f32 v88, v106, v107
	v_cvt_pk_bf16_f32 v89, v108, v109
	v_pk_fma_f32 v[120:121], v[184:185], s[16:17], v[120:121] op_sel_hi:[1,0,1]
	v_pk_fma_f32 v[118:119], v[182:183], s[16:17], v[118:119] op_sel_hi:[1,0,1]
	v_pk_fma_f32 v[122:123], v[190:191], s[16:17], v[90:91] op_sel_hi:[1,0,1]
	v_cvt_pk_bf16_f32 v90, v168, v169
	v_cvt_pk_bf16_f32 v91, v166, v167
	global_store_dwordx4 v[228:229], v[88:91], off offset:256
	v_pk_fma_f32 v[116:117], v[188:189], s[16:17], v[116:117] op_sel_hi:[1,0,1]
	v_pk_fma_f32 v[114:115], v[186:187], s[16:17], v[114:115] op_sel_hi:[1,0,1]
	v_cvt_pk_bf16_f32 v88, v118, v119
	v_cvt_pk_bf16_f32 v89, v120, v121
	v_pk_fma_f32 v[96:97], v[196:197], s[16:17], v[96:97] op_sel_hi:[1,0,1]
	v_pk_fma_f32 v[94:95], v[194:195], s[16:17], v[94:95] op_sel_hi:[1,0,1]
	v_cvt_pk_bf16_f32 v90, v114, v115
	v_cvt_pk_bf16_f32 v91, v116, v117
	global_store_dwordx4 v[222:223], v[88:91], off
	v_pk_fma_f32 v[92:93], v[192:193], s[16:17], v[92:93] op_sel_hi:[1,0,1]
	v_pk_fma_f32 v[112:113], v[200:201], s[16:17], v[112:113] op_sel_hi:[1,0,1]
	v_cvt_pk_bf16_f32 v88, v94, v95
	v_cvt_pk_bf16_f32 v89, v96, v97
	v_pk_fma_f32 v[110:111], v[198:199], s[16:17], v[110:111] op_sel_hi:[1,0,1]
	v_cvt_pk_bf16_f32 v90, v122, v123
	v_cvt_pk_bf16_f32 v91, v92, v93
	global_store_dwordx4 v[222:223], v[88:91], off offset:256
	v_pk_fma_f32 v[104:105], v[204:205], s[16:17], v[104:105] op_sel_hi:[1,0,1]
	v_pk_fma_f32 v[102:103], v[202:203], s[16:17], v[102:103] op_sel_hi:[1,0,1]
	v_cvt_pk_bf16_f32 v88, v110, v111
	v_cvt_pk_bf16_f32 v89, v112, v113
	v_pk_fma_f32 v[86:87], v[206:207], s[16:17], v[86:87] op_sel_hi:[1,0,1]
	v_cvt_pk_bf16_f32 v90, v102, v103
	v_cvt_pk_bf16_f32 v91, v104, v105
	global_store_dwordx4 v[224:225], v[88:91], off
	v_pk_fma_f32 v[82:83], v[214:215], s[16:17], v[82:83] op_sel_hi:[1,0,1]
	v_pk_fma_f32 v[72:73], v[136:137], s[16:17], v[72:73] op_sel_hi:[1,0,1]
	v_pk_fma_f32 v[88:89], v[212:213], s[16:17], v[80:81] op_sel_hi:[1,0,1]
	v_pk_fma_f32 v[80:81], v[210:211], s[16:17], v[78:79] op_sel_hi:[1,0,1]
	v_cvt_pk_bf16_f32 v78, v86, v87
	v_cvt_pk_bf16_f32 v79, v124, v125
	v_pk_fma_f32 v[70:71], v[134:135], s[16:17], v[70:71] op_sel_hi:[1,0,1]
	v_cvt_pk_bf16_f32 v80, v80, v81
	v_cvt_pk_bf16_f32 v81, v88, v89
	global_store_dwordx4 v[224:225], v[78:81], off offset:256
	v_add_u32_e32 v134, 0xa0, v158
	v_ashrrev_i32_e32 v135, 31, v134
	v_lshlrev_b64 v[78:79], 11, v[226:227]
	v_lshl_add_u64 v[78:79], s[0:1], 0, v[78:79]
; __device__ __forceinline__ unsigned cvt_pk_bf16(float lo, float hi) { unsigned r; asm volatile("v_cvt_pk_bf16_f32 %0, %1, %2" : "=v"(r) : "v"(lo), "v"(hi)); return r; }
; #define PG8_BAR __builtin_amdgcn_s_barrier()
;     __device__ __forceinline__ void operator()(const f32x4 (&acc)[2][2][4][2], const Unit& u, int wr, int wc, int fr, int fq) const {
;         const int row0 = u.pm * BM + wr * 64 + fr, col0 = u.pn * BM + wc * 32 + 8 * fq;
; #pragma unroll
;         for (int ai = 0; ai < 2; ++ai) {
;             f32x4 h0[4][2], h1[4][2];
; #pragma unroll
;             for (int m = 0; m < 4; ++m)
; #pragma unroll
;                 for (int bj = 0; bj < 2; ++bj) { const size_t i = (size_t)(row0 + ai * HALF + m * 16) * 1024 + col0 + bj * HALF; h0[m][bj] = *(const f32x4*)(hin + i); h1[m][bj] = *(const f32x4*)(hin + i + 4); }
; #pragma unroll
;             for (int m = 0; m < 4; ++m)
; #pragma unroll
;                 for (int bj = 0; bj < 2; ++bj) { const size_t i = (size_t)(row0 + ai * HALF + m * 16) * 1024 + col0 + bj * HALF;
;                     const f32x4 o0 = h0[m][bj] * alpha + acc[ai][bj][m][0], o1 = h1[m][bj] * alpha + acc[ai][bj][m][1];
;                     u32x4 w; w.x = cvt_pk_bf16(o0[0], o0[1]); w.y = cvt_pk_bf16(o0[2], o0[3]); w.z = cvt_pk_bf16(o1[0], o1[1]); w.w = cvt_pk_bf16(o1[2], o1[3]);
;                     *(u32x4*)(hout + i) = w; }
;         }
;     }
; template <class Epi, class Sched, bool ALIGN_EPI = false, bool SP2 = false>
; __device__ __forceinline__ void gemm_phase(PG8_LAS unsigned char* lds, const Gemm g, const Sched& S, const Epi& E) {
;     ...
;         if (!has_next) break;
; #pragma unroll
;         for (int a = 0; a < 2; ++a)
; #pragma unroll
;             for (int b = 0; b < 2; ++b)
; #pragma unroll
;                 for (int m = 0; m < 4; ++m)
; #pragma unroll
;                     for (int n = 0; n < 2; ++n) acc[a][b][m][n] = (f32x4){0.f, 0.f, 0.f, 0.f};
;         cur = nxt; cA = nA; cB = nB; ++ui;
;         if constexpr (ALIGN_EPI) { if (wr == 1) PG8_BAR; }
	v_pk_fma_f32 v[80:81], v[216:217], s[16:17], v[84:85] op_sel_hi:[1,0,1]
	v_pk_fma_f32 v[84:85], v[220:221], s[16:17], v[76:77] op_sel_hi:[1,0,1]
	v_pk_fma_f32 v[76:77], v[218:219], s[16:17], v[74:75] op_sel_hi:[1,0,1]
	v_cvt_pk_bf16_f32 v74, v82, v83
	v_cvt_pk_bf16_f32 v75, v80, v81
	v_lshl_add_u64 v[78:79], v[78:79], 0, v[154:155]
	v_cvt_pk_bf16_f32 v76, v76, v77
	v_cvt_pk_bf16_f32 v77, v84, v85
	global_store_dwordx4 v[78:79], v[74:77], off
	v_lshlrev_b64 v[98:99], 12, v[134:135]
	v_lshl_add_u64 v[110:111], v[156:157], 0, v[98:99]
	v_pk_fma_f32 v[74:75], v[132:133], s[16:17], v[68:69] op_sel_hi:[1,0,1]
	v_pk_fma_f32 v[68:69], v[130:131], s[16:17], v[66:67] op_sel_hi:[1,0,1]
	v_add_u32_e32 v130, 0x80, v158
	v_cvt_pk_bf16_f32 v66, v70, v71
	v_cvt_pk_bf16_f32 v67, v72, v73
	v_ashrrev_i32_e32 v131, 31, v130
	v_cvt_pk_bf16_f32 v68, v68, v69
	v_cvt_pk_bf16_f32 v69, v74, v75
	global_store_dwordx4 v[78:79], v[66:69], off offset:256
	v_add_u32_e32 v132, 0x90, v158
	v_ashrrev_i32_e32 v133, 31, v132
	v_lshlrev_b64 v[66:67], 12, v[130:131]
	v_lshl_add_u64 v[78:79], v[156:157], 0, v[66:67]
	global_load_dwordx4 v[66:69], v[78:79], off
	global_load_dwordx4 v[70:73], v[78:79], off offset:16
	global_load_dwordx4 v[74:77], v[78:79], off offset:528
	s_nop 0
	global_load_dwordx4 v[78:81], v[78:79], off offset:512
	v_lshlrev_b64 v[82:83], 12, v[132:133]
	v_lshl_add_u64 v[94:95], v[156:157], 0, v[82:83]
	global_load_dwordx4 v[82:85], v[94:95], off
	global_load_dwordx4 v[86:89], v[94:95], off offset:16
	global_load_dwordx4 v[90:93], v[94:95], off offset:512
	s_nop 0
	global_load_dwordx4 v[94:97], v[94:95], off offset:528
	s_nop 0
	global_load_dwordx4 v[98:101], v[110:111], off
	global_load_dwordx4 v[102:105], v[110:111], off offset:16
	global_load_dwordx4 v[106:109], v[110:111], off offset:512
	s_nop 0
	global_load_dwordx4 v[110:113], v[110:111], off offset:528
	v_add_u32_e32 v136, 0xb0, v158
	v_ashrrev_i32_e32 v137, 31, v136
	v_lshlrev_b64 v[114:115], 12, v[136:137]
	v_lshl_add_u64 v[126:127], v[156:157], 0, v[114:115]
	global_load_dwordx4 v[114:117], v[126:127], off
	global_load_dwordx4 v[118:121], v[126:127], off offset:16
	global_load_dwordx4 v[122:125], v[126:127], off offset:512
	s_nop 0
	global_load_dwordx4 v[126:129], v[126:127], off offset:528
	v_lshlrev_b64 v[130:131], 11, v[130:131]
	v_lshl_add_u64 v[130:131], s[0:1], 0, v[130:131]
	v_lshlrev_b64 v[132:133], 11, v[132:133]
	v_lshl_add_u64 v[130:131], v[130:131], 0, v[154:155]
	s_waitcnt vmcnt(15)
	v_pk_fma_f32 v[64:65], v[68:69], s[16:17], v[64:65] op_sel_hi:[1,0,1]
	v_pk_fma_f32 v[62:63], v[66:67], s[16:17], v[62:63] op_sel_hi:[1,0,1]
	s_waitcnt vmcnt(13)
	v_pk_fma_f32 v[68:69], v[74:75], s[16:17], v[42:43] op_sel_hi:[1,0,1]
	s_waitcnt vmcnt(12)
	v_pk_fma_f32 v[46:47], v[78:79], s[16:17], v[46:47] op_sel_hi:[1,0,1]
	v_cvt_pk_bf16_f32 v42, v62, v63
	v_cvt_pk_bf16_f32 v43, v64, v65
	v_pk_fma_f32 v[60:61], v[72:73], s[16:17], v[60:61] op_sel_hi:[1,0,1]
	v_pk_fma_f32 v[58:59], v[70:71], s[16:17], v[58:59] op_sel_hi:[1,0,1]
	v_pk_fma_f32 v[48:49], v[80:81], s[16:17], v[48:49] op_sel_hi:[1,0,1]
	v_pk_fma_f32 v[66:67], v[76:77], s[16:17], v[44:45] op_sel_hi:[1,0,1]
	v_cvt_pk_bf16_f32 v44, v58, v59
	v_cvt_pk_bf16_f32 v45, v60, v61
	global_store_dwordx4 v[130:131], v[42:45], off
	s_waitcnt vmcnt(12)
	v_pk_fma_f32 v[56:57], v[84:85], s[16:17], v[56:57] op_sel_hi:[1,0,1]
	v_pk_fma_f32 v[54:55], v[82:83], s[16:17], v[54:55] op_sel_hi:[1,0,1]
	v_cvt_pk_bf16_f32 v42, v46, v47
	v_cvt_pk_bf16_f32 v43, v48, v49
	v_lshl_add_u64 v[46:47], s[0:1], 0, v[132:133]
	v_cvt_pk_bf16_f32 v44, v68, v69
	v_cvt_pk_bf16_f32 v45, v66, v67
	global_store_dwordx4 v[130:131], v[42:45], off offset:256
	v_lshl_add_u64 v[46:47], v[46:47], 0, v[154:155]
	s_waitcnt vmcnt(12)
	v_pk_fma_f32 v[52:53], v[88:89], s[16:17], v[52:53] op_sel_hi:[1,0,1]
	v_cvt_pk_bf16_f32 v42, v54, v55
	v_cvt_pk_bf16_f32 v43, v56, v57
	v_pk_fma_f32 v[50:51], v[86:87], s[16:17], v[50:51] op_sel_hi:[1,0,1]
	s_waitcnt vmcnt(11)
	v_pk_fma_f32 v[40:41], v[92:93], s[16:17], v[40:41] op_sel_hi:[1,0,1]
	v_cvt_pk_bf16_f32 v44, v50, v51
	v_cvt_pk_bf16_f32 v45, v52, v53
	global_store_dwordx4 v[46:47], v[42:45], off
	v_pk_fma_f32 v[38:39], v[90:91], s[16:17], v[38:39] op_sel_hi:[1,0,1]
	s_waitcnt vmcnt(10)
	v_pk_fma_f32 v[34:35], v[98:99], s[16:17], v[34:35] op_sel_hi:[1,0,1]
	v_pk_fma_f32 v[42:43], v[96:97], s[16:17], v[32:33] op_sel_hi:[1,0,1]
	v_pk_fma_f32 v[32:33], v[94:95], s[16:17], v[30:31] op_sel_hi:[1,0,1]
	v_cvt_pk_bf16_f32 v30, v38, v39
	v_cvt_pk_bf16_f32 v31, v40, v41
	s_waitcnt vmcnt(8)
	v_pk_fma_f32 v[24:25], v[108:109], s[16:17], v[24:25] op_sel_hi:[1,0,1]
	v_cvt_pk_bf16_f32 v32, v32, v33
	v_cvt_pk_bf16_f32 v33, v42, v43
	global_store_dwordx4 v[46:47], v[30:33], off offset:256
	v_pk_fma_f32 v[22:23], v[106:107], s[16:17], v[22:23] op_sel_hi:[1,0,1]
	s_waitcnt vmcnt(7)
	v_pk_fma_f32 v[18:19], v[114:115], s[16:17], v[18:19] op_sel_hi:[1,0,1]
	v_lshlrev_b64 v[30:31], 11, v[134:135]
	v_lshl_add_u64 v[30:31], s[0:1], 0, v[30:31]
	v_pk_fma_f32 v[32:33], v[100:101], s[16:17], v[36:37] op_sel_hi:[1,0,1]
	v_pk_fma_f32 v[36:37], v[104:105], s[16:17], v[28:29] op_sel_hi:[1,0,1]
	v_pk_fma_f32 v[28:29], v[102:103], s[16:17], v[26:27] op_sel_hi:[1,0,1]
	v_cvt_pk_bf16_f32 v26, v34, v35
	v_cvt_pk_bf16_f32 v27, v32, v33
	v_lshl_add_u64 v[30:31], v[30:31], 0, v[154:155]
	v_cvt_pk_bf16_f32 v28, v28, v29
	v_cvt_pk_bf16_f32 v29, v36, v37
	global_store_dwordx4 v[30:31], v[26:29], off
	s_waitcnt vmcnt(6)
	v_pk_fma_f32 v[8:9], v[124:125], s[16:17], v[8:9] op_sel_hi:[1,0,1]
	v_pk_fma_f32 v[6:7], v[122:123], s[16:17], v[6:7] op_sel_hi:[1,0,1]
	v_pk_fma_f32 v[26:27], v[112:113], s[16:17], v[16:17] op_sel_hi:[1,0,1]
	v_pk_fma_f32 v[16:17], v[110:111], s[16:17], v[14:15] op_sel_hi:[1,0,1]
	v_cvt_pk_bf16_f32 v14, v22, v23
	v_cvt_pk_bf16_f32 v15, v24, v25
	s_nop 0
	v_cvt_pk_bf16_f32 v16, v16, v17
	v_cvt_pk_bf16_f32 v17, v26, v27
	global_store_dwordx4 v[30:31], v[14:17], off offset:256
	s_nop 1
	v_lshlrev_b64 v[14:15], 11, v[136:137]
	v_lshl_add_u64 v[14:15], s[0:1], 0, v[14:15]
	v_pk_fma_f32 v[16:17], v[116:117], s[16:17], v[20:21] op_sel_hi:[1,0,1]
	v_pk_fma_f32 v[20:21], v[120:121], s[16:17], v[12:13] op_sel_hi:[1,0,1]
	v_pk_fma_f32 v[12:13], v[118:119], s[16:17], v[10:11] op_sel_hi:[1,0,1]
	v_cvt_pk_bf16_f32 v10, v18, v19
	v_cvt_pk_bf16_f32 v11, v16, v17
	v_lshl_add_u64 v[14:15], v[14:15], 0, v[154:155]
	v_cvt_pk_bf16_f32 v12, v12, v13
	v_cvt_pk_bf16_f32 v13, v20, v21
	global_store_dwordx4 v[14:15], v[10:13], off
	s_waitcnt vmcnt(7)
	s_nop 0
	v_pk_fma_f32 v[10:11], v[128:129], s[16:17], v[4:5] op_sel_hi:[1,0,1]
	v_pk_fma_f32 v[4:5], v[126:127], s[16:17], v[2:3] op_sel_hi:[1,0,1]
	v_cvt_pk_bf16_f32 v2, v6, v7
	v_cvt_pk_bf16_f32 v3, v8, v9
	s_nop 0
	v_cvt_pk_bf16_f32 v4, v4, v5
	v_cvt_pk_bf16_f32 v5, v10, v11
	global_store_dwordx4 v[14:15], v[2:5], off offset:256
	s_cbranch_vccnz .LBB0_603
	s_andn2_b64 vcc, exec, s[12:13]
	s_cbranch_vccnz .LBB0_602
	s_mov_b32 s98, 1
	s_branch .LBB0_602

; #define PG8_STAGE(bufoff, gbase, voff) do { _Pragma("unroll") for (int _i = 0; _i < 2; ++_i) \
;         __builtin_amdgcn_global_load_lds((const unsigned*)((const char*)(gbase) + (voff)[_i]), (PG8_LAS unsigned*)(lds + (bufoff) + ldsw + _i * 8192), 16, 0, 0); } while (0)
; #define PG8_LDA(dst, b, h) do { _Pragma("unroll") for (int m = 0; m < 4; ++m) _Pragma("unroll") for (int k = 0; k < 2; ++k) dst[m][k] = *(const PG8_LAS bf16x8*)(lds + PG8_SA(b, h) + aoff + m * 2048 + k * 1024); } while (0)
; #define PG8_LDB(dst, b, h) do { _Pragma("unroll") for (int n = 0; n < 2; ++n) _Pragma("unroll") for (int k = 0; k < 2; ++k) dst[n][k] = *(const PG8_LAS bf16x8*)(lds + PG8_SB(b, h) + boff + n * 2048 + k * 1024); } while (0)
; #define PG8_MMA(ai, bj, At, Bt) do { __builtin_amdgcn_s_setprio(1); _Pragma("unroll") for (int m = 0; m < 4; ++m) _Pragma("unroll") for (int n = 0; n < 2; ++n) _Pragma("unroll") for (int k = 0; k < 2; ++k) \
;         acc[ai][bj][m][n] = __builtin_amdgcn_mfma_f32_16x16x32_bf16(Bt[n][k], At[m][k], acc[ai][bj][m][n], 0, 0, 0); __builtin_amdgcn_s_setprio(0); } while (0)
; #define PG8_WAIT_V(n) asm volatile("s_waitcnt vmcnt(" #n ")" ::: "memory")
; #define PG8_WAIT_L(n) asm volatile("s_waitcnt lgkmcnt(" #n ")" ::: "memory")
; #define PG8_BAR __builtin_amdgcn_s_barrier()
; #define PG8_SCHED __builtin_amdgcn_sched_barrier(0)
; template <class Epi, class Sched, bool ALIGN_EPI = false, bool SP2 = false>
; __device__ __forceinline__ void gemm_phase(PG8_LAS unsigned char* lds, const Gemm g, const Sched& S, const Epi& E) {
;     ...
;             PG8_LDB(B0, 0, 0); PG8_LDB(B1, 0, 1); PG8_SCHED; PG8_LDA(At, 0, 0); PG8_STAGE(PG8_SA(1, 1), a1 + hstepA, voffA);
;             PG8_WAIT_V(8); PG8_WAIT_L(0); PG8_BAR; PG8_MMA(0, 0, At, B0); PG8_MMA(0, 1, At, B1); PG8_BAR; PG8_SCHED;
;     ...
;         for (int a = 0; a < 2; ++a)
; #pragma unroll
;             for (int b = 0; b < 2; ++b)
; #pragma unroll
;                 for (int m = 0; m < 4; ++m)
; #pragma unroll
;                     for (int n = 0; n < 2; ++n) acc[a][b][m][n] = (f32x4){0.f, 0.f, 0.f, 0.f};
;         cur = nxt; cA = nA; cB = nB; ++ui;
;         if constexpr (ALIGN_EPI) { if (wr == 1) PG8_BAR; }
.LBB0_1106:
	s_ashr_i32 s47, s46, 31
	s_lshl_b64 s[0:1], s[46:47], 19
	v_readlane_b32 s18, v253, 31
	v_readlane_b32 s19, v253, 32
	s_add_u32 s66, s18, s0
	s_addc_u32 s67, s19, s1
	s_and_b64 s[0:1], s[12:13], exec
	s_cselect_b32 s5, s67, s73
	s_cselect_b32 s15, s66, s72
	s_add_u32 s18, s72, 0x100
	v_mov_b32_e32 v2, 0
	s_addc_u32 s19, s73, 0
	s_mov_b32 s20, -2
	v_mov_b32_e32 v3, v2
	v_mov_b32_e32 v4, v2
	v_mov_b32_e32 v5, v2
	v_mov_b32_e32 v6, v2
	v_mov_b32_e32 v7, v2
	v_mov_b32_e32 v8, v2
	v_mov_b32_e32 v9, v2
	v_mov_b32_e32 v22, v2
	v_mov_b32_e32 v23, v2
	v_mov_b32_e32 v24, v2
	v_mov_b32_e32 v25, v2
	v_mov_b32_e32 v38, v2
	v_mov_b32_e32 v39, v2
	v_mov_b32_e32 v40, v2
	v_mov_b32_e32 v41, v2
	v_mov_b32_e32 v46, v2
	v_mov_b32_e32 v47, v2
	v_mov_b32_e32 v48, v2
	v_mov_b32_e32 v49, v2
	v_mov_b32_e32 v54, v2
	v_mov_b32_e32 v55, v2
	v_mov_b32_e32 v56, v2
	v_mov_b32_e32 v57, v2
	v_mov_b32_e32 v58, v2
	v_mov_b32_e32 v59, v2
	v_mov_b32_e32 v60, v2
	v_mov_b32_e32 v61, v2
	v_mov_b32_e32 v62, v2
	v_mov_b32_e32 v63, v2
	v_mov_b32_e32 v64, v2
	v_mov_b32_e32 v65, v2
	v_mov_b32_e32 v10, v2
	v_mov_b32_e32 v11, v2
	v_mov_b32_e32 v12, v2
	v_mov_b32_e32 v13, v2
	v_mov_b32_e32 v26, v2
	v_mov_b32_e32 v27, v2
	v_mov_b32_e32 v28, v2
	v_mov_b32_e32 v29, v2
	v_mov_b32_e32 v14, v2
	v_mov_b32_e32 v15, v2
	v_mov_b32_e32 v16, v2
	v_mov_b32_e32 v17, v2
	v_mov_b32_e32 v30, v2
	v_mov_b32_e32 v31, v2
	v_mov_b32_e32 v32, v2
	v_mov_b32_e32 v33, v2
	v_mov_b32_e32 v18, v2
	v_mov_b32_e32 v19, v2
	v_mov_b32_e32 v20, v2
	v_mov_b32_e32 v21, v2
	v_mov_b32_e32 v34, v2
	v_mov_b32_e32 v35, v2
	v_mov_b32_e32 v36, v2
	v_mov_b32_e32 v37, v2
	v_mov_b32_e32 v42, v2
	v_mov_b32_e32 v43, v2
	v_mov_b32_e32 v44, v2
	v_mov_b32_e32 v45, v2
	v_mov_b32_e32 v50, v2
	v_mov_b32_e32 v51, v2
	v_mov_b32_e32 v52, v2
	v_mov_b32_e32 v53, v2
	v_mov_b32_e32 v66, v2
	v_mov_b32_e32 v67, v2
	v_mov_b32_e32 v68, v2
	v_mov_b32_e32 v69, v2
	v_mov_b32_e32 v70, v2
	v_mov_b32_e32 v71, v2
	v_mov_b32_e32 v72, v2
	v_mov_b32_e32 v73, v2
	v_mov_b32_e32 v86, v2
	v_mov_b32_e32 v87, v2
	v_mov_b32_e32 v88, v2
	v_mov_b32_e32 v89, v2
	v_mov_b32_e32 v102, v2
	v_mov_b32_e32 v103, v2
	v_mov_b32_e32 v104, v2
	v_mov_b32_e32 v105, v2
	v_mov_b32_e32 v110, v2
	v_mov_b32_e32 v111, v2
	v_mov_b32_e32 v112, v2
	v_mov_b32_e32 v113, v2
	v_mov_b32_e32 v118, v2
	v_mov_b32_e32 v119, v2
	v_mov_b32_e32 v120, v2
	v_mov_b32_e32 v121, v2
	v_mov_b32_e32 v122, v2
	v_mov_b32_e32 v123, v2
	v_mov_b32_e32 v124, v2
	v_mov_b32_e32 v125, v2
	v_mov_b32_e32 v158, v2
	v_mov_b32_e32 v159, v2
	v_mov_b32_e32 v160, v2
	v_mov_b32_e32 v161, v2
	v_mov_b32_e32 v74, v2
	v_mov_b32_e32 v75, v2
	v_mov_b32_e32 v76, v2
	v_mov_b32_e32 v77, v2
	v_mov_b32_e32 v90, v2
	v_mov_b32_e32 v91, v2
	v_mov_b32_e32 v92, v2
	v_mov_b32_e32 v93, v2
	v_mov_b32_e32 v78, v2
	v_mov_b32_e32 v79, v2
	v_mov_b32_e32 v80, v2
	v_mov_b32_e32 v81, v2
	v_mov_b32_e32 v94, v2
	v_mov_b32_e32 v95, v2
	v_mov_b32_e32 v96, v2
	v_mov_b32_e32 v97, v2
	v_mov_b32_e32 v82, v2
	v_mov_b32_e32 v83, v2
	v_mov_b32_e32 v84, v2
	v_mov_b32_e32 v85, v2
	v_mov_b32_e32 v98, v2
	v_mov_b32_e32 v99, v2
	v_mov_b32_e32 v100, v2
	v_mov_b32_e32 v101, v2
	v_mov_b32_e32 v106, v2
	v_mov_b32_e32 v107, v2
	v_mov_b32_e32 v108, v2
	v_mov_b32_e32 v109, v2
	v_mov_b32_e32 v114, v2
	v_mov_b32_e32 v115, v2
	v_mov_b32_e32 v116, v2
	v_mov_b32_e32 v117, v2
	s_cmp_eq_u32 s98, 1
	s_cbranch_scc0 .Ldefer_2
	s_barrier
	s_mov_b32 s98, 0
.Ldefer_2:
.LBB0_1107:
	ds_read_b128 v[126:129], v205
	ds_read_b128 v[130:133], v205 offset:1024
	ds_read_b128 v[134:137], v205 offset:2048
	ds_read_b128 v[138:141], v205 offset:3072
	ds_read_b128 v[142:145], v206
	ds_read_b128 v[146:149], v206 offset:1024
	ds_read_b128 v[150:153], v206 offset:2048
	ds_read_b128 v[154:157], v206 offset:3072
	s_add_u32 s12, s70, 0x100
	s_addc_u32 s13, s71, 0
	s_cmp_eq_u32 s20, 12
	s_cselect_b32 s79, s51, s13
	s_cselect_b32 s78, s50, s12
	s_cselect_b32 s73, s5, s19
	s_cselect_b32 s72, s15, s18
	v_lshl_add_u64 v[226:227], s[70:71], 0, v[192:193]
	s_add_i32 m0, s80, 0xc000
	ds_read_b128 v[162:165], v207
	ds_read_b128 v[166:169], v207 offset:1024
	ds_read_b128 v[170:173], v207 offset:2048
	ds_read_b128 v[174:177], v207 offset:3072
	ds_read_b128 v[210:213], v207 offset:4096
	ds_read_b128 v[214:217], v207 offset:5120
	ds_read_b128 v[218:221], v207 offset:6144
	ds_read_b128 v[222:225], v207 offset:7168
	global_load_lds_dwordx4 v[226:227], off
	v_lshl_add_u64 v[226:227], s[70:71], 0, v[194:195]
	s_add_i32 m0, s80, 0xe000
	s_nop 0
	global_load_lds_dwordx4 v[226:227], off
	s_waitcnt vmcnt(8)
	s_waitcnt lgkmcnt(0)
	s_setprio 1
	s_barrier
; #define PG8_STAGE(bufoff, gbase, voff) do { _Pragma("unroll") for (int _i = 0; _i < 2; ++_i) \
;         __builtin_amdgcn_global_load_lds((const unsigned*)((const char*)(gbase) + (voff)[_i]), (PG8_LAS unsigned*)(lds + (bufoff) + ldsw + _i * 8192), 16, 0, 0); } while (0)
; #define PG8_LDA(dst, b, h) do { _Pragma("unroll") for (int m = 0; m < 4; ++m) _Pragma("unroll") for (int k = 0; k < 2; ++k) dst[m][k] = *(const PG8_LAS bf16x8*)(lds + PG8_SA(b, h) + aoff + m * 2048 + k * 1024); } while (0)
; #define PG8_LDB(dst, b, h) do { _Pragma("unroll") for (int n = 0; n < 2; ++n) _Pragma("unroll") for (int k = 0; k < 2; ++k) dst[n][k] = *(const PG8_LAS bf16x8*)(lds + PG8_SB(b, h) + boff + n * 2048 + k * 1024); } while (0)
; #define PG8_MMA(ai, bj, At, Bt) do { __builtin_amdgcn_s_setprio(1); _Pragma("unroll") for (int m = 0; m < 4; ++m) _Pragma("unroll") for (int n = 0; n < 2; ++n) _Pragma("unroll") for (int k = 0; k < 2; ++k) \
;         acc[ai][bj][m][n] = __builtin_amdgcn_mfma_f32_16x16x32_bf16(Bt[n][k], At[m][k], acc[ai][bj][m][n], 0, 0, 0); __builtin_amdgcn_s_setprio(0); } while (0)
; #define PG8_WAIT_V(n) asm volatile("s_waitcnt vmcnt(" #n ")" ::: "memory")
; #define PG8_WAIT_L(n) asm volatile("s_waitcnt lgkmcnt(" #n ")" ::: "memory")
; #define PG8_BAR __builtin_amdgcn_s_barrier()
; #define PG8_SCHED __builtin_amdgcn_sched_barrier(0)
; template <class Epi, class Sched, bool ALIGN_EPI = false, bool SP2 = false>
; __device__ __forceinline__ void gemm_phase(PG8_LAS unsigned char* lds, const Gemm g, const Sched& S, const Epi& E) {
;     ...
;             PG8_LDB(B0, 0, 0); PG8_LDB(B1, 0, 1); PG8_SCHED; PG8_LDA(At, 0, 0); PG8_STAGE(PG8_SA(1, 1), a1 + hstepA, voffA);
;             PG8_WAIT_V(8); PG8_WAIT_L(0); PG8_BAR; PG8_MMA(0, 0, At, B0); PG8_MMA(0, 1, At, B1); PG8_BAR; PG8_SCHED;
;             PG8_LDA(At, 0, 1); PG8_STAGE(PG8_SB(0, 0), b2, voffB); PG8_STAGE(PG8_SB(0, 1), b2 + hstepB, voffB); PG8_STAGE(PG8_SA(0, 0), a2, voffA);
;             PG8_WAIT_V(8); PG8_WAIT_L(0); PG8_BAR; PG8_MMA(1, 0, At, B0); PG8_MMA(1, 1, At, B1); PG8_BAR; PG8_SCHED;
	v_mfma_f32_16x16x32_bf16 v[114:117], v[126:129], v[162:165], v[114:117]
	v_mfma_f32_16x16x32_bf16 v[106:109], v[134:137], v[162:165], v[106:109]
	v_mfma_f32_16x16x32_bf16 v[98:101], v[126:129], v[170:173], v[98:101]
	v_mfma_f32_16x16x32_bf16 v[82:85], v[134:137], v[170:173], v[82:85]
	v_mfma_f32_16x16x32_bf16 v[94:97], v[126:129], v[210:213], v[94:97]
	v_mfma_f32_16x16x32_bf16 v[78:81], v[134:137], v[210:213], v[78:81]
	v_mfma_f32_16x16x32_bf16 v[90:93], v[126:129], v[218:221], v[90:93]
	v_mfma_f32_16x16x32_bf16 v[74:77], v[134:137], v[218:221], v[74:77]
	v_mfma_f32_16x16x32_bf16 v[114:117], v[130:133], v[166:169], v[114:117]
	v_mfma_f32_16x16x32_bf16 v[106:109], v[138:141], v[166:169], v[106:109]
	v_mfma_f32_16x16x32_bf16 v[98:101], v[130:133], v[174:177], v[98:101]
	v_mfma_f32_16x16x32_bf16 v[82:85], v[138:141], v[174:177], v[82:85]
	v_mfma_f32_16x16x32_bf16 v[94:97], v[130:133], v[214:217], v[94:97]
	v_mfma_f32_16x16x32_bf16 v[78:81], v[138:141], v[214:217], v[78:81]
	v_mfma_f32_16x16x32_bf16 v[90:93], v[130:133], v[222:225], v[90:93]
	v_mfma_f32_16x16x32_bf16 v[74:77], v[138:141], v[222:225], v[74:77]
	s_setprio 0
	s_setprio 1
	v_mfma_f32_16x16x32_bf16 v[158:161], v[142:145], v[162:165], v[158:161]
	v_mfma_f32_16x16x32_bf16 v[122:125], v[150:153], v[162:165], v[122:125]
	v_mfma_f32_16x16x32_bf16 v[118:121], v[142:145], v[170:173], v[118:121]
	v_mfma_f32_16x16x32_bf16 v[110:113], v[150:153], v[170:173], v[110:113]
	v_mfma_f32_16x16x32_bf16 v[102:105], v[142:145], v[210:213], v[102:105]
	v_mfma_f32_16x16x32_bf16 v[86:89], v[150:153], v[210:213], v[86:89]
	v_mfma_f32_16x16x32_bf16 v[70:73], v[142:145], v[218:221], v[70:73]
	v_mfma_f32_16x16x32_bf16 v[66:69], v[150:153], v[218:221], v[66:69]
	v_mfma_f32_16x16x32_bf16 v[158:161], v[146:149], v[166:169], v[158:161]
	v_mfma_f32_16x16x32_bf16 v[122:125], v[154:157], v[166:169], v[122:125]
	v_mfma_f32_16x16x32_bf16 v[118:121], v[146:149], v[174:177], v[118:121]
	v_mfma_f32_16x16x32_bf16 v[110:113], v[154:157], v[174:177], v[110:113]
	v_mfma_f32_16x16x32_bf16 v[102:105], v[146:149], v[214:217], v[102:105]
	v_mfma_f32_16x16x32_bf16 v[86:89], v[154:157], v[214:217], v[86:89]
	v_mfma_f32_16x16x32_bf16 v[70:73], v[146:149], v[222:225], v[70:73]
	v_mfma_f32_16x16x32_bf16 v[66:69], v[154:157], v[222:225], v[66:69]
	s_setprio 0
	s_barrier
	s_add_i32 s0, s88, s69
	v_lshl_add_u64 v[226:227], s[72:73], 0, v[180:181]
	s_mov_b32 m0, s0
	ds_read_b128 v[162:165], v207 offset:16384
	ds_read_b128 v[166:169], v207 offset:17408
	ds_read_b128 v[170:173], v207 offset:18432
	ds_read_b128 v[174:177], v207 offset:19456
	ds_read_b128 v[210:213], v207 offset:20480
	ds_read_b128 v[214:217], v207 offset:21504
	ds_read_b128 v[218:221], v207 offset:22528
	ds_read_b128 v[222:225], v207 offset:23552
	global_load_lds_dwordx4 v[226:227], off
	s_add_i32 m0, s0, 0x2000
	s_add_u32 s0, s72, 0x40000
	v_lshl_add_u64 v[228:229], s[72:73], 0, v[184:185]
	s_addc_u32 s1, s73, 0
	s_add_i32 s2, s89, s69
	global_load_lds_dwordx4 v[228:229], off
	v_lshl_add_u64 v[230:231], s[0:1], 0, v[180:181]
	s_mov_b32 m0, s2
	v_lshl_add_u64 v[232:233], s[78:79], 0, v[182:183]
	global_load_lds_dwordx4 v[230:231], off
	v_lshl_add_u64 v[230:231], s[0:1], 0, v[184:185]
	s_add_i32 m0, s2, 0x2000
	s_nop 0
	global_load_lds_dwordx4 v[230:231], off
	v_lshl_add_u64 v[230:231], s[78:79], 0, v[178:179]
	s_mov_b32 m0, s80
	s_nop 0
	global_load_lds_dwordx4 v[230:231], off
	s_mov_b32 m0, s81
	s_nop 0
	global_load_lds_dwordx4 v[232:233], off
	s_waitcnt vmcnt(8)
	s_waitcnt lgkmcnt(0)
	s_setprio 1
	s_barrier
	v_mfma_f32_16x16x32_bf16 v[50:53], v[126:129], v[162:165], v[50:53]
	v_mfma_f32_16x16x32_bf16 v[42:45], v[134:137], v[162:165], v[42:45]
	v_mfma_f32_16x16x32_bf16 v[34:37], v[126:129], v[170:173], v[34:37]
	v_mfma_f32_16x16x32_bf16 v[18:21], v[134:137], v[170:173], v[18:21]
	v_mfma_f32_16x16x32_bf16 v[30:33], v[126:129], v[210:213], v[30:33]
	v_mfma_f32_16x16x32_bf16 v[14:17], v[134:137], v[210:213], v[14:17]
	v_mfma_f32_16x16x32_bf16 v[26:29], v[126:129], v[218:221], v[26:29]
	v_mfma_f32_16x16x32_bf16 v[10:13], v[134:137], v[218:221], v[10:13]
	v_mfma_f32_16x16x32_bf16 v[50:53], v[130:133], v[166:169], v[50:53]
	v_mfma_f32_16x16x32_bf16 v[42:45], v[138:141], v[166:169], v[42:45]
	v_mfma_f32_16x16x32_bf16 v[34:37], v[130:133], v[174:177], v[34:37]
	v_mfma_f32_16x16x32_bf16 v[18:21], v[138:141], v[174:177], v[18:21]
	v_mfma_f32_16x16x32_bf16 v[30:33], v[130:133], v[214:217], v[30:33]
	v_mfma_f32_16x16x32_bf16 v[14:17], v[138:141], v[214:217], v[14:17]
	v_mfma_f32_16x16x32_bf16 v[26:29], v[130:133], v[222:225], v[26:29]
	v_mfma_f32_16x16x32_bf16 v[10:13], v[138:141], v[222:225], v[10:13]
	s_setprio 0
	s_setprio 1
	v_mfma_f32_16x16x32_bf16 v[62:65], v[142:145], v[162:165], v[62:65]
	v_mfma_f32_16x16x32_bf16 v[58:61], v[150:153], v[162:165], v[58:61]
	v_mfma_f32_16x16x32_bf16 v[54:57], v[142:145], v[170:173], v[54:57]
	v_mfma_f32_16x16x32_bf16 v[46:49], v[150:153], v[170:173], v[46:49]
	v_mfma_f32_16x16x32_bf16 v[38:41], v[142:145], v[210:213], v[38:41]
	v_mfma_f32_16x16x32_bf16 v[22:25], v[150:153], v[210:213], v[22:25]
	v_mfma_f32_16x16x32_bf16 v[6:9], v[142:145], v[218:221], v[6:9]
	v_mfma_f32_16x16x32_bf16 v[2:5], v[150:153], v[218:221], v[2:5]
	v_mfma_f32_16x16x32_bf16 v[62:65], v[146:149], v[166:169], v[62:65]
	v_mfma_f32_16x16x32_bf16 v[58:61], v[154:157], v[166:169], v[58:61]
	v_mfma_f32_16x16x32_bf16 v[54:57], v[146:149], v[174:177], v[54:57]
	v_mfma_f32_16x16x32_bf16 v[46:49], v[154:157], v[174:177], v[46:49]
	v_mfma_f32_16x16x32_bf16 v[38:41], v[146:149], v[214:217], v[38:41]
	v_mfma_f32_16x16x32_bf16 v[22:25], v[154:157], v[214:217], v[22:25]
	v_mfma_f32_16x16x32_bf16 v[6:9], v[146:149], v[222:225], v[6:9]
	v_mfma_f32_16x16x32_bf16 v[2:5], v[154:157], v[222:225], v[2:5]
	s_setprio 0
	s_barrier
; #define PG8_STAGE(bufoff, gbase, voff) do { _Pragma("unroll") for (int _i = 0; _i < 2; ++_i) \
;         __builtin_amdgcn_global_load_lds((const unsigned*)((const char*)(gbase) + (voff)[_i]), (PG8_LAS unsigned*)(lds + (bufoff) + ldsw + _i * 8192), 16, 0, 0); } while (0)
; #define PG8_LDA(dst, b, h) do { _Pragma("unroll") for (int m = 0; m < 4; ++m) _Pragma("unroll") for (int k = 0; k < 2; ++k) dst[m][k] = *(const PG8_LAS bf16x8*)(lds + PG8_SA(b, h) + aoff + m * 2048 + k * 1024); } while (0)
; #define PG8_LDB(dst, b, h) do { _Pragma("unroll") for (int n = 0; n < 2; ++n) _Pragma("unroll") for (int k = 0; k < 2; ++k) dst[n][k] = *(const PG8_LAS bf16x8*)(lds + PG8_SB(b, h) + boff + n * 2048 + k * 1024); } while (0)
; #define PG8_MMA(ai, bj, At, Bt) do { __builtin_amdgcn_s_setprio(1); _Pragma("unroll") for (int m = 0; m < 4; ++m) _Pragma("unroll") for (int n = 0; n < 2; ++n) _Pragma("unroll") for (int k = 0; k < 2; ++k) \
;         acc[ai][bj][m][n] = __builtin_amdgcn_mfma_f32_16x16x32_bf16(Bt[n][k], At[m][k], acc[ai][bj][m][n], 0, 0, 0); __builtin_amdgcn_s_setprio(0); } while (0)
; #define PG8_WAIT_V(n) asm volatile("s_waitcnt vmcnt(" #n ")" ::: "memory")
; #define PG8_WAIT_L(n) asm volatile("s_waitcnt lgkmcnt(" #n ")" ::: "memory")
; #define PG8_BAR __builtin_amdgcn_s_barrier()
; #define PG8_SCHED __builtin_amdgcn_sched_barrier(0)
; template <class Epi, class Sched, bool ALIGN_EPI = false, bool SP2 = false>
; __device__ __forceinline__ void gemm_phase(PG8_LAS unsigned char* lds, const Gemm g, const Sched& S, const Epi& E) {
;     ...
;             PG8_LDB(B0, 1, 0); PG8_LDB(B1, 1, 1); PG8_SCHED; PG8_LDA(At, 1, 0); PG8_STAGE(PG8_SA(0, 1), a2 + hstepA, voffA);
;             PG8_WAIT_V(8); PG8_WAIT_L(0); PG8_BAR; PG8_MMA(0, 0, At, B0); PG8_MMA(0, 1, At, B1); PG8_BAR; PG8_SCHED;
;             PG8_LDA(At, 1, 1); PG8_STAGE(PG8_SB(1, 0), b3, voffB); PG8_STAGE(PG8_SB(1, 1), b3 + hstepB, voffB); PG8_STAGE(PG8_SA(1, 0), a3, voffA);
;             PG8_WAIT_V(8); PG8_WAIT_L(0); PG8_BAR; PG8_MMA(1, 0, At, B0); PG8_MMA(1, 1, At, B1); PG8_BAR; PG8_SCHED;
;     ...
;         if constexpr (ALIGN_EPI) { if (wr == 0) PG8_BAR; }
	ds_read_b128 v[126:129], v208
	ds_read_b128 v[130:133], v208 offset:1024
	ds_read_b128 v[134:137], v208 offset:2048
	ds_read_b128 v[138:141], v208 offset:3072
	ds_read_b128 v[142:145], v209
	ds_read_b128 v[146:149], v209 offset:1024
	ds_read_b128 v[150:153], v209 offset:2048
	ds_read_b128 v[154:157], v209 offset:3072
	s_add_u32 s0, s78, 0x40000
	s_addc_u32 s1, s79, 0
	s_mov_b32 m0, s82
	v_lshl_add_u64 v[234:235], s[0:1], 0, v[178:179]
	ds_read_b128 v[162:165], v207 offset:32768
	ds_read_b128 v[166:169], v207 offset:33792
	ds_read_b128 v[170:173], v207 offset:34816
	ds_read_b128 v[174:177], v207 offset:35840
	ds_read_b128 v[210:213], v207 offset:36864
	ds_read_b128 v[214:217], v207 offset:37888
	ds_read_b128 v[218:221], v207 offset:38912
	ds_read_b128 v[222:225], v207 offset:39936
	global_load_lds_dwordx4 v[234:235], off
	v_lshl_add_u64 v[234:235], s[0:1], 0, v[182:183]
	s_mov_b32 m0, s83
	s_nop 0
	global_load_lds_dwordx4 v[234:235], off
	s_waitcnt vmcnt(8)
	s_waitcnt lgkmcnt(0)
	s_setprio 1
	s_barrier
	v_mfma_f32_16x16x32_bf16 v[114:117], v[126:129], v[162:165], v[114:117]
	v_mfma_f32_16x16x32_bf16 v[106:109], v[134:137], v[162:165], v[106:109]
	v_mfma_f32_16x16x32_bf16 v[98:101], v[126:129], v[170:173], v[98:101]
	v_mfma_f32_16x16x32_bf16 v[82:85], v[134:137], v[170:173], v[82:85]
	v_mfma_f32_16x16x32_bf16 v[94:97], v[126:129], v[210:213], v[94:97]
	v_mfma_f32_16x16x32_bf16 v[78:81], v[134:137], v[210:213], v[78:81]
	v_mfma_f32_16x16x32_bf16 v[90:93], v[126:129], v[218:221], v[90:93]
	v_mfma_f32_16x16x32_bf16 v[74:77], v[134:137], v[218:221], v[74:77]
	v_mfma_f32_16x16x32_bf16 v[114:117], v[130:133], v[166:169], v[114:117]
	v_mfma_f32_16x16x32_bf16 v[106:109], v[138:141], v[166:169], v[106:109]
	v_mfma_f32_16x16x32_bf16 v[98:101], v[130:133], v[174:177], v[98:101]
	v_mfma_f32_16x16x32_bf16 v[82:85], v[138:141], v[174:177], v[82:85]
	v_mfma_f32_16x16x32_bf16 v[94:97], v[130:133], v[214:217], v[94:97]
	v_mfma_f32_16x16x32_bf16 v[78:81], v[138:141], v[214:217], v[78:81]
	v_mfma_f32_16x16x32_bf16 v[90:93], v[130:133], v[222:225], v[90:93]
	v_mfma_f32_16x16x32_bf16 v[74:77], v[138:141], v[222:225], v[74:77]
	s_setprio 0
	s_setprio 1
	v_mfma_f32_16x16x32_bf16 v[158:161], v[142:145], v[162:165], v[158:161]
	v_mfma_f32_16x16x32_bf16 v[122:125], v[150:153], v[162:165], v[122:125]
	v_mfma_f32_16x16x32_bf16 v[118:121], v[142:145], v[170:173], v[118:121]
	v_mfma_f32_16x16x32_bf16 v[110:113], v[150:153], v[170:173], v[110:113]
	v_mfma_f32_16x16x32_bf16 v[102:105], v[142:145], v[210:213], v[102:105]
	v_mfma_f32_16x16x32_bf16 v[86:89], v[150:153], v[210:213], v[86:89]
	v_mfma_f32_16x16x32_bf16 v[70:73], v[142:145], v[218:221], v[70:73]
	v_mfma_f32_16x16x32_bf16 v[66:69], v[150:153], v[218:221], v[66:69]
	v_mfma_f32_16x16x32_bf16 v[158:161], v[146:149], v[166:169], v[158:161]
	v_mfma_f32_16x16x32_bf16 v[122:125], v[154:157], v[166:169], v[122:125]
	v_mfma_f32_16x16x32_bf16 v[118:121], v[146:149], v[174:177], v[118:121]
	v_mfma_f32_16x16x32_bf16 v[110:113], v[154:157], v[174:177], v[110:113]
	v_mfma_f32_16x16x32_bf16 v[102:105], v[146:149], v[214:217], v[102:105]
	v_mfma_f32_16x16x32_bf16 v[86:89], v[154:157], v[214:217], v[86:89]
	v_mfma_f32_16x16x32_bf16 v[70:73], v[146:149], v[222:225], v[70:73]
	v_mfma_f32_16x16x32_bf16 v[66:69], v[154:157], v[222:225], v[66:69]
	s_setprio 0
	s_barrier
	s_add_i32 s0, s90, s69
	v_lshl_add_u64 v[226:227], v[226:227], 0, s[38:39]
	s_mov_b32 m0, s0
	ds_read_b128 v[162:165], v207 offset:49152
	ds_read_b128 v[166:169], v207 offset:50176
	ds_read_b128 v[170:173], v207 offset:51200
	ds_read_b128 v[174:177], v207 offset:52224
	ds_read_b128 v[210:213], v207 offset:53248
	ds_read_b128 v[214:217], v207 offset:54272
	ds_read_b128 v[218:221], v207 offset:55296
	ds_read_b128 v[222:225], v207 offset:56320
	global_load_lds_dwordx4 v[226:227], off
	s_add_i32 m0, s0, 0x2000
	s_add_u32 s0, s72, 0x40080
	v_lshl_add_u64 v[226:227], v[228:229], 0, s[38:39]
	s_addc_u32 s1, s73, 0
	s_add_i32 s2, s91, s69
	global_load_lds_dwordx4 v[226:227], off
	v_lshl_add_u64 v[226:227], s[0:1], 0, v[180:181]
	s_mov_b32 m0, s2
	s_nop 0
	global_load_lds_dwordx4 v[226:227], off
	v_lshl_add_u64 v[226:227], s[0:1], 0, v[184:185]
	s_add_i32 m0, s2, 0x2000
	s_nop 0
	global_load_lds_dwordx4 v[226:227], off
	v_lshl_add_u64 v[226:227], v[230:231], 0, s[38:39]
	s_mov_b32 m0, s84
	s_nop 0
	global_load_lds_dwordx4 v[226:227], off
	v_lshl_add_u64 v[226:227], v[232:233], 0, s[38:39]
	s_mov_b32 m0, s85
	s_nop 0
	global_load_lds_dwordx4 v[226:227], off
	s_waitcnt vmcnt(8)
	s_waitcnt lgkmcnt(0)
	s_setprio 1
	s_barrier
	v_mfma_f32_16x16x32_bf16 v[50:53], v[126:129], v[162:165], v[50:53]
	v_mfma_f32_16x16x32_bf16 v[42:45], v[134:137], v[162:165], v[42:45]
	v_mfma_f32_16x16x32_bf16 v[34:37], v[126:129], v[170:173], v[34:37]
	v_mfma_f32_16x16x32_bf16 v[18:21], v[134:137], v[170:173], v[18:21]
	v_mfma_f32_16x16x32_bf16 v[30:33], v[126:129], v[210:213], v[30:33]
	v_mfma_f32_16x16x32_bf16 v[14:17], v[134:137], v[210:213], v[14:17]
	v_mfma_f32_16x16x32_bf16 v[26:29], v[126:129], v[218:221], v[26:29]
	v_mfma_f32_16x16x32_bf16 v[10:13], v[134:137], v[218:221], v[10:13]
	v_mfma_f32_16x16x32_bf16 v[50:53], v[130:133], v[166:169], v[50:53]
	v_mfma_f32_16x16x32_bf16 v[42:45], v[138:141], v[166:169], v[42:45]
	v_mfma_f32_16x16x32_bf16 v[34:37], v[130:133], v[174:177], v[34:37]
	v_mfma_f32_16x16x32_bf16 v[18:21], v[138:141], v[174:177], v[18:21]
	v_mfma_f32_16x16x32_bf16 v[30:33], v[130:133], v[214:217], v[30:33]
	v_mfma_f32_16x16x32_bf16 v[14:17], v[138:141], v[214:217], v[14:17]
	v_mfma_f32_16x16x32_bf16 v[26:29], v[130:133], v[222:225], v[26:29]
	v_mfma_f32_16x16x32_bf16 v[10:13], v[138:141], v[222:225], v[10:13]
	s_setprio 0
	s_setprio 1
	v_mfma_f32_16x16x32_bf16 v[62:65], v[142:145], v[162:165], v[62:65]
	v_mfma_f32_16x16x32_bf16 v[58:61], v[150:153], v[162:165], v[58:61]
	v_mfma_f32_16x16x32_bf16 v[54:57], v[142:145], v[170:173], v[54:57]
	v_mfma_f32_16x16x32_bf16 v[46:49], v[150:153], v[170:173], v[46:49]
	v_mfma_f32_16x16x32_bf16 v[38:41], v[142:145], v[210:213], v[38:41]
	v_mfma_f32_16x16x32_bf16 v[22:25], v[150:153], v[210:213], v[22:25]
	v_mfma_f32_16x16x32_bf16 v[6:9], v[142:145], v[218:221], v[6:9]
	v_mfma_f32_16x16x32_bf16 v[2:5], v[150:153], v[218:221], v[2:5]
	v_mfma_f32_16x16x32_bf16 v[62:65], v[146:149], v[166:169], v[62:65]
	v_mfma_f32_16x16x32_bf16 v[58:61], v[154:157], v[166:169], v[58:61]
	v_mfma_f32_16x16x32_bf16 v[54:57], v[146:149], v[174:177], v[54:57]
	v_mfma_f32_16x16x32_bf16 v[46:49], v[154:157], v[174:177], v[46:49]
	v_mfma_f32_16x16x32_bf16 v[38:41], v[146:149], v[214:217], v[38:41]
	v_mfma_f32_16x16x32_bf16 v[22:25], v[154:157], v[214:217], v[22:25]
	v_mfma_f32_16x16x32_bf16 v[6:9], v[146:149], v[222:225], v[6:9]
	v_mfma_f32_16x16x32_bf16 v[2:5], v[154:157], v[222:225], v[2:5]
	s_setprio 0
	s_barrier
	s_add_i32 s20, s20, 2
	s_add_u32 s18, s18, 0x100
	s_addc_u32 s19, s19, 0
	s_cmp_gt_u32 s20, 13
	s_mov_b64 s[70:71], s[12:13]
	s_cbranch_scc0 .LBB0_1107
	s_and_b64 vcc, exec, s[42:43]
	s_cbranch_vccz .LBB0_1110
	s_barrier

;     __device__ __forceinline__ void run(const f32x4 (&acc)[2][2][4][2], const Unit& u, int wr, int wc, int fr, int fq, const PG8_LAS unsigned char* sp) const {
;     ...
;         for (int ai = 0; ai < 2; ++ai) {
;             const int rb64 = u.pm * BM + ai * HALF + wr * 64;
;             f32x4 H2[2], H3[2];
;             { const unsigned a2[4] = {hr2[ai].x, hr2[ai].y, hr2[ai].z, hr2[ai].w}, a3[4] = {hr3[ai].x, hr3[ai].y, hr3[ai].z, hr3[ai].w};
; #pragma unroll
;               for (int q = 0; q < 4; ++q) { H2[q >> 1][2 * (q & 1)] = __builtin_bit_cast(float, a2[q] << 16); H2[q >> 1][2 * (q & 1) + 1] = __builtin_bit_cast(float, a2[q] & 0xffff0000u);
;                                             H3[q >> 1][2 * (q & 1)] = __builtin_bit_cast(float, a3[q] << 16); H3[q >> 1][2 * (q & 1) + 1] = __builtin_bit_cast(float, a3[q] & 0xffff0000u); } }
;             f32x4 S2[2], S3[2];
; #pragma unroll
;             for (int n = 0; n < 2; ++n)
; #pragma unroll
;                 for (int e = 0; e < 4; ++e) { S2[n][e] = dpp_old<0x111>(H2[n][e], acc[ai][0][2][n][e]); S3[n][e] = dpp_old<0x111>(H3[n][e], acc[ai][0][3][n][e]); }
; #pragma unroll
;             for (int m = 0; m < 4; ++m) {
;                 u32x4 w;
; #pragma unroll
;                 for (int n = 0; n < 2; ++n) {
;                     const f32x4 G0 = acc[ai][0][0][n], G1 = acc[ai][0][1][n], G2 = acc[ai][0][2][n];
;                     const f32x4 Gv = acc[ai][0][m][n], Uv = acc[ai][1][m][n];
;                     const f32x4 g1 = (m == 0) ? S3[n] : (m == 1) ? G0 : (m == 2) ? G1 : G2, g2 = (m == 0) ? S2[n] : (m == 1) ? S3[n] : (m == 2) ? G0 : G1;
;                     f32x2e oh[2];
; #pragma unroll
;                     for (int hq = 0; hq < 2; ++hq) {
;                         const f32x2e g2p = hq ? g2.hi : g2.lo, g1p = hq ? g1.hi : g1.lo, Gp = hq ? Gv.hi : Gv.lo, Up = hq ? Uv.hi : Uv.lo;
;                         const f32x2e w0p = hq ? w0[n].hi : w0[n].lo, w1p = hq ? w1[n].hi : w1[n].lo, w2p = hq ? w2[n].hi : w2[n].lo, bp = hq ? bb[n].hi : bb[n].lo;
;                         const f32x2e y = __builtin_elementwise_fma(w0p, g2p, __builtin_elementwise_fma(w1p, g1p, __builtin_elementwise_fma(w2p, Gp, bp)));
;                         const f32x2e t = y * -1.4426950408889634f;
;                         f32x2e den; den.x = __builtin_amdgcn_exp2f(t.x); den.y = __builtin_amdgcn_exp2f(t.y); den = den + 1.f;
.LBB0_1114:
	s_or_b64 exec, exec, s[12:13]
	s_waitcnt lgkmcnt(0)
	v_lshlrev_b32_e32 v216, 16, v174
	v_and_b32_e32 v217, 0xffff0000, v174
	v_lshlrev_b32_e32 v214, 16, v170
	v_and_b32_e32 v215, 0xffff0000, v170
	v_lshlrev_b32_e32 v174, 16, v175
	v_and_b32_e32 v175, 0xffff0000, v175
	v_mov_b32_dpp v216, v90 row_shr:1 row_mask:0xf bank_mask:0xf
	v_mov_b32_dpp v217, v91 row_shr:1 row_mask:0xf bank_mask:0xf
	v_pk_fma_f32 v[224:225], v[150:151], v[114:115], v[154:155]
	v_lshlrev_b32_e32 v170, 16, v171
	v_and_b32_e32 v171, 0xffff0000, v171
	v_mov_b32_dpp v214, v94 row_shr:1 row_mask:0xf bank_mask:0xf
	v_mov_b32_dpp v215, v95 row_shr:1 row_mask:0xf bank_mask:0xf
	v_mov_b32_dpp v174, v92 row_shr:1 row_mask:0xf bank_mask:0xf
	v_mov_b32_dpp v175, v93 row_shr:1 row_mask:0xf bank_mask:0xf
	v_pk_fma_f32 v[222:223], v[152:153], v[116:117], v[156:157]
	v_pk_fma_f32 v[224:225], v[146:147], v[216:217], v[224:225]
	v_mov_b32_dpp v170, v96 row_shr:1 row_mask:0xf bank_mask:0xf
	v_mov_b32_dpp v171, v97 row_shr:1 row_mask:0xf bank_mask:0xf
	v_pk_fma_f32 v[214:215], v[142:143], v[214:215], v[224:225]
	v_pk_fma_f32 v[222:223], v[148:149], v[174:175], v[222:223]
	v_pk_mul_f32 v[224:225], v[214:215], s[44:45] op_sel_hi:[1,0]
	v_pk_fma_f32 v[170:171], v[144:145], v[170:171], v[222:223]
	v_exp_f32_e32 v224, v224
	v_exp_f32_e32 v225, v225
	v_pk_mul_f32 v[222:223], v[170:171], s[44:45] op_sel_hi:[1,0]
	v_lshlrev_b32_e32 v220, 16, v176
	v_exp_f32_e32 v222, v222
	v_exp_f32_e32 v223, v223
	v_pk_add_f32 v[224:225], v[224:225], 1.0 op_sel_hi:[1,0]
	v_and_b32_e32 v221, 0xffff0000, v176
	v_rcp_f32_e32 v224, v224
	v_rcp_f32_e32 v225, v225
	v_pk_add_f32 v[222:223], v[222:223], 1.0 op_sel_hi:[1,0]
	v_lshlrev_b32_e32 v218, 16, v172
	v_rcp_f32_e32 v222, v222
	v_rcp_f32_e32 v223, v223
	v_pk_mul_f32 v[214:215], v[214:215], v[224:225]
	v_and_b32_e32 v219, 0xffff0000, v172
	v_lshlrev_b32_e32 v176, 16, v177
	v_and_b32_e32 v177, 0xffff0000, v177
	v_mov_b32_dpp v220, v74 row_shr:1 row_mask:0xf bank_mask:0xf
	v_mov_b32_dpp v221, v75 row_shr:1 row_mask:0xf bank_mask:0xf
	v_pk_mul_f32 v[158:159], v[158:159], v[214:215]
	v_pk_mul_f32 v[170:171], v[170:171], v[222:223]
	v_pk_fma_f32 v[214:215], v[134:135], v[106:107], v[138:139]
	v_lshlrev_b32_e32 v172, 16, v173
	v_and_b32_e32 v173, 0xffff0000, v173
	v_mov_b32_dpp v218, v78 row_shr:1 row_mask:0xf bank_mask:0xf
	v_mov_b32_dpp v219, v79 row_shr:1 row_mask:0xf bank_mask:0xf
	v_mov_b32_dpp v176, v76 row_shr:1 row_mask:0xf bank_mask:0xf
	v_mov_b32_dpp v177, v77 row_shr:1 row_mask:0xf bank_mask:0xf
	v_pk_mul_f32 v[160:161], v[160:161], v[170:171]
	v_pk_fma_f32 v[170:171], v[136:137], v[108:109], v[140:141]
	v_pk_fma_f32 v[214:215], v[130:131], v[220:221], v[214:215]
	v_mov_b32_dpp v172, v80 row_shr:1 row_mask:0xf bank_mask:0xf
	v_mov_b32_dpp v173, v81 row_shr:1 row_mask:0xf bank_mask:0xf
	v_pk_fma_f32 v[214:215], v[126:127], v[218:219], v[214:215]
	v_pk_fma_f32 v[170:171], v[132:133], v[176:177], v[170:171]
	v_pk_mul_f32 v[218:219], v[214:215], s[44:45] op_sel_hi:[1,0]
	v_pk_fma_f32 v[170:171], v[128:129], v[172:173], v[170:171]
	v_exp_f32_e32 v218, v218
	v_exp_f32_e32 v219, v219
	v_pk_mul_f32 v[172:173], v[170:171], s[44:45] op_sel_hi:[1,0]
	v_cvt_pk_bf16_f32 v158, v158, v159
	v_cvt_pk_bf16_f32 v159, v160, v161
	v_pk_add_f32 v[218:219], v[218:219], 1.0 op_sel_hi:[1,0]
	v_exp_f32_e32 v172, v172
	v_exp_f32_e32 v173, v173
	v_rcp_f32_e32 v218, v218
	v_rcp_f32_e32 v219, v219
	v_lshl_or_b32 v212, s14, 7, v202
	v_pk_add_f32 v[172:173], v[172:173], 1.0 op_sel_hi:[1,0]
	v_ashrrev_i32_e32 v213, 31, v212
	v_rcp_f32_e32 v172, v172
	v_rcp_f32_e32 v173, v173
	v_pk_mul_f32 v[160:161], v[214:215], v[218:219]
	v_or_b32_e32 v210, s0, v201
	v_pk_mul_f32 v[122:123], v[122:123], v[160:161]
	v_pk_mul_f32 v[160:161], v[170:171], v[172:173]
	v_pk_fma_f32 v[172:173], v[152:153], v[100:101], v[156:157]
	v_pk_mul_f32 v[124:125], v[124:125], v[160:161]
	v_cvt_pk_bf16_f32 v160, v122, v123
	v_pk_fma_f32 v[172:173], v[148:149], v[116:117], v[172:173]
	v_cvt_pk_bf16_f32 v161, v124, v125
	v_lshlrev_b64 v[124:125], 1, v[212:213]
	v_pk_fma_f32 v[212:213], v[150:151], v[98:99], v[154:155]
	v_pk_fma_f32 v[172:173], v[144:145], v[174:175], v[172:173]
	v_pk_fma_f32 v[212:213], v[146:147], v[114:115], v[212:213]
	v_pk_mul_f32 v[174:175], v[172:173], s[44:45] op_sel_hi:[1,0]
	v_pk_fma_f32 v[212:213], v[142:143], v[216:217], v[212:213]
	v_exp_f32_e32 v174, v174
	v_pk_mul_f32 v[214:215], v[212:213], s[44:45] op_sel_hi:[1,0]
	v_exp_f32_e32 v175, v175
	v_exp_f32_e32 v214, v214
	v_exp_f32_e32 v215, v215
	v_readlane_b32 s0, v253, 29
	v_readlane_b32 s1, v253, 30
	v_pk_add_f32 v[174:175], v[174:175], 1.0 op_sel_hi:[1,0]
	v_pk_add_f32 v[214:215], v[214:215], 1.0 op_sel_hi:[1,0]
	v_mov_b64_e32 v[122:123], s[0:1]
	v_rcp_f32_e32 v214, v214
	v_rcp_f32_e32 v215, v215
	v_rcp_f32_e32 v174, v174
	v_rcp_f32_e32 v175, v175
	v_mad_i64_i32 v[170:171], s[0:1], v210, s45, v[122:123]
	v_lshl_add_u64 v[170:171], v[170:171], 0, v[124:125]
	global_store_dwordx4 v[170:171], v[158:161], off
	v_pk_fma_f32 v[90:91], v[150:151], v[90:91], v[154:155]
	v_pk_fma_f32 v[74:75], v[134:135], v[74:75], v[138:139]
	v_pk_mul_f32 v[158:159], v[212:213], v[214:215]
	v_pk_fma_f32 v[160:161], v[134:135], v[82:83], v[138:139]
	v_pk_mul_f32 v[118:119], v[118:119], v[158:159]
	v_pk_mul_f32 v[158:159], v[172:173], v[174:175]
	v_pk_fma_f32 v[160:161], v[130:131], v[106:107], v[160:161]
	v_pk_mul_f32 v[120:121], v[120:121], v[158:159]
	v_pk_fma_f32 v[158:159], v[136:137], v[84:85], v[140:141]
	v_pk_fma_f32 v[160:161], v[126:127], v[220:221], v[160:161]
	v_pk_fma_f32 v[158:159], v[132:133], v[108:109], v[158:159]
; __device__ __forceinline__ unsigned cvt_pk_bf16(float lo, float hi) { unsigned r; asm volatile("v_cvt_pk_bf16_f32 %0, %1, %2" : "=v"(r) : "v"(lo), "v"(hi)); return r; }
;     __device__ __forceinline__ void run(const f32x4 (&acc)[2][2][4][2], const Unit& u, int wr, int wc, int fr, int fq, const PG8_LAS unsigned char* sp) const {
;     ...
;             for (int m = 0; m < 4; ++m) {
;                 u32x4 w;
; #pragma unroll
;                 for (int n = 0; n < 2; ++n) {
;                     const f32x4 G0 = acc[ai][0][0][n], G1 = acc[ai][0][1][n], G2 = acc[ai][0][2][n];
;                     const f32x4 Gv = acc[ai][0][m][n], Uv = acc[ai][1][m][n];
;                     const f32x4 g1 = (m == 0) ? S3[n] : (m == 1) ? G0 : (m == 2) ? G1 : G2, g2 = (m == 0) ? S2[n] : (m == 1) ? S3[n] : (m == 2) ? G0 : G1;
;                     f32x2e oh[2];
; #pragma unroll
;                     for (int hq = 0; hq < 2; ++hq) {
;                         const f32x2e g2p = hq ? g2.hi : g2.lo, g1p = hq ? g1.hi : g1.lo, Gp = hq ? Gv.hi : Gv.lo, Up = hq ? Uv.hi : Uv.lo;
;                         const f32x2e w0p = hq ? w0[n].hi : w0[n].lo, w1p = hq ? w1[n].hi : w1[n].lo, w2p = hq ? w2[n].hi : w2[n].lo, bp = hq ? bb[n].hi : bb[n].lo;
;                         const f32x2e y = __builtin_elementwise_fma(w0p, g2p, __builtin_elementwise_fma(w1p, g1p, __builtin_elementwise_fma(w2p, Gp, bp)));
;                         const f32x2e t = y * -1.4426950408889634f;
;                         f32x2e den; den.x = __builtin_amdgcn_exp2f(t.x); den.y = __builtin_amdgcn_exp2f(t.y); den = den + 1.f;
;                         f32x2e r; r.x = __builtin_amdgcn_rcpf(den.x); r.y = __builtin_amdgcn_rcpf(den.y);
;                         oh[hq] = y * r * Up;
;                     }
;                     if (n == 0) { w.x = cvt_pk_bf16(oh[0].x, oh[0].y); w.y = cvt_pk_bf16(oh[1].x, oh[1].y); } else { w.z = cvt_pk_bf16(oh[0].x, oh[0].y); w.w = cvt_pk_bf16(oh[1].x, oh[1].y); }
;                 }
;                 *(u32x4*)(act + (size_t)(rb64 + 4 * fr + m) * dff + ch0) = w;
;             }
	v_pk_mul_f32 v[170:171], v[160:161], s[44:45] op_sel_hi:[1,0]
	v_pk_fma_f32 v[158:159], v[128:129], v[176:177], v[158:159]
	v_exp_f32_e32 v170, v170
	v_exp_f32_e32 v171, v171
	v_pk_mul_f32 v[172:173], v[158:159], s[44:45] op_sel_hi:[1,0]
	v_cvt_pk_bf16_f32 v118, v118, v119
	v_cvt_pk_bf16_f32 v119, v120, v121
	v_pk_add_f32 v[170:171], v[170:171], 1.0 op_sel_hi:[1,0]
	v_exp_f32_e32 v172, v172
	v_exp_f32_e32 v173, v173
	v_rcp_f32_e32 v170, v170
	v_rcp_f32_e32 v171, v171
	v_pk_fma_f32 v[90:91], v[146:147], v[94:95], v[90:91]
	v_pk_add_f32 v[172:173], v[172:173], 1.0 op_sel_hi:[1,0]
	v_pk_fma_f32 v[90:91], v[142:143], v[98:99], v[90:91]
	v_rcp_f32_e32 v172, v172
	v_rcp_f32_e32 v173, v173
	v_pk_mul_f32 v[120:121], v[160:161], v[170:171]
	v_pk_fma_f32 v[76:77], v[136:137], v[76:77], v[140:141]
	v_pk_mul_f32 v[110:111], v[110:111], v[120:121]
	v_pk_mul_f32 v[120:121], v[158:159], v[172:173]
	v_pk_fma_f32 v[158:159], v[150:151], v[94:95], v[154:155]
	v_pk_mul_f32 v[112:113], v[112:113], v[120:121]
	v_cvt_pk_bf16_f32 v120, v110, v111
	v_pk_fma_f32 v[158:159], v[146:147], v[98:99], v[158:159]
	v_cvt_pk_bf16_f32 v121, v112, v113
	v_pk_fma_f32 v[112:113], v[152:153], v[96:97], v[156:157]
	v_pk_fma_f32 v[114:115], v[142:143], v[114:115], v[158:159]
	v_pk_fma_f32 v[112:113], v[148:149], v[100:101], v[112:113]
	v_or_b32_e32 v110, 1, v210
	v_pk_fma_f32 v[112:113], v[144:145], v[116:117], v[112:113]
	v_pk_mul_f32 v[116:117], v[114:115], s[44:45] op_sel_hi:[1,0]
	v_pk_mul_f32 v[158:159], v[112:113], s[44:45] op_sel_hi:[1,0]
	v_exp_f32_e32 v116, v116
	v_exp_f32_e32 v117, v117
	v_exp_f32_e32 v158, v158
	v_exp_f32_e32 v159, v159
	v_mad_i64_i32 v[110:111], s[0:1], v110, s45, v[122:123]
	v_pk_add_f32 v[116:117], v[116:117], 1.0 op_sel_hi:[1,0]
	v_pk_add_f32 v[158:159], v[158:159], 1.0 op_sel_hi:[1,0]
	v_rcp_f32_e32 v116, v116
	v_rcp_f32_e32 v117, v117
	v_rcp_f32_e32 v158, v158
	v_rcp_f32_e32 v159, v159
	v_lshl_add_u64 v[110:111], v[110:111], 0, v[124:125]
	global_store_dwordx4 v[110:111], v[118:121], off
	v_pk_mul_f32 v[110:111], v[114:115], v[116:117]
	v_pk_fma_f32 v[74:75], v[130:131], v[78:79], v[74:75]
	v_pk_mul_f32 v[102:103], v[102:103], v[110:111]
	v_pk_mul_f32 v[110:111], v[112:113], v[158:159]
	v_pk_fma_f32 v[112:113], v[134:135], v[78:79], v[138:139]
	v_pk_mul_f32 v[104:105], v[104:105], v[110:111]
	v_pk_fma_f32 v[110:111], v[136:137], v[80:81], v[140:141]
	v_pk_fma_f32 v[112:113], v[130:131], v[82:83], v[112:113]
	v_pk_fma_f32 v[110:111], v[132:133], v[84:85], v[110:111]
	v_pk_fma_f32 v[106:107], v[126:127], v[106:107], v[112:113]
	v_pk_fma_f32 v[108:109], v[128:129], v[108:109], v[110:111]
	v_pk_mul_f32 v[110:111], v[106:107], s[44:45] op_sel_hi:[1,0]
	v_pk_mul_f32 v[112:113], v[108:109], s[44:45] op_sel_hi:[1,0]
	v_exp_f32_e32 v110, v110
	v_exp_f32_e32 v111, v111
	v_exp_f32_e32 v112, v112
	v_exp_f32_e32 v113, v113
	v_cvt_pk_bf16_f32 v102, v102, v103
	v_pk_add_f32 v[110:111], v[110:111], 1.0 op_sel_hi:[1,0]
	v_cvt_pk_bf16_f32 v103, v104, v105
	v_pk_add_f32 v[112:113], v[112:113], 1.0 op_sel_hi:[1,0]
	v_rcp_f32_e32 v110, v110
	v_rcp_f32_e32 v111, v111
	v_rcp_f32_e32 v112, v112
	v_rcp_f32_e32 v113, v113
	v_pk_fma_f32 v[76:77], v[132:133], v[80:81], v[76:77]
	v_pk_mul_f32 v[104:105], v[106:107], v[110:111]
	v_pk_fma_f32 v[74:75], v[126:127], v[82:83], v[74:75]
	v_pk_mul_f32 v[86:87], v[86:87], v[104:105]
	v_pk_mul_f32 v[104:105], v[108:109], v[112:113]
	v_pk_fma_f32 v[76:77], v[128:129], v[84:85], v[76:77]
	v_pk_mul_f32 v[88:89], v[88:89], v[104:105]
	v_cvt_pk_bf16_f32 v104, v86, v87
	v_pk_mul_f32 v[78:79], v[74:75], s[44:45] op_sel_hi:[1,0]
	v_cvt_pk_bf16_f32 v105, v88, v89
	v_pk_fma_f32 v[88:89], v[152:153], v[92:93], v[156:157]
	v_pk_mul_f32 v[92:93], v[90:91], s[44:45] op_sel_hi:[1,0]
	v_pk_fma_f32 v[88:89], v[148:149], v[96:97], v[88:89]
	v_exp_f32_e32 v92, v92
	v_pk_fma_f32 v[88:89], v[144:145], v[100:101], v[88:89]
	v_exp_f32_e32 v93, v93
	v_pk_mul_f32 v[94:95], v[88:89], s[44:45] op_sel_hi:[1,0]
	v_exp_f32_e32 v78, v78
	v_exp_f32_e32 v94, v94
	v_exp_f32_e32 v95, v95
	v_exp_f32_e32 v79, v79
	v_pk_mul_f32 v[80:81], v[76:77], s[44:45] op_sel_hi:[1,0]
	v_pk_add_f32 v[92:93], v[92:93], 1.0 op_sel_hi:[1,0]
	v_exp_f32_e32 v80, v80
	v_exp_f32_e32 v81, v81
	v_rcp_f32_e32 v92, v92
	v_rcp_f32_e32 v93, v93
	v_pk_add_f32 v[94:95], v[94:95], 1.0 op_sel_hi:[1,0]
	v_or_b32_e32 v86, 2, v210
	v_rcp_f32_e32 v94, v94
	v_rcp_f32_e32 v95, v95
	v_mad_i64_i32 v[86:87], s[0:1], v86, s45, v[122:123]
	v_pk_add_f32 v[78:79], v[78:79], 1.0 op_sel_hi:[1,0]
	v_lshl_add_u64 v[86:87], v[86:87], 0, v[124:125]
	v_rcp_f32_e32 v78, v78
	v_rcp_f32_e32 v79, v79
	v_pk_add_f32 v[80:81], v[80:81], 1.0 op_sel_hi:[1,0]
	global_store_dwordx4 v[86:87], v[102:105], off
	v_pk_mul_f32 v[86:87], v[90:91], v[92:93]
	v_rcp_f32_e32 v80, v80
	v_rcp_f32_e32 v81, v81
	v_pk_mul_f32 v[70:71], v[70:71], v[86:87]
	v_pk_mul_f32 v[86:87], v[88:89], v[94:95]
	v_cvt_pk_bf16_f32 v70, v70, v71
	v_pk_fma_f32 v[84:85], v[150:151], v[50:51], v[154:155]
	v_pk_mul_f32 v[72:73], v[72:73], v[86:87]
	v_pk_fma_f32 v[82:83], v[152:153], v[52:53], v[156:157]
	v_cvt_pk_bf16_f32 v71, v72, v73
	v_pk_mul_f32 v[72:73], v[74:75], v[78:79]
	v_lshlrev_b32_e32 v74, 16, v164
	v_pk_mul_f32 v[66:67], v[66:67], v[72:73]
	v_pk_mul_f32 v[72:73], v[76:77], v[80:81]
	v_lshlrev_b32_e32 v76, 16, v168
	v_pk_mul_f32 v[68:69], v[68:69], v[72:73]
	v_cvt_pk_bf16_f32 v72, v66, v67
	v_or_b32_e32 v66, 3, v210
	v_mad_i64_i32 v[66:67], s[0:1], v66, s45, v[122:123]
	v_cvt_pk_bf16_f32 v73, v68, v69
	v_lshl_add_u64 v[66:67], v[66:67], 0, v[124:125]
	v_lshlrev_b32_e32 v68, 16, v166
	v_and_b32_e32 v69, 0xffff0000, v166
	global_store_dwordx4 v[66:67], v[70:73], off
;     __device__ __forceinline__ void run(const f32x4 (&acc)[2][2][4][2], const Unit& u, int wr, int wc, int fr, int fq, const PG8_LAS unsigned char* sp) const {
;     ...
;         for (int ai = 0; ai < 2; ++ai) {
;             const int rb64 = u.pm * BM + ai * HALF + wr * 64;
;             f32x4 H2[2], H3[2];
;             { const unsigned a2[4] = {hr2[ai].x, hr2[ai].y, hr2[ai].z, hr2[ai].w}, a3[4] = {hr3[ai].x, hr3[ai].y, hr3[ai].z, hr3[ai].w};
; #pragma unroll
;               for (int q = 0; q < 4; ++q) { H2[q >> 1][2 * (q & 1)] = __builtin_bit_cast(float, a2[q] << 16); H2[q >> 1][2 * (q & 1) + 1] = __builtin_bit_cast(float, a2[q] & 0xffff0000u);
;                                             H3[q >> 1][2 * (q & 1)] = __builtin_bit_cast(float, a3[q] << 16); H3[q >> 1][2 * (q & 1) + 1] = __builtin_bit_cast(float, a3[q] & 0xffff0000u); } }
;             f32x4 S2[2], S3[2];
; #pragma unroll
;             for (int n = 0; n < 2; ++n)
; #pragma unroll
;                 for (int e = 0; e < 4; ++e) { S2[n][e] = dpp_old<0x111>(H2[n][e], acc[ai][0][2][n][e]); S3[n][e] = dpp_old<0x111>(H3[n][e], acc[ai][0][3][n][e]); }
; #pragma unroll
;             for (int m = 0; m < 4; ++m) {
;                 u32x4 w;
; #pragma unroll
;                 for (int n = 0; n < 2; ++n) {
;                     const f32x4 G0 = acc[ai][0][0][n], G1 = acc[ai][0][1][n], G2 = acc[ai][0][2][n];
;                     const f32x4 Gv = acc[ai][0][m][n], Uv = acc[ai][1][m][n];
;                     const f32x4 g1 = (m == 0) ? S3[n] : (m == 1) ? G0 : (m == 2) ? G1 : G2, g2 = (m == 0) ? S2[n] : (m == 1) ? S3[n] : (m == 2) ? G0 : G1;
;                     f32x2e oh[2];
; #pragma unroll
;                     for (int hq = 0; hq < 2; ++hq) {
;                         const f32x2e g2p = hq ? g2.hi : g2.lo, g1p = hq ? g1.hi : g1.lo, Gp = hq ? Gv.hi : Gv.lo, Up = hq ? Uv.hi : Uv.lo;
;                         const f32x2e w0p = hq ? w0[n].hi : w0[n].lo, w1p = hq ? w1[n].hi : w1[n].lo, w2p = hq ? w2[n].hi : w2[n].lo, bp = hq ? bb[n].hi : bb[n].lo;
;                         const f32x2e y = __builtin_elementwise_fma(w0p, g2p, __builtin_elementwise_fma(w1p, g1p, __builtin_elementwise_fma(w2p, Gp, bp)));
;                         const f32x2e t = y * -1.4426950408889634f;
;                         f32x2e den; den.x = __builtin_amdgcn_exp2f(t.x); den.y = __builtin_amdgcn_exp2f(t.y); den = den + 1.f;
	v_lshlrev_b32_e32 v66, 16, v162
	v_and_b32_e32 v67, 0xffff0000, v162
	v_lshlrev_b32_e32 v72, 16, v167
	v_and_b32_e32 v73, 0xffff0000, v167
	v_mov_b32_dpp v68, v26 row_shr:1 row_mask:0xf bank_mask:0xf
	v_mov_b32_dpp v69, v27 row_shr:1 row_mask:0xf bank_mask:0xf
	v_lshlrev_b32_e32 v70, 16, v163
	v_and_b32_e32 v71, 0xffff0000, v163
	v_mov_b32_dpp v66, v30 row_shr:1 row_mask:0xf bank_mask:0xf
	v_mov_b32_dpp v67, v31 row_shr:1 row_mask:0xf bank_mask:0xf
	v_mov_b32_dpp v72, v28 row_shr:1 row_mask:0xf bank_mask:0xf
	v_mov_b32_dpp v73, v29 row_shr:1 row_mask:0xf bank_mask:0xf
	v_pk_fma_f32 v[84:85], v[146:147], v[68:69], v[84:85]
	v_mov_b32_dpp v70, v32 row_shr:1 row_mask:0xf bank_mask:0xf
	v_mov_b32_dpp v71, v33 row_shr:1 row_mask:0xf bank_mask:0xf
	v_pk_fma_f32 v[66:67], v[142:143], v[66:67], v[84:85]
	v_pk_fma_f32 v[82:83], v[148:149], v[72:73], v[82:83]
	v_pk_mul_f32 v[84:85], v[66:67], s[44:45] op_sel_hi:[1,0]
	v_pk_fma_f32 v[70:71], v[144:145], v[70:71], v[82:83]
	v_exp_f32_e32 v84, v84
	v_exp_f32_e32 v85, v85
	v_pk_mul_f32 v[82:83], v[70:71], s[44:45] op_sel_hi:[1,0]
	v_and_b32_e32 v77, 0xffff0000, v168
	v_exp_f32_e32 v82, v82
	v_exp_f32_e32 v83, v83
	v_pk_add_f32 v[84:85], v[84:85], 1.0 op_sel_hi:[1,0]
	v_and_b32_e32 v75, 0xffff0000, v164
	v_rcp_f32_e32 v84, v84
	v_rcp_f32_e32 v85, v85
	v_pk_add_f32 v[82:83], v[82:83], 1.0 op_sel_hi:[1,0]
	v_lshlrev_b32_e32 v80, 16, v169
	v_rcp_f32_e32 v82, v82
	v_rcp_f32_e32 v83, v83
	v_pk_mul_f32 v[66:67], v[66:67], v[84:85]
	v_and_b32_e32 v81, 0xffff0000, v169
	v_mov_b32_dpp v76, v10 row_shr:1 row_mask:0xf bank_mask:0xf
	v_mov_b32_dpp v77, v11 row_shr:1 row_mask:0xf bank_mask:0xf
	v_pk_mul_f32 v[62:63], v[62:63], v[66:67]
	v_pk_mul_f32 v[66:67], v[70:71], v[82:83]
	v_pk_fma_f32 v[70:71], v[134:135], v[42:43], v[138:139]
	v_lshlrev_b32_e32 v78, 16, v165
	v_and_b32_e32 v79, 0xffff0000, v165
	v_mov_b32_dpp v74, v14 row_shr:1 row_mask:0xf bank_mask:0xf
	v_mov_b32_dpp v75, v15 row_shr:1 row_mask:0xf bank_mask:0xf
	v_mov_b32_dpp v80, v12 row_shr:1 row_mask:0xf bank_mask:0xf
	v_mov_b32_dpp v81, v13 row_shr:1 row_mask:0xf bank_mask:0xf
	v_pk_mul_f32 v[64:65], v[64:65], v[66:67]
	v_pk_fma_f32 v[66:67], v[136:137], v[44:45], v[140:141]
	v_pk_fma_f32 v[70:71], v[130:131], v[76:77], v[70:71]
	v_mov_b32_dpp v78, v16 row_shr:1 row_mask:0xf bank_mask:0xf
	v_mov_b32_dpp v79, v17 row_shr:1 row_mask:0xf bank_mask:0xf
	v_pk_fma_f32 v[70:71], v[126:127], v[74:75], v[70:71]
	v_pk_fma_f32 v[66:67], v[132:133], v[80:81], v[66:67]
	v_pk_mul_f32 v[74:75], v[70:71], s[44:45] op_sel_hi:[1,0]
	v_pk_fma_f32 v[66:67], v[128:129], v[78:79], v[66:67]
	v_exp_f32_e32 v74, v74
	v_exp_f32_e32 v75, v75
	v_pk_mul_f32 v[78:79], v[66:67], s[44:45] op_sel_hi:[1,0]
	v_cvt_pk_bf16_f32 v62, v62, v63
	v_cvt_pk_bf16_f32 v63, v64, v65
	v_pk_add_f32 v[74:75], v[74:75], 1.0 op_sel_hi:[1,0]
	v_exp_f32_e32 v78, v78
	v_exp_f32_e32 v79, v79
	v_rcp_f32_e32 v74, v74
	v_rcp_f32_e32 v75, v75
	v_add_u32_e32 v86, 0x80, v210
	v_pk_add_f32 v[78:79], v[78:79], 1.0 op_sel_hi:[1,0]
	v_pk_fma_f32 v[26:27], v[150:151], v[26:27], v[154:155]
	v_rcp_f32_e32 v78, v78
	v_rcp_f32_e32 v79, v79
	v_pk_mul_f32 v[64:65], v[70:71], v[74:75]
	v_pk_fma_f32 v[26:27], v[146:147], v[30:31], v[26:27]
	v_pk_mul_f32 v[58:59], v[58:59], v[64:65]
	v_pk_mul_f32 v[64:65], v[66:67], v[78:79]
	v_pk_fma_f32 v[66:67], v[150:151], v[34:35], v[154:155]
	v_pk_mul_f32 v[60:61], v[60:61], v[64:65]
	v_cvt_pk_bf16_f32 v64, v58, v59
	v_pk_fma_f32 v[66:67], v[146:147], v[50:51], v[66:67]
	v_cvt_pk_bf16_f32 v65, v60, v61
	v_pk_fma_f32 v[60:61], v[152:153], v[36:37], v[156:157]
	v_pk_fma_f32 v[66:67], v[142:143], v[68:69], v[66:67]
	v_pk_fma_f32 v[60:61], v[148:149], v[52:53], v[60:61]
	v_pk_mul_f32 v[68:69], v[66:67], s[44:45] op_sel_hi:[1,0]
	v_pk_fma_f32 v[60:61], v[144:145], v[72:73], v[60:61]
	v_exp_f32_e32 v68, v68
	v_exp_f32_e32 v69, v69
	v_pk_mul_f32 v[70:71], v[60:61], s[44:45] op_sel_hi:[1,0]
	v_mad_i64_i32 v[58:59], s[0:1], v86, s45, v[122:123]
	v_exp_f32_e32 v70, v70
	v_exp_f32_e32 v71, v71
	v_pk_add_f32 v[68:69], v[68:69], 1.0 op_sel_hi:[1,0]
	v_lshl_add_u64 v[58:59], v[58:59], 0, v[124:125]
	v_rcp_f32_e32 v68, v68
	v_rcp_f32_e32 v69, v69
	v_pk_add_f32 v[70:71], v[70:71], 1.0 op_sel_hi:[1,0]
	global_store_dwordx4 v[58:59], v[62:65], off
	v_rcp_f32_e32 v70, v70
	v_rcp_f32_e32 v71, v71
	v_pk_mul_f32 v[58:59], v[66:67], v[68:69]
	v_pk_fma_f32 v[26:27], v[142:143], v[34:35], v[26:27]
	v_pk_mul_f32 v[54:55], v[54:55], v[58:59]
	v_pk_mul_f32 v[58:59], v[60:61], v[70:71]
	v_pk_fma_f32 v[60:61], v[134:135], v[18:19], v[138:139]
	v_pk_mul_f32 v[56:57], v[56:57], v[58:59]
	v_pk_fma_f32 v[58:59], v[136:137], v[20:21], v[140:141]
	v_pk_fma_f32 v[60:61], v[130:131], v[42:43], v[60:61]
	v_pk_fma_f32 v[58:59], v[132:133], v[44:45], v[58:59]
	v_pk_fma_f32 v[60:61], v[126:127], v[76:77], v[60:61]
	v_pk_fma_f32 v[58:59], v[128:129], v[80:81], v[58:59]
	v_pk_mul_f32 v[62:63], v[60:61], s[44:45] op_sel_hi:[1,0]
	v_pk_mul_f32 v[64:65], v[58:59], s[44:45] op_sel_hi:[1,0]
	v_exp_f32_e32 v62, v62
	v_exp_f32_e32 v63, v63
; __device__ __forceinline__ unsigned cvt_pk_bf16(float lo, float hi) { unsigned r; asm volatile("v_cvt_pk_bf16_f32 %0, %1, %2" : "=v"(r) : "v"(lo), "v"(hi)); return r; }
;     __device__ __forceinline__ void run(const f32x4 (&acc)[2][2][4][2], const Unit& u, int wr, int wc, int fr, int fq, const PG8_LAS unsigned char* sp) const {
;     ...
;             for (int m = 0; m < 4; ++m) {
;                 u32x4 w;
; #pragma unroll
;                 for (int n = 0; n < 2; ++n) {
;                     const f32x4 G0 = acc[ai][0][0][n], G1 = acc[ai][0][1][n], G2 = acc[ai][0][2][n];
;                     const f32x4 Gv = acc[ai][0][m][n], Uv = acc[ai][1][m][n];
;                     const f32x4 g1 = (m == 0) ? S3[n] : (m == 1) ? G0 : (m == 2) ? G1 : G2, g2 = (m == 0) ? S2[n] : (m == 1) ? S3[n] : (m == 2) ? G0 : G1;
;                     f32x2e oh[2];
; #pragma unroll
;                     for (int hq = 0; hq < 2; ++hq) {
;                         const f32x2e g2p = hq ? g2.hi : g2.lo, g1p = hq ? g1.hi : g1.lo, Gp = hq ? Gv.hi : Gv.lo, Up = hq ? Uv.hi : Uv.lo;
;                         const f32x2e w0p = hq ? w0[n].hi : w0[n].lo, w1p = hq ? w1[n].hi : w1[n].lo, w2p = hq ? w2[n].hi : w2[n].lo, bp = hq ? bb[n].hi : bb[n].lo;
;                         const f32x2e y = __builtin_elementwise_fma(w0p, g2p, __builtin_elementwise_fma(w1p, g1p, __builtin_elementwise_fma(w2p, Gp, bp)));
;                         const f32x2e t = y * -1.4426950408889634f;
;                         f32x2e den; den.x = __builtin_amdgcn_exp2f(t.x); den.y = __builtin_amdgcn_exp2f(t.y); den = den + 1.f;
;                         f32x2e r; r.x = __builtin_amdgcn_rcpf(den.x); r.y = __builtin_amdgcn_rcpf(den.y);
;                         oh[hq] = y * r * Up;
;                     }
;                     if (n == 0) { w.x = cvt_pk_bf16(oh[0].x, oh[0].y); w.y = cvt_pk_bf16(oh[1].x, oh[1].y); } else { w.z = cvt_pk_bf16(oh[0].x, oh[0].y); w.w = cvt_pk_bf16(oh[1].x, oh[1].y); }
;                 }
;                 *(u32x4*)(act + (size_t)(rb64 + 4 * fr + m) * dff + ch0) = w;
;             }
; template <class Epi, class Sched, bool ALIGN_EPI = false, bool SP2 = false>
; __device__ __forceinline__ void gemm_phase(PG8_LAS unsigned char* lds, const Gemm g, const Sched& S, const Epi& E) {
;     ...
;         cur = nxt; cA = nA; cB = nB; ++ui;
;         if constexpr (ALIGN_EPI) { if (wr == 1) PG8_BAR; }
	v_exp_f32_e32 v64, v64
	v_exp_f32_e32 v65, v65
	v_cvt_pk_bf16_f32 v54, v54, v55
	v_pk_add_f32 v[62:63], v[62:63], 1.0 op_sel_hi:[1,0]
	v_cvt_pk_bf16_f32 v55, v56, v57
	v_pk_add_f32 v[64:65], v[64:65], 1.0 op_sel_hi:[1,0]
	v_rcp_f32_e32 v62, v62
	v_rcp_f32_e32 v63, v63
	v_rcp_f32_e32 v64, v64
	v_rcp_f32_e32 v65, v65
	v_pk_fma_f32 v[10:11], v[134:135], v[10:11], v[138:139]
	v_pk_mul_f32 v[56:57], v[60:61], v[62:63]
	v_pk_fma_f32 v[12:13], v[136:137], v[12:13], v[140:141]
	v_pk_mul_f32 v[46:47], v[46:47], v[56:57]
	v_pk_mul_f32 v[56:57], v[58:59], v[64:65]
	v_pk_fma_f32 v[58:59], v[150:151], v[30:31], v[154:155]
	v_pk_mul_f32 v[48:49], v[48:49], v[56:57]
	v_cvt_pk_bf16_f32 v56, v46, v47
	v_pk_fma_f32 v[58:59], v[146:147], v[34:35], v[58:59]
	v_cvt_pk_bf16_f32 v57, v48, v49
	v_pk_fma_f32 v[48:49], v[152:153], v[32:33], v[156:157]
	v_pk_fma_f32 v[50:51], v[142:143], v[50:51], v[58:59]
	v_pk_fma_f32 v[48:49], v[148:149], v[36:37], v[48:49]
	v_add_u32_e32 v46, 0x81, v210
	v_pk_fma_f32 v[48:49], v[144:145], v[52:53], v[48:49]
	v_pk_mul_f32 v[52:53], v[50:51], s[44:45] op_sel_hi:[1,0]
	v_pk_mul_f32 v[58:59], v[48:49], s[44:45] op_sel_hi:[1,0]
	v_exp_f32_e32 v52, v52
	v_exp_f32_e32 v53, v53
	v_exp_f32_e32 v58, v58
	v_exp_f32_e32 v59, v59
	v_mad_i64_i32 v[46:47], s[0:1], v46, s45, v[122:123]
	v_pk_add_f32 v[52:53], v[52:53], 1.0 op_sel_hi:[1,0]
	v_pk_add_f32 v[58:59], v[58:59], 1.0 op_sel_hi:[1,0]
	v_rcp_f32_e32 v52, v52
	v_rcp_f32_e32 v53, v53
	v_rcp_f32_e32 v58, v58
	v_rcp_f32_e32 v59, v59
	v_lshl_add_u64 v[46:47], v[46:47], 0, v[124:125]
	global_store_dwordx4 v[46:47], v[54:57], off
	v_pk_mul_f32 v[46:47], v[50:51], v[52:53]
	v_pk_fma_f32 v[10:11], v[130:131], v[14:15], v[10:11]
	v_pk_mul_f32 v[38:39], v[38:39], v[46:47]
	v_pk_mul_f32 v[46:47], v[48:49], v[58:59]
	v_pk_fma_f32 v[48:49], v[134:135], v[14:15], v[138:139]
	v_pk_mul_f32 v[40:41], v[40:41], v[46:47]
	v_pk_fma_f32 v[46:47], v[136:137], v[16:17], v[140:141]
	v_pk_fma_f32 v[48:49], v[130:131], v[18:19], v[48:49]
	v_pk_fma_f32 v[46:47], v[132:133], v[20:21], v[46:47]
	v_pk_fma_f32 v[42:43], v[126:127], v[42:43], v[48:49]
	v_pk_fma_f32 v[44:45], v[128:129], v[44:45], v[46:47]
	v_pk_mul_f32 v[46:47], v[42:43], s[44:45] op_sel_hi:[1,0]
	v_pk_mul_f32 v[48:49], v[44:45], s[44:45] op_sel_hi:[1,0]
	v_exp_f32_e32 v46, v46
	v_exp_f32_e32 v47, v47
	v_exp_f32_e32 v48, v48
	v_exp_f32_e32 v49, v49
	v_cvt_pk_bf16_f32 v38, v38, v39
	v_pk_add_f32 v[46:47], v[46:47], 1.0 op_sel_hi:[1,0]
	v_cvt_pk_bf16_f32 v39, v40, v41
	v_pk_add_f32 v[48:49], v[48:49], 1.0 op_sel_hi:[1,0]
	v_rcp_f32_e32 v46, v46
	v_rcp_f32_e32 v47, v47
	v_rcp_f32_e32 v48, v48
	v_rcp_f32_e32 v49, v49
	v_pk_fma_f32 v[12:13], v[132:133], v[16:17], v[12:13]
	v_pk_mul_f32 v[40:41], v[42:43], v[46:47]
	v_pk_fma_f32 v[10:11], v[126:127], v[18:19], v[10:11]
	v_pk_mul_f32 v[22:23], v[22:23], v[40:41]
	v_pk_mul_f32 v[40:41], v[44:45], v[48:49]
	v_pk_fma_f32 v[12:13], v[128:129], v[20:21], v[12:13]
	v_pk_mul_f32 v[24:25], v[24:25], v[40:41]
	v_cvt_pk_bf16_f32 v40, v22, v23
	v_pk_mul_f32 v[14:15], v[10:11], s[44:45] op_sel_hi:[1,0]
	v_cvt_pk_bf16_f32 v41, v24, v25
	v_pk_fma_f32 v[24:25], v[152:153], v[28:29], v[156:157]
	v_pk_mul_f32 v[28:29], v[26:27], s[44:45] op_sel_hi:[1,0]
	v_pk_fma_f32 v[24:25], v[148:149], v[32:33], v[24:25]
	v_exp_f32_e32 v28, v28
	v_pk_fma_f32 v[24:25], v[144:145], v[36:37], v[24:25]
	v_exp_f32_e32 v29, v29
	v_pk_mul_f32 v[30:31], v[24:25], s[44:45] op_sel_hi:[1,0]
	v_exp_f32_e32 v14, v14
	v_exp_f32_e32 v30, v30
	v_exp_f32_e32 v31, v31
	v_exp_f32_e32 v15, v15
	v_pk_mul_f32 v[16:17], v[12:13], s[44:45] op_sel_hi:[1,0]
	v_pk_add_f32 v[28:29], v[28:29], 1.0 op_sel_hi:[1,0]
	v_exp_f32_e32 v16, v16
	v_exp_f32_e32 v17, v17
	v_rcp_f32_e32 v28, v28
	v_rcp_f32_e32 v29, v29
	v_pk_add_f32 v[30:31], v[30:31], 1.0 op_sel_hi:[1,0]
	v_add_u32_e32 v22, 0x82, v210
	v_rcp_f32_e32 v30, v30
	v_rcp_f32_e32 v31, v31
	v_mad_i64_i32 v[22:23], s[0:1], v22, s45, v[122:123]
	v_pk_add_f32 v[14:15], v[14:15], 1.0 op_sel_hi:[1,0]
	v_lshl_add_u64 v[22:23], v[22:23], 0, v[124:125]
	v_rcp_f32_e32 v14, v14
	v_rcp_f32_e32 v15, v15
	v_pk_add_f32 v[16:17], v[16:17], 1.0 op_sel_hi:[1,0]
	global_store_dwordx4 v[22:23], v[38:41], off
	v_pk_mul_f32 v[22:23], v[26:27], v[28:29]
	v_rcp_f32_e32 v16, v16
	v_rcp_f32_e32 v17, v17
	v_pk_mul_f32 v[6:7], v[6:7], v[22:23]
	v_pk_mul_f32 v[22:23], v[24:25], v[30:31]
	v_cvt_pk_bf16_f32 v6, v6, v7
	s_and_b64 vcc, exec, s[10:11]
	v_pk_mul_f32 v[8:9], v[8:9], v[22:23]
	s_mov_b64 s[10:11], -1
	v_cvt_pk_bf16_f32 v7, v8, v9
	v_pk_mul_f32 v[8:9], v[10:11], v[14:15]
	s_nop 0
	v_pk_mul_f32 v[2:3], v[2:3], v[8:9]
	v_pk_mul_f32 v[8:9], v[12:13], v[16:17]
	s_nop 0
	v_pk_mul_f32 v[4:5], v[4:5], v[8:9]
	v_cvt_pk_bf16_f32 v8, v2, v3
	v_add_u32_e32 v2, 0x83, v210
	v_mad_i64_i32 v[2:3], s[0:1], v2, s45, v[122:123]
	v_lshl_add_u64 v[2:3], v[2:3], 0, v[124:125]
	v_cvt_pk_bf16_f32 v9, v4, v5
	global_store_dwordx4 v[2:3], v[6:9], off
	s_cbranch_vccnz .LBB0_1099
	s_andn2_b64 vcc, exec, s[40:41]
	s_cbranch_vccnz .LBB0_1098
	s_mov_b32 s98, 1
	s_branch .LBB0_1098

; #define PG8_STAGE(bufoff, gbase, voff) do { _Pragma("unroll") for (int _i = 0; _i < 2; ++_i) \
;         __builtin_amdgcn_global_load_lds((const unsigned*)((const char*)(gbase) + (voff)[_i]), (PG8_LAS unsigned*)(lds + (bufoff) + ldsw + _i * 8192), 16, 0, 0); } while (0)
; #define PG8_LDA(dst, b, h) do { _Pragma("unroll") for (int m = 0; m < 4; ++m) _Pragma("unroll") for (int k = 0; k < 2; ++k) dst[m][k] = *(const PG8_LAS bf16x8*)(lds + PG8_SA(b, h) + aoff + m * 2048 + k * 1024); } while (0)
; #define PG8_LDB(dst, b, h) do { _Pragma("unroll") for (int n = 0; n < 2; ++n) _Pragma("unroll") for (int k = 0; k < 2; ++k) dst[n][k] = *(const PG8_LAS bf16x8*)(lds + PG8_SB(b, h) + boff + n * 2048 + k * 1024); } while (0)
; #define PG8_MMA(ai, bj, At, Bt) do { __builtin_amdgcn_s_setprio(1); _Pragma("unroll") for (int m = 0; m < 4; ++m) _Pragma("unroll") for (int n = 0; n < 2; ++n) _Pragma("unroll") for (int k = 0; k < 2; ++k) \
;         acc[ai][bj][m][n] = __builtin_amdgcn_mfma_f32_16x16x32_bf16(Bt[n][k], At[m][k], acc[ai][bj][m][n], 0, 0, 0); __builtin_amdgcn_s_setprio(0); } while (0)
; template <class Epi, class Sched, bool ALIGN_EPI = false, bool SP2 = false>
; __device__ __forceinline__ void gemm_phase(PG8_LAS unsigned char* lds, const Gemm g, const Sched& S, const Epi& E) {
;     ...
;         for (int t = 0; t < nt; t += 2) {
;             const bool last = (t == nt - 2);
;             const char* a1 = cA + (size_t)(t + 1) * kstep;
;             const char* a2 = last ? nA : cA + (size_t)(t + 2) * kstep; const char* b2 = last ? nB : cB + (size_t)(t + 2) * kstep;
;             const char* a3 = a2 + kstep; const char* b3 = b2 + kstep;
;             if (last && has_next) S.a_ready(nxt);
;             if constexpr (SP2) {
;             PG8_LDB(B0, 0, 0); PG8_LDB(B1, 0, 1); PG8_SCHED; PG8_LDA(At, 0, 0); PG8_STAGE(PG8_SA(1, 1), a1 + hstepA, voffA);
;             PG8_WAIT_V(8); PG8_WAIT_L(0); PG8_BAR; PG8_MMA(0, 0, At, B0); PG8_MMA(0, 1, At, B1); PG8_BAR; PG8_SCHED;
;     ...
; #pragma unroll
;         for (int a = 0; a < 2; ++a)
; #pragma unroll
;             for (int b = 0; b < 2; ++b)
; #pragma unroll
;                 for (int m = 0; m < 4; ++m)
; #pragma unroll
;                     for (int n = 0; n < 2; ++n) acc[a][b][m][n] = (f32x4){0.f, 0.f, 0.f, 0.f};
;         cur = nxt; cA = nA; cB = nB; ++ui;
;         if constexpr (ALIGN_EPI) { if (wr == 1) PG8_BAR; }
.LBB0_1197:
	s_add_u32 s4, s70, 0x100
	v_mov_b32_e32 v2, 0
	s_addc_u32 s5, s71, 0
	s_mov_b32 s7, -2
	v_mov_b32_e32 v3, v2
	v_mov_b32_e32 v4, v2
	v_mov_b32_e32 v5, v2
	v_mov_b32_e32 v6, v2
	v_mov_b32_e32 v7, v2
	v_mov_b32_e32 v8, v2
	v_mov_b32_e32 v9, v2
	v_mov_b32_e32 v18, v2
	v_mov_b32_e32 v19, v2
	v_mov_b32_e32 v20, v2
	v_mov_b32_e32 v21, v2
	v_mov_b32_e32 v22, v2
	v_mov_b32_e32 v23, v2
	v_mov_b32_e32 v24, v2
	v_mov_b32_e32 v25, v2
	v_mov_b32_e32 v34, v2
	v_mov_b32_e32 v35, v2
	v_mov_b32_e32 v36, v2
	v_mov_b32_e32 v37, v2
	v_mov_b32_e32 v38, v2
	v_mov_b32_e32 v39, v2
	v_mov_b32_e32 v40, v2
	v_mov_b32_e32 v41, v2
	v_mov_b32_e32 v50, v2
	v_mov_b32_e32 v51, v2
	v_mov_b32_e32 v52, v2
	v_mov_b32_e32 v53, v2
	v_mov_b32_e32 v54, v2
	v_mov_b32_e32 v55, v2
	v_mov_b32_e32 v56, v2
	v_mov_b32_e32 v57, v2
	v_mov_b32_e32 v10, v2
	v_mov_b32_e32 v11, v2
	v_mov_b32_e32 v12, v2
	v_mov_b32_e32 v13, v2
	v_mov_b32_e32 v14, v2
	v_mov_b32_e32 v15, v2
	v_mov_b32_e32 v16, v2
	v_mov_b32_e32 v17, v2
	v_mov_b32_e32 v26, v2
	v_mov_b32_e32 v27, v2
	v_mov_b32_e32 v28, v2
	v_mov_b32_e32 v29, v2
	v_mov_b32_e32 v30, v2
	v_mov_b32_e32 v31, v2
	v_mov_b32_e32 v32, v2
	v_mov_b32_e32 v33, v2
	v_mov_b32_e32 v42, v2
	v_mov_b32_e32 v43, v2
	v_mov_b32_e32 v44, v2
	v_mov_b32_e32 v45, v2
	v_mov_b32_e32 v46, v2
	v_mov_b32_e32 v47, v2
	v_mov_b32_e32 v48, v2
	v_mov_b32_e32 v49, v2
	v_mov_b32_e32 v58, v2
	v_mov_b32_e32 v59, v2
	v_mov_b32_e32 v60, v2
	v_mov_b32_e32 v61, v2
	v_mov_b32_e32 v62, v2
	v_mov_b32_e32 v63, v2
	v_mov_b32_e32 v64, v2
	v_mov_b32_e32 v65, v2
	v_mov_b32_e32 v66, v2
	v_mov_b32_e32 v67, v2
	v_mov_b32_e32 v68, v2
	v_mov_b32_e32 v69, v2
	v_mov_b32_e32 v70, v2
	v_mov_b32_e32 v71, v2
	v_mov_b32_e32 v72, v2
	v_mov_b32_e32 v73, v2
	v_mov_b32_e32 v82, v2
	v_mov_b32_e32 v83, v2
	v_mov_b32_e32 v84, v2
	v_mov_b32_e32 v85, v2
	v_mov_b32_e32 v86, v2
	v_mov_b32_e32 v87, v2
	v_mov_b32_e32 v88, v2
	v_mov_b32_e32 v89, v2
	v_mov_b32_e32 v98, v2
	v_mov_b32_e32 v99, v2
	v_mov_b32_e32 v100, v2
	v_mov_b32_e32 v101, v2
	v_mov_b32_e32 v102, v2
	v_mov_b32_e32 v103, v2
	v_mov_b32_e32 v104, v2
	v_mov_b32_e32 v105, v2
	v_mov_b32_e32 v114, v2
	v_mov_b32_e32 v115, v2
	v_mov_b32_e32 v116, v2
	v_mov_b32_e32 v117, v2
	v_mov_b32_e32 v118, v2
	v_mov_b32_e32 v119, v2
	v_mov_b32_e32 v120, v2
	v_mov_b32_e32 v121, v2
	v_mov_b32_e32 v74, v2
	v_mov_b32_e32 v75, v2
	v_mov_b32_e32 v76, v2
	v_mov_b32_e32 v77, v2
	v_mov_b32_e32 v78, v2
	v_mov_b32_e32 v79, v2
	v_mov_b32_e32 v80, v2
	v_mov_b32_e32 v81, v2
	v_mov_b32_e32 v90, v2
	v_mov_b32_e32 v91, v2
	v_mov_b32_e32 v92, v2
	v_mov_b32_e32 v93, v2
	v_mov_b32_e32 v94, v2
	v_mov_b32_e32 v95, v2
	v_mov_b32_e32 v96, v2
	v_mov_b32_e32 v97, v2
	v_mov_b32_e32 v106, v2
	v_mov_b32_e32 v107, v2
	v_mov_b32_e32 v108, v2
	v_mov_b32_e32 v109, v2
	v_mov_b32_e32 v110, v2
	v_mov_b32_e32 v111, v2
	v_mov_b32_e32 v112, v2
	v_mov_b32_e32 v113, v2
	v_mov_b32_e32 v122, v2
	v_mov_b32_e32 v123, v2
	v_mov_b32_e32 v124, v2
	v_mov_b32_e32 v125, v2
	v_mov_b32_e32 v126, v2
	v_mov_b32_e32 v127, v2
	v_mov_b32_e32 v128, v2
	v_mov_b32_e32 v129, v2
	s_cmp_eq_u32 s98, 1
	s_cbranch_scc0 .Ldefer_3
	s_barrier
	s_mov_b32 s98, 0
.Ldefer_3:
.LBB0_1198:
	ds_read_b128 v[130:133], v207
	ds_read_b128 v[134:137], v207 offset:1024
	ds_read_b128 v[138:141], v207 offset:2048
	ds_read_b128 v[142:145], v207 offset:3072
	ds_read_b128 v[146:149], v208
	ds_read_b128 v[150:153], v208 offset:1024
	ds_read_b128 v[154:157], v208 offset:2048
	ds_read_b128 v[158:161], v208 offset:3072
	s_add_u32 s70, s68, 0x100
	s_addc_u32 s71, s69, 0
	s_cmp_eq_u32 s7, 40
	s_cselect_b32 s77, s13, s71
	s_cselect_b32 s76, s12, s70
	s_cselect_b32 s73, s51, s5
	s_cselect_b32 s72, s50, s4
	v_lshl_add_u64 v[188:189], s[68:69], 0, v[176:177]
	s_add_i32 m0, s78, 0xc000
	ds_read_b128 v[184:187], v209
	ds_read_b128 v[212:215], v209 offset:1024
	ds_read_b128 v[216:219], v209 offset:2048
	ds_read_b128 v[220:223], v209 offset:3072
	ds_read_b128 v[224:227], v209 offset:4096
	ds_read_b128 v[228:231], v209 offset:5120
	ds_read_b128 v[232:235], v209 offset:6144
	ds_read_b128 v[236:239], v209 offset:7168
	global_load_lds_dwordx4 v[188:189], off
	v_lshl_add_u64 v[188:189], s[68:69], 0, v[178:179]
	s_add_i32 m0, s78, 0xe000
	s_nop 0
	global_load_lds_dwordx4 v[188:189], off
	s_waitcnt vmcnt(8)
	s_waitcnt lgkmcnt(0)
	s_setprio 1
	s_barrier
	v_mfma_f32_16x16x32_bf16 v[126:129], v[130:133], v[184:187], v[126:129]
	v_mfma_f32_16x16x32_bf16 v[122:125], v[138:141], v[184:187], v[122:125]
	v_mfma_f32_16x16x32_bf16 v[110:113], v[130:133], v[216:219], v[110:113]
	v_mfma_f32_16x16x32_bf16 v[106:109], v[138:141], v[216:219], v[106:109]
	v_mfma_f32_16x16x32_bf16 v[94:97], v[130:133], v[224:227], v[94:97]
	v_mfma_f32_16x16x32_bf16 v[90:93], v[138:141], v[224:227], v[90:93]
	v_mfma_f32_16x16x32_bf16 v[78:81], v[130:133], v[232:235], v[78:81]
	v_mfma_f32_16x16x32_bf16 v[74:77], v[138:141], v[232:235], v[74:77]
	v_mfma_f32_16x16x32_bf16 v[126:129], v[134:137], v[212:215], v[126:129]
	v_mfma_f32_16x16x32_bf16 v[122:125], v[142:145], v[212:215], v[122:125]
	v_mfma_f32_16x16x32_bf16 v[110:113], v[134:137], v[220:223], v[110:113]
	v_mfma_f32_16x16x32_bf16 v[106:109], v[142:145], v[220:223], v[106:109]
	v_mfma_f32_16x16x32_bf16 v[94:97], v[134:137], v[228:231], v[94:97]
	v_mfma_f32_16x16x32_bf16 v[90:93], v[142:145], v[228:231], v[90:93]
	v_mfma_f32_16x16x32_bf16 v[78:81], v[134:137], v[236:239], v[78:81]
	v_mfma_f32_16x16x32_bf16 v[74:77], v[142:145], v[236:239], v[74:77]
	s_setprio 0
	s_setprio 1
	v_mfma_f32_16x16x32_bf16 v[118:121], v[146:149], v[184:187], v[118:121]
	v_mfma_f32_16x16x32_bf16 v[114:117], v[154:157], v[184:187], v[114:117]
	v_mfma_f32_16x16x32_bf16 v[102:105], v[146:149], v[216:219], v[102:105]
	v_mfma_f32_16x16x32_bf16 v[98:101], v[154:157], v[216:219], v[98:101]
	v_mfma_f32_16x16x32_bf16 v[86:89], v[146:149], v[224:227], v[86:89]
	v_mfma_f32_16x16x32_bf16 v[82:85], v[154:157], v[224:227], v[82:85]
	v_mfma_f32_16x16x32_bf16 v[70:73], v[146:149], v[232:235], v[70:73]
	v_mfma_f32_16x16x32_bf16 v[66:69], v[154:157], v[232:235], v[66:69]
	v_mfma_f32_16x16x32_bf16 v[118:121], v[150:153], v[212:215], v[118:121]
	v_mfma_f32_16x16x32_bf16 v[114:117], v[158:161], v[212:215], v[114:117]
	v_mfma_f32_16x16x32_bf16 v[102:105], v[150:153], v[220:223], v[102:105]
	v_mfma_f32_16x16x32_bf16 v[98:101], v[158:161], v[220:223], v[98:101]
	v_mfma_f32_16x16x32_bf16 v[86:89], v[150:153], v[228:231], v[86:89]
	v_mfma_f32_16x16x32_bf16 v[82:85], v[158:161], v[228:231], v[82:85]
	v_mfma_f32_16x16x32_bf16 v[70:73], v[150:153], v[236:239], v[70:73]
	v_mfma_f32_16x16x32_bf16 v[66:69], v[158:161], v[236:239], v[66:69]
	s_setprio 0
	s_barrier
; #define PG8_STAGE(bufoff, gbase, voff) do { _Pragma("unroll") for (int _i = 0; _i < 2; ++_i) \
;         __builtin_amdgcn_global_load_lds((const unsigned*)((const char*)(gbase) + (voff)[_i]), (PG8_LAS unsigned*)(lds + (bufoff) + ldsw + _i * 8192), 16, 0, 0); } while (0)
; #define PG8_LDA(dst, b, h) do { _Pragma("unroll") for (int m = 0; m < 4; ++m) _Pragma("unroll") for (int k = 0; k < 2; ++k) dst[m][k] = *(const PG8_LAS bf16x8*)(lds + PG8_SA(b, h) + aoff + m * 2048 + k * 1024); } while (0)
; #define PG8_LDB(dst, b, h) do { _Pragma("unroll") for (int n = 0; n < 2; ++n) _Pragma("unroll") for (int k = 0; k < 2; ++k) dst[n][k] = *(const PG8_LAS bf16x8*)(lds + PG8_SB(b, h) + boff + n * 2048 + k * 1024); } while (0)
; #define PG8_MMA(ai, bj, At, Bt) do { __builtin_amdgcn_s_setprio(1); _Pragma("unroll") for (int m = 0; m < 4; ++m) _Pragma("unroll") for (int n = 0; n < 2; ++n) _Pragma("unroll") for (int k = 0; k < 2; ++k) \
;         acc[ai][bj][m][n] = __builtin_amdgcn_mfma_f32_16x16x32_bf16(Bt[n][k], At[m][k], acc[ai][bj][m][n], 0, 0, 0); __builtin_amdgcn_s_setprio(0); } while (0)
; #define PG8_WAIT_V(n) asm volatile("s_waitcnt vmcnt(" #n ")" ::: "memory")
; #define PG8_WAIT_L(n) asm volatile("s_waitcnt lgkmcnt(" #n ")" ::: "memory")
; #define PG8_BAR __builtin_amdgcn_s_barrier()
; #define PG8_SCHED __builtin_amdgcn_sched_barrier(0)
; template <class Epi, class Sched, bool ALIGN_EPI = false, bool SP2 = false>
; __device__ __forceinline__ void gemm_phase(PG8_LAS unsigned char* lds, const Gemm g, const Sched& S, const Epi& E) {
;     ...
;             PG8_WAIT_V(8); PG8_WAIT_L(0); PG8_BAR; PG8_MMA(0, 0, At, B0); PG8_MMA(0, 1, At, B1); PG8_BAR; PG8_SCHED;
;             PG8_LDA(At, 0, 1); PG8_STAGE(PG8_SB(0, 0), b2, voffB); PG8_STAGE(PG8_SB(0, 1), b2 + hstepB, voffB); PG8_STAGE(PG8_SA(0, 0), a2, voffA);
;             PG8_WAIT_V(8); PG8_WAIT_L(0); PG8_BAR; PG8_MMA(1, 0, At, B0); PG8_MMA(1, 1, At, B1); PG8_BAR; PG8_SCHED;
;             PG8_LDB(B0, 1, 0); PG8_LDB(B1, 1, 1); PG8_SCHED; PG8_LDA(At, 1, 0); PG8_STAGE(PG8_SA(0, 1), a2 + hstepA, voffA);
;             PG8_WAIT_V(8); PG8_WAIT_L(0); PG8_BAR; PG8_MMA(0, 0, At, B0); PG8_MMA(0, 1, At, B1); PG8_BAR; PG8_SCHED;
	s_add_i32 s0, s85, s67
	v_lshl_add_u64 v[188:189], s[72:73], 0, v[162:163]
	s_mov_b32 m0, s0
	ds_read_b128 v[184:187], v209 offset:16384
	ds_read_b128 v[212:215], v209 offset:17408
	ds_read_b128 v[216:219], v209 offset:18432
	ds_read_b128 v[220:223], v209 offset:19456
	ds_read_b128 v[224:227], v209 offset:20480
	ds_read_b128 v[228:231], v209 offset:21504
	ds_read_b128 v[232:235], v209 offset:22528
	ds_read_b128 v[236:239], v209 offset:23552
	global_load_lds_dwordx4 v[188:189], off
	s_add_i32 m0, s0, 0x2000
	s_add_u32 s0, s72, 0xb0000
	v_lshl_add_u64 v[240:241], s[72:73], 0, v[168:169]
	s_addc_u32 s1, s73, 0
	s_add_i32 s2, s86, s67
	global_load_lds_dwordx4 v[240:241], off
	v_lshl_add_u64 v[242:243], s[0:1], 0, v[162:163]
	s_mov_b32 m0, s2
	v_lshl_add_u64 v[244:245], s[76:77], 0, v[166:167]
	global_load_lds_dwordx4 v[242:243], off
	v_lshl_add_u64 v[242:243], s[0:1], 0, v[168:169]
	s_add_i32 m0, s2, 0x2000
	s_nop 0
	global_load_lds_dwordx4 v[242:243], off
	v_lshl_add_u64 v[242:243], s[76:77], 0, v[164:165]
	s_mov_b32 m0, s78
	s_nop 0
	global_load_lds_dwordx4 v[242:243], off
	s_mov_b32 m0, s79
	s_nop 0
	global_load_lds_dwordx4 v[244:245], off
	s_waitcnt vmcnt(8)
	s_waitcnt lgkmcnt(0)
	s_setprio 1
	s_barrier
	v_mfma_f32_16x16x32_bf16 v[62:65], v[130:133], v[184:187], v[62:65]
	v_mfma_f32_16x16x32_bf16 v[58:61], v[138:141], v[184:187], v[58:61]
	v_mfma_f32_16x16x32_bf16 v[46:49], v[130:133], v[216:219], v[46:49]
	v_mfma_f32_16x16x32_bf16 v[42:45], v[138:141], v[216:219], v[42:45]
	v_mfma_f32_16x16x32_bf16 v[30:33], v[130:133], v[224:227], v[30:33]
	v_mfma_f32_16x16x32_bf16 v[26:29], v[138:141], v[224:227], v[26:29]
	v_mfma_f32_16x16x32_bf16 v[14:17], v[130:133], v[232:235], v[14:17]
	v_mfma_f32_16x16x32_bf16 v[10:13], v[138:141], v[232:235], v[10:13]
	v_mfma_f32_16x16x32_bf16 v[62:65], v[134:137], v[212:215], v[62:65]
	v_mfma_f32_16x16x32_bf16 v[58:61], v[142:145], v[212:215], v[58:61]
	v_mfma_f32_16x16x32_bf16 v[46:49], v[134:137], v[220:223], v[46:49]
	v_mfma_f32_16x16x32_bf16 v[42:45], v[142:145], v[220:223], v[42:45]
	v_mfma_f32_16x16x32_bf16 v[30:33], v[134:137], v[228:231], v[30:33]
	v_mfma_f32_16x16x32_bf16 v[26:29], v[142:145], v[228:231], v[26:29]
	v_mfma_f32_16x16x32_bf16 v[14:17], v[134:137], v[236:239], v[14:17]
	v_mfma_f32_16x16x32_bf16 v[10:13], v[142:145], v[236:239], v[10:13]
	s_setprio 0
	s_setprio 1
	v_mfma_f32_16x16x32_bf16 v[54:57], v[146:149], v[184:187], v[54:57]
	v_mfma_f32_16x16x32_bf16 v[50:53], v[154:157], v[184:187], v[50:53]
	v_mfma_f32_16x16x32_bf16 v[38:41], v[146:149], v[216:219], v[38:41]
	v_mfma_f32_16x16x32_bf16 v[34:37], v[154:157], v[216:219], v[34:37]
	v_mfma_f32_16x16x32_bf16 v[22:25], v[146:149], v[224:227], v[22:25]
	v_mfma_f32_16x16x32_bf16 v[18:21], v[154:157], v[224:227], v[18:21]
	v_mfma_f32_16x16x32_bf16 v[6:9], v[146:149], v[232:235], v[6:9]
	v_mfma_f32_16x16x32_bf16 v[2:5], v[154:157], v[232:235], v[2:5]
	v_mfma_f32_16x16x32_bf16 v[54:57], v[150:153], v[212:215], v[54:57]
	v_mfma_f32_16x16x32_bf16 v[50:53], v[158:161], v[212:215], v[50:53]
	v_mfma_f32_16x16x32_bf16 v[38:41], v[150:153], v[220:223], v[38:41]
	v_mfma_f32_16x16x32_bf16 v[34:37], v[158:161], v[220:223], v[34:37]
	v_mfma_f32_16x16x32_bf16 v[22:25], v[150:153], v[228:231], v[22:25]
	v_mfma_f32_16x16x32_bf16 v[18:21], v[158:161], v[228:231], v[18:21]
	v_mfma_f32_16x16x32_bf16 v[6:9], v[150:153], v[236:239], v[6:9]
	v_mfma_f32_16x16x32_bf16 v[2:5], v[158:161], v[236:239], v[2:5]
	s_setprio 0
	s_barrier
	ds_read_b128 v[130:133], v210
	ds_read_b128 v[134:137], v210 offset:1024
	ds_read_b128 v[138:141], v210 offset:2048
	ds_read_b128 v[142:145], v210 offset:3072
	ds_read_b128 v[146:149], v211
	ds_read_b128 v[150:153], v211 offset:1024
	ds_read_b128 v[154:157], v211 offset:2048
	ds_read_b128 v[158:161], v211 offset:3072
	s_add_u32 s0, s76, 0xb0000
	s_addc_u32 s1, s77, 0
	s_mov_b32 m0, s80
	v_lshl_add_u64 v[246:247], s[0:1], 0, v[164:165]
	ds_read_b128 v[184:187], v209 offset:32768
	ds_read_b128 v[212:215], v209 offset:33792
	ds_read_b128 v[216:219], v209 offset:34816
	ds_read_b128 v[220:223], v209 offset:35840
	ds_read_b128 v[224:227], v209 offset:36864
	ds_read_b128 v[228:231], v209 offset:37888
	ds_read_b128 v[232:235], v209 offset:38912
	ds_read_b128 v[236:239], v209 offset:39936
	global_load_lds_dwordx4 v[246:247], off
	v_lshl_add_u64 v[246:247], s[0:1], 0, v[166:167]
	s_mov_b32 m0, s81
	s_nop 0
	global_load_lds_dwordx4 v[246:247], off
	s_waitcnt vmcnt(8)
	s_waitcnt lgkmcnt(0)
	s_setprio 1
	s_barrier
; #define PG8_STAGE(bufoff, gbase, voff) do { _Pragma("unroll") for (int _i = 0; _i < 2; ++_i) \
;         __builtin_amdgcn_global_load_lds((const unsigned*)((const char*)(gbase) + (voff)[_i]), (PG8_LAS unsigned*)(lds + (bufoff) + ldsw + _i * 8192), 16, 0, 0); } while (0)
; #define PG8_WAIT_V(n) asm volatile("s_waitcnt vmcnt(" #n ")" ::: "memory")
; #define PG8_WAIT_L(n) asm volatile("s_waitcnt lgkmcnt(" #n ")" ::: "memory")
; template <class Epi, class Sched, bool ALIGN_EPI = false, bool SP2 = false>
; __device__ __forceinline__ void gemm_phase(PG8_LAS unsigned char* lds, const Gemm g, const Sched& S, const Epi& E) {
;     ...
;             PG8_WAIT_V(8); PG8_WAIT_L(0); PG8_BAR; PG8_MMA(0, 0, At, B0); PG8_MMA(0, 1, At, B1); PG8_BAR; PG8_SCHED;
;             PG8_LDA(At, 1, 1); PG8_STAGE(PG8_SB(1, 0), b3, voffB); PG8_STAGE(PG8_SB(1, 1), b3 + hstepB, voffB); PG8_STAGE(PG8_SA(1, 0), a3, voffA);
;             PG8_WAIT_V(8); PG8_WAIT_L(0); PG8_BAR; PG8_MMA(1, 0, At, B0); PG8_MMA(1, 1, At, B1); PG8_BAR; PG8_SCHED;
;             } else {
;             PG8_LDB(B0, 0, 0); PG8_SCHED; PG8_LDA(At, 0, 0); PG8_STAGE(PG8_SA(1, 1), a1 + hstepA, voffA);
;             PG8_WAIT_L(8); PG8_BAR; PG8_WAIT_L(0); PG8_MMA(0, 0, At, B0); PG8_BAR; PG8_SCHED;
;             PG8_LDB(B1, 0, 1); PG8_STAGE(PG8_SB(0, 0), b2, voffB);
;             PG8_BAR; PG8_WAIT_L(0); PG8_MMA(0, 1, At, B1); PG8_BAR;
;             PG8_LDA(At, 0, 1); PG8_STAGE(PG8_SA(0, 0), a2, voffA);
;             PG8_BAR; PG8_WAIT_L(0); PG8_MMA(1, 0, At, B0); PG8_BAR; PG8_SCHED;
;             PG8_STAGE(PG8_SB(0, 1), b2 + hstepB, voffB);
;             PG8_WAIT_V(6); PG8_BAR; PG8_MMA(1, 1, At, B1); PG8_BAR;
;             PG8_LDB(B0, 1, 0); PG8_SCHED; PG8_LDA(At, 1, 0); PG8_STAGE(PG8_SA(0, 1), a2 + hstepA, voffA);
;             PG8_WAIT_L(8); PG8_BAR; PG8_WAIT_L(0); PG8_MMA(0, 0, At, B0); PG8_BAR; PG8_SCHED;
;             PG8_LDB(B1, 1, 1); PG8_STAGE(PG8_SB(1, 0), b3, voffB);
;             PG8_BAR; PG8_WAIT_L(0); PG8_MMA(0, 1, At, B1); PG8_BAR;
;             PG8_LDA(At, 1, 1); PG8_STAGE(PG8_SA(1, 0), a3, voffA);
;             PG8_BAR; PG8_WAIT_L(0); PG8_MMA(1, 0, At, B0); PG8_BAR; PG8_SCHED;
;             PG8_STAGE(PG8_SB(1, 1), b3 + hstepB, voffB);
;             PG8_WAIT_V(6); PG8_BAR; PG8_MMA(1, 1, At, B1); PG8_BAR;
;             }
;         }
;         if constexpr (ALIGN_EPI) { if (wr == 0) PG8_BAR; }
	v_mfma_f32_16x16x32_bf16 v[126:129], v[130:133], v[184:187], v[126:129]
	v_mfma_f32_16x16x32_bf16 v[122:125], v[138:141], v[184:187], v[122:125]
	v_mfma_f32_16x16x32_bf16 v[110:113], v[130:133], v[216:219], v[110:113]
	v_mfma_f32_16x16x32_bf16 v[106:109], v[138:141], v[216:219], v[106:109]
	v_mfma_f32_16x16x32_bf16 v[94:97], v[130:133], v[224:227], v[94:97]
	v_mfma_f32_16x16x32_bf16 v[90:93], v[138:141], v[224:227], v[90:93]
	v_mfma_f32_16x16x32_bf16 v[78:81], v[130:133], v[232:235], v[78:81]
	v_mfma_f32_16x16x32_bf16 v[74:77], v[138:141], v[232:235], v[74:77]
	v_mfma_f32_16x16x32_bf16 v[126:129], v[134:137], v[212:215], v[126:129]
	v_mfma_f32_16x16x32_bf16 v[122:125], v[142:145], v[212:215], v[122:125]
	v_mfma_f32_16x16x32_bf16 v[110:113], v[134:137], v[220:223], v[110:113]
	v_mfma_f32_16x16x32_bf16 v[106:109], v[142:145], v[220:223], v[106:109]
	v_mfma_f32_16x16x32_bf16 v[94:97], v[134:137], v[228:231], v[94:97]
	v_mfma_f32_16x16x32_bf16 v[90:93], v[142:145], v[228:231], v[90:93]
	v_mfma_f32_16x16x32_bf16 v[78:81], v[134:137], v[236:239], v[78:81]
	v_mfma_f32_16x16x32_bf16 v[74:77], v[142:145], v[236:239], v[74:77]
	s_setprio 0
	s_setprio 1
	v_mfma_f32_16x16x32_bf16 v[118:121], v[146:149], v[184:187], v[118:121]
	v_mfma_f32_16x16x32_bf16 v[114:117], v[154:157], v[184:187], v[114:117]
	v_mfma_f32_16x16x32_bf16 v[102:105], v[146:149], v[216:219], v[102:105]
	v_mfma_f32_16x16x32_bf16 v[98:101], v[154:157], v[216:219], v[98:101]
	v_mfma_f32_16x16x32_bf16 v[86:89], v[146:149], v[224:227], v[86:89]
	v_mfma_f32_16x16x32_bf16 v[82:85], v[154:157], v[224:227], v[82:85]
	v_mfma_f32_16x16x32_bf16 v[70:73], v[146:149], v[232:235], v[70:73]
	v_mfma_f32_16x16x32_bf16 v[66:69], v[154:157], v[232:235], v[66:69]
	v_mfma_f32_16x16x32_bf16 v[118:121], v[150:153], v[212:215], v[118:121]
	v_mfma_f32_16x16x32_bf16 v[114:117], v[158:161], v[212:215], v[114:117]
	v_mfma_f32_16x16x32_bf16 v[102:105], v[150:153], v[220:223], v[102:105]
	v_mfma_f32_16x16x32_bf16 v[98:101], v[158:161], v[220:223], v[98:101]
	v_mfma_f32_16x16x32_bf16 v[86:89], v[150:153], v[228:231], v[86:89]
	v_mfma_f32_16x16x32_bf16 v[82:85], v[158:161], v[228:231], v[82:85]
	v_mfma_f32_16x16x32_bf16 v[70:73], v[150:153], v[236:239], v[70:73]
	v_mfma_f32_16x16x32_bf16 v[66:69], v[158:161], v[236:239], v[66:69]
	s_setprio 0
	s_barrier
	s_add_i32 s0, s87, s67
	v_lshl_add_u64 v[188:189], v[188:189], 0, s[36:37]
	s_mov_b32 m0, s0
	ds_read_b128 v[184:187], v209 offset:49152
	ds_read_b128 v[212:215], v209 offset:50176
	ds_read_b128 v[216:219], v209 offset:51200
	ds_read_b128 v[220:223], v209 offset:52224
	ds_read_b128 v[224:227], v209 offset:53248
	ds_read_b128 v[228:231], v209 offset:54272
	ds_read_b128 v[232:235], v209 offset:55296
	ds_read_b128 v[236:239], v209 offset:56320
	global_load_lds_dwordx4 v[188:189], off
	s_add_i32 m0, s0, 0x2000
	s_add_u32 s0, s72, 0xb0080
	v_lshl_add_u64 v[188:189], v[240:241], 0, s[36:37]
	s_addc_u32 s1, s73, 0
	s_add_i32 s2, s88, s67
	global_load_lds_dwordx4 v[188:189], off
	v_lshl_add_u64 v[188:189], s[0:1], 0, v[162:163]
	s_mov_b32 m0, s2
	s_nop 0
	global_load_lds_dwordx4 v[188:189], off
	v_lshl_add_u64 v[188:189], s[0:1], 0, v[168:169]
	s_add_i32 m0, s2, 0x2000
	s_nop 0
	global_load_lds_dwordx4 v[188:189], off
	v_lshl_add_u64 v[188:189], v[242:243], 0, s[36:37]
	s_mov_b32 m0, s82
	s_nop 0
	global_load_lds_dwordx4 v[188:189], off
	v_lshl_add_u64 v[188:189], v[244:245], 0, s[36:37]
	s_mov_b32 m0, s83
	s_nop 0
	global_load_lds_dwordx4 v[188:189], off
	s_waitcnt vmcnt(8)
	s_waitcnt lgkmcnt(0)
	s_setprio 1
	s_barrier
	v_mfma_f32_16x16x32_bf16 v[62:65], v[130:133], v[184:187], v[62:65]
	v_mfma_f32_16x16x32_bf16 v[58:61], v[138:141], v[184:187], v[58:61]
	v_mfma_f32_16x16x32_bf16 v[46:49], v[130:133], v[216:219], v[46:49]
	v_mfma_f32_16x16x32_bf16 v[42:45], v[138:141], v[216:219], v[42:45]
	v_mfma_f32_16x16x32_bf16 v[30:33], v[130:133], v[224:227], v[30:33]
	v_mfma_f32_16x16x32_bf16 v[26:29], v[138:141], v[224:227], v[26:29]
	v_mfma_f32_16x16x32_bf16 v[14:17], v[130:133], v[232:235], v[14:17]
	v_mfma_f32_16x16x32_bf16 v[10:13], v[138:141], v[232:235], v[10:13]
	v_mfma_f32_16x16x32_bf16 v[62:65], v[134:137], v[212:215], v[62:65]
	v_mfma_f32_16x16x32_bf16 v[58:61], v[142:145], v[212:215], v[58:61]
	v_mfma_f32_16x16x32_bf16 v[46:49], v[134:137], v[220:223], v[46:49]
	v_mfma_f32_16x16x32_bf16 v[42:45], v[142:145], v[220:223], v[42:45]
	v_mfma_f32_16x16x32_bf16 v[30:33], v[134:137], v[228:231], v[30:33]
	v_mfma_f32_16x16x32_bf16 v[26:29], v[142:145], v[228:231], v[26:29]
	v_mfma_f32_16x16x32_bf16 v[14:17], v[134:137], v[236:239], v[14:17]
	v_mfma_f32_16x16x32_bf16 v[10:13], v[142:145], v[236:239], v[10:13]
	s_setprio 0
	s_setprio 1
	v_mfma_f32_16x16x32_bf16 v[54:57], v[146:149], v[184:187], v[54:57]
	v_mfma_f32_16x16x32_bf16 v[50:53], v[154:157], v[184:187], v[50:53]
	v_mfma_f32_16x16x32_bf16 v[38:41], v[146:149], v[216:219], v[38:41]
	v_mfma_f32_16x16x32_bf16 v[34:37], v[154:157], v[216:219], v[34:37]
	v_mfma_f32_16x16x32_bf16 v[22:25], v[146:149], v[224:227], v[22:25]
	v_mfma_f32_16x16x32_bf16 v[18:21], v[154:157], v[224:227], v[18:21]
	v_mfma_f32_16x16x32_bf16 v[6:9], v[146:149], v[232:235], v[6:9]
	v_mfma_f32_16x16x32_bf16 v[2:5], v[154:157], v[232:235], v[2:5]
	v_mfma_f32_16x16x32_bf16 v[54:57], v[150:153], v[212:215], v[54:57]
	v_mfma_f32_16x16x32_bf16 v[50:53], v[158:161], v[212:215], v[50:53]
	v_mfma_f32_16x16x32_bf16 v[38:41], v[150:153], v[220:223], v[38:41]
	v_mfma_f32_16x16x32_bf16 v[34:37], v[158:161], v[220:223], v[34:37]
	v_mfma_f32_16x16x32_bf16 v[22:25], v[150:153], v[228:231], v[22:25]
	v_mfma_f32_16x16x32_bf16 v[18:21], v[158:161], v[228:231], v[18:21]
	v_mfma_f32_16x16x32_bf16 v[6:9], v[150:153], v[236:239], v[6:9]
	v_mfma_f32_16x16x32_bf16 v[2:5], v[158:161], v[236:239], v[2:5]
	s_setprio 0
	s_barrier
	s_add_i32 s7, s7, 2
	s_add_u32 s4, s4, 0x100
	s_addc_u32 s5, s5, 0
	s_cmp_gt_u32 s7, 41
	s_mov_b64 s[68:69], s[70:71]
	s_cbranch_scc0 .LBB0_1198
	s_and_b64 vcc, exec, s[40:41]
	s_cbranch_vccz .LBB0_1201
	s_barrier
; #define RL_LOAD(PW, AI) do { _Pragma("unroll") for (int m = 0; m < 4; ++m) _Pragma("unroll") for (int bj = 0; bj < 2; ++bj) (PW)[m][bj] = *(const u32x4*)(hin + (size_t)(row0 + (AI) * HALF + m * 16) * 1024 + col0 + bj * HALF); } while (0)
;     __device__ __forceinline__ void run(const f32x4 (&acc)[2][2][4][2], const Unit& u, int wr, int wc, int fr, int fq, const PG8_LAS unsigned char* sp) const {
;     ...
;         const int rl0 = wr * 64 + fr, cl0 = wc * 32 + 8 * fq;
;         const int row0 = u.pm * BM + rl0, col0 = u.pn * BM + cl0;
;         u32x4 pwa[4][2], pwb[4][2];
;     ...
;         RL_LOAD(pwa, 0);
;         RL_ROW(pwa, 0, 0); RL_ROW(pwa, 0, 1);
;         RL_LOAD(pwb, 1);
.LBB0_1201:
	s_lshl_b32 s7, s66, 8
	v_lshl_or_b32 v130, s6, 8, v190
	v_add_u32_e32 v134, s7, v1
	v_ashrrev_i32_e32 v131, 31, v130
	v_readlane_b32 s14, v253, 21
	v_lshlrev_b64 v[184:185], 1, v[130:131]
	v_readlane_b32 s15, v253, 22
	v_ashrrev_i32_e32 v135, 31, v134
	v_lshlrev_b64 v[132:133], 11, v[134:135]
	v_lshl_add_u64 v[130:131], s[14:15], 0, v[184:185]
	v_lshl_add_u64 v[186:187], v[130:131], 0, v[132:133]
	global_load_dwordx4 v[154:157], v[186:187], off
	global_load_dwordx4 v[146:149], v[186:187], off offset:256
	v_or_b32_e32 v136, 16, v134
	v_or_b32_e32 v138, 32, v134
	v_or_b32_e32 v134, 48, v134
	v_ashrrev_i32_e32 v137, 31, v136
	v_ashrrev_i32_e32 v139, 31, v138
	v_ashrrev_i32_e32 v135, 31, v134
	v_lshlrev_b64 v[136:137], 11, v[136:137]
	v_lshlrev_b64 v[138:139], 11, v[138:139]
	v_lshlrev_b64 v[134:135], 11, v[134:135]
	v_lshl_add_u64 v[132:133], s[14:15], 0, v[132:133]
	v_lshl_add_u64 v[136:137], v[130:131], 0, v[136:137]
	v_lshl_add_u64 v[138:139], v[130:131], 0, v[138:139]
	v_lshl_add_u64 v[130:131], v[130:131], 0, v[134:135]
	v_lshl_add_u64 v[188:189], v[132:133], 0, v[184:185]
	global_load_dwordx4 v[158:161], v[136:137], off
	global_load_dwordx4 v[150:153], v[136:137], off offset:256
	global_load_dwordx4 v[142:145], v[138:139], off
	s_nop 0
	global_load_dwordx4 v[138:141], v[138:139], off offset:256
	s_nop 0
	global_load_dwordx4 v[134:137], v[130:131], off
	s_nop 0
	global_load_dwordx4 v[130:133], v[130:131], off offset:256
	s_mul_hi_u32 s0, s43, 0xaaaaaaab
	s_lshr_b32 s0, s0, 1
	s_mul_i32 s0, s0, 3
	s_sub_i32 s0, s43, s0
	s_lshl_b32 s0, s0, 12
	s_add_i32 s4, s0, 0
	s_add_i32 s4, s4, 0x20000
	v_add_u32_e32 v213, s4, v191
	v_add_u32_e32 v212, s4, v192
	ds_read_b64 v[230:231], v213
	ds_read_b128 v[214:217], v212 offset:2048
	ds_read_b128 v[218:221], v212 offset:2064
	ds_read_b128 v[222:225], v212 offset:3072
	ds_read_b128 v[226:229], v212 offset:3088
	s_mov_b64 s[0:1], 0x40000
	s_waitcnt vmcnt(0)
	v_lshlrev_b32_e32 v213, 16, v154
	v_and_b32_e32 v154, 0xffff0000, v154
	v_lshlrev_b32_e32 v232, 16, v155
	v_and_b32_e32 v155, 0xffff0000, v155
	v_lshlrev_b32_e32 v233, 16, v156
	v_and_b32_e32 v156, 0xffff0000, v156
	v_lshlrev_b32_e32 v234, 16, v157
	v_and_b32_e32 v157, 0xffff0000, v157
	v_lshlrev_b32_e32 v235, 16, v146
	v_and_b32_e32 v236, 0xffff0000, v146
	v_lshlrev_b32_e32 v237, 16, v147
	v_and_b32_e32 v238, 0xffff0000, v147
	v_lshlrev_b32_e32 v239, 16, v148
	v_and_b32_e32 v240, 0xffff0000, v148
	v_lshlrev_b32_e32 v241, 16, v149
	v_and_b32_e32 v242, 0xffff0000, v149
	s_waitcnt lgkmcnt(4)
	v_sub_f32_e32 v147, v154, v230
	v_sub_f32_e32 v146, v213, v230
	v_sub_f32_e32 v149, v155, v230
	v_sub_f32_e32 v148, v232, v230
	v_sub_f32_e32 v155, v156, v230
	v_sub_f32_e32 v154, v233, v230
	v_sub_f32_e32 v157, v157, v230
	v_sub_f32_e32 v156, v234, v230
	v_pk_mul_f32 v[148:149], v[230:231], v[148:149] op_sel:[1,0]
	v_pk_mul_f32 v[146:147], v[230:231], v[146:147] op_sel:[1,0]
	v_pk_mul_f32 v[156:157], v[230:231], v[156:157] op_sel:[1,0]
	v_pk_mul_f32 v[154:155], v[230:231], v[154:155] op_sel:[1,0]
	s_waitcnt lgkmcnt(1)
	v_pk_fma_f32 v[146:147], v[214:215], v[146:147], v[222:223]
	v_pk_fma_f32 v[148:149], v[216:217], v[148:149], v[224:225]
	s_waitcnt lgkmcnt(0)
	v_pk_fma_f32 v[154:155], v[218:219], v[154:155], v[226:227]
	v_pk_fma_f32 v[156:157], v[220:221], v[156:157], v[228:229]
	v_pk_fma_f32 v[128:129], v[148:149], s[42:43], v[128:129] op_sel_hi:[1,0,1]
	v_pk_fma_f32 v[126:127], v[146:147], s[42:43], v[126:127] op_sel_hi:[1,0,1]
	v_pk_fma_f32 v[146:147], v[156:157], s[42:43], v[124:125] op_sel_hi:[1,0,1]
	v_pk_fma_f32 v[124:125], v[154:155], s[42:43], v[122:123] op_sel_hi:[1,0,1]
	v_cvt_pk_bf16_f32 v122, v126, v127
	v_cvt_pk_bf16_f32 v123, v128, v129
	v_sub_f32_e32 v233, v236, v230
	v_cvt_pk_bf16_f32 v124, v124, v125
	v_cvt_pk_bf16_f32 v125, v146, v147
	ds_read_b128 v[126:129], v212 offset:2560
	ds_read_b128 v[146:149], v212 offset:2576
	ds_read_b128 v[154:157], v212 offset:3584
	ds_read_b128 v[214:217], v212 offset:3600
	v_sub_f32_e32 v232, v235, v230
	global_store_dwordx4 v[188:189], v[122:125], off
	v_lshlrev_b32_e32 v213, 16, v142
	v_and_b32_e32 v142, 0xffff0000, v142
	v_sub_f32_e32 v123, v238, v230
	v_sub_f32_e32 v122, v237, v230
	v_pk_mul_f32 v[122:123], v[230:231], v[122:123] op_sel:[1,0]
	v_pk_mul_f32 v[124:125], v[230:231], v[232:233] op_sel:[1,0]
	s_waitcnt lgkmcnt(1)
	v_pk_fma_f32 v[122:123], v[122:123], v[128:129], v[156:157]
	v_pk_fma_f32 v[124:125], v[124:125], v[126:127], v[154:155]
	v_pk_fma_f32 v[120:121], v[122:123], s[42:43], v[120:121] op_sel_hi:[1,0,1]
	v_pk_fma_f32 v[118:119], v[124:125], s[42:43], v[118:119] op_sel_hi:[1,0,1]
	v_sub_f32_e32 v123, v240, v230
	v_sub_f32_e32 v122, v239, v230
	v_sub_f32_e32 v125, v242, v230
	v_sub_f32_e32 v124, v241, v230
	v_pk_mul_f32 v[124:125], v[230:231], v[124:125] op_sel:[1,0]
	v_pk_mul_f32 v[122:123], v[230:231], v[122:123] op_sel:[1,0]
	s_waitcnt lgkmcnt(0)
	v_pk_fma_f32 v[124:125], v[124:125], v[148:149], v[216:217]
	v_pk_fma_f32 v[122:123], v[122:123], v[146:147], v[214:215]
	v_pk_fma_f32 v[124:125], v[124:125], s[42:43], v[116:117] op_sel_hi:[1,0,1]
	v_pk_fma_f32 v[116:117], v[122:123], s[42:43], v[114:115] op_sel_hi:[1,0,1]
	v_cvt_pk_bf16_f32 v114, v118, v119
	v_cvt_pk_bf16_f32 v115, v120, v121
	v_lshlrev_b32_e32 v154, 16, v158
	v_cvt_pk_bf16_f32 v116, v116, v117
	v_cvt_pk_bf16_f32 v117, v124, v125
	global_store_dwordx4 v[188:189], v[114:117], off offset:256
	v_and_b32_e32 v155, 0xffff0000, v158
	v_lshlrev_b32_e32 v156, 16, v159
	v_add_u32_e32 v116, s4, v194
	ds_read_b64 v[146:147], v116
	v_add_u32_e32 v114, s7, v193
	v_ashrrev_i32_e32 v115, 31, v114
	v_lshlrev_b64 v[148:149], 11, v[114:115]
	ds_read_b128 v[114:117], v212 offset:2048
	ds_read_b128 v[118:121], v212 offset:2064
	ds_read_b128 v[122:125], v212 offset:3072
	ds_read_b128 v[126:129], v212 offset:3088
	v_and_b32_e32 v157, 0xffff0000, v159
	s_waitcnt lgkmcnt(4)
; #define RL_LOAD(PW, AI) do { _Pragma("unroll") for (int m = 0; m < 4; ++m) _Pragma("unroll") for (int bj = 0; bj < 2; ++bj) (PW)[m][bj] = *(const u32x4*)(hin + (size_t)(row0 + (AI) * HALF + m * 16) * 1024 + col0 + bj * HALF); } while (0)
;     __device__ __forceinline__ void run(const f32x4 (&acc)[2][2][4][2], const Unit& u, int wr, int wc, int fr, int fq, const PG8_LAS unsigned char* sp) const {
;     ...
;         RL_LOAD(pwa, 0);
;         RL_ROW(pwa, 0, 0); RL_ROW(pwa, 0, 1);
;         RL_LOAD(pwb, 1);
;         RL_ROW(pwa, 0, 2); RL_ROW(pwa, 0, 3);
	v_sub_f32_e32 v155, v155, v146
	v_sub_f32_e32 v154, v154, v146
	v_sub_f32_e32 v157, v157, v146
	v_sub_f32_e32 v156, v156, v146
	v_pk_mul_f32 v[156:157], v[146:147], v[156:157] op_sel:[1,0]
	v_pk_mul_f32 v[154:155], v[146:147], v[154:155] op_sel:[1,0]
	v_lshlrev_b32_e32 v158, 16, v160
	v_and_b32_e32 v159, 0xffff0000, v160
	v_lshlrev_b32_e32 v160, 16, v161
	v_and_b32_e32 v161, 0xffff0000, v161
	s_waitcnt lgkmcnt(1)
	v_pk_fma_f32 v[114:115], v[114:115], v[154:155], v[122:123]
	v_pk_fma_f32 v[116:117], v[116:117], v[156:157], v[124:125]
	v_pk_fma_f32 v[110:111], v[114:115], s[42:43], v[110:111] op_sel_hi:[1,0,1]
	v_pk_fma_f32 v[112:113], v[116:117], s[42:43], v[112:113] op_sel_hi:[1,0,1]
	v_sub_f32_e32 v115, v159, v146
	v_sub_f32_e32 v114, v158, v146
	v_sub_f32_e32 v117, v161, v146
	v_sub_f32_e32 v116, v160, v146
	v_pk_mul_f32 v[116:117], v[146:147], v[116:117] op_sel:[1,0]
	v_pk_mul_f32 v[114:115], v[146:147], v[114:115] op_sel:[1,0]
	s_waitcnt lgkmcnt(0)
	v_pk_fma_f32 v[116:117], v[120:121], v[116:117], v[128:129]
	v_pk_fma_f32 v[114:115], v[118:119], v[114:115], v[126:127]
	v_pk_fma_f32 v[116:117], v[116:117], s[42:43], v[108:109] op_sel_hi:[1,0,1]
	v_pk_fma_f32 v[108:109], v[114:115], s[42:43], v[106:107] op_sel_hi:[1,0,1]
	v_cvt_pk_bf16_f32 v106, v110, v111
	v_lshl_add_u64 v[110:111], s[14:15], 0, v[148:149]
	v_lshl_add_u64 v[122:123], v[110:111], 0, v[184:185]
	v_cvt_pk_bf16_f32 v107, v112, v113
	v_cvt_pk_bf16_f32 v108, v108, v109
	v_cvt_pk_bf16_f32 v109, v116, v117
	global_store_dwordx4 v[122:123], v[106:109], off
	ds_read_b128 v[106:109], v212 offset:2560
	ds_read_b128 v[110:113], v212 offset:2576
	ds_read_b128 v[114:117], v212 offset:3584
	ds_read_b128 v[118:121], v212 offset:3600
	v_lshlrev_b32_e32 v124, 16, v150
	v_and_b32_e32 v125, 0xffff0000, v150
	v_lshlrev_b32_e32 v126, 16, v151
	v_and_b32_e32 v127, 0xffff0000, v151
	v_sub_f32_e32 v125, v125, v146
	v_sub_f32_e32 v124, v124, v146
	v_sub_f32_e32 v127, v127, v146
	v_sub_f32_e32 v126, v126, v146
	v_pk_mul_f32 v[126:127], v[146:147], v[126:127] op_sel:[1,0]
	v_pk_mul_f32 v[124:125], v[146:147], v[124:125] op_sel:[1,0]
	v_lshlrev_b32_e32 v128, 16, v152
	v_and_b32_e32 v129, 0xffff0000, v152
	v_lshlrev_b32_e32 v148, 16, v153
	v_and_b32_e32 v149, 0xffff0000, v153
	s_waitcnt lgkmcnt(1)
	v_pk_fma_f32 v[106:107], v[124:125], v[106:107], v[114:115]
	v_pk_fma_f32 v[108:109], v[126:127], v[108:109], v[116:117]
	v_pk_fma_f32 v[102:103], v[106:107], s[42:43], v[102:103] op_sel_hi:[1,0,1]
	v_pk_fma_f32 v[104:105], v[108:109], s[42:43], v[104:105] op_sel_hi:[1,0,1]
	v_sub_f32_e32 v107, v129, v146
	v_sub_f32_e32 v106, v128, v146
	v_sub_f32_e32 v109, v149, v146
	v_sub_f32_e32 v108, v148, v146
	v_pk_mul_f32 v[108:109], v[146:147], v[108:109] op_sel:[1,0]
	v_pk_mul_f32 v[106:107], v[146:147], v[106:107] op_sel:[1,0]
	s_waitcnt lgkmcnt(0)
	v_pk_fma_f32 v[108:109], v[108:109], v[112:113], v[120:121]
	v_pk_fma_f32 v[106:107], v[106:107], v[110:111], v[118:119]
	v_pk_fma_f32 v[108:109], v[108:109], s[42:43], v[100:101] op_sel_hi:[1,0,1]
	v_pk_fma_f32 v[100:101], v[106:107], s[42:43], v[98:99] op_sel_hi:[1,0,1]
	v_cvt_pk_bf16_f32 v98, v102, v103
	v_cvt_pk_bf16_f32 v99, v104, v105
	v_add_u32_e32 v148, s4, v196
	v_cvt_pk_bf16_f32 v100, v100, v101
	v_cvt_pk_bf16_f32 v101, v108, v109
	global_store_dwordx4 v[122:123], v[98:101], off offset:256
	v_add_u32_e32 v146, s7, v195
	v_ashrrev_i32_e32 v147, 31, v146
	v_lshl_add_u64 v[98:99], v[186:187], 0, s[0:1]
	s_mov_b32 s0, 0x40000
	v_add_co_u32_e32 v100, vcc, s0, v186
	s_mov_b64 s[0:1], 0x48000
	s_nop 0
	v_addc_co_u32_e32 v101, vcc, 0, v187, vcc
	global_load_dwordx4 v[126:129], v[100:101], off
	global_load_dwordx4 v[122:125], v[98:99], off offset:256
	v_lshl_add_u64 v[98:99], v[186:187], 0, s[0:1]
	s_mov_b32 s0, 0x48000
	v_add_co_u32_e32 v100, vcc, s0, v186
	v_lshlrev_b64 v[188:189], 11, v[146:147]
	s_nop 0
	v_addc_co_u32_e32 v101, vcc, 0, v187, vcc
	global_load_dwordx4 v[118:121], v[100:101], off
	global_load_dwordx4 v[114:117], v[98:99], off offset:256
	v_add_co_u32_e32 v100, vcc, s89, v186
	v_lshl_add_u64 v[98:99], v[186:187], 0, s[44:45]
	s_nop 0
	v_addc_co_u32_e32 v101, vcc, 0, v187, vcc
	global_load_dwordx4 v[110:113], v[100:101], off
	global_load_dwordx4 v[106:109], v[98:99], off offset:256
	v_add_co_u32_e32 v100, vcc, s90, v186
	v_lshl_add_u64 v[98:99], v[186:187], 0, s[46:47]
	s_nop 0
	v_addc_co_u32_e32 v101, vcc, 0, v187, vcc
	global_load_dwordx4 v[102:105], v[100:101], off
	s_nop 0
	global_load_dwordx4 v[98:101], v[98:99], off offset:256
	ds_read_b64 v[186:187], v148
	ds_read_b128 v[146:149], v212 offset:2048
	ds_read_b128 v[150:153], v212 offset:2064
	ds_read_b128 v[154:157], v212 offset:3072
	ds_read_b128 v[158:161], v212 offset:3088
	v_lshlrev_b32_e32 v214, 16, v143
	v_and_b32_e32 v215, 0xffff0000, v143
	v_lshlrev_b32_e32 v216, 16, v144
	v_and_b32_e32 v217, 0xffff0000, v144
	v_lshlrev_b32_e32 v218, 16, v145
	v_and_b32_e32 v219, 0xffff0000, v145
	s_waitcnt lgkmcnt(4)
	v_sub_f32_e32 v143, v142, v186
	v_sub_f32_e32 v142, v213, v186
	v_sub_f32_e32 v145, v215, v186
	v_sub_f32_e32 v144, v214, v186
	v_pk_mul_f32 v[144:145], v[186:187], v[144:145] op_sel:[1,0]
	v_pk_mul_f32 v[142:143], v[186:187], v[142:143] op_sel:[1,0]
	s_waitcnt lgkmcnt(1)
	v_pk_fma_f32 v[144:145], v[148:149], v[144:145], v[156:157]
	v_pk_fma_f32 v[142:143], v[146:147], v[142:143], v[154:155]
	v_pk_fma_f32 v[96:97], v[144:145], s[42:43], v[96:97] op_sel_hi:[1,0,1]
	v_pk_fma_f32 v[94:95], v[142:143], s[42:43], v[94:95] op_sel_hi:[1,0,1]
	v_sub_f32_e32 v143, v217, v186
	v_sub_f32_e32 v142, v216, v186
	v_sub_f32_e32 v145, v219, v186
	v_sub_f32_e32 v144, v218, v186
	v_pk_mul_f32 v[144:145], v[186:187], v[144:145] op_sel:[1,0]
	v_pk_mul_f32 v[142:143], v[186:187], v[142:143] op_sel:[1,0]
	s_waitcnt lgkmcnt(0)
; #define RL_LOAD(PW, AI) do { _Pragma("unroll") for (int m = 0; m < 4; ++m) _Pragma("unroll") for (int bj = 0; bj < 2; ++bj) (PW)[m][bj] = *(const u32x4*)(hin + (size_t)(row0 + (AI) * HALF + m * 16) * 1024 + col0 + bj * HALF); } while (0)
;     __device__ __forceinline__ void run(const f32x4 (&acc)[2][2][4][2], const Unit& u, int wr, int wc, int fr, int fq, const PG8_LAS unsigned char* sp) const {
;     ...
;         RL_LOAD(pwa, 0);
;         RL_ROW(pwa, 0, 0); RL_ROW(pwa, 0, 1);
;         RL_LOAD(pwb, 1);
;         RL_ROW(pwa, 0, 2); RL_ROW(pwa, 0, 3);
	v_pk_fma_f32 v[144:145], v[152:153], v[144:145], v[160:161]
	v_pk_fma_f32 v[142:143], v[150:151], v[142:143], v[158:159]
	v_pk_fma_f32 v[144:145], v[144:145], s[42:43], v[92:93] op_sel_hi:[1,0,1]
	v_pk_fma_f32 v[92:93], v[142:143], s[42:43], v[90:91] op_sel_hi:[1,0,1]
	v_cvt_pk_bf16_f32 v90, v94, v95
	v_lshl_add_u64 v[94:95], s[14:15], 0, v[188:189]
	v_lshl_add_u64 v[150:151], v[94:95], 0, v[184:185]
	v_cvt_pk_bf16_f32 v91, v96, v97
	v_cvt_pk_bf16_f32 v92, v92, v93
	v_cvt_pk_bf16_f32 v93, v144, v145
	global_store_dwordx4 v[150:151], v[90:93], off
	ds_read_b128 v[90:93], v212 offset:2560
	ds_read_b128 v[94:97], v212 offset:2576
	ds_read_b128 v[142:145], v212 offset:3584
	ds_read_b128 v[146:149], v212 offset:3600
	v_lshlrev_b32_e32 v152, 16, v138
	v_and_b32_e32 v138, 0xffff0000, v138
	v_lshlrev_b32_e32 v153, 16, v139
	v_and_b32_e32 v154, 0xffff0000, v139
	v_lshlrev_b32_e32 v155, 16, v140
	v_and_b32_e32 v156, 0xffff0000, v140
	v_lshlrev_b32_e32 v157, 16, v141
	v_and_b32_e32 v158, 0xffff0000, v141
	v_sub_f32_e32 v139, v138, v186
	v_sub_f32_e32 v138, v152, v186
	v_sub_f32_e32 v141, v154, v186
	v_sub_f32_e32 v140, v153, v186
	v_pk_mul_f32 v[140:141], v[186:187], v[140:141] op_sel:[1,0]
	v_pk_mul_f32 v[138:139], v[186:187], v[138:139] op_sel:[1,0]
	s_waitcnt lgkmcnt(1)
	v_pk_fma_f32 v[92:93], v[140:141], v[92:93], v[144:145]
	v_pk_fma_f32 v[90:91], v[138:139], v[90:91], v[142:143]
	v_pk_fma_f32 v[88:89], v[92:93], s[42:43], v[88:89] op_sel_hi:[1,0,1]
	v_pk_fma_f32 v[86:87], v[90:91], s[42:43], v[86:87] op_sel_hi:[1,0,1]
	v_sub_f32_e32 v91, v156, v186
	v_sub_f32_e32 v90, v155, v186
	v_sub_f32_e32 v93, v158, v186
	v_sub_f32_e32 v92, v157, v186
	v_pk_mul_f32 v[92:93], v[186:187], v[92:93] op_sel:[1,0]
	v_pk_mul_f32 v[90:91], v[186:187], v[90:91] op_sel:[1,0]
	s_waitcnt lgkmcnt(0)
	v_pk_fma_f32 v[92:93], v[92:93], v[96:97], v[148:149]
	v_pk_fma_f32 v[90:91], v[90:91], v[94:95], v[146:147]
	v_pk_fma_f32 v[92:93], v[92:93], s[42:43], v[84:85] op_sel_hi:[1,0,1]
	v_pk_fma_f32 v[84:85], v[90:91], s[42:43], v[82:83] op_sel_hi:[1,0,1]
	v_cvt_pk_bf16_f32 v82, v86, v87
	v_cvt_pk_bf16_f32 v83, v88, v89
	v_lshlrev_b32_e32 v142, 16, v134
	v_cvt_pk_bf16_f32 v84, v84, v85
	v_cvt_pk_bf16_f32 v85, v92, v93
	global_store_dwordx4 v[150:151], v[82:85], off offset:256
	v_and_b32_e32 v134, 0xffff0000, v134
	v_lshlrev_b32_e32 v143, 16, v135
	v_add_u32_e32 v84, s4, v198
	ds_read_b64 v[138:139], v84
	v_add_u32_e32 v82, s7, v197
	v_ashrrev_i32_e32 v83, 31, v82
	v_lshlrev_b64 v[140:141], 11, v[82:83]
	ds_read_b128 v[82:85], v212 offset:2048
	ds_read_b128 v[86:89], v212 offset:2064
	ds_read_b128 v[90:93], v212 offset:3072
	ds_read_b128 v[94:97], v212 offset:3088
	v_and_b32_e32 v144, 0xffff0000, v135
	v_lshlrev_b32_e32 v145, 16, v136
	v_and_b32_e32 v146, 0xffff0000, v136
	v_lshlrev_b32_e32 v147, 16, v137
	v_and_b32_e32 v148, 0xffff0000, v137
	s_waitcnt lgkmcnt(4)
	v_sub_f32_e32 v135, v134, v138
	v_sub_f32_e32 v134, v142, v138
	v_sub_f32_e32 v137, v144, v138
	v_sub_f32_e32 v136, v143, v138
	v_pk_mul_f32 v[136:137], v[138:139], v[136:137] op_sel:[1,0]
	v_pk_mul_f32 v[134:135], v[138:139], v[134:135] op_sel:[1,0]
	s_waitcnt lgkmcnt(1)
	v_pk_fma_f32 v[84:85], v[84:85], v[136:137], v[92:93]
	v_pk_fma_f32 v[82:83], v[82:83], v[134:135], v[90:91]
	v_pk_fma_f32 v[80:81], v[84:85], s[42:43], v[80:81] op_sel_hi:[1,0,1]
	v_pk_fma_f32 v[78:79], v[82:83], s[42:43], v[78:79] op_sel_hi:[1,0,1]
	v_sub_f32_e32 v83, v146, v138
	v_sub_f32_e32 v82, v145, v138
	v_sub_f32_e32 v85, v148, v138
	v_sub_f32_e32 v84, v147, v138
	v_pk_mul_f32 v[84:85], v[138:139], v[84:85] op_sel:[1,0]
	v_pk_mul_f32 v[82:83], v[138:139], v[82:83] op_sel:[1,0]
	s_waitcnt lgkmcnt(0)
	v_pk_fma_f32 v[84:85], v[88:89], v[84:85], v[96:97]
	v_pk_fma_f32 v[82:83], v[86:87], v[82:83], v[94:95]
	v_pk_fma_f32 v[84:85], v[84:85], s[42:43], v[76:77] op_sel_hi:[1,0,1]
	v_pk_fma_f32 v[76:77], v[82:83], s[42:43], v[74:75] op_sel_hi:[1,0,1]
	v_cvt_pk_bf16_f32 v74, v78, v79
	v_lshl_add_u64 v[78:79], s[14:15], 0, v[140:141]
	v_lshl_add_u64 v[90:91], v[78:79], 0, v[184:185]
	v_cvt_pk_bf16_f32 v75, v80, v81
	v_cvt_pk_bf16_f32 v76, v76, v77
	v_cvt_pk_bf16_f32 v77, v84, v85
	global_store_dwordx4 v[90:91], v[74:77], off
	ds_read_b128 v[74:77], v212 offset:2560
	ds_read_b128 v[78:81], v212 offset:2576
	ds_read_b128 v[82:85], v212 offset:3584
	ds_read_b128 v[86:89], v212 offset:3600
	v_lshlrev_b32_e32 v92, 16, v130
	v_and_b32_e32 v93, 0xffff0000, v130
	v_lshlrev_b32_e32 v94, 16, v131
	v_and_b32_e32 v95, 0xffff0000, v131
	v_sub_f32_e32 v93, v93, v138
	v_sub_f32_e32 v92, v92, v138
	v_sub_f32_e32 v95, v95, v138
	v_sub_f32_e32 v94, v94, v138
	v_pk_mul_f32 v[94:95], v[138:139], v[94:95] op_sel:[1,0]
	v_pk_mul_f32 v[92:93], v[138:139], v[92:93] op_sel:[1,0]
	v_lshlrev_b32_e32 v96, 16, v132
	v_and_b32_e32 v97, 0xffff0000, v132
	v_lshlrev_b32_e32 v130, 16, v133
	v_and_b32_e32 v131, 0xffff0000, v133
	s_waitcnt lgkmcnt(1)
	v_pk_fma_f32 v[74:75], v[92:93], v[74:75], v[82:83]
	v_pk_fma_f32 v[76:77], v[94:95], v[76:77], v[84:85]
	v_pk_fma_f32 v[70:71], v[74:75], s[42:43], v[70:71] op_sel_hi:[1,0,1]
	v_pk_fma_f32 v[72:73], v[76:77], s[42:43], v[72:73] op_sel_hi:[1,0,1]
	v_sub_f32_e32 v75, v97, v138
	v_sub_f32_e32 v74, v96, v138
	v_sub_f32_e32 v77, v131, v138
	v_sub_f32_e32 v76, v130, v138
	v_pk_mul_f32 v[76:77], v[138:139], v[76:77] op_sel:[1,0]
	v_pk_mul_f32 v[74:75], v[138:139], v[74:75] op_sel:[1,0]
	s_waitcnt lgkmcnt(0)
	v_pk_fma_f32 v[76:77], v[76:77], v[80:81], v[88:89]
	v_pk_fma_f32 v[74:75], v[74:75], v[78:79], v[86:87]
	v_pk_fma_f32 v[76:77], v[76:77], s[42:43], v[68:69] op_sel_hi:[1,0,1]
	v_pk_fma_f32 v[68:69], v[74:75], s[42:43], v[66:67] op_sel_hi:[1,0,1]
	v_cvt_pk_bf16_f32 v66, v70, v71
	v_cvt_pk_bf16_f32 v67, v72, v73
	s_waitcnt vmcnt(10)
; #define RL_LOAD(PW, AI) do { _Pragma("unroll") for (int m = 0; m < 4; ++m) _Pragma("unroll") for (int bj = 0; bj < 2; ++bj) (PW)[m][bj] = *(const u32x4*)(hin + (size_t)(row0 + (AI) * HALF + m * 16) * 1024 + col0 + bj * HALF); } while (0)
;     __device__ __forceinline__ void run(const f32x4 (&acc)[2][2][4][2], const Unit& u, int wr, int wc, int fr, int fq, const PG8_LAS unsigned char* sp) const {
;     ...
;         RL_LOAD(pwa, 0);
;         RL_ROW(pwa, 0, 0); RL_ROW(pwa, 0, 1);
;         RL_LOAD(pwb, 1);
;         RL_ROW(pwa, 0, 2); RL_ROW(pwa, 0, 3);
;         RL_ROW(pwb, 1, 0); RL_ROW(pwb, 1, 1); RL_ROW(pwb, 1, 2); RL_ROW(pwb, 1, 3);
	v_lshlrev_b32_e32 v86, 16, v126
	v_cvt_pk_bf16_f32 v68, v68, v69
	v_cvt_pk_bf16_f32 v69, v76, v77
	global_store_dwordx4 v[90:91], v[66:69], off offset:256
	v_and_b32_e32 v87, 0xffff0000, v126
	v_lshlrev_b32_e32 v88, 16, v127
	v_add_u32_e32 v68, s4, v200
	ds_read_b64 v[82:83], v68
	v_add_u32_e32 v66, s7, v199
	v_ashrrev_i32_e32 v67, 31, v66
	v_lshlrev_b64 v[84:85], 11, v[66:67]
	ds_read_b128 v[66:69], v212 offset:2048
	ds_read_b128 v[70:73], v212 offset:2064
	ds_read_b128 v[74:77], v212 offset:3072
	ds_read_b128 v[78:81], v212 offset:3088
	v_and_b32_e32 v89, 0xffff0000, v127
	s_waitcnt lgkmcnt(4)
	v_sub_f32_e32 v87, v87, v82
	v_sub_f32_e32 v86, v86, v82
	v_sub_f32_e32 v89, v89, v82
	v_sub_f32_e32 v88, v88, v82
	v_pk_mul_f32 v[88:89], v[82:83], v[88:89] op_sel:[1,0]
	v_pk_mul_f32 v[86:87], v[82:83], v[86:87] op_sel:[1,0]
	v_lshlrev_b32_e32 v90, 16, v128
	v_and_b32_e32 v91, 0xffff0000, v128
	v_lshlrev_b32_e32 v92, 16, v129
	v_and_b32_e32 v93, 0xffff0000, v129
	s_waitcnt lgkmcnt(1)
	v_pk_fma_f32 v[66:67], v[66:67], v[86:87], v[74:75]
	v_pk_fma_f32 v[68:69], v[68:69], v[88:89], v[76:77]
	v_pk_fma_f32 v[62:63], v[66:67], s[42:43], v[62:63] op_sel_hi:[1,0,1]
	v_pk_fma_f32 v[64:65], v[68:69], s[42:43], v[64:65] op_sel_hi:[1,0,1]
	v_sub_f32_e32 v67, v91, v82
	v_sub_f32_e32 v66, v90, v82
	v_sub_f32_e32 v69, v93, v82
	v_sub_f32_e32 v68, v92, v82
	v_pk_mul_f32 v[68:69], v[82:83], v[68:69] op_sel:[1,0]
	v_pk_mul_f32 v[66:67], v[82:83], v[66:67] op_sel:[1,0]
	s_waitcnt lgkmcnt(0)
	v_pk_fma_f32 v[68:69], v[72:73], v[68:69], v[80:81]
	v_pk_fma_f32 v[66:67], v[70:71], v[66:67], v[78:79]
	v_pk_fma_f32 v[68:69], v[68:69], s[42:43], v[60:61] op_sel_hi:[1,0,1]
	v_pk_fma_f32 v[60:61], v[66:67], s[42:43], v[58:59] op_sel_hi:[1,0,1]
	v_cvt_pk_bf16_f32 v58, v62, v63
	v_lshl_add_u64 v[62:63], s[14:15], 0, v[84:85]
	v_lshl_add_u64 v[74:75], v[62:63], 0, v[184:185]
	v_cvt_pk_bf16_f32 v59, v64, v65
	v_cvt_pk_bf16_f32 v60, v60, v61
	v_cvt_pk_bf16_f32 v61, v68, v69
	global_store_dwordx4 v[74:75], v[58:61], off
	ds_read_b128 v[58:61], v212 offset:2560
	ds_read_b128 v[62:65], v212 offset:2576
	ds_read_b128 v[66:69], v212 offset:3584
	ds_read_b128 v[70:73], v212 offset:3600
	s_waitcnt vmcnt(11)
	v_lshlrev_b32_e32 v76, 16, v122
	v_and_b32_e32 v77, 0xffff0000, v122
	v_lshlrev_b32_e32 v78, 16, v123
	v_and_b32_e32 v79, 0xffff0000, v123
	v_sub_f32_e32 v77, v77, v82
	v_sub_f32_e32 v76, v76, v82
	v_sub_f32_e32 v79, v79, v82
	v_sub_f32_e32 v78, v78, v82
	v_pk_mul_f32 v[78:79], v[82:83], v[78:79] op_sel:[1,0]
	v_pk_mul_f32 v[76:77], v[82:83], v[76:77] op_sel:[1,0]
	v_lshlrev_b32_e32 v80, 16, v124
	v_and_b32_e32 v81, 0xffff0000, v124
	v_lshlrev_b32_e32 v84, 16, v125
	v_and_b32_e32 v85, 0xffff0000, v125
	s_waitcnt lgkmcnt(1)
	v_pk_fma_f32 v[58:59], v[76:77], v[58:59], v[66:67]
	v_pk_fma_f32 v[60:61], v[78:79], v[60:61], v[68:69]
	v_pk_fma_f32 v[54:55], v[58:59], s[42:43], v[54:55] op_sel_hi:[1,0,1]
	v_pk_fma_f32 v[56:57], v[60:61], s[42:43], v[56:57] op_sel_hi:[1,0,1]
	v_sub_f32_e32 v59, v81, v82
	v_sub_f32_e32 v58, v80, v82
	v_sub_f32_e32 v61, v85, v82
	v_sub_f32_e32 v60, v84, v82
	v_pk_mul_f32 v[60:61], v[82:83], v[60:61] op_sel:[1,0]
	v_pk_mul_f32 v[58:59], v[82:83], v[58:59] op_sel:[1,0]
	s_waitcnt lgkmcnt(0)
	v_pk_fma_f32 v[60:61], v[60:61], v[64:65], v[72:73]
	v_pk_fma_f32 v[58:59], v[58:59], v[62:63], v[70:71]
	v_pk_fma_f32 v[60:61], v[60:61], s[42:43], v[52:53] op_sel_hi:[1,0,1]
	v_pk_fma_f32 v[52:53], v[58:59], s[42:43], v[50:51] op_sel_hi:[1,0,1]
	v_cvt_pk_bf16_f32 v50, v54, v55
	v_cvt_pk_bf16_f32 v51, v56, v57
	s_waitcnt vmcnt(10)
	v_lshlrev_b32_e32 v70, 16, v118
	v_cvt_pk_bf16_f32 v52, v52, v53
	v_cvt_pk_bf16_f32 v53, v60, v61
	global_store_dwordx4 v[74:75], v[50:53], off offset:256
	v_and_b32_e32 v71, 0xffff0000, v118
	v_lshlrev_b32_e32 v72, 16, v119
	v_add_u32_e32 v52, s4, v202
	ds_read_b64 v[66:67], v52
	v_add_u32_e32 v50, s7, v201
	v_ashrrev_i32_e32 v51, 31, v50
	v_lshlrev_b64 v[68:69], 11, v[50:51]
	ds_read_b128 v[50:53], v212 offset:2048
	ds_read_b128 v[54:57], v212 offset:2064
	ds_read_b128 v[58:61], v212 offset:3072
	ds_read_b128 v[62:65], v212 offset:3088
	v_and_b32_e32 v73, 0xffff0000, v119
	s_waitcnt lgkmcnt(4)
	v_sub_f32_e32 v71, v71, v66
	v_sub_f32_e32 v70, v70, v66
	v_sub_f32_e32 v73, v73, v66
	v_sub_f32_e32 v72, v72, v66
	v_pk_mul_f32 v[72:73], v[66:67], v[72:73] op_sel:[1,0]
	v_pk_mul_f32 v[70:71], v[66:67], v[70:71] op_sel:[1,0]
	v_lshlrev_b32_e32 v74, 16, v120
	v_and_b32_e32 v75, 0xffff0000, v120
	v_lshlrev_b32_e32 v76, 16, v121
	v_and_b32_e32 v77, 0xffff0000, v121
	s_waitcnt lgkmcnt(1)
	v_pk_fma_f32 v[50:51], v[50:51], v[70:71], v[58:59]
	v_pk_fma_f32 v[52:53], v[52:53], v[72:73], v[60:61]
	v_pk_fma_f32 v[46:47], v[50:51], s[42:43], v[46:47] op_sel_hi:[1,0,1]
	v_pk_fma_f32 v[48:49], v[52:53], s[42:43], v[48:49] op_sel_hi:[1,0,1]
	v_sub_f32_e32 v51, v75, v66
	v_sub_f32_e32 v50, v74, v66
	v_sub_f32_e32 v53, v77, v66
	v_sub_f32_e32 v52, v76, v66
	v_pk_mul_f32 v[52:53], v[66:67], v[52:53] op_sel:[1,0]
	v_pk_mul_f32 v[50:51], v[66:67], v[50:51] op_sel:[1,0]
	s_waitcnt lgkmcnt(0)
	v_pk_fma_f32 v[52:53], v[56:57], v[52:53], v[64:65]
	v_pk_fma_f32 v[50:51], v[54:55], v[50:51], v[62:63]
	v_pk_fma_f32 v[52:53], v[52:53], s[42:43], v[44:45] op_sel_hi:[1,0,1]
	v_pk_fma_f32 v[44:45], v[50:51], s[42:43], v[42:43] op_sel_hi:[1,0,1]
	v_cvt_pk_bf16_f32 v42, v46, v47
	v_lshl_add_u64 v[46:47], s[14:15], 0, v[68:69]
	v_lshl_add_u64 v[58:59], v[46:47], 0, v[184:185]
	v_cvt_pk_bf16_f32 v43, v48, v49
	v_cvt_pk_bf16_f32 v44, v44, v45
	v_cvt_pk_bf16_f32 v45, v52, v53
	global_store_dwordx4 v[58:59], v[42:45], off
	ds_read_b128 v[42:45], v212 offset:2560
	ds_read_b128 v[46:49], v212 offset:2576
	ds_read_b128 v[50:53], v212 offset:3584
	ds_read_b128 v[54:57], v212 offset:3600
	s_waitcnt vmcnt(11)
; #define RL_LOAD(PW, AI) do { _Pragma("unroll") for (int m = 0; m < 4; ++m) _Pragma("unroll") for (int bj = 0; bj < 2; ++bj) (PW)[m][bj] = *(const u32x4*)(hin + (size_t)(row0 + (AI) * HALF + m * 16) * 1024 + col0 + bj * HALF); } while (0)
;     __device__ __forceinline__ void run(const f32x4 (&acc)[2][2][4][2], const Unit& u, int wr, int wc, int fr, int fq, const PG8_LAS unsigned char* sp) const {
;     ...
;         RL_LOAD(pwa, 0);
;         RL_ROW(pwa, 0, 0); RL_ROW(pwa, 0, 1);
;         RL_LOAD(pwb, 1);
;         RL_ROW(pwa, 0, 2); RL_ROW(pwa, 0, 3);
;         RL_ROW(pwb, 1, 0); RL_ROW(pwb, 1, 1); RL_ROW(pwb, 1, 2); RL_ROW(pwb, 1, 3);
	v_lshlrev_b32_e32 v60, 16, v114
	v_and_b32_e32 v61, 0xffff0000, v114
	v_lshlrev_b32_e32 v62, 16, v115
	v_and_b32_e32 v63, 0xffff0000, v115
	v_sub_f32_e32 v61, v61, v66
	v_sub_f32_e32 v60, v60, v66
	v_sub_f32_e32 v63, v63, v66
	v_sub_f32_e32 v62, v62, v66
	v_pk_mul_f32 v[62:63], v[66:67], v[62:63] op_sel:[1,0]
	v_pk_mul_f32 v[60:61], v[66:67], v[60:61] op_sel:[1,0]
	v_lshlrev_b32_e32 v64, 16, v116
	v_and_b32_e32 v65, 0xffff0000, v116
	v_lshlrev_b32_e32 v68, 16, v117
	v_and_b32_e32 v69, 0xffff0000, v117
	s_waitcnt lgkmcnt(1)
	v_pk_fma_f32 v[42:43], v[60:61], v[42:43], v[50:51]
	v_pk_fma_f32 v[44:45], v[62:63], v[44:45], v[52:53]
	v_pk_fma_f32 v[38:39], v[42:43], s[42:43], v[38:39] op_sel_hi:[1,0,1]
	v_pk_fma_f32 v[40:41], v[44:45], s[42:43], v[40:41] op_sel_hi:[1,0,1]
	v_sub_f32_e32 v43, v65, v66
	v_sub_f32_e32 v42, v64, v66
	v_sub_f32_e32 v45, v69, v66
	v_sub_f32_e32 v44, v68, v66
	v_pk_mul_f32 v[44:45], v[66:67], v[44:45] op_sel:[1,0]
	v_pk_mul_f32 v[42:43], v[66:67], v[42:43] op_sel:[1,0]
	s_waitcnt lgkmcnt(0)
	v_pk_fma_f32 v[44:45], v[44:45], v[48:49], v[56:57]
	v_pk_fma_f32 v[42:43], v[42:43], v[46:47], v[54:55]
	v_pk_fma_f32 v[44:45], v[44:45], s[42:43], v[36:37] op_sel_hi:[1,0,1]
	v_pk_fma_f32 v[36:37], v[42:43], s[42:43], v[34:35] op_sel_hi:[1,0,1]
	v_cvt_pk_bf16_f32 v34, v38, v39
	v_cvt_pk_bf16_f32 v35, v40, v41
	s_waitcnt vmcnt(10)
	v_lshlrev_b32_e32 v54, 16, v110
	v_cvt_pk_bf16_f32 v36, v36, v37
	v_cvt_pk_bf16_f32 v37, v44, v45
	global_store_dwordx4 v[58:59], v[34:37], off offset:256
	v_and_b32_e32 v55, 0xffff0000, v110
	v_lshlrev_b32_e32 v56, 16, v111
	v_add_u32_e32 v36, s4, v204
	ds_read_b64 v[50:51], v36
	v_add_u32_e32 v34, s7, v203
	v_ashrrev_i32_e32 v35, 31, v34
	v_lshlrev_b64 v[52:53], 11, v[34:35]
	ds_read_b128 v[34:37], v212 offset:2048
	ds_read_b128 v[38:41], v212 offset:2064
	ds_read_b128 v[42:45], v212 offset:3072
	ds_read_b128 v[46:49], v212 offset:3088
	v_and_b32_e32 v57, 0xffff0000, v111
	s_waitcnt lgkmcnt(4)
	v_sub_f32_e32 v55, v55, v50
	v_sub_f32_e32 v54, v54, v50
	v_sub_f32_e32 v57, v57, v50
	v_sub_f32_e32 v56, v56, v50
	v_pk_mul_f32 v[56:57], v[50:51], v[56:57] op_sel:[1,0]
	v_pk_mul_f32 v[54:55], v[50:51], v[54:55] op_sel:[1,0]
	v_lshlrev_b32_e32 v58, 16, v112
	v_and_b32_e32 v59, 0xffff0000, v112
	v_lshlrev_b32_e32 v60, 16, v113
	v_and_b32_e32 v61, 0xffff0000, v113
	s_waitcnt lgkmcnt(1)
	v_pk_fma_f32 v[34:35], v[34:35], v[54:55], v[42:43]
	v_pk_fma_f32 v[36:37], v[36:37], v[56:57], v[44:45]
	v_pk_fma_f32 v[30:31], v[34:35], s[42:43], v[30:31] op_sel_hi:[1,0,1]
	v_pk_fma_f32 v[32:33], v[36:37], s[42:43], v[32:33] op_sel_hi:[1,0,1]
	v_sub_f32_e32 v35, v59, v50
	v_sub_f32_e32 v34, v58, v50
	v_sub_f32_e32 v37, v61, v50
	v_sub_f32_e32 v36, v60, v50
	v_pk_mul_f32 v[36:37], v[50:51], v[36:37] op_sel:[1,0]
	v_pk_mul_f32 v[34:35], v[50:51], v[34:35] op_sel:[1,0]
	s_waitcnt lgkmcnt(0)
	v_pk_fma_f32 v[36:37], v[40:41], v[36:37], v[48:49]
	v_pk_fma_f32 v[34:35], v[38:39], v[34:35], v[46:47]
	v_pk_fma_f32 v[36:37], v[36:37], s[42:43], v[28:29] op_sel_hi:[1,0,1]
	v_pk_fma_f32 v[28:29], v[34:35], s[42:43], v[26:27] op_sel_hi:[1,0,1]
	v_cvt_pk_bf16_f32 v26, v30, v31
	v_lshl_add_u64 v[30:31], s[14:15], 0, v[52:53]
	v_lshl_add_u64 v[42:43], v[30:31], 0, v[184:185]
	v_cvt_pk_bf16_f32 v27, v32, v33
	v_cvt_pk_bf16_f32 v28, v28, v29
	v_cvt_pk_bf16_f32 v29, v36, v37
	global_store_dwordx4 v[42:43], v[26:29], off
	ds_read_b128 v[26:29], v212 offset:2560
	ds_read_b128 v[30:33], v212 offset:2576
	ds_read_b128 v[34:37], v212 offset:3584
	ds_read_b128 v[38:41], v212 offset:3600
	s_waitcnt vmcnt(11)
	v_lshlrev_b32_e32 v44, 16, v106
	v_and_b32_e32 v45, 0xffff0000, v106
	v_lshlrev_b32_e32 v46, 16, v107
	v_and_b32_e32 v47, 0xffff0000, v107
	v_sub_f32_e32 v45, v45, v50
	v_sub_f32_e32 v44, v44, v50
	v_sub_f32_e32 v47, v47, v50
	v_sub_f32_e32 v46, v46, v50
	v_pk_mul_f32 v[46:47], v[50:51], v[46:47] op_sel:[1,0]
	v_pk_mul_f32 v[44:45], v[50:51], v[44:45] op_sel:[1,0]
	v_lshlrev_b32_e32 v48, 16, v108
	v_and_b32_e32 v49, 0xffff0000, v108
	v_lshlrev_b32_e32 v52, 16, v109
	v_and_b32_e32 v53, 0xffff0000, v109
	s_waitcnt lgkmcnt(1)
	v_pk_fma_f32 v[26:27], v[44:45], v[26:27], v[34:35]
	v_pk_fma_f32 v[28:29], v[46:47], v[28:29], v[36:37]
	v_pk_fma_f32 v[22:23], v[26:27], s[42:43], v[22:23] op_sel_hi:[1,0,1]
	v_pk_fma_f32 v[24:25], v[28:29], s[42:43], v[24:25] op_sel_hi:[1,0,1]
	v_sub_f32_e32 v27, v49, v50
	v_sub_f32_e32 v26, v48, v50
	v_sub_f32_e32 v29, v53, v50
	v_sub_f32_e32 v28, v52, v50
	v_pk_mul_f32 v[28:29], v[50:51], v[28:29] op_sel:[1,0]
	v_pk_mul_f32 v[26:27], v[50:51], v[26:27] op_sel:[1,0]
	s_waitcnt lgkmcnt(0)
; #define RL_LOAD(PW, AI) do { _Pragma("unroll") for (int m = 0; m < 4; ++m) _Pragma("unroll") for (int bj = 0; bj < 2; ++bj) (PW)[m][bj] = *(const u32x4*)(hin + (size_t)(row0 + (AI) * HALF + m * 16) * 1024 + col0 + bj * HALF); } while (0)
; #define PG8_BAR __builtin_amdgcn_s_barrier()
;     __device__ __forceinline__ void run(const f32x4 (&acc)[2][2][4][2], const Unit& u, int wr, int wc, int fr, int fq, const PG8_LAS unsigned char* sp) const {
;     ...
;         RL_LOAD(pwa, 0);
;         RL_ROW(pwa, 0, 0); RL_ROW(pwa, 0, 1);
;         RL_LOAD(pwb, 1);
;         RL_ROW(pwa, 0, 2); RL_ROW(pwa, 0, 3);
;         RL_ROW(pwb, 1, 0); RL_ROW(pwb, 1, 1); RL_ROW(pwb, 1, 2); RL_ROW(pwb, 1, 3);
; template <class Epi, class Sched, bool ALIGN_EPI = false, bool SP2 = false>
; __device__ __forceinline__ void gemm_phase(PG8_LAS unsigned char* lds, const Gemm g, const Sched& S, const Epi& E) {
;     ...
;         cur = nxt; cA = nA; cB = nB; ++ui;
;         if constexpr (ALIGN_EPI) { if (wr == 1) PG8_BAR; }
	v_pk_fma_f32 v[28:29], v[28:29], v[32:33], v[40:41]
	v_pk_fma_f32 v[26:27], v[26:27], v[30:31], v[38:39]
	v_pk_fma_f32 v[28:29], v[28:29], s[42:43], v[20:21] op_sel_hi:[1,0,1]
	v_pk_fma_f32 v[20:21], v[26:27], s[42:43], v[18:19] op_sel_hi:[1,0,1]
	v_cvt_pk_bf16_f32 v18, v22, v23
	v_cvt_pk_bf16_f32 v19, v24, v25
	s_waitcnt vmcnt(10)
	v_lshlrev_b32_e32 v38, 16, v102
	v_cvt_pk_bf16_f32 v20, v20, v21
	v_cvt_pk_bf16_f32 v21, v28, v29
	global_store_dwordx4 v[42:43], v[18:21], off offset:256
	v_and_b32_e32 v39, 0xffff0000, v102
	v_lshlrev_b32_e32 v40, 16, v103
	v_add_u32_e32 v20, s4, v206
	ds_read_b64 v[34:35], v20
	v_add_u32_e32 v18, s7, v205
	v_ashrrev_i32_e32 v19, 31, v18
	v_lshlrev_b64 v[36:37], 11, v[18:19]
	ds_read_b128 v[18:21], v212 offset:2048
	ds_read_b128 v[22:25], v212 offset:2064
	ds_read_b128 v[26:29], v212 offset:3072
	ds_read_b128 v[30:33], v212 offset:3088
	v_and_b32_e32 v41, 0xffff0000, v103
	s_waitcnt lgkmcnt(4)
	v_sub_f32_e32 v39, v39, v34
	v_sub_f32_e32 v38, v38, v34
	v_sub_f32_e32 v41, v41, v34
	v_sub_f32_e32 v40, v40, v34
	v_pk_mul_f32 v[40:41], v[34:35], v[40:41] op_sel:[1,0]
	v_pk_mul_f32 v[38:39], v[34:35], v[38:39] op_sel:[1,0]
	v_lshlrev_b32_e32 v42, 16, v104
	v_and_b32_e32 v43, 0xffff0000, v104
	v_lshlrev_b32_e32 v44, 16, v105
	v_and_b32_e32 v45, 0xffff0000, v105
	s_waitcnt lgkmcnt(1)
	v_pk_fma_f32 v[18:19], v[18:19], v[38:39], v[26:27]
	v_pk_fma_f32 v[20:21], v[20:21], v[40:41], v[28:29]
	v_pk_fma_f32 v[14:15], v[18:19], s[42:43], v[14:15] op_sel_hi:[1,0,1]
	v_pk_fma_f32 v[16:17], v[20:21], s[42:43], v[16:17] op_sel_hi:[1,0,1]
	v_sub_f32_e32 v19, v43, v34
	v_sub_f32_e32 v18, v42, v34
	v_sub_f32_e32 v21, v45, v34
	v_sub_f32_e32 v20, v44, v34
	v_pk_mul_f32 v[20:21], v[34:35], v[20:21] op_sel:[1,0]
	v_pk_mul_f32 v[18:19], v[34:35], v[18:19] op_sel:[1,0]
	s_waitcnt lgkmcnt(0)
	v_pk_fma_f32 v[20:21], v[24:25], v[20:21], v[32:33]
	v_pk_fma_f32 v[18:19], v[22:23], v[18:19], v[30:31]
	v_pk_fma_f32 v[20:21], v[20:21], s[42:43], v[12:13] op_sel_hi:[1,0,1]
	v_pk_fma_f32 v[12:13], v[18:19], s[42:43], v[10:11] op_sel_hi:[1,0,1]
	v_cvt_pk_bf16_f32 v10, v14, v15
	v_lshl_add_u64 v[14:15], s[14:15], 0, v[36:37]
	v_lshl_add_u64 v[26:27], v[14:15], 0, v[184:185]
	v_cvt_pk_bf16_f32 v11, v16, v17
	v_cvt_pk_bf16_f32 v12, v12, v13
	v_cvt_pk_bf16_f32 v13, v20, v21
	global_store_dwordx4 v[26:27], v[10:13], off
	ds_read_b128 v[10:13], v212 offset:2560
	ds_read_b128 v[14:17], v212 offset:2576
	ds_read_b128 v[18:21], v212 offset:3584
	ds_read_b128 v[22:25], v212 offset:3600
	s_waitcnt vmcnt(11)
	v_lshlrev_b32_e32 v28, 16, v98
	v_and_b32_e32 v29, 0xffff0000, v98
	v_lshlrev_b32_e32 v30, 16, v99
	v_and_b32_e32 v31, 0xffff0000, v99
	v_sub_f32_e32 v29, v29, v34
	v_sub_f32_e32 v28, v28, v34
	v_sub_f32_e32 v31, v31, v34
	v_sub_f32_e32 v30, v30, v34
	v_pk_mul_f32 v[30:31], v[34:35], v[30:31] op_sel:[1,0]
	v_pk_mul_f32 v[28:29], v[34:35], v[28:29] op_sel:[1,0]
	v_lshlrev_b32_e32 v32, 16, v100
	v_and_b32_e32 v33, 0xffff0000, v100
	v_lshlrev_b32_e32 v36, 16, v101
	v_and_b32_e32 v37, 0xffff0000, v101
	s_waitcnt lgkmcnt(1)
	v_pk_fma_f32 v[10:11], v[28:29], v[10:11], v[18:19]
	v_pk_fma_f32 v[12:13], v[30:31], v[12:13], v[20:21]
	v_pk_fma_f32 v[6:7], v[10:11], s[42:43], v[6:7] op_sel_hi:[1,0,1]
	v_pk_fma_f32 v[8:9], v[12:13], s[42:43], v[8:9] op_sel_hi:[1,0,1]
	v_sub_f32_e32 v11, v33, v34
	v_sub_f32_e32 v10, v32, v34
	v_sub_f32_e32 v13, v37, v34
	v_sub_f32_e32 v12, v36, v34
	v_pk_mul_f32 v[12:13], v[34:35], v[12:13] op_sel:[1,0]
	v_pk_mul_f32 v[10:11], v[34:35], v[10:11] op_sel:[1,0]
	s_waitcnt lgkmcnt(0)
	v_pk_fma_f32 v[12:13], v[12:13], v[16:17], v[24:25]
	v_pk_fma_f32 v[10:11], v[10:11], v[14:15], v[22:23]
	v_pk_fma_f32 v[12:13], v[12:13], s[42:43], v[4:5] op_sel_hi:[1,0,1]
	v_pk_fma_f32 v[4:5], v[10:11], s[42:43], v[2:3] op_sel_hi:[1,0,1]
	s_and_b64 vcc, exec, s[10:11]
	s_mov_b64 s[10:11], -1
	v_cvt_pk_bf16_f32 v2, v6, v7
	v_cvt_pk_bf16_f32 v3, v8, v9
	v_cvt_pk_bf16_f32 v4, v4, v5
	v_cvt_pk_bf16_f32 v5, v12, v13
	global_store_dwordx4 v[26:27], v[2:5], off offset:256
	s_cbranch_vccnz .LBB0_1182
	s_andn2_b64 vcc, exec, s[38:39]
	s_cbranch_vccnz .LBB0_1181
	s_mov_b32 s98, 1
	s_branch .LBB0_1181

;     __device__ __forceinline__ bool next(int i, Unit& u) const { if (!S.next(i, u)) return false; if (u.pn >= 4) u.pn += 2; return true; }
; #define PG8_STAGE(bufoff, gbase, voff) do { _Pragma("unroll") for (int _i = 0; _i < 2; ++_i) \
;         __builtin_amdgcn_global_load_lds((const unsigned*)((const char*)(gbase) + (voff)[_i]), (PG8_LAS unsigned*)(lds + (bufoff) + ldsw + _i * 8192), 16, 0, 0); } while (0)
; #define PG8_LDA(dst, b, h) do { _Pragma("unroll") for (int m = 0; m < 4; ++m) _Pragma("unroll") for (int k = 0; k < 2; ++k) dst[m][k] = *(const PG8_LAS bf16x8*)(lds + PG8_SA(b, h) + aoff + m * 2048 + k * 1024); } while (0)
; #define PG8_WAIT_V(n) asm volatile("s_waitcnt vmcnt(" #n ")" ::: "memory")
; #define PG8_BAR __builtin_amdgcn_s_barrier()
; template <class Epi, class Sched, bool ALIGN_EPI = false, bool SP2 = false>
; __device__ __forceinline__ void gemm_phase(PG8_LAS unsigned char* lds, const Gemm g, const Sched& S, const Epi& E) {
;     ...
;         const bool has_next = S.next(ui + 1, nxt);
;         if constexpr (Epi::LDS_PF) { if (has_next) E.prefetch(nxt, lds + STAGE_BYTES + ((ui + 1) % 3) * 4096, wid, lane); }
;         const char* nA = has_next ? (const char*)g.A + (size_t)nxt.pm * tstepA : cA; const char* nB = has_next ? (const char*)g.Bt + (size_t)nxt.pn * tstepB : cB;
;         for (int t = 0; t < nt; t += 2) {
;             const bool last = (t == nt - 2);
;             const char* a1 = cA + (size_t)(t + 1) * kstep;
;             const char* a2 = last ? nA : cA + (size_t)(t + 2) * kstep; const char* b2 = last ? nB : cB + (size_t)(t + 2) * kstep;
;             const char* a3 = a2 + kstep; const char* b3 = b2 + kstep;
;             if (last && has_next) S.a_ready(nxt);
;             if constexpr (SP2) {
;             PG8_LDB(B0, 0, 0); PG8_LDB(B1, 0, 1); PG8_SCHED; PG8_LDA(At, 0, 0); PG8_STAGE(PG8_SA(1, 1), a1 + hstepA, voffA);
;             PG8_WAIT_V(8); PG8_WAIT_L(0); PG8_BAR; PG8_MMA(0, 0, At, B0); PG8_MMA(0, 1, At, B1); PG8_BAR; PG8_SCHED;
;     ...
; #pragma unroll
;         for (int a = 0; a < 2; ++a)
; #pragma unroll
;             for (int b = 0; b < 2; ++b)
; #pragma unroll
;                 for (int m = 0; m < 4; ++m)
; #pragma unroll
;                     for (int n = 0; n < 2; ++n) acc[a][b][m][n] = (f32x4){0.f, 0.f, 0.f, 0.f};
;         cur = nxt; cA = nA; cB = nB; ++ui;
;         if constexpr (ALIGN_EPI) { if (wr == 1) PG8_BAR; }
.LBB0_1341:
	s_mov_b32 s36, s0
	s_ashr_i32 s37, s0, 31
	s_mov_b32 s38, s1
	s_lshl_b64 s[0:1], s[36:37], 19
	v_readlane_b32 s4, v253, 23
	v_readlane_b32 s5, v253, 24
	s_add_u32 s42, s4, s0
	s_addc_u32 s43, s5, s1
	s_and_b64 s[0:1], s[40:41], exec
	s_cselect_b32 s4, s43, s51
	s_cselect_b32 s5, s42, s50
	s_ashr_i32 s39, s38, 31
	s_lshl_b64 s[0:1], s[38:39], 19
	s_add_u32 s44, s34, s0
	s_addc_u32 s45, s35, s1
	s_and_b64 s[0:1], s[40:41], exec
	s_cselect_b32 s18, s45, s67
	s_cselect_b32 s19, s44, s66
	s_add_u32 s50, s50, 0x40080
	s_addc_u32 s51, s51, 0
	s_add_u32 s37, s66, 0x100
	v_mov_b32_e32 v2, 0
	s_addc_u32 s39, s67, 0
	s_mov_b32 s79, -2
	v_mov_b32_e32 v3, v2
	v_mov_b32_e32 v4, v2
	v_mov_b32_e32 v5, v2
	v_mov_b32_e32 v6, v2
	v_mov_b32_e32 v7, v2
	v_mov_b32_e32 v8, v2
	v_mov_b32_e32 v9, v2
	v_mov_b32_e32 v10, v2
	v_mov_b32_e32 v11, v2
	v_mov_b32_e32 v12, v2
	v_mov_b32_e32 v13, v2
	v_mov_b32_e32 v18, v2
	v_mov_b32_e32 v19, v2
	v_mov_b32_e32 v20, v2
	v_mov_b32_e32 v21, v2
	v_mov_b32_e32 v26, v2
	v_mov_b32_e32 v27, v2
	v_mov_b32_e32 v28, v2
	v_mov_b32_e32 v29, v2
	v_mov_b32_e32 v34, v2
	v_mov_b32_e32 v35, v2
	v_mov_b32_e32 v36, v2
	v_mov_b32_e32 v37, v2
	v_mov_b32_e32 v42, v2
	v_mov_b32_e32 v43, v2
	v_mov_b32_e32 v44, v2
	v_mov_b32_e32 v45, v2
	v_mov_b32_e32 v50, v2
	v_mov_b32_e32 v51, v2
	v_mov_b32_e32 v52, v2
	v_mov_b32_e32 v53, v2
	v_mov_b32_e32 v14, v2
	v_mov_b32_e32 v15, v2
	v_mov_b32_e32 v16, v2
	v_mov_b32_e32 v17, v2
	v_mov_b32_e32 v22, v2
	v_mov_b32_e32 v23, v2
	v_mov_b32_e32 v24, v2
	v_mov_b32_e32 v25, v2
	v_mov_b32_e32 v30, v2
	v_mov_b32_e32 v31, v2
	v_mov_b32_e32 v32, v2
	v_mov_b32_e32 v33, v2
	v_mov_b32_e32 v38, v2
	v_mov_b32_e32 v39, v2
	v_mov_b32_e32 v40, v2
	v_mov_b32_e32 v41, v2
	v_mov_b32_e32 v46, v2
	v_mov_b32_e32 v47, v2
	v_mov_b32_e32 v48, v2
	v_mov_b32_e32 v49, v2
	v_mov_b32_e32 v54, v2
	v_mov_b32_e32 v55, v2
	v_mov_b32_e32 v56, v2
	v_mov_b32_e32 v57, v2
	v_mov_b32_e32 v58, v2
	v_mov_b32_e32 v59, v2
	v_mov_b32_e32 v60, v2
	v_mov_b32_e32 v61, v2
	v_mov_b32_e32 v62, v2
	v_mov_b32_e32 v63, v2
	v_mov_b32_e32 v64, v2
	v_mov_b32_e32 v65, v2
	v_mov_b32_e32 v66, v2
	v_mov_b32_e32 v67, v2
	v_mov_b32_e32 v68, v2
	v_mov_b32_e32 v69, v2
	v_mov_b32_e32 v70, v2
	v_mov_b32_e32 v71, v2
	v_mov_b32_e32 v72, v2
	v_mov_b32_e32 v73, v2
	v_mov_b32_e32 v74, v2
	v_mov_b32_e32 v75, v2
	v_mov_b32_e32 v76, v2
	v_mov_b32_e32 v77, v2
	v_mov_b32_e32 v82, v2
	v_mov_b32_e32 v83, v2
	v_mov_b32_e32 v84, v2
	v_mov_b32_e32 v85, v2
	v_mov_b32_e32 v90, v2
	v_mov_b32_e32 v91, v2
	v_mov_b32_e32 v92, v2
	v_mov_b32_e32 v93, v2
	v_mov_b32_e32 v98, v2
	v_mov_b32_e32 v99, v2
	v_mov_b32_e32 v100, v2
	v_mov_b32_e32 v101, v2
	v_mov_b32_e32 v106, v2
	v_mov_b32_e32 v107, v2
	v_mov_b32_e32 v108, v2
	v_mov_b32_e32 v109, v2
	v_mov_b32_e32 v114, v2
	v_mov_b32_e32 v115, v2
	v_mov_b32_e32 v116, v2
	v_mov_b32_e32 v117, v2
	v_mov_b32_e32 v78, v2
	v_mov_b32_e32 v79, v2
	v_mov_b32_e32 v80, v2
	v_mov_b32_e32 v81, v2
	v_mov_b32_e32 v86, v2
	v_mov_b32_e32 v87, v2
	v_mov_b32_e32 v88, v2
	v_mov_b32_e32 v89, v2
	v_mov_b32_e32 v94, v2
	v_mov_b32_e32 v95, v2
	v_mov_b32_e32 v96, v2
	v_mov_b32_e32 v97, v2
	v_mov_b32_e32 v102, v2
	v_mov_b32_e32 v103, v2
	v_mov_b32_e32 v104, v2
	v_mov_b32_e32 v105, v2
	v_mov_b32_e32 v110, v2
	v_mov_b32_e32 v111, v2
	v_mov_b32_e32 v112, v2
	v_mov_b32_e32 v113, v2
	v_mov_b32_e32 v118, v2
	v_mov_b32_e32 v119, v2
	v_mov_b32_e32 v120, v2
	v_mov_b32_e32 v121, v2
	v_mov_b32_e32 v122, v2
	v_mov_b32_e32 v123, v2
	v_mov_b32_e32 v124, v2
	v_mov_b32_e32 v125, v2
	v_mov_b32_e32 v126, v2
	v_mov_b32_e32 v127, v2
	v_mov_b32_e32 v128, v2
	v_mov_b32_e32 v129, v2
	s_cmp_eq_u32 s98, 1
	s_cbranch_scc0 .Ldefer_4
	s_barrier
	s_mov_b32 s98, 0
.Ldefer_4:
.LBB0_1342:
	ds_read_b128 v[144:147], v150
	ds_read_b128 v[156:159], v150 offset:1024
	ds_read_b128 v[160:163], v150 offset:2048
	ds_read_b128 v[164:167], v150 offset:3072
	ds_read_b128 v[168:171], v151
	ds_read_b128 v[172:175], v151 offset:1024
	ds_read_b128 v[176:179], v151 offset:2048
	ds_read_b128 v[180:183], v151 offset:3072
	s_add_u32 s0, s50, 0xfffc0080
	s_addc_u32 s1, s51, -1
	s_cmp_eq_u32 s79, 12
	s_cselect_b32 s69, s4, s1
	s_cselect_b32 s68, s5, s0
	s_cselect_b32 s67, s18, s39
	s_cselect_b32 s66, s19, s37
	v_lshl_add_u64 v[216:217], s[50:51], 0, v[138:139]
	s_add_i32 m0, s14, 0xc000
	ds_read_b128 v[184:187], v152
	ds_read_b128 v[188:191], v152 offset:1024
	ds_read_b128 v[192:195], v152 offset:2048
	ds_read_b128 v[196:199], v152 offset:3072
	ds_read_b128 v[200:203], v152 offset:4096
	ds_read_b128 v[204:207], v152 offset:5120
	ds_read_b128 v[208:211], v152 offset:6144
	ds_read_b128 v[212:215], v152 offset:7168
	global_load_lds_dwordx4 v[216:217], off
	v_lshl_add_u64 v[216:217], s[50:51], 0, v[140:141]
	s_add_i32 m0, s14, 0xe000
	s_nop 0
	global_load_lds_dwordx4 v[216:217], off
	s_waitcnt vmcnt(8)
	s_waitcnt lgkmcnt(0)
	s_setprio 1
	s_barrier
; #define PG8_STAGE(bufoff, gbase, voff) do { _Pragma("unroll") for (int _i = 0; _i < 2; ++_i) \
;         __builtin_amdgcn_global_load_lds((const unsigned*)((const char*)(gbase) + (voff)[_i]), (PG8_LAS unsigned*)(lds + (bufoff) + ldsw + _i * 8192), 16, 0, 0); } while (0)
; #define PG8_LDA(dst, b, h) do { _Pragma("unroll") for (int m = 0; m < 4; ++m) _Pragma("unroll") for (int k = 0; k < 2; ++k) dst[m][k] = *(const PG8_LAS bf16x8*)(lds + PG8_SA(b, h) + aoff + m * 2048 + k * 1024); } while (0)
; #define PG8_LDB(dst, b, h) do { _Pragma("unroll") for (int n = 0; n < 2; ++n) _Pragma("unroll") for (int k = 0; k < 2; ++k) dst[n][k] = *(const PG8_LAS bf16x8*)(lds + PG8_SB(b, h) + boff + n * 2048 + k * 1024); } while (0)
; #define PG8_MMA(ai, bj, At, Bt) do { __builtin_amdgcn_s_setprio(1); _Pragma("unroll") for (int m = 0; m < 4; ++m) _Pragma("unroll") for (int n = 0; n < 2; ++n) _Pragma("unroll") for (int k = 0; k < 2; ++k) \
;         acc[ai][bj][m][n] = __builtin_amdgcn_mfma_f32_16x16x32_bf16(Bt[n][k], At[m][k], acc[ai][bj][m][n], 0, 0, 0); __builtin_amdgcn_s_setprio(0); } while (0)
; #define PG8_WAIT_V(n) asm volatile("s_waitcnt vmcnt(" #n ")" ::: "memory")
; #define PG8_WAIT_L(n) asm volatile("s_waitcnt lgkmcnt(" #n ")" ::: "memory")
; #define PG8_BAR __builtin_amdgcn_s_barrier()
; #define PG8_SCHED __builtin_amdgcn_sched_barrier(0)
; template <class Epi, class Sched, bool ALIGN_EPI = false, bool SP2 = false>
; __device__ __forceinline__ void gemm_phase(PG8_LAS unsigned char* lds, const Gemm g, const Sched& S, const Epi& E) {
;     ...
;             PG8_WAIT_V(8); PG8_WAIT_L(0); PG8_BAR; PG8_MMA(0, 0, At, B0); PG8_MMA(0, 1, At, B1); PG8_BAR; PG8_SCHED;
;             PG8_LDA(At, 0, 1); PG8_STAGE(PG8_SB(0, 0), b2, voffB); PG8_STAGE(PG8_SB(0, 1), b2 + hstepB, voffB); PG8_STAGE(PG8_SA(0, 0), a2, voffA);
;             PG8_WAIT_V(8); PG8_WAIT_L(0); PG8_BAR; PG8_MMA(1, 0, At, B0); PG8_MMA(1, 1, At, B1); PG8_BAR; PG8_SCHED;
;             PG8_LDB(B0, 1, 0); PG8_LDB(B1, 1, 1); PG8_SCHED; PG8_LDA(At, 1, 0); PG8_STAGE(PG8_SA(0, 1), a2 + hstepA, voffA);
;             PG8_WAIT_V(8); PG8_WAIT_L(0); PG8_BAR; PG8_MMA(0, 0, At, B0); PG8_MMA(0, 1, At, B1); PG8_BAR; PG8_SCHED;
	v_mfma_f32_16x16x32_bf16 v[126:129], v[144:147], v[184:187], v[126:129]
	v_mfma_f32_16x16x32_bf16 v[122:125], v[160:163], v[184:187], v[122:125]
	v_mfma_f32_16x16x32_bf16 v[118:121], v[144:147], v[192:195], v[118:121]
	v_mfma_f32_16x16x32_bf16 v[110:113], v[160:163], v[192:195], v[110:113]
	v_mfma_f32_16x16x32_bf16 v[102:105], v[144:147], v[200:203], v[102:105]
	v_mfma_f32_16x16x32_bf16 v[94:97], v[160:163], v[200:203], v[94:97]
	v_mfma_f32_16x16x32_bf16 v[86:89], v[144:147], v[208:211], v[86:89]
	v_mfma_f32_16x16x32_bf16 v[78:81], v[160:163], v[208:211], v[78:81]
	v_mfma_f32_16x16x32_bf16 v[126:129], v[156:159], v[188:191], v[126:129]
	v_mfma_f32_16x16x32_bf16 v[122:125], v[164:167], v[188:191], v[122:125]
	v_mfma_f32_16x16x32_bf16 v[118:121], v[156:159], v[196:199], v[118:121]
	v_mfma_f32_16x16x32_bf16 v[110:113], v[164:167], v[196:199], v[110:113]
	v_mfma_f32_16x16x32_bf16 v[102:105], v[156:159], v[204:207], v[102:105]
	v_mfma_f32_16x16x32_bf16 v[94:97], v[164:167], v[204:207], v[94:97]
	v_mfma_f32_16x16x32_bf16 v[86:89], v[156:159], v[212:215], v[86:89]
	v_mfma_f32_16x16x32_bf16 v[78:81], v[164:167], v[212:215], v[78:81]
	s_setprio 0
	s_setprio 1
	v_mfma_f32_16x16x32_bf16 v[114:117], v[168:171], v[184:187], v[114:117]
	v_mfma_f32_16x16x32_bf16 v[106:109], v[176:179], v[184:187], v[106:109]
	v_mfma_f32_16x16x32_bf16 v[98:101], v[168:171], v[192:195], v[98:101]
	v_mfma_f32_16x16x32_bf16 v[90:93], v[176:179], v[192:195], v[90:93]
	v_mfma_f32_16x16x32_bf16 v[82:85], v[168:171], v[200:203], v[82:85]
	v_mfma_f32_16x16x32_bf16 v[74:77], v[176:179], v[200:203], v[74:77]
	v_mfma_f32_16x16x32_bf16 v[70:73], v[168:171], v[208:211], v[70:73]
	v_mfma_f32_16x16x32_bf16 v[66:69], v[176:179], v[208:211], v[66:69]
	v_mfma_f32_16x16x32_bf16 v[114:117], v[172:175], v[188:191], v[114:117]
	v_mfma_f32_16x16x32_bf16 v[106:109], v[180:183], v[188:191], v[106:109]
	v_mfma_f32_16x16x32_bf16 v[98:101], v[172:175], v[196:199], v[98:101]
	v_mfma_f32_16x16x32_bf16 v[90:93], v[180:183], v[196:199], v[90:93]
	v_mfma_f32_16x16x32_bf16 v[82:85], v[172:175], v[204:207], v[82:85]
	v_mfma_f32_16x16x32_bf16 v[74:77], v[180:183], v[204:207], v[74:77]
	v_mfma_f32_16x16x32_bf16 v[70:73], v[172:175], v[212:215], v[70:73]
	v_mfma_f32_16x16x32_bf16 v[66:69], v[180:183], v[212:215], v[66:69]
	s_setprio 0
	s_barrier
	s_add_i32 s0, s75, s3
	v_lshl_add_u64 v[216:217], s[66:67], 0, v[134:135]
	s_mov_b32 m0, s0
	ds_read_b128 v[184:187], v152 offset:16384
	ds_read_b128 v[188:191], v152 offset:17408
	ds_read_b128 v[192:195], v152 offset:18432
	ds_read_b128 v[196:199], v152 offset:19456
	ds_read_b128 v[200:203], v152 offset:20480
	ds_read_b128 v[204:207], v152 offset:21504
	ds_read_b128 v[208:211], v152 offset:22528
	ds_read_b128 v[212:215], v152 offset:23552
	global_load_lds_dwordx4 v[216:217], off
	s_add_i32 m0, s0, 0x2000
	s_add_u32 s0, s66, 0x40000
	v_lshl_add_u64 v[218:219], s[66:67], 0, v[130:131]
	s_addc_u32 s1, s67, 0
	s_add_i32 s2, s76, s3
	global_load_lds_dwordx4 v[218:219], off
	v_lshl_add_u64 v[220:221], s[0:1], 0, v[134:135]
	s_mov_b32 m0, s2
	v_lshl_add_u64 v[222:223], s[68:69], 0, v[132:133]
	global_load_lds_dwordx4 v[220:221], off
	v_lshl_add_u64 v[220:221], s[0:1], 0, v[130:131]
	s_add_i32 m0, s2, 0x2000
	s_nop 0
	global_load_lds_dwordx4 v[220:221], off
	v_lshl_add_u64 v[220:221], s[68:69], 0, v[136:137]
	s_mov_b32 m0, s14
	s_nop 0
	global_load_lds_dwordx4 v[220:221], off
	s_mov_b32 m0, s15
	s_nop 0
	global_load_lds_dwordx4 v[222:223], off
	s_waitcnt vmcnt(8)
	s_waitcnt lgkmcnt(0)
	s_setprio 1
	s_barrier
	v_mfma_f32_16x16x32_bf16 v[62:65], v[144:147], v[184:187], v[62:65]
	v_mfma_f32_16x16x32_bf16 v[58:61], v[160:163], v[184:187], v[58:61]
	v_mfma_f32_16x16x32_bf16 v[54:57], v[144:147], v[192:195], v[54:57]
	v_mfma_f32_16x16x32_bf16 v[46:49], v[160:163], v[192:195], v[46:49]
	v_mfma_f32_16x16x32_bf16 v[38:41], v[144:147], v[200:203], v[38:41]
	v_mfma_f32_16x16x32_bf16 v[30:33], v[160:163], v[200:203], v[30:33]
	v_mfma_f32_16x16x32_bf16 v[22:25], v[144:147], v[208:211], v[22:25]
	v_mfma_f32_16x16x32_bf16 v[14:17], v[160:163], v[208:211], v[14:17]
	v_mfma_f32_16x16x32_bf16 v[62:65], v[156:159], v[188:191], v[62:65]
	v_mfma_f32_16x16x32_bf16 v[58:61], v[164:167], v[188:191], v[58:61]
	v_mfma_f32_16x16x32_bf16 v[54:57], v[156:159], v[196:199], v[54:57]
	v_mfma_f32_16x16x32_bf16 v[46:49], v[164:167], v[196:199], v[46:49]
	v_mfma_f32_16x16x32_bf16 v[38:41], v[156:159], v[204:207], v[38:41]
	v_mfma_f32_16x16x32_bf16 v[30:33], v[164:167], v[204:207], v[30:33]
	v_mfma_f32_16x16x32_bf16 v[22:25], v[156:159], v[212:215], v[22:25]
	v_mfma_f32_16x16x32_bf16 v[14:17], v[164:167], v[212:215], v[14:17]
	s_setprio 0
	s_setprio 1
	v_mfma_f32_16x16x32_bf16 v[50:53], v[168:171], v[184:187], v[50:53]
	v_mfma_f32_16x16x32_bf16 v[42:45], v[176:179], v[184:187], v[42:45]
	v_mfma_f32_16x16x32_bf16 v[34:37], v[168:171], v[192:195], v[34:37]
	v_mfma_f32_16x16x32_bf16 v[26:29], v[176:179], v[192:195], v[26:29]
	v_mfma_f32_16x16x32_bf16 v[18:21], v[168:171], v[200:203], v[18:21]
	v_mfma_f32_16x16x32_bf16 v[10:13], v[176:179], v[200:203], v[10:13]
	v_mfma_f32_16x16x32_bf16 v[6:9], v[168:171], v[208:211], v[6:9]
	v_mfma_f32_16x16x32_bf16 v[2:5], v[176:179], v[208:211], v[2:5]
	v_mfma_f32_16x16x32_bf16 v[50:53], v[172:175], v[188:191], v[50:53]
	v_mfma_f32_16x16x32_bf16 v[42:45], v[180:183], v[188:191], v[42:45]
	v_mfma_f32_16x16x32_bf16 v[34:37], v[172:175], v[196:199], v[34:37]
	v_mfma_f32_16x16x32_bf16 v[26:29], v[180:183], v[196:199], v[26:29]
	v_mfma_f32_16x16x32_bf16 v[18:21], v[172:175], v[204:207], v[18:21]
	v_mfma_f32_16x16x32_bf16 v[10:13], v[180:183], v[204:207], v[10:13]
	v_mfma_f32_16x16x32_bf16 v[6:9], v[172:175], v[212:215], v[6:9]
	v_mfma_f32_16x16x32_bf16 v[2:5], v[180:183], v[212:215], v[2:5]
	s_setprio 0
	s_barrier
; #define PG8_STAGE(bufoff, gbase, voff) do { _Pragma("unroll") for (int _i = 0; _i < 2; ++_i) \
;         __builtin_amdgcn_global_load_lds((const unsigned*)((const char*)(gbase) + (voff)[_i]), (PG8_LAS unsigned*)(lds + (bufoff) + ldsw + _i * 8192), 16, 0, 0); } while (0)
; #define PG8_WAIT_V(n) asm volatile("s_waitcnt vmcnt(" #n ")" ::: "memory")
; #define PG8_WAIT_L(n) asm volatile("s_waitcnt lgkmcnt(" #n ")" ::: "memory")
; template <class Epi, class Sched, bool ALIGN_EPI = false, bool SP2 = false>
; __device__ __forceinline__ void gemm_phase(PG8_LAS unsigned char* lds, const Gemm g, const Sched& S, const Epi& E) {
;     ...
;             PG8_WAIT_V(8); PG8_WAIT_L(0); PG8_BAR; PG8_MMA(0, 0, At, B0); PG8_MMA(0, 1, At, B1); PG8_BAR; PG8_SCHED;
;             PG8_LDA(At, 1, 1); PG8_STAGE(PG8_SB(1, 0), b3, voffB); PG8_STAGE(PG8_SB(1, 1), b3 + hstepB, voffB); PG8_STAGE(PG8_SA(1, 0), a3, voffA);
;             PG8_WAIT_V(8); PG8_WAIT_L(0); PG8_BAR; PG8_MMA(1, 0, At, B0); PG8_MMA(1, 1, At, B1); PG8_BAR; PG8_SCHED;
;             } else {
;             PG8_LDB(B0, 0, 0); PG8_SCHED; PG8_LDA(At, 0, 0); PG8_STAGE(PG8_SA(1, 1), a1 + hstepA, voffA);
;             PG8_WAIT_L(8); PG8_BAR; PG8_WAIT_L(0); PG8_MMA(0, 0, At, B0); PG8_BAR; PG8_SCHED;
;             PG8_LDB(B1, 0, 1); PG8_STAGE(PG8_SB(0, 0), b2, voffB);
;             PG8_BAR; PG8_WAIT_L(0); PG8_MMA(0, 1, At, B1); PG8_BAR;
;             PG8_LDA(At, 0, 1); PG8_STAGE(PG8_SA(0, 0), a2, voffA);
;             PG8_BAR; PG8_WAIT_L(0); PG8_MMA(1, 0, At, B0); PG8_BAR; PG8_SCHED;
;             PG8_STAGE(PG8_SB(0, 1), b2 + hstepB, voffB);
;             PG8_WAIT_V(6); PG8_BAR; PG8_MMA(1, 1, At, B1); PG8_BAR;
;             PG8_LDB(B0, 1, 0); PG8_SCHED; PG8_LDA(At, 1, 0); PG8_STAGE(PG8_SA(0, 1), a2 + hstepA, voffA);
;             PG8_WAIT_L(8); PG8_BAR; PG8_WAIT_L(0); PG8_MMA(0, 0, At, B0); PG8_BAR; PG8_SCHED;
;             PG8_LDB(B1, 1, 1); PG8_STAGE(PG8_SB(1, 0), b3, voffB);
;             PG8_BAR; PG8_WAIT_L(0); PG8_MMA(0, 1, At, B1); PG8_BAR;
;             PG8_LDA(At, 1, 1); PG8_STAGE(PG8_SA(1, 0), a3, voffA);
;             PG8_BAR; PG8_WAIT_L(0); PG8_MMA(1, 0, At, B0); PG8_BAR; PG8_SCHED;
;             PG8_STAGE(PG8_SB(1, 1), b3 + hstepB, voffB);
;             PG8_WAIT_V(6); PG8_BAR; PG8_MMA(1, 1, At, B1); PG8_BAR;
;             }
;         }
;         if constexpr (ALIGN_EPI) { if (wr == 0) PG8_BAR; }
	ds_read_b128 v[144:147], v153
	ds_read_b128 v[156:159], v153 offset:1024
	ds_read_b128 v[160:163], v153 offset:2048
	ds_read_b128 v[164:167], v153 offset:3072
	ds_read_b128 v[168:171], v154
	ds_read_b128 v[172:175], v154 offset:1024
	ds_read_b128 v[176:179], v154 offset:2048
	ds_read_b128 v[180:183], v154 offset:3072
	s_add_u32 s0, s68, 0x40000
	s_addc_u32 s1, s69, 0
	s_mov_b32 m0, s20
	v_lshl_add_u64 v[224:225], s[0:1], 0, v[136:137]
	ds_read_b128 v[184:187], v152 offset:32768
	ds_read_b128 v[188:191], v152 offset:33792
	ds_read_b128 v[192:195], v152 offset:34816
	ds_read_b128 v[196:199], v152 offset:35840
	ds_read_b128 v[200:203], v152 offset:36864
	ds_read_b128 v[204:207], v152 offset:37888
	ds_read_b128 v[208:211], v152 offset:38912
	ds_read_b128 v[212:215], v152 offset:39936
	global_load_lds_dwordx4 v[224:225], off
	v_lshl_add_u64 v[224:225], s[0:1], 0, v[132:133]
	s_mov_b32 m0, s21
	s_nop 0
	global_load_lds_dwordx4 v[224:225], off
	s_waitcnt vmcnt(8)
	s_waitcnt lgkmcnt(0)
	s_setprio 1
	s_barrier
	v_mfma_f32_16x16x32_bf16 v[126:129], v[144:147], v[184:187], v[126:129]
	v_mfma_f32_16x16x32_bf16 v[122:125], v[160:163], v[184:187], v[122:125]
	v_mfma_f32_16x16x32_bf16 v[118:121], v[144:147], v[192:195], v[118:121]
	v_mfma_f32_16x16x32_bf16 v[110:113], v[160:163], v[192:195], v[110:113]
	v_mfma_f32_16x16x32_bf16 v[102:105], v[144:147], v[200:203], v[102:105]
	v_mfma_f32_16x16x32_bf16 v[94:97], v[160:163], v[200:203], v[94:97]
	v_mfma_f32_16x16x32_bf16 v[86:89], v[144:147], v[208:211], v[86:89]
	v_mfma_f32_16x16x32_bf16 v[78:81], v[160:163], v[208:211], v[78:81]
	v_mfma_f32_16x16x32_bf16 v[126:129], v[156:159], v[188:191], v[126:129]
	v_mfma_f32_16x16x32_bf16 v[122:125], v[164:167], v[188:191], v[122:125]
	v_mfma_f32_16x16x32_bf16 v[118:121], v[156:159], v[196:199], v[118:121]
	v_mfma_f32_16x16x32_bf16 v[110:113], v[164:167], v[196:199], v[110:113]
	v_mfma_f32_16x16x32_bf16 v[102:105], v[156:159], v[204:207], v[102:105]
	v_mfma_f32_16x16x32_bf16 v[94:97], v[164:167], v[204:207], v[94:97]
	v_mfma_f32_16x16x32_bf16 v[86:89], v[156:159], v[212:215], v[86:89]
	v_mfma_f32_16x16x32_bf16 v[78:81], v[164:167], v[212:215], v[78:81]
	s_setprio 0
	s_setprio 1
	v_mfma_f32_16x16x32_bf16 v[114:117], v[168:171], v[184:187], v[114:117]
	v_mfma_f32_16x16x32_bf16 v[106:109], v[176:179], v[184:187], v[106:109]
	v_mfma_f32_16x16x32_bf16 v[98:101], v[168:171], v[192:195], v[98:101]
	v_mfma_f32_16x16x32_bf16 v[90:93], v[176:179], v[192:195], v[90:93]
	v_mfma_f32_16x16x32_bf16 v[82:85], v[168:171], v[200:203], v[82:85]
	v_mfma_f32_16x16x32_bf16 v[74:77], v[176:179], v[200:203], v[74:77]
	v_mfma_f32_16x16x32_bf16 v[70:73], v[168:171], v[208:211], v[70:73]
	v_mfma_f32_16x16x32_bf16 v[66:69], v[176:179], v[208:211], v[66:69]
	v_mfma_f32_16x16x32_bf16 v[114:117], v[172:175], v[188:191], v[114:117]
	v_mfma_f32_16x16x32_bf16 v[106:109], v[180:183], v[188:191], v[106:109]
	v_mfma_f32_16x16x32_bf16 v[98:101], v[172:175], v[196:199], v[98:101]
	v_mfma_f32_16x16x32_bf16 v[90:93], v[180:183], v[196:199], v[90:93]
	v_mfma_f32_16x16x32_bf16 v[82:85], v[172:175], v[204:207], v[82:85]
	v_mfma_f32_16x16x32_bf16 v[74:77], v[180:183], v[204:207], v[74:77]
	v_mfma_f32_16x16x32_bf16 v[70:73], v[172:175], v[212:215], v[70:73]
	v_mfma_f32_16x16x32_bf16 v[66:69], v[180:183], v[212:215], v[66:69]
	s_setprio 0
	s_barrier
	s_add_i32 s0, s77, s3
	v_lshl_add_u64 v[216:217], v[216:217], 0, s[8:9]
	s_mov_b32 m0, s0
	ds_read_b128 v[184:187], v152 offset:49152
	ds_read_b128 v[188:191], v152 offset:50176
	ds_read_b128 v[192:195], v152 offset:51200
	ds_read_b128 v[196:199], v152 offset:52224
	ds_read_b128 v[200:203], v152 offset:53248
	ds_read_b128 v[204:207], v152 offset:54272
	ds_read_b128 v[208:211], v152 offset:55296
	ds_read_b128 v[212:215], v152 offset:56320
	global_load_lds_dwordx4 v[216:217], off
	s_add_i32 m0, s0, 0x2000
	s_add_u32 s0, s66, 0x40080
	v_lshl_add_u64 v[216:217], v[218:219], 0, s[8:9]
	s_addc_u32 s1, s67, 0
	s_add_i32 s2, s78, s3
	global_load_lds_dwordx4 v[216:217], off
	v_lshl_add_u64 v[216:217], s[0:1], 0, v[134:135]
	s_mov_b32 m0, s2
	s_nop 0
	global_load_lds_dwordx4 v[216:217], off
	v_lshl_add_u64 v[216:217], s[0:1], 0, v[130:131]
	s_add_i32 m0, s2, 0x2000
	s_nop 0
	global_load_lds_dwordx4 v[216:217], off
	v_lshl_add_u64 v[216:217], v[220:221], 0, s[8:9]
	s_mov_b32 m0, s47
	s_nop 0
	global_load_lds_dwordx4 v[216:217], off
	v_lshl_add_u64 v[216:217], v[222:223], 0, s[8:9]
	s_mov_b32 m0, s49
	s_nop 0
	global_load_lds_dwordx4 v[216:217], off
	s_waitcnt vmcnt(8)
	s_waitcnt lgkmcnt(0)
	s_setprio 1
	s_barrier
	v_mfma_f32_16x16x32_bf16 v[62:65], v[144:147], v[184:187], v[62:65]
	v_mfma_f32_16x16x32_bf16 v[58:61], v[160:163], v[184:187], v[58:61]
	v_mfma_f32_16x16x32_bf16 v[54:57], v[144:147], v[192:195], v[54:57]
	v_mfma_f32_16x16x32_bf16 v[46:49], v[160:163], v[192:195], v[46:49]
	v_mfma_f32_16x16x32_bf16 v[38:41], v[144:147], v[200:203], v[38:41]
	v_mfma_f32_16x16x32_bf16 v[30:33], v[160:163], v[200:203], v[30:33]
	v_mfma_f32_16x16x32_bf16 v[22:25], v[144:147], v[208:211], v[22:25]
	v_mfma_f32_16x16x32_bf16 v[14:17], v[160:163], v[208:211], v[14:17]
	v_mfma_f32_16x16x32_bf16 v[62:65], v[156:159], v[188:191], v[62:65]
	v_mfma_f32_16x16x32_bf16 v[58:61], v[164:167], v[188:191], v[58:61]
	v_mfma_f32_16x16x32_bf16 v[54:57], v[156:159], v[196:199], v[54:57]
	v_mfma_f32_16x16x32_bf16 v[46:49], v[164:167], v[196:199], v[46:49]
	v_mfma_f32_16x16x32_bf16 v[38:41], v[156:159], v[204:207], v[38:41]
	v_mfma_f32_16x16x32_bf16 v[30:33], v[164:167], v[204:207], v[30:33]
	v_mfma_f32_16x16x32_bf16 v[22:25], v[156:159], v[212:215], v[22:25]
	v_mfma_f32_16x16x32_bf16 v[14:17], v[164:167], v[212:215], v[14:17]
	s_setprio 0
	s_setprio 1
	v_mfma_f32_16x16x32_bf16 v[50:53], v[168:171], v[184:187], v[50:53]
	v_mfma_f32_16x16x32_bf16 v[42:45], v[176:179], v[184:187], v[42:45]
	v_mfma_f32_16x16x32_bf16 v[34:37], v[168:171], v[192:195], v[34:37]
	v_mfma_f32_16x16x32_bf16 v[26:29], v[176:179], v[192:195], v[26:29]
	v_mfma_f32_16x16x32_bf16 v[18:21], v[168:171], v[200:203], v[18:21]
	v_mfma_f32_16x16x32_bf16 v[10:13], v[176:179], v[200:203], v[10:13]
	v_mfma_f32_16x16x32_bf16 v[6:9], v[168:171], v[208:211], v[6:9]
	v_mfma_f32_16x16x32_bf16 v[2:5], v[176:179], v[208:211], v[2:5]
	v_mfma_f32_16x16x32_bf16 v[50:53], v[172:175], v[188:191], v[50:53]
	v_mfma_f32_16x16x32_bf16 v[42:45], v[180:183], v[188:191], v[42:45]
	v_mfma_f32_16x16x32_bf16 v[34:37], v[172:175], v[196:199], v[34:37]
	v_mfma_f32_16x16x32_bf16 v[26:29], v[180:183], v[196:199], v[26:29]
	v_mfma_f32_16x16x32_bf16 v[18:21], v[172:175], v[204:207], v[18:21]
	v_mfma_f32_16x16x32_bf16 v[10:13], v[180:183], v[204:207], v[10:13]
	v_mfma_f32_16x16x32_bf16 v[6:9], v[172:175], v[212:215], v[6:9]
	v_mfma_f32_16x16x32_bf16 v[2:5], v[180:183], v[212:215], v[2:5]
	s_setprio 0
	s_barrier
	s_add_i32 s79, s79, 2
	s_add_u32 s50, s50, 0x100
	s_addc_u32 s51, s51, 0
	s_add_u32 s37, s37, 0x100
	s_addc_u32 s39, s39, 0
	s_cmp_gt_u32 s79, 13
	s_cbranch_scc0 .LBB0_1342
	s_and_b64 vcc, exec, s[12:13]
	s_cbranch_vccz .LBB0_1345
	s_barrier
; __device__ __forceinline__ unsigned cvt_pk_bf16(float lo, float hi) { unsigned r; asm volatile("v_cvt_pk_bf16_f32 %0, %1, %2" : "=v"(r) : "v"(lo), "v"(hi)); return r; }
; #define PG8_BAR __builtin_amdgcn_s_barrier()
;     __device__ __forceinline__ void operator()(const f32x4 (&acc)[2][2][4][2], const Unit& u, int wr, int wc, int fr, int fq) const {
;         const int gi = u.pm < 0 ? 1 : 0, row0 = (u.pm - gi * pm0) * BM + wr * 64 + fr, col0 = (u.pn - gi * pn0) * BM + wc * 32 + 8 * fq;
;         bf16_t* O = proj + (long long)gi * (long long)(vts - proj); const int ldc = ldp + gi * (ldv - ldp);
; #pragma unroll
;         for (int ai = 0; ai < 2; ++ai)
; #pragma unroll
;             for (int m = 0; m < 4; ++m) { const int row = row0 + ai * HALF + m * 16; bf16_t* rowp = O + (size_t)row * ldc + col0;
; #pragma unroll
;                 for (int bj = 0; bj < 2; ++bj) { const f32x4 v0 = acc[ai][bj][m][0], v1 = acc[ai][bj][m][1];
;                     u32x4 w; w.x = cvt_pk_bf16(v0[0], v0[1]); w.y = cvt_pk_bf16(v0[2], v0[3]); w.z = cvt_pk_bf16(v1[0], v1[1]); w.w = cvt_pk_bf16(v1[2], v1[3]);
;                     *(u32x4*)(rowp + bj * HALF) = w; } }
; template <class Epi, class Sched, bool ALIGN_EPI = false, bool SP2 = false>
; __device__ __forceinline__ void gemm_phase(PG8_LAS unsigned char* lds, const Gemm g, const Sched& S, const Epi& E) {
;     ...
;         cur = nxt; cA = nA; cB = nB; ++ui;
;         if constexpr (ALIGN_EPI) { if (wr == 1) PG8_BAR; }
.LBB0_1345:
	s_ashr_i32 s0, s46, 31
	s_and_b32 s1, s0, 52
	s_add_i32 s2, s1, s46
	s_and_b32 s1, s0, 0xffffc8
	s_add_i32 s4, s1, s48
	s_and_b32 s0, s0, 0xf400000
	v_readlane_b32 s18, v253, 25
	v_readlane_b32 s19, v253, 26
	s_add_u32 s0, s18, s0
	s_addc_u32 s1, s19, 0
	v_lshl_or_b32 v144, s4, 8, v149
	s_cmp_lt_i32 s46, 0
	v_lshl_add_u32 v146, s2, 8, v148
	v_ashrrev_i32_e32 v145, 31, v144
	v_lshl_add_u64 v[144:145], v[144:145], 1, s[0:1]
	v_ashrrev_i32_e32 v147, 31, v146
	s_cselect_b32 s1, 15, 11
	v_lshlrev_b64 v[156:157], s1, v[146:147]
	v_lshl_add_u64 v[156:157], v[156:157], 1, v[144:145]
	v_cvt_pk_bf16_f32 v126, v126, v127
	v_cvt_pk_bf16_f32 v127, v128, v129
	v_cvt_pk_bf16_f32 v128, v122, v123
	v_cvt_pk_bf16_f32 v129, v124, v125
	global_store_dwordx4 v[156:157], v[126:129], off
	v_cvt_pk_bf16_f32 v114, v114, v115
	v_cvt_pk_bf16_f32 v115, v116, v117
	v_cvt_pk_bf16_f32 v116, v106, v107
	v_or_b32_e32 v106, 16, v146
	v_ashrrev_i32_e32 v107, 31, v106
	v_lshlrev_b64 v[106:107], s1, v[106:107]
	v_cvt_pk_bf16_f32 v117, v108, v109
	global_store_dwordx4 v[156:157], v[114:117], off offset:256
	s_andn2_b64 vcc, exec, s[40:41]
	s_mov_b64 s[40:41], -1
	v_lshl_add_u64 v[114:115], v[106:107], 1, v[144:145]
	v_cvt_pk_bf16_f32 v106, v118, v119
	v_cvt_pk_bf16_f32 v107, v120, v121
	v_cvt_pk_bf16_f32 v108, v110, v111
	v_cvt_pk_bf16_f32 v109, v112, v113
	global_store_dwordx4 v[114:115], v[106:109], off
	v_cvt_pk_bf16_f32 v98, v98, v99
	v_cvt_pk_bf16_f32 v99, v100, v101
	v_cvt_pk_bf16_f32 v100, v90, v91
	v_or_b32_e32 v90, 32, v146
	v_ashrrev_i32_e32 v91, 31, v90
	v_lshlrev_b64 v[90:91], s1, v[90:91]
	v_cvt_pk_bf16_f32 v101, v92, v93
	global_store_dwordx4 v[114:115], v[98:101], off offset:256
	s_nop 1
	v_lshl_add_u64 v[98:99], v[90:91], 1, v[144:145]
	v_cvt_pk_bf16_f32 v90, v102, v103
	v_cvt_pk_bf16_f32 v91, v104, v105
	v_cvt_pk_bf16_f32 v92, v94, v95
	v_cvt_pk_bf16_f32 v93, v96, v97
	global_store_dwordx4 v[98:99], v[90:93], off
	v_cvt_pk_bf16_f32 v82, v82, v83
	v_cvt_pk_bf16_f32 v83, v84, v85
	v_cvt_pk_bf16_f32 v84, v74, v75
	v_or_b32_e32 v74, 48, v146
	v_ashrrev_i32_e32 v75, 31, v74
	v_lshlrev_b64 v[74:75], s1, v[74:75]
	v_cvt_pk_bf16_f32 v85, v76, v77
	global_store_dwordx4 v[98:99], v[82:85], off offset:256
	s_nop 1
	v_lshl_add_u64 v[82:83], v[74:75], 1, v[144:145]
	v_cvt_pk_bf16_f32 v74, v86, v87
	v_cvt_pk_bf16_f32 v75, v88, v89
	v_cvt_pk_bf16_f32 v76, v78, v79
	v_cvt_pk_bf16_f32 v77, v80, v81
	global_store_dwordx4 v[82:83], v[74:77], off
	v_cvt_pk_bf16_f32 v70, v70, v71
	v_cvt_pk_bf16_f32 v71, v72, v73
	v_cvt_pk_bf16_f32 v72, v66, v67
	v_add_u32_e32 v66, 0x80, v146
	v_ashrrev_i32_e32 v67, 31, v66
	v_lshlrev_b64 v[66:67], s1, v[66:67]
	v_lshl_add_u64 v[66:67], v[66:67], 1, v[144:145]
	v_cvt_pk_bf16_f32 v73, v68, v69
	global_store_dwordx4 v[82:83], v[70:73], off offset:256
	v_cvt_pk_bf16_f32 v62, v62, v63
	v_cvt_pk_bf16_f32 v63, v64, v65
	v_cvt_pk_bf16_f32 v64, v58, v59
	v_cvt_pk_bf16_f32 v65, v60, v61
	global_store_dwordx4 v[66:67], v[62:65], off
	v_cvt_pk_bf16_f32 v50, v50, v51
	v_cvt_pk_bf16_f32 v51, v52, v53
	v_cvt_pk_bf16_f32 v52, v42, v43
	v_add_u32_e32 v42, 0x90, v146
	v_ashrrev_i32_e32 v43, 31, v42
	v_lshlrev_b64 v[42:43], s1, v[42:43]
	v_cvt_pk_bf16_f32 v53, v44, v45
	global_store_dwordx4 v[66:67], v[50:53], off offset:256
	s_nop 1
	v_lshl_add_u64 v[50:51], v[42:43], 1, v[144:145]
	v_cvt_pk_bf16_f32 v42, v54, v55
	v_cvt_pk_bf16_f32 v43, v56, v57
	v_cvt_pk_bf16_f32 v44, v46, v47
	v_cvt_pk_bf16_f32 v45, v48, v49
	global_store_dwordx4 v[50:51], v[42:45], off
	v_cvt_pk_bf16_f32 v34, v34, v35
	v_cvt_pk_bf16_f32 v35, v36, v37
	v_cvt_pk_bf16_f32 v36, v26, v27
	v_add_u32_e32 v26, 0xa0, v146
	v_ashrrev_i32_e32 v27, 31, v26
	v_lshlrev_b64 v[26:27], s1, v[26:27]
	v_cvt_pk_bf16_f32 v37, v28, v29
	global_store_dwordx4 v[50:51], v[34:37], off offset:256
	s_nop 1
	v_lshl_add_u64 v[34:35], v[26:27], 1, v[144:145]
	v_cvt_pk_bf16_f32 v26, v38, v39
	v_cvt_pk_bf16_f32 v27, v40, v41
	v_cvt_pk_bf16_f32 v28, v30, v31
	v_cvt_pk_bf16_f32 v29, v32, v33
	global_store_dwordx4 v[34:35], v[26:29], off
	v_cvt_pk_bf16_f32 v18, v18, v19
	v_cvt_pk_bf16_f32 v19, v20, v21
	v_cvt_pk_bf16_f32 v20, v10, v11
	v_add_u32_e32 v10, 0xb0, v146
	v_ashrrev_i32_e32 v11, 31, v10
	v_lshlrev_b64 v[10:11], s1, v[10:11]
	v_cvt_pk_bf16_f32 v21, v12, v13
	global_store_dwordx4 v[34:35], v[18:21], off offset:256
	s_nop 1
	v_lshl_add_u64 v[18:19], v[10:11], 1, v[144:145]
	v_cvt_pk_bf16_f32 v10, v22, v23
	v_cvt_pk_bf16_f32 v11, v24, v25
	v_cvt_pk_bf16_f32 v12, v14, v15
	v_cvt_pk_bf16_f32 v13, v16, v17
	global_store_dwordx4 v[18:19], v[10:13], off
	v_cvt_pk_bf16_f32 v6, v6, v7
	v_cvt_pk_bf16_f32 v7, v8, v9
	v_cvt_pk_bf16_f32 v8, v2, v3
	v_cvt_pk_bf16_f32 v9, v4, v5
	global_store_dwordx4 v[18:19], v[6:9], off offset:256
	s_cbranch_vccnz .LBB0_1333
	s_andn2_b64 vcc, exec, s[10:11]
	s_cbranch_vccnz .LBB0_1332
	s_mov_b32 s98, 1
	s_branch .LBB0_1332

; #define PG8_STAGE(bufoff, gbase, voff) do { _Pragma("unroll") for (int _i = 0; _i < 2; ++_i) \
;         __builtin_amdgcn_global_load_lds((const unsigned*)((const char*)(gbase) + (voff)[_i]), (PG8_LAS unsigned*)(lds + (bufoff) + ldsw + _i * 8192), 16, 0, 0); } while (0)
; #define PG8_LDA(dst, b, h) do { _Pragma("unroll") for (int m = 0; m < 4; ++m) _Pragma("unroll") for (int k = 0; k < 2; ++k) dst[m][k] = *(const PG8_LAS bf16x8*)(lds + PG8_SA(b, h) + aoff + m * 2048 + k * 1024); } while (0)
; #define PG8_LDB(dst, b, h) do { _Pragma("unroll") for (int n = 0; n < 2; ++n) _Pragma("unroll") for (int k = 0; k < 2; ++k) dst[n][k] = *(const PG8_LAS bf16x8*)(lds + PG8_SB(b, h) + boff + n * 2048 + k * 1024); } while (0)
; #define PG8_MMA(ai, bj, At, Bt) do { __builtin_amdgcn_s_setprio(1); _Pragma("unroll") for (int m = 0; m < 4; ++m) _Pragma("unroll") for (int n = 0; n < 2; ++n) _Pragma("unroll") for (int k = 0; k < 2; ++k) \
;         acc[ai][bj][m][n] = __builtin_amdgcn_mfma_f32_16x16x32_bf16(Bt[n][k], At[m][k], acc[ai][bj][m][n], 0, 0, 0); __builtin_amdgcn_s_setprio(0); } while (0)
; #define PG8_WAIT_V(n) asm volatile("s_waitcnt vmcnt(" #n ")" ::: "memory")
; #define PG8_BAR __builtin_amdgcn_s_barrier()
; template <class Epi, class Sched, bool ALIGN_EPI = false, bool SP2 = false>
; __device__ __forceinline__ void gemm_phase(PG8_LAS unsigned char* lds, const Gemm g, const Sched& S, const Epi& E) {
;     ...
;         for (int t = 0; t < nt; t += 2) {
;             const bool last = (t == nt - 2);
;             const char* a1 = cA + (size_t)(t + 1) * kstep;
;             const char* a2 = last ? nA : cA + (size_t)(t + 2) * kstep; const char* b2 = last ? nB : cB + (size_t)(t + 2) * kstep;
;             const char* a3 = a2 + kstep; const char* b3 = b2 + kstep;
;             if (last && has_next) S.a_ready(nxt);
;             if constexpr (SP2) {
;             PG8_LDB(B0, 0, 0); PG8_LDB(B1, 0, 1); PG8_SCHED; PG8_LDA(At, 0, 0); PG8_STAGE(PG8_SA(1, 1), a1 + hstepA, voffA);
;             PG8_WAIT_V(8); PG8_WAIT_L(0); PG8_BAR; PG8_MMA(0, 0, At, B0); PG8_MMA(0, 1, At, B1); PG8_BAR; PG8_SCHED;
;             PG8_LDA(At, 0, 1); PG8_STAGE(PG8_SB(0, 0), b2, voffB); PG8_STAGE(PG8_SB(0, 1), b2 + hstepB, voffB); PG8_STAGE(PG8_SA(0, 0), a2, voffA);
;             PG8_WAIT_V(8); PG8_WAIT_L(0); PG8_BAR; PG8_MMA(1, 0, At, B0); PG8_MMA(1, 1, At, B1); PG8_BAR; PG8_SCHED;
.LBB0_1453:
	s_add_u32 s2, s70, s18
	s_addc_u32 s3, s71, 0
	s_add_u32 s19, s2, 0x100
	s_addc_u32 s22, s3, 0
	s_and_b64 s[0:1], s[74:75], exec
	s_cselect_b32 s79, s5, s22
	s_cselect_b32 s78, s47, s19
	s_add_u32 s0, s68, s18
	s_addc_u32 s1, s69, 0
	s_add_u32 s18, s0, 0x100
	s_addc_u32 s19, s1, 0
	s_and_b64 s[0:1], s[74:75], exec
	s_cselect_b32 s81, s45, s19
	s_cselect_b32 s80, s95, s18
	s_add_u32 s84, s2, 0x80080
	s_addc_u32 s85, s3, 0
	s_add_i32 s22, s89, s88
	ds_read_b128 v[142:145], v155
	ds_read_b128 v[146:149], v155 offset:1024
	ds_read_b128 v[162:165], v155 offset:2048
	ds_read_b128 v[166:169], v155 offset:3072
	ds_read_b128 v[170:173], v158
	ds_read_b128 v[174:177], v158 offset:1024
	ds_read_b128 v[178:181], v158 offset:2048
	ds_read_b128 v[182:185], v158 offset:3072
	s_add_i32 m0, s6, 0xc000
	s_add_i32 s2, s6, 0xe000
	s_add_i32 s1, s22, 0x2000
	s_add_u32 s82, s80, 0x10000
	s_addc_u32 s83, s81, 0
	s_add_i32 s0, s90, s88
	s_add_i32 s57, s0, 0x2000
	s_add_u32 s76, s78, 0x80000
	s_addc_u32 s77, s79, 0
	s_add_i32 s97, s91, s88
	s_add_i32 s19, s97, 0x2000
	s_add_u32 s74, s80, 0x10080
	s_addc_u32 s75, s81, 0
	s_add_i32 s96, s92, s88
	s_add_i32 s18, s96, 0x2000
	v_lshl_add_u64 v[152:153], s[84:85], 0, v[136:137]
	ds_read_b128 v[186:189], v159
	ds_read_b128 v[190:193], v159 offset:1024
	ds_read_b128 v[194:197], v159 offset:2048
	ds_read_b128 v[198:201], v159 offset:3072
	ds_read_b128 v[202:205], v159 offset:4096
	ds_read_b128 v[206:209], v159 offset:5120
	ds_read_b128 v[210:213], v159 offset:6144
	ds_read_b128 v[214:217], v159 offset:7168
	global_load_lds_dwordx4 v[152:153], off
	v_lshl_add_u64 v[152:153], s[84:85], 0, v[132:133]
	s_mov_b32 m0, s2
	s_nop 0
	global_load_lds_dwordx4 v[152:153], off
	s_waitcnt vmcnt(8)
	s_waitcnt lgkmcnt(0)
	s_setprio 1
	s_barrier
	v_mfma_f32_16x16x32_bf16 v[126:129], v[142:145], v[186:189], v[126:129]
	v_mfma_f32_16x16x32_bf16 v[122:125], v[162:165], v[186:189], v[122:125]
	v_mfma_f32_16x16x32_bf16 v[118:121], v[142:145], v[194:197], v[118:121]
	v_mfma_f32_16x16x32_bf16 v[114:117], v[162:165], v[194:197], v[114:117]
	v_mfma_f32_16x16x32_bf16 v[106:109], v[142:145], v[202:205], v[106:109]
	v_mfma_f32_16x16x32_bf16 v[98:101], v[162:165], v[202:205], v[98:101]
	v_mfma_f32_16x16x32_bf16 v[82:85], v[142:145], v[210:213], v[82:85]
	v_mfma_f32_16x16x32_bf16 v[74:77], v[162:165], v[210:213], v[74:77]
	v_mfma_f32_16x16x32_bf16 v[126:129], v[146:149], v[190:193], v[126:129]
	v_mfma_f32_16x16x32_bf16 v[122:125], v[166:169], v[190:193], v[122:125]
	v_mfma_f32_16x16x32_bf16 v[118:121], v[146:149], v[198:201], v[118:121]
	v_mfma_f32_16x16x32_bf16 v[114:117], v[166:169], v[198:201], v[114:117]
	v_mfma_f32_16x16x32_bf16 v[106:109], v[146:149], v[206:209], v[106:109]
	v_mfma_f32_16x16x32_bf16 v[98:101], v[166:169], v[206:209], v[98:101]
	v_mfma_f32_16x16x32_bf16 v[82:85], v[146:149], v[214:217], v[82:85]
	v_mfma_f32_16x16x32_bf16 v[74:77], v[166:169], v[214:217], v[74:77]
	s_setprio 0
	s_setprio 1
	v_mfma_f32_16x16x32_bf16 v[110:113], v[170:173], v[186:189], v[110:113]
	v_mfma_f32_16x16x32_bf16 v[102:105], v[178:181], v[186:189], v[102:105]
	v_mfma_f32_16x16x32_bf16 v[94:97], v[170:173], v[194:197], v[94:97]
	v_mfma_f32_16x16x32_bf16 v[90:93], v[178:181], v[194:197], v[90:93]
	v_mfma_f32_16x16x32_bf16 v[86:89], v[170:173], v[202:205], v[86:89]
	v_mfma_f32_16x16x32_bf16 v[78:81], v[178:181], v[202:205], v[78:81]
	v_mfma_f32_16x16x32_bf16 v[70:73], v[170:173], v[210:213], v[70:73]
	v_mfma_f32_16x16x32_bf16 v[66:69], v[178:181], v[210:213], v[66:69]
	v_mfma_f32_16x16x32_bf16 v[110:113], v[174:177], v[190:193], v[110:113]
	v_mfma_f32_16x16x32_bf16 v[102:105], v[182:185], v[190:193], v[102:105]
	v_mfma_f32_16x16x32_bf16 v[94:97], v[174:177], v[198:201], v[94:97]
	v_mfma_f32_16x16x32_bf16 v[90:93], v[182:185], v[198:201], v[90:93]
	v_mfma_f32_16x16x32_bf16 v[86:89], v[174:177], v[206:209], v[86:89]
	v_mfma_f32_16x16x32_bf16 v[78:81], v[182:185], v[206:209], v[78:81]
	v_mfma_f32_16x16x32_bf16 v[70:73], v[174:177], v[214:217], v[70:73]
	v_mfma_f32_16x16x32_bf16 v[66:69], v[182:185], v[214:217], v[66:69]
	s_setprio 0
	s_barrier
	s_mov_b32 m0, s22
	v_lshl_add_u64 v[152:153], s[80:81], 0, v[134:135]
	ds_read_b128 v[186:189], v159 offset:16384
	ds_read_b128 v[190:193], v159 offset:17408
	ds_read_b128 v[194:197], v159 offset:18432
	ds_read_b128 v[198:201], v159 offset:19456
	ds_read_b128 v[202:205], v159 offset:20480
	ds_read_b128 v[206:209], v159 offset:21504
	ds_read_b128 v[210:213], v159 offset:22528
	ds_read_b128 v[214:217], v159 offset:23552
	global_load_lds_dwordx4 v[152:153], off
	v_lshl_add_u64 v[156:157], s[80:81], 0, v[130:131]
	s_mov_b32 m0, s1
	v_lshl_add_u64 v[218:219], s[82:83], 0, v[134:135]
	global_load_lds_dwordx4 v[156:157], off
	s_mov_b32 m0, s0
	v_lshl_add_u64 v[220:221], s[78:79], 0, v[132:133]
	global_load_lds_dwordx4 v[218:219], off
	v_lshl_add_u64 v[218:219], s[82:83], 0, v[130:131]
	s_mov_b32 m0, s57
	s_nop 0
	global_load_lds_dwordx4 v[218:219], off
	v_lshl_add_u64 v[218:219], s[78:79], 0, v[136:137]
	s_mov_b32 m0, s6
	s_nop 0
	global_load_lds_dwordx4 v[218:219], off
	s_mov_b32 m0, s7
	s_nop 0
	global_load_lds_dwordx4 v[220:221], off
	s_waitcnt vmcnt(8)
	s_waitcnt lgkmcnt(0)
	s_setprio 1
	s_barrier
; #define PG8_STAGE(bufoff, gbase, voff) do { _Pragma("unroll") for (int _i = 0; _i < 2; ++_i) \
;         __builtin_amdgcn_global_load_lds((const unsigned*)((const char*)(gbase) + (voff)[_i]), (PG8_LAS unsigned*)(lds + (bufoff) + ldsw + _i * 8192), 16, 0, 0); } while (0)
; #define PG8_LDA(dst, b, h) do { _Pragma("unroll") for (int m = 0; m < 4; ++m) _Pragma("unroll") for (int k = 0; k < 2; ++k) dst[m][k] = *(const PG8_LAS bf16x8*)(lds + PG8_SA(b, h) + aoff + m * 2048 + k * 1024); } while (0)
; #define PG8_LDB(dst, b, h) do { _Pragma("unroll") for (int n = 0; n < 2; ++n) _Pragma("unroll") for (int k = 0; k < 2; ++k) dst[n][k] = *(const PG8_LAS bf16x8*)(lds + PG8_SB(b, h) + boff + n * 2048 + k * 1024); } while (0)
; #define PG8_MMA(ai, bj, At, Bt) do { __builtin_amdgcn_s_setprio(1); _Pragma("unroll") for (int m = 0; m < 4; ++m) _Pragma("unroll") for (int n = 0; n < 2; ++n) _Pragma("unroll") for (int k = 0; k < 2; ++k) \
;         acc[ai][bj][m][n] = __builtin_amdgcn_mfma_f32_16x16x32_bf16(Bt[n][k], At[m][k], acc[ai][bj][m][n], 0, 0, 0); __builtin_amdgcn_s_setprio(0); } while (0)
; #define PG8_WAIT_V(n) asm volatile("s_waitcnt vmcnt(" #n ")" ::: "memory")
; #define PG8_WAIT_L(n) asm volatile("s_waitcnt lgkmcnt(" #n ")" ::: "memory")
; #define PG8_BAR __builtin_amdgcn_s_barrier()
; #define PG8_SCHED __builtin_amdgcn_sched_barrier(0)
; template <class Epi, class Sched, bool ALIGN_EPI = false, bool SP2 = false>
; __device__ __forceinline__ void gemm_phase(PG8_LAS unsigned char* lds, const Gemm g, const Sched& S, const Epi& E) {
;     ...
;             PG8_WAIT_V(8); PG8_WAIT_L(0); PG8_BAR; PG8_MMA(1, 0, At, B0); PG8_MMA(1, 1, At, B1); PG8_BAR; PG8_SCHED;
;             PG8_LDB(B0, 1, 0); PG8_LDB(B1, 1, 1); PG8_SCHED; PG8_LDA(At, 1, 0); PG8_STAGE(PG8_SA(0, 1), a2 + hstepA, voffA);
;             PG8_WAIT_V(8); PG8_WAIT_L(0); PG8_BAR; PG8_MMA(0, 0, At, B0); PG8_MMA(0, 1, At, B1); PG8_BAR; PG8_SCHED;
	v_mfma_f32_16x16x32_bf16 v[62:65], v[142:145], v[186:189], v[62:65]
	v_mfma_f32_16x16x32_bf16 v[58:61], v[162:165], v[186:189], v[58:61]
	v_mfma_f32_16x16x32_bf16 v[50:53], v[142:145], v[194:197], v[50:53]
	v_mfma_f32_16x16x32_bf16 v[42:45], v[162:165], v[194:197], v[42:45]
	v_mfma_f32_16x16x32_bf16 v[34:37], v[142:145], v[202:205], v[34:37]
	v_mfma_f32_16x16x32_bf16 v[26:29], v[162:165], v[202:205], v[26:29]
	v_mfma_f32_16x16x32_bf16 v[18:21], v[142:145], v[210:213], v[18:21]
	v_mfma_f32_16x16x32_bf16 v[10:13], v[162:165], v[210:213], v[10:13]
	v_mfma_f32_16x16x32_bf16 v[62:65], v[146:149], v[190:193], v[62:65]
	v_mfma_f32_16x16x32_bf16 v[58:61], v[166:169], v[190:193], v[58:61]
	v_mfma_f32_16x16x32_bf16 v[50:53], v[146:149], v[198:201], v[50:53]
	v_mfma_f32_16x16x32_bf16 v[42:45], v[166:169], v[198:201], v[42:45]
	v_mfma_f32_16x16x32_bf16 v[34:37], v[146:149], v[206:209], v[34:37]
	v_mfma_f32_16x16x32_bf16 v[26:29], v[166:169], v[206:209], v[26:29]
	v_mfma_f32_16x16x32_bf16 v[18:21], v[146:149], v[214:217], v[18:21]
	v_mfma_f32_16x16x32_bf16 v[10:13], v[166:169], v[214:217], v[10:13]
	s_setprio 0
	s_setprio 1
	v_mfma_f32_16x16x32_bf16 v[54:57], v[170:173], v[186:189], v[54:57]
	v_mfma_f32_16x16x32_bf16 v[46:49], v[178:181], v[186:189], v[46:49]
	v_mfma_f32_16x16x32_bf16 v[38:41], v[170:173], v[194:197], v[38:41]
	v_mfma_f32_16x16x32_bf16 v[30:33], v[178:181], v[194:197], v[30:33]
	v_mfma_f32_16x16x32_bf16 v[22:25], v[170:173], v[202:205], v[22:25]
	v_mfma_f32_16x16x32_bf16 v[14:17], v[178:181], v[202:205], v[14:17]
	v_mfma_f32_16x16x32_bf16 v[6:9], v[170:173], v[210:213], v[6:9]
	v_mfma_f32_16x16x32_bf16 v[2:5], v[178:181], v[210:213], v[2:5]
	v_mfma_f32_16x16x32_bf16 v[54:57], v[174:177], v[190:193], v[54:57]
	v_mfma_f32_16x16x32_bf16 v[46:49], v[182:185], v[190:193], v[46:49]
	v_mfma_f32_16x16x32_bf16 v[38:41], v[174:177], v[198:201], v[38:41]
	v_mfma_f32_16x16x32_bf16 v[30:33], v[182:185], v[198:201], v[30:33]
	v_mfma_f32_16x16x32_bf16 v[22:25], v[174:177], v[206:209], v[22:25]
	v_mfma_f32_16x16x32_bf16 v[14:17], v[182:185], v[206:209], v[14:17]
	v_mfma_f32_16x16x32_bf16 v[6:9], v[174:177], v[214:217], v[6:9]
	v_mfma_f32_16x16x32_bf16 v[2:5], v[182:185], v[214:217], v[2:5]
	s_setprio 0
	s_barrier
	ds_read_b128 v[142:145], v160
	ds_read_b128 v[146:149], v160 offset:1024
	ds_read_b128 v[162:165], v160 offset:2048
	ds_read_b128 v[166:169], v160 offset:3072
	ds_read_b128 v[170:173], v161
	ds_read_b128 v[174:177], v161 offset:1024
	ds_read_b128 v[178:181], v161 offset:2048
	ds_read_b128 v[182:185], v161 offset:3072
	s_mov_b32 m0, s14
	v_lshl_add_u64 v[222:223], s[76:77], 0, v[136:137]
	ds_read_b128 v[186:189], v159 offset:32768
	ds_read_b128 v[190:193], v159 offset:33792
	ds_read_b128 v[194:197], v159 offset:34816
	ds_read_b128 v[198:201], v159 offset:35840
	ds_read_b128 v[202:205], v159 offset:36864
	ds_read_b128 v[206:209], v159 offset:37888
	ds_read_b128 v[210:213], v159 offset:38912
	ds_read_b128 v[214:217], v159 offset:39936
	global_load_lds_dwordx4 v[222:223], off
	v_lshl_add_u64 v[222:223], s[76:77], 0, v[132:133]
	s_mov_b32 m0, s15
	s_nop 0
	global_load_lds_dwordx4 v[222:223], off
	s_waitcnt vmcnt(8)
	s_waitcnt lgkmcnt(0)
	s_setprio 1
	s_barrier
	v_mfma_f32_16x16x32_bf16 v[126:129], v[142:145], v[186:189], v[126:129]
	v_mfma_f32_16x16x32_bf16 v[122:125], v[162:165], v[186:189], v[122:125]
	v_mfma_f32_16x16x32_bf16 v[118:121], v[142:145], v[194:197], v[118:121]
	v_mfma_f32_16x16x32_bf16 v[114:117], v[162:165], v[194:197], v[114:117]
	v_mfma_f32_16x16x32_bf16 v[106:109], v[142:145], v[202:205], v[106:109]
	v_mfma_f32_16x16x32_bf16 v[98:101], v[162:165], v[202:205], v[98:101]
	v_mfma_f32_16x16x32_bf16 v[82:85], v[142:145], v[210:213], v[82:85]
	v_mfma_f32_16x16x32_bf16 v[74:77], v[162:165], v[210:213], v[74:77]
	v_mfma_f32_16x16x32_bf16 v[126:129], v[146:149], v[190:193], v[126:129]
	v_mfma_f32_16x16x32_bf16 v[122:125], v[166:169], v[190:193], v[122:125]
	v_mfma_f32_16x16x32_bf16 v[118:121], v[146:149], v[198:201], v[118:121]
	v_mfma_f32_16x16x32_bf16 v[114:117], v[166:169], v[198:201], v[114:117]
	v_mfma_f32_16x16x32_bf16 v[106:109], v[146:149], v[206:209], v[106:109]
	v_mfma_f32_16x16x32_bf16 v[98:101], v[166:169], v[206:209], v[98:101]
	v_mfma_f32_16x16x32_bf16 v[82:85], v[146:149], v[214:217], v[82:85]
	v_mfma_f32_16x16x32_bf16 v[74:77], v[166:169], v[214:217], v[74:77]
	s_setprio 0
	s_setprio 1
	v_mfma_f32_16x16x32_bf16 v[110:113], v[170:173], v[186:189], v[110:113]
	v_mfma_f32_16x16x32_bf16 v[102:105], v[178:181], v[186:189], v[102:105]
	v_mfma_f32_16x16x32_bf16 v[94:97], v[170:173], v[194:197], v[94:97]
	v_mfma_f32_16x16x32_bf16 v[90:93], v[178:181], v[194:197], v[90:93]
	v_mfma_f32_16x16x32_bf16 v[86:89], v[170:173], v[202:205], v[86:89]
	v_mfma_f32_16x16x32_bf16 v[78:81], v[178:181], v[202:205], v[78:81]
	v_mfma_f32_16x16x32_bf16 v[70:73], v[170:173], v[210:213], v[70:73]
	v_mfma_f32_16x16x32_bf16 v[66:69], v[178:181], v[210:213], v[66:69]
	v_mfma_f32_16x16x32_bf16 v[110:113], v[174:177], v[190:193], v[110:113]
	v_mfma_f32_16x16x32_bf16 v[102:105], v[182:185], v[190:193], v[102:105]
	v_mfma_f32_16x16x32_bf16 v[94:97], v[174:177], v[198:201], v[94:97]
	v_mfma_f32_16x16x32_bf16 v[90:93], v[182:185], v[198:201], v[90:93]
	v_mfma_f32_16x16x32_bf16 v[86:89], v[174:177], v[206:209], v[86:89]
	v_mfma_f32_16x16x32_bf16 v[78:81], v[182:185], v[206:209], v[78:81]
	v_mfma_f32_16x16x32_bf16 v[70:73], v[174:177], v[214:217], v[70:73]
	v_mfma_f32_16x16x32_bf16 v[66:69], v[182:185], v[214:217], v[66:69]
	s_setprio 0
	s_barrier
; #define PG8_STAGE(bufoff, gbase, voff) do { _Pragma("unroll") for (int _i = 0; _i < 2; ++_i) \
;         __builtin_amdgcn_global_load_lds((const unsigned*)((const char*)(gbase) + (voff)[_i]), (PG8_LAS unsigned*)(lds + (bufoff) + ldsw + _i * 8192), 16, 0, 0); } while (0)
; #define PG8_WAIT_V(n) asm volatile("s_waitcnt vmcnt(" #n ")" ::: "memory")
; #define PG8_WAIT_L(n) asm volatile("s_waitcnt lgkmcnt(" #n ")" ::: "memory")
; template <class Epi, class Sched, bool ALIGN_EPI = false, bool SP2 = false>
; __device__ __forceinline__ void gemm_phase(PG8_LAS unsigned char* lds, const Gemm g, const Sched& S, const Epi& E) {
;     ...
;             PG8_WAIT_V(8); PG8_WAIT_L(0); PG8_BAR; PG8_MMA(0, 0, At, B0); PG8_MMA(0, 1, At, B1); PG8_BAR; PG8_SCHED;
;             PG8_LDA(At, 1, 1); PG8_STAGE(PG8_SB(1, 0), b3, voffB); PG8_STAGE(PG8_SB(1, 1), b3 + hstepB, voffB); PG8_STAGE(PG8_SA(1, 0), a3, voffA);
;             PG8_WAIT_V(8); PG8_WAIT_L(0); PG8_BAR; PG8_MMA(1, 0, At, B0); PG8_MMA(1, 1, At, B1); PG8_BAR; PG8_SCHED;
;             } else {
;             PG8_LDB(B0, 0, 0); PG8_SCHED; PG8_LDA(At, 0, 0); PG8_STAGE(PG8_SA(1, 1), a1 + hstepA, voffA);
;             PG8_WAIT_L(8); PG8_BAR; PG8_WAIT_L(0); PG8_MMA(0, 0, At, B0); PG8_BAR; PG8_SCHED;
;             PG8_LDB(B1, 0, 1); PG8_STAGE(PG8_SB(0, 0), b2, voffB);
;             PG8_BAR; PG8_WAIT_L(0); PG8_MMA(0, 1, At, B1); PG8_BAR;
;             PG8_LDA(At, 0, 1); PG8_STAGE(PG8_SA(0, 0), a2, voffA);
;             PG8_BAR; PG8_WAIT_L(0); PG8_MMA(1, 0, At, B0); PG8_BAR; PG8_SCHED;
;             PG8_STAGE(PG8_SB(0, 1), b2 + hstepB, voffB);
;             PG8_WAIT_V(6); PG8_BAR; PG8_MMA(1, 1, At, B1); PG8_BAR;
;             PG8_LDB(B0, 1, 0); PG8_SCHED; PG8_LDA(At, 1, 0); PG8_STAGE(PG8_SA(0, 1), a2 + hstepA, voffA);
;             PG8_WAIT_L(8); PG8_BAR; PG8_WAIT_L(0); PG8_MMA(0, 0, At, B0); PG8_BAR; PG8_SCHED;
;             PG8_LDB(B1, 1, 1); PG8_STAGE(PG8_SB(1, 0), b3, voffB);
;             PG8_BAR; PG8_WAIT_L(0); PG8_MMA(0, 1, At, B1); PG8_BAR;
;             PG8_LDA(At, 1, 1); PG8_STAGE(PG8_SA(1, 0), a3, voffA);
;             PG8_BAR; PG8_WAIT_L(0); PG8_MMA(1, 0, At, B0); PG8_BAR; PG8_SCHED;
;             PG8_STAGE(PG8_SB(1, 1), b3 + hstepB, voffB);
;             PG8_WAIT_V(6); PG8_BAR; PG8_MMA(1, 1, At, B1); PG8_BAR;
;             }
;         }
;         if constexpr (ALIGN_EPI) { if (wr == 0) PG8_BAR; }
	s_mov_b32 m0, s97
	v_lshl_add_u64 v[152:153], v[152:153], 0, s[10:11]
	ds_read_b128 v[186:189], v159 offset:49152
	ds_read_b128 v[190:193], v159 offset:50176
	ds_read_b128 v[194:197], v159 offset:51200
	ds_read_b128 v[198:201], v159 offset:52224
	ds_read_b128 v[202:205], v159 offset:53248
	ds_read_b128 v[206:209], v159 offset:54272
	ds_read_b128 v[210:213], v159 offset:55296
	ds_read_b128 v[214:217], v159 offset:56320
	global_load_lds_dwordx4 v[152:153], off
	v_lshl_add_u64 v[152:153], v[156:157], 0, s[10:11]
	s_mov_b32 m0, s19
	s_nop 0
	global_load_lds_dwordx4 v[152:153], off
	v_lshl_add_u64 v[152:153], s[74:75], 0, v[134:135]
	s_mov_b32 m0, s96
	s_nop 0
	global_load_lds_dwordx4 v[152:153], off
	v_lshl_add_u64 v[152:153], s[74:75], 0, v[130:131]
	s_mov_b32 m0, s18
	s_nop 0
	global_load_lds_dwordx4 v[152:153], off
	v_lshl_add_u64 v[152:153], v[218:219], 0, s[10:11]
	s_mov_b32 m0, s20
	s_nop 0
	global_load_lds_dwordx4 v[152:153], off
	v_lshl_add_u64 v[152:153], v[220:221], 0, s[10:11]
	s_mov_b32 m0, s21
	s_nop 0
	global_load_lds_dwordx4 v[152:153], off
	s_waitcnt vmcnt(8)
	s_waitcnt lgkmcnt(0)
	s_setprio 1
	s_barrier
	v_mfma_f32_16x16x32_bf16 v[62:65], v[142:145], v[186:189], v[62:65]
	v_mfma_f32_16x16x32_bf16 v[58:61], v[162:165], v[186:189], v[58:61]
	v_mfma_f32_16x16x32_bf16 v[50:53], v[142:145], v[194:197], v[50:53]
	v_mfma_f32_16x16x32_bf16 v[42:45], v[162:165], v[194:197], v[42:45]
	v_mfma_f32_16x16x32_bf16 v[34:37], v[142:145], v[202:205], v[34:37]
	v_mfma_f32_16x16x32_bf16 v[26:29], v[162:165], v[202:205], v[26:29]
	v_mfma_f32_16x16x32_bf16 v[18:21], v[142:145], v[210:213], v[18:21]
	v_mfma_f32_16x16x32_bf16 v[10:13], v[162:165], v[210:213], v[10:13]
	v_mfma_f32_16x16x32_bf16 v[62:65], v[146:149], v[190:193], v[62:65]
	v_mfma_f32_16x16x32_bf16 v[58:61], v[166:169], v[190:193], v[58:61]
	v_mfma_f32_16x16x32_bf16 v[50:53], v[146:149], v[198:201], v[50:53]
	v_mfma_f32_16x16x32_bf16 v[42:45], v[166:169], v[198:201], v[42:45]
	v_mfma_f32_16x16x32_bf16 v[34:37], v[146:149], v[206:209], v[34:37]
	v_mfma_f32_16x16x32_bf16 v[26:29], v[166:169], v[206:209], v[26:29]
	v_mfma_f32_16x16x32_bf16 v[18:21], v[146:149], v[214:217], v[18:21]
	v_mfma_f32_16x16x32_bf16 v[10:13], v[166:169], v[214:217], v[10:13]
	s_setprio 0
	s_setprio 1
	v_mfma_f32_16x16x32_bf16 v[54:57], v[170:173], v[186:189], v[54:57]
	v_mfma_f32_16x16x32_bf16 v[46:49], v[178:181], v[186:189], v[46:49]
	v_mfma_f32_16x16x32_bf16 v[38:41], v[170:173], v[194:197], v[38:41]
	v_mfma_f32_16x16x32_bf16 v[30:33], v[178:181], v[194:197], v[30:33]
	v_mfma_f32_16x16x32_bf16 v[22:25], v[170:173], v[202:205], v[22:25]
	v_mfma_f32_16x16x32_bf16 v[14:17], v[178:181], v[202:205], v[14:17]
	v_mfma_f32_16x16x32_bf16 v[6:9], v[170:173], v[210:213], v[6:9]
	v_mfma_f32_16x16x32_bf16 v[2:5], v[178:181], v[210:213], v[2:5]
	v_mfma_f32_16x16x32_bf16 v[54:57], v[174:177], v[190:193], v[54:57]
	v_mfma_f32_16x16x32_bf16 v[46:49], v[182:185], v[190:193], v[46:49]
	v_mfma_f32_16x16x32_bf16 v[38:41], v[174:177], v[198:201], v[38:41]
	v_mfma_f32_16x16x32_bf16 v[30:33], v[182:185], v[198:201], v[30:33]
	v_mfma_f32_16x16x32_bf16 v[22:25], v[174:177], v[206:209], v[22:25]
	v_mfma_f32_16x16x32_bf16 v[14:17], v[182:185], v[206:209], v[14:17]
	v_mfma_f32_16x16x32_bf16 v[6:9], v[174:177], v[214:217], v[6:9]
	v_mfma_f32_16x16x32_bf16 v[2:5], v[182:185], v[214:217], v[2:5]
	s_setprio 0
	s_barrier
	s_movk_i32 s18, 0x100
	s_andn2_b64 vcc, exec, s[72:73]
	s_mov_b64 s[74:75], -1
	s_mov_b64 s[72:73], 0
	s_cbranch_vccz .LBB0_1453
	s_and_b64 vcc, exec, s[42:43]
	s_cbranch_vccz .LBB0_1456
	s_barrier

; #define PG8_STAGE(bufoff, gbase, voff) do { _Pragma("unroll") for (int _i = 0; _i < 2; ++_i) \
;         __builtin_amdgcn_global_load_lds((const unsigned*)((const char*)(gbase) + (voff)[_i]), (PG8_LAS unsigned*)(lds + (bufoff) + ldsw + _i * 8192), 16, 0, 0); } while (0)
; #define PG8_LDA(dst, b, h) do { _Pragma("unroll") for (int m = 0; m < 4; ++m) _Pragma("unroll") for (int k = 0; k < 2; ++k) dst[m][k] = *(const PG8_LAS bf16x8*)(lds + PG8_SA(b, h) + aoff + m * 2048 + k * 1024); } while (0)
; #define PG8_LDB(dst, b, h) do { _Pragma("unroll") for (int n = 0; n < 2; ++n) _Pragma("unroll") for (int k = 0; k < 2; ++k) dst[n][k] = *(const PG8_LAS bf16x8*)(lds + PG8_SB(b, h) + boff + n * 2048 + k * 1024); } while (0)
; #define PG8_MMA(ai, bj, At, Bt) do { __builtin_amdgcn_s_setprio(1); _Pragma("unroll") for (int m = 0; m < 4; ++m) _Pragma("unroll") for (int n = 0; n < 2; ++n) _Pragma("unroll") for (int k = 0; k < 2; ++k) \
;         acc[ai][bj][m][n] = __builtin_amdgcn_mfma_f32_16x16x32_bf16(Bt[n][k], At[m][k], acc[ai][bj][m][n], 0, 0, 0); __builtin_amdgcn_s_setprio(0); } while (0)
; #define PG8_WAIT_V(n) asm volatile("s_waitcnt vmcnt(" #n ")" ::: "memory")
; #define PG8_BAR __builtin_amdgcn_s_barrier()
; template <class Epi, class Sched, bool ALIGN_EPI = false, bool SP2 = false>
; __device__ __forceinline__ void gemm_phase(PG8_LAS unsigned char* lds, const Gemm g, const Sched& S, const Epi& E) {
;     ...
;         for (int t = 0; t < nt; t += 2) {
;             const bool last = (t == nt - 2);
;             const char* a1 = cA + (size_t)(t + 1) * kstep;
;             const char* a2 = last ? nA : cA + (size_t)(t + 2) * kstep; const char* b2 = last ? nB : cB + (size_t)(t + 2) * kstep;
;             const char* a3 = a2 + kstep; const char* b3 = b2 + kstep;
;             if (last && has_next) S.a_ready(nxt);
;             if constexpr (SP2) {
;             PG8_LDB(B0, 0, 0); PG8_LDB(B1, 0, 1); PG8_SCHED; PG8_LDA(At, 0, 0); PG8_STAGE(PG8_SA(1, 1), a1 + hstepA, voffA);
;             PG8_WAIT_V(8); PG8_WAIT_L(0); PG8_BAR; PG8_MMA(0, 0, At, B0); PG8_MMA(0, 1, At, B1); PG8_BAR; PG8_SCHED;
;             PG8_LDA(At, 0, 1); PG8_STAGE(PG8_SB(0, 0), b2, voffB); PG8_STAGE(PG8_SB(0, 1), b2 + hstepB, voffB); PG8_STAGE(PG8_SA(0, 0), a2, voffA);
;             PG8_WAIT_V(8); PG8_WAIT_L(0); PG8_BAR; PG8_MMA(1, 0, At, B0); PG8_MMA(1, 1, At, B1); PG8_BAR; PG8_SCHED;
.LBB0_1477:
	s_add_u32 s2, s74, s19
	s_addc_u32 s3, s75, 0
	s_add_u32 s22, s2, 0x100
	s_addc_u32 s23, s3, 0
	s_and_b64 s[0:1], s[78:79], exec
	s_cselect_b32 s83, s5, s23
	s_cselect_b32 s82, s51, s22
	s_add_u32 s0, s72, s19
	s_addc_u32 s1, s73, 0
	s_add_u32 s19, s0, 0x100
	s_addc_u32 s22, s1, 0
	s_and_b64 s[0:1], s[78:79], exec
	s_cselect_b32 s85, s49, s22
	s_cselect_b32 s84, s18, s19
	s_add_u32 s88, s2, 0x80080
	s_addc_u32 s89, s3, 0
	s_add_i32 s23, s94, s14
	ds_read_b128 v[142:145], v153
	ds_read_b128 v[162:165], v153 offset:1024
	ds_read_b128 v[166:169], v153 offset:2048
	ds_read_b128 v[170:173], v153 offset:3072
	ds_read_b128 v[174:177], v157
	ds_read_b128 v[178:181], v157 offset:1024
	ds_read_b128 v[182:185], v157 offset:2048
	ds_read_b128 v[186:189], v157 offset:3072
	s_add_i32 m0, s6, 0xc000
	s_add_i32 s2, s6, 0xe000
	s_add_i32 s1, s23, 0x2000
	s_add_u32 s86, s84, 0x10000
	s_addc_u32 s87, s85, 0
	s_add_i32 s0, s95, s14
	s_add_i32 s22, s0, 0x2000
	s_add_u32 s80, s82, 0x80000
	s_addc_u32 s81, s83, 0
	s_add_i32 vcc_lo, s96, s14
	s_add_i32 s57, vcc_lo, 0x2000
	s_add_u32 s78, s84, 0x10080
	s_addc_u32 s79, s85, 0
	s_add_i32 vcc_hi, s97, s14
	s_add_i32 s19, vcc_hi, 0x2000
	v_lshl_add_u64 v[146:147], s[88:89], 0, v[130:131]
	ds_read_b128 v[190:193], v158
	ds_read_b128 v[194:197], v158 offset:1024
	ds_read_b128 v[198:201], v158 offset:2048
	ds_read_b128 v[202:205], v158 offset:3072
	ds_read_b128 v[206:209], v158 offset:4096
	ds_read_b128 v[210:213], v158 offset:5120
	ds_read_b128 v[214:217], v158 offset:6144
	ds_read_b128 v[218:221], v158 offset:7168
	global_load_lds_dwordx4 v[146:147], off
	v_lshl_add_u64 v[146:147], s[88:89], 0, v[134:135]
	s_mov_b32 m0, s2
	s_nop 0
	global_load_lds_dwordx4 v[146:147], off
	s_waitcnt vmcnt(8)
	s_waitcnt lgkmcnt(0)
	s_setprio 1
	s_barrier
	v_mfma_f32_16x16x32_bf16 v[126:129], v[142:145], v[190:193], v[126:129]
	v_mfma_f32_16x16x32_bf16 v[122:125], v[166:169], v[190:193], v[122:125]
	v_mfma_f32_16x16x32_bf16 v[118:121], v[142:145], v[198:201], v[118:121]
	v_mfma_f32_16x16x32_bf16 v[114:117], v[166:169], v[198:201], v[114:117]
	v_mfma_f32_16x16x32_bf16 v[106:109], v[142:145], v[206:209], v[106:109]
	v_mfma_f32_16x16x32_bf16 v[98:101], v[166:169], v[206:209], v[98:101]
	v_mfma_f32_16x16x32_bf16 v[82:85], v[142:145], v[214:217], v[82:85]
	v_mfma_f32_16x16x32_bf16 v[74:77], v[166:169], v[214:217], v[74:77]
	v_mfma_f32_16x16x32_bf16 v[126:129], v[162:165], v[194:197], v[126:129]
	v_mfma_f32_16x16x32_bf16 v[122:125], v[170:173], v[194:197], v[122:125]
	v_mfma_f32_16x16x32_bf16 v[118:121], v[162:165], v[202:205], v[118:121]
	v_mfma_f32_16x16x32_bf16 v[114:117], v[170:173], v[202:205], v[114:117]
	v_mfma_f32_16x16x32_bf16 v[106:109], v[162:165], v[210:213], v[106:109]
	v_mfma_f32_16x16x32_bf16 v[98:101], v[170:173], v[210:213], v[98:101]
	v_mfma_f32_16x16x32_bf16 v[82:85], v[162:165], v[218:221], v[82:85]
	v_mfma_f32_16x16x32_bf16 v[74:77], v[170:173], v[218:221], v[74:77]
	s_setprio 0
	s_setprio 1
	v_mfma_f32_16x16x32_bf16 v[110:113], v[174:177], v[190:193], v[110:113]
	v_mfma_f32_16x16x32_bf16 v[102:105], v[182:185], v[190:193], v[102:105]
	v_mfma_f32_16x16x32_bf16 v[94:97], v[174:177], v[198:201], v[94:97]
	v_mfma_f32_16x16x32_bf16 v[90:93], v[182:185], v[198:201], v[90:93]
	v_mfma_f32_16x16x32_bf16 v[86:89], v[174:177], v[206:209], v[86:89]
	v_mfma_f32_16x16x32_bf16 v[78:81], v[182:185], v[206:209], v[78:81]
	v_mfma_f32_16x16x32_bf16 v[70:73], v[174:177], v[214:217], v[70:73]
	v_mfma_f32_16x16x32_bf16 v[66:69], v[182:185], v[214:217], v[66:69]
	v_mfma_f32_16x16x32_bf16 v[110:113], v[178:181], v[194:197], v[110:113]
	v_mfma_f32_16x16x32_bf16 v[102:105], v[186:189], v[194:197], v[102:105]
	v_mfma_f32_16x16x32_bf16 v[94:97], v[178:181], v[202:205], v[94:97]
	v_mfma_f32_16x16x32_bf16 v[90:93], v[186:189], v[202:205], v[90:93]
	v_mfma_f32_16x16x32_bf16 v[86:89], v[178:181], v[210:213], v[86:89]
	v_mfma_f32_16x16x32_bf16 v[78:81], v[186:189], v[210:213], v[78:81]
	v_mfma_f32_16x16x32_bf16 v[70:73], v[178:181], v[218:221], v[70:73]
	v_mfma_f32_16x16x32_bf16 v[66:69], v[186:189], v[218:221], v[66:69]
	s_setprio 0
	s_barrier
	s_mov_b32 m0, s23
	v_lshl_add_u64 v[146:147], s[84:85], 0, v[132:133]
	ds_read_b128 v[190:193], v158 offset:16384
	ds_read_b128 v[194:197], v158 offset:17408
	ds_read_b128 v[198:201], v158 offset:18432
	ds_read_b128 v[202:205], v158 offset:19456
	ds_read_b128 v[206:209], v158 offset:20480
	ds_read_b128 v[210:213], v158 offset:21504
	ds_read_b128 v[214:217], v158 offset:22528
	ds_read_b128 v[218:221], v158 offset:23552
	global_load_lds_dwordx4 v[146:147], off
	v_lshl_add_u64 v[150:151], s[84:85], 0, v[136:137]
	s_mov_b32 m0, s1
	v_lshl_add_u64 v[154:155], s[86:87], 0, v[132:133]
	global_load_lds_dwordx4 v[150:151], off
	s_mov_b32 m0, s0
	v_lshl_add_u64 v[222:223], s[82:83], 0, v[134:135]
	global_load_lds_dwordx4 v[154:155], off
	v_lshl_add_u64 v[154:155], s[86:87], 0, v[136:137]
	s_mov_b32 m0, s22
	s_nop 0
	global_load_lds_dwordx4 v[154:155], off
	v_lshl_add_u64 v[154:155], s[82:83], 0, v[130:131]
	s_mov_b32 m0, s6
	s_nop 0
	global_load_lds_dwordx4 v[154:155], off
	s_mov_b32 m0, s7
	s_nop 0
	global_load_lds_dwordx4 v[222:223], off
	s_waitcnt vmcnt(8)
	s_waitcnt lgkmcnt(0)
	s_setprio 1
	s_barrier
; #define PG8_STAGE(bufoff, gbase, voff) do { _Pragma("unroll") for (int _i = 0; _i < 2; ++_i) \
;         __builtin_amdgcn_global_load_lds((const unsigned*)((const char*)(gbase) + (voff)[_i]), (PG8_LAS unsigned*)(lds + (bufoff) + ldsw + _i * 8192), 16, 0, 0); } while (0)
; #define PG8_LDA(dst, b, h) do { _Pragma("unroll") for (int m = 0; m < 4; ++m) _Pragma("unroll") for (int k = 0; k < 2; ++k) dst[m][k] = *(const PG8_LAS bf16x8*)(lds + PG8_SA(b, h) + aoff + m * 2048 + k * 1024); } while (0)
; #define PG8_LDB(dst, b, h) do { _Pragma("unroll") for (int n = 0; n < 2; ++n) _Pragma("unroll") for (int k = 0; k < 2; ++k) dst[n][k] = *(const PG8_LAS bf16x8*)(lds + PG8_SB(b, h) + boff + n * 2048 + k * 1024); } while (0)
; #define PG8_MMA(ai, bj, At, Bt) do { __builtin_amdgcn_s_setprio(1); _Pragma("unroll") for (int m = 0; m < 4; ++m) _Pragma("unroll") for (int n = 0; n < 2; ++n) _Pragma("unroll") for (int k = 0; k < 2; ++k) \
;         acc[ai][bj][m][n] = __builtin_amdgcn_mfma_f32_16x16x32_bf16(Bt[n][k], At[m][k], acc[ai][bj][m][n], 0, 0, 0); __builtin_amdgcn_s_setprio(0); } while (0)
; #define PG8_WAIT_V(n) asm volatile("s_waitcnt vmcnt(" #n ")" ::: "memory")
; #define PG8_WAIT_L(n) asm volatile("s_waitcnt lgkmcnt(" #n ")" ::: "memory")
; #define PG8_BAR __builtin_amdgcn_s_barrier()
; #define PG8_SCHED __builtin_amdgcn_sched_barrier(0)
; template <class Epi, class Sched, bool ALIGN_EPI = false, bool SP2 = false>
; __device__ __forceinline__ void gemm_phase(PG8_LAS unsigned char* lds, const Gemm g, const Sched& S, const Epi& E) {
;     ...
;             PG8_WAIT_V(8); PG8_WAIT_L(0); PG8_BAR; PG8_MMA(1, 0, At, B0); PG8_MMA(1, 1, At, B1); PG8_BAR; PG8_SCHED;
;             PG8_LDB(B0, 1, 0); PG8_LDB(B1, 1, 1); PG8_SCHED; PG8_LDA(At, 1, 0); PG8_STAGE(PG8_SA(0, 1), a2 + hstepA, voffA);
;             PG8_WAIT_V(8); PG8_WAIT_L(0); PG8_BAR; PG8_MMA(0, 0, At, B0); PG8_MMA(0, 1, At, B1); PG8_BAR; PG8_SCHED;
	v_mfma_f32_16x16x32_bf16 v[62:65], v[142:145], v[190:193], v[62:65]
	v_mfma_f32_16x16x32_bf16 v[58:61], v[166:169], v[190:193], v[58:61]
	v_mfma_f32_16x16x32_bf16 v[50:53], v[142:145], v[198:201], v[50:53]
	v_mfma_f32_16x16x32_bf16 v[42:45], v[166:169], v[198:201], v[42:45]
	v_mfma_f32_16x16x32_bf16 v[34:37], v[142:145], v[206:209], v[34:37]
	v_mfma_f32_16x16x32_bf16 v[26:29], v[166:169], v[206:209], v[26:29]
	v_mfma_f32_16x16x32_bf16 v[18:21], v[142:145], v[214:217], v[18:21]
	v_mfma_f32_16x16x32_bf16 v[10:13], v[166:169], v[214:217], v[10:13]
	v_mfma_f32_16x16x32_bf16 v[62:65], v[162:165], v[194:197], v[62:65]
	v_mfma_f32_16x16x32_bf16 v[58:61], v[170:173], v[194:197], v[58:61]
	v_mfma_f32_16x16x32_bf16 v[50:53], v[162:165], v[202:205], v[50:53]
	v_mfma_f32_16x16x32_bf16 v[42:45], v[170:173], v[202:205], v[42:45]
	v_mfma_f32_16x16x32_bf16 v[34:37], v[162:165], v[210:213], v[34:37]
	v_mfma_f32_16x16x32_bf16 v[26:29], v[170:173], v[210:213], v[26:29]
	v_mfma_f32_16x16x32_bf16 v[18:21], v[162:165], v[218:221], v[18:21]
	v_mfma_f32_16x16x32_bf16 v[10:13], v[170:173], v[218:221], v[10:13]
	s_setprio 0
	s_setprio 1
	v_mfma_f32_16x16x32_bf16 v[54:57], v[174:177], v[190:193], v[54:57]
	v_mfma_f32_16x16x32_bf16 v[46:49], v[182:185], v[190:193], v[46:49]
	v_mfma_f32_16x16x32_bf16 v[38:41], v[174:177], v[198:201], v[38:41]
	v_mfma_f32_16x16x32_bf16 v[30:33], v[182:185], v[198:201], v[30:33]
	v_mfma_f32_16x16x32_bf16 v[22:25], v[174:177], v[206:209], v[22:25]
	v_mfma_f32_16x16x32_bf16 v[14:17], v[182:185], v[206:209], v[14:17]
	v_mfma_f32_16x16x32_bf16 v[6:9], v[174:177], v[214:217], v[6:9]
	v_mfma_f32_16x16x32_bf16 v[2:5], v[182:185], v[214:217], v[2:5]
	v_mfma_f32_16x16x32_bf16 v[54:57], v[178:181], v[194:197], v[54:57]
	v_mfma_f32_16x16x32_bf16 v[46:49], v[186:189], v[194:197], v[46:49]
	v_mfma_f32_16x16x32_bf16 v[38:41], v[178:181], v[202:205], v[38:41]
	v_mfma_f32_16x16x32_bf16 v[30:33], v[186:189], v[202:205], v[30:33]
	v_mfma_f32_16x16x32_bf16 v[22:25], v[178:181], v[210:213], v[22:25]
	v_mfma_f32_16x16x32_bf16 v[14:17], v[186:189], v[210:213], v[14:17]
	v_mfma_f32_16x16x32_bf16 v[6:9], v[178:181], v[218:221], v[6:9]
	v_mfma_f32_16x16x32_bf16 v[2:5], v[186:189], v[218:221], v[2:5]
	s_setprio 0
	s_barrier
	ds_read_b128 v[142:145], v159
	ds_read_b128 v[162:165], v159 offset:1024
	ds_read_b128 v[166:169], v159 offset:2048
	ds_read_b128 v[170:173], v159 offset:3072
	ds_read_b128 v[174:177], v160
	ds_read_b128 v[178:181], v160 offset:1024
	ds_read_b128 v[182:185], v160 offset:2048
	ds_read_b128 v[186:189], v160 offset:3072
	s_mov_b32 m0, s15
	v_lshl_add_u64 v[224:225], s[80:81], 0, v[130:131]
	ds_read_b128 v[190:193], v158 offset:32768
	ds_read_b128 v[194:197], v158 offset:33792
	ds_read_b128 v[198:201], v158 offset:34816
	ds_read_b128 v[202:205], v158 offset:35840
	ds_read_b128 v[206:209], v158 offset:36864
	ds_read_b128 v[210:213], v158 offset:37888
	ds_read_b128 v[214:217], v158 offset:38912
	ds_read_b128 v[218:221], v158 offset:39936
	global_load_lds_dwordx4 v[224:225], off
	v_lshl_add_u64 v[224:225], s[80:81], 0, v[134:135]
	s_mov_b32 m0, s20
	s_nop 0
	global_load_lds_dwordx4 v[224:225], off
	s_waitcnt vmcnt(8)
	s_waitcnt lgkmcnt(0)
	s_setprio 1
	s_barrier
	v_mfma_f32_16x16x32_bf16 v[126:129], v[142:145], v[190:193], v[126:129]
	v_mfma_f32_16x16x32_bf16 v[122:125], v[166:169], v[190:193], v[122:125]
	v_mfma_f32_16x16x32_bf16 v[118:121], v[142:145], v[198:201], v[118:121]
	v_mfma_f32_16x16x32_bf16 v[114:117], v[166:169], v[198:201], v[114:117]
	v_mfma_f32_16x16x32_bf16 v[106:109], v[142:145], v[206:209], v[106:109]
	v_mfma_f32_16x16x32_bf16 v[98:101], v[166:169], v[206:209], v[98:101]
	v_mfma_f32_16x16x32_bf16 v[82:85], v[142:145], v[214:217], v[82:85]
	v_mfma_f32_16x16x32_bf16 v[74:77], v[166:169], v[214:217], v[74:77]
	v_mfma_f32_16x16x32_bf16 v[126:129], v[162:165], v[194:197], v[126:129]
	v_mfma_f32_16x16x32_bf16 v[122:125], v[170:173], v[194:197], v[122:125]
	v_mfma_f32_16x16x32_bf16 v[118:121], v[162:165], v[202:205], v[118:121]
	v_mfma_f32_16x16x32_bf16 v[114:117], v[170:173], v[202:205], v[114:117]
	v_mfma_f32_16x16x32_bf16 v[106:109], v[162:165], v[210:213], v[106:109]
	v_mfma_f32_16x16x32_bf16 v[98:101], v[170:173], v[210:213], v[98:101]
	v_mfma_f32_16x16x32_bf16 v[82:85], v[162:165], v[218:221], v[82:85]
	v_mfma_f32_16x16x32_bf16 v[74:77], v[170:173], v[218:221], v[74:77]
	s_setprio 0
	s_setprio 1
	v_mfma_f32_16x16x32_bf16 v[110:113], v[174:177], v[190:193], v[110:113]
	v_mfma_f32_16x16x32_bf16 v[102:105], v[182:185], v[190:193], v[102:105]
	v_mfma_f32_16x16x32_bf16 v[94:97], v[174:177], v[198:201], v[94:97]
	v_mfma_f32_16x16x32_bf16 v[90:93], v[182:185], v[198:201], v[90:93]
	v_mfma_f32_16x16x32_bf16 v[86:89], v[174:177], v[206:209], v[86:89]
	v_mfma_f32_16x16x32_bf16 v[78:81], v[182:185], v[206:209], v[78:81]
	v_mfma_f32_16x16x32_bf16 v[70:73], v[174:177], v[214:217], v[70:73]
	v_mfma_f32_16x16x32_bf16 v[66:69], v[182:185], v[214:217], v[66:69]
	v_mfma_f32_16x16x32_bf16 v[110:113], v[178:181], v[194:197], v[110:113]
	v_mfma_f32_16x16x32_bf16 v[102:105], v[186:189], v[194:197], v[102:105]
	v_mfma_f32_16x16x32_bf16 v[94:97], v[178:181], v[202:205], v[94:97]
	v_mfma_f32_16x16x32_bf16 v[90:93], v[186:189], v[202:205], v[90:93]
	v_mfma_f32_16x16x32_bf16 v[86:89], v[178:181], v[210:213], v[86:89]
	v_mfma_f32_16x16x32_bf16 v[78:81], v[186:189], v[210:213], v[78:81]
	v_mfma_f32_16x16x32_bf16 v[70:73], v[178:181], v[218:221], v[70:73]
	v_mfma_f32_16x16x32_bf16 v[66:69], v[186:189], v[218:221], v[66:69]
	s_setprio 0
	s_barrier
; #define PG8_STAGE(bufoff, gbase, voff) do { _Pragma("unroll") for (int _i = 0; _i < 2; ++_i) \
;         __builtin_amdgcn_global_load_lds((const unsigned*)((const char*)(gbase) + (voff)[_i]), (PG8_LAS unsigned*)(lds + (bufoff) + ldsw + _i * 8192), 16, 0, 0); } while (0)
; #define PG8_WAIT_V(n) asm volatile("s_waitcnt vmcnt(" #n ")" ::: "memory")
; #define PG8_WAIT_L(n) asm volatile("s_waitcnt lgkmcnt(" #n ")" ::: "memory")
; template <class Epi, class Sched, bool ALIGN_EPI = false, bool SP2 = false>
; __device__ __forceinline__ void gemm_phase(PG8_LAS unsigned char* lds, const Gemm g, const Sched& S, const Epi& E) {
;     ...
;             PG8_WAIT_V(8); PG8_WAIT_L(0); PG8_BAR; PG8_MMA(0, 0, At, B0); PG8_MMA(0, 1, At, B1); PG8_BAR; PG8_SCHED;
;             PG8_LDA(At, 1, 1); PG8_STAGE(PG8_SB(1, 0), b3, voffB); PG8_STAGE(PG8_SB(1, 1), b3 + hstepB, voffB); PG8_STAGE(PG8_SA(1, 0), a3, voffA);
;             PG8_WAIT_V(8); PG8_WAIT_L(0); PG8_BAR; PG8_MMA(1, 0, At, B0); PG8_MMA(1, 1, At, B1); PG8_BAR; PG8_SCHED;
;             } else {
;             PG8_LDB(B0, 0, 0); PG8_SCHED; PG8_LDA(At, 0, 0); PG8_STAGE(PG8_SA(1, 1), a1 + hstepA, voffA);
;             PG8_WAIT_L(8); PG8_BAR; PG8_WAIT_L(0); PG8_MMA(0, 0, At, B0); PG8_BAR; PG8_SCHED;
;             PG8_LDB(B1, 0, 1); PG8_STAGE(PG8_SB(0, 0), b2, voffB);
;             PG8_BAR; PG8_WAIT_L(0); PG8_MMA(0, 1, At, B1); PG8_BAR;
;             PG8_LDA(At, 0, 1); PG8_STAGE(PG8_SA(0, 0), a2, voffA);
;             PG8_BAR; PG8_WAIT_L(0); PG8_MMA(1, 0, At, B0); PG8_BAR; PG8_SCHED;
;             PG8_STAGE(PG8_SB(0, 1), b2 + hstepB, voffB);
;             PG8_WAIT_V(6); PG8_BAR; PG8_MMA(1, 1, At, B1); PG8_BAR;
;             PG8_LDB(B0, 1, 0); PG8_SCHED; PG8_LDA(At, 1, 0); PG8_STAGE(PG8_SA(0, 1), a2 + hstepA, voffA);
;             PG8_WAIT_L(8); PG8_BAR; PG8_WAIT_L(0); PG8_MMA(0, 0, At, B0); PG8_BAR; PG8_SCHED;
;             PG8_LDB(B1, 1, 1); PG8_STAGE(PG8_SB(1, 0), b3, voffB);
;             PG8_BAR; PG8_WAIT_L(0); PG8_MMA(0, 1, At, B1); PG8_BAR;
;             PG8_LDA(At, 1, 1); PG8_STAGE(PG8_SA(1, 0), a3, voffA);
;             PG8_BAR; PG8_WAIT_L(0); PG8_MMA(1, 0, At, B0); PG8_BAR; PG8_SCHED;
;             PG8_STAGE(PG8_SB(1, 1), b3 + hstepB, voffB);
;             PG8_WAIT_V(6); PG8_BAR; PG8_MMA(1, 1, At, B1); PG8_BAR;
;             }
;         }
;         if constexpr (ALIGN_EPI) { if (wr == 0) PG8_BAR; }
	s_mov_b32 m0, vcc_lo
	v_lshl_add_u64 v[146:147], v[146:147], 0, s[40:41]
	ds_read_b128 v[190:193], v158 offset:49152
	ds_read_b128 v[194:197], v158 offset:50176
	ds_read_b128 v[198:201], v158 offset:51200
	ds_read_b128 v[202:205], v158 offset:52224
	ds_read_b128 v[206:209], v158 offset:53248
	ds_read_b128 v[210:213], v158 offset:54272
	ds_read_b128 v[214:217], v158 offset:55296
	ds_read_b128 v[218:221], v158 offset:56320
	global_load_lds_dwordx4 v[146:147], off
	v_lshl_add_u64 v[146:147], v[150:151], 0, s[40:41]
	s_mov_b32 m0, s57
	s_nop 0
	global_load_lds_dwordx4 v[146:147], off
	v_lshl_add_u64 v[146:147], s[78:79], 0, v[132:133]
	s_mov_b32 m0, vcc_hi
	s_nop 0
	global_load_lds_dwordx4 v[146:147], off
	v_lshl_add_u64 v[146:147], s[78:79], 0, v[136:137]
	s_mov_b32 m0, s19
	s_nop 0
	global_load_lds_dwordx4 v[146:147], off
	v_lshl_add_u64 v[146:147], v[154:155], 0, s[40:41]
	s_mov_b32 m0, s21
	s_nop 0
	global_load_lds_dwordx4 v[146:147], off
	v_lshl_add_u64 v[146:147], v[222:223], 0, s[40:41]
	s_mov_b32 m0, s71
	s_nop 0
	global_load_lds_dwordx4 v[146:147], off
	s_waitcnt vmcnt(8)
	s_waitcnt lgkmcnt(0)
	s_setprio 1
	s_barrier
	v_mfma_f32_16x16x32_bf16 v[62:65], v[142:145], v[190:193], v[62:65]
	v_mfma_f32_16x16x32_bf16 v[58:61], v[166:169], v[190:193], v[58:61]
	v_mfma_f32_16x16x32_bf16 v[50:53], v[142:145], v[198:201], v[50:53]
	v_mfma_f32_16x16x32_bf16 v[42:45], v[166:169], v[198:201], v[42:45]
	v_mfma_f32_16x16x32_bf16 v[34:37], v[142:145], v[206:209], v[34:37]
	v_mfma_f32_16x16x32_bf16 v[26:29], v[166:169], v[206:209], v[26:29]
	v_mfma_f32_16x16x32_bf16 v[18:21], v[142:145], v[214:217], v[18:21]
	v_mfma_f32_16x16x32_bf16 v[10:13], v[166:169], v[214:217], v[10:13]
	v_mfma_f32_16x16x32_bf16 v[62:65], v[162:165], v[194:197], v[62:65]
	v_mfma_f32_16x16x32_bf16 v[58:61], v[170:173], v[194:197], v[58:61]
	v_mfma_f32_16x16x32_bf16 v[50:53], v[162:165], v[202:205], v[50:53]
	v_mfma_f32_16x16x32_bf16 v[42:45], v[170:173], v[202:205], v[42:45]
	v_mfma_f32_16x16x32_bf16 v[34:37], v[162:165], v[210:213], v[34:37]
	v_mfma_f32_16x16x32_bf16 v[26:29], v[170:173], v[210:213], v[26:29]
	v_mfma_f32_16x16x32_bf16 v[18:21], v[162:165], v[218:221], v[18:21]
	v_mfma_f32_16x16x32_bf16 v[10:13], v[170:173], v[218:221], v[10:13]
	s_setprio 0
	s_setprio 1
	v_mfma_f32_16x16x32_bf16 v[54:57], v[174:177], v[190:193], v[54:57]
	v_mfma_f32_16x16x32_bf16 v[46:49], v[182:185], v[190:193], v[46:49]
	v_mfma_f32_16x16x32_bf16 v[38:41], v[174:177], v[198:201], v[38:41]
	v_mfma_f32_16x16x32_bf16 v[30:33], v[182:185], v[198:201], v[30:33]
	v_mfma_f32_16x16x32_bf16 v[22:25], v[174:177], v[206:209], v[22:25]
	v_mfma_f32_16x16x32_bf16 v[14:17], v[182:185], v[206:209], v[14:17]
	v_mfma_f32_16x16x32_bf16 v[6:9], v[174:177], v[214:217], v[6:9]
	v_mfma_f32_16x16x32_bf16 v[2:5], v[182:185], v[214:217], v[2:5]
	v_mfma_f32_16x16x32_bf16 v[54:57], v[178:181], v[194:197], v[54:57]
	v_mfma_f32_16x16x32_bf16 v[46:49], v[186:189], v[194:197], v[46:49]
	v_mfma_f32_16x16x32_bf16 v[38:41], v[178:181], v[202:205], v[38:41]
	v_mfma_f32_16x16x32_bf16 v[30:33], v[186:189], v[202:205], v[30:33]
	v_mfma_f32_16x16x32_bf16 v[22:25], v[178:181], v[210:213], v[22:25]
	v_mfma_f32_16x16x32_bf16 v[14:17], v[186:189], v[210:213], v[14:17]
	v_mfma_f32_16x16x32_bf16 v[6:9], v[178:181], v[218:221], v[6:9]
	v_mfma_f32_16x16x32_bf16 v[2:5], v[186:189], v[218:221], v[2:5]
	s_setprio 0
	s_barrier
	s_movk_i32 s19, 0x100
	s_andn2_b64 vcc, exec, s[76:77]
	s_mov_b64 s[78:79], -1
	s_mov_b64 s[76:77], 0
	s_cbranch_vccz .LBB0_1477
	s_and_b64 vcc, exec, s[46:47]
	s_cbranch_vccz .LBB0_1480
	s_barrier

;     __device__ __forceinline__ bool next(int i, Unit& u) const { if (!S.next(i, u)) return false; if (u.pn >= 4) u.pn += 2; return true; }
; #define PG8_STAGE(bufoff, gbase, voff) do { _Pragma("unroll") for (int _i = 0; _i < 2; ++_i) \
;         __builtin_amdgcn_global_load_lds((const unsigned*)((const char*)(gbase) + (voff)[_i]), (PG8_LAS unsigned*)(lds + (bufoff) + ldsw + _i * 8192), 16, 0, 0); } while (0)
; #define PG8_LDA(dst, b, h) do { _Pragma("unroll") for (int m = 0; m < 4; ++m) _Pragma("unroll") for (int k = 0; k < 2; ++k) dst[m][k] = *(const PG8_LAS bf16x8*)(lds + PG8_SA(b, h) + aoff + m * 2048 + k * 1024); } while (0)
; #define PG8_WAIT_V(n) asm volatile("s_waitcnt vmcnt(" #n ")" ::: "memory")
; #define PG8_BAR __builtin_amdgcn_s_barrier()
; template <class Epi, class Sched, bool ALIGN_EPI = false, bool SP2 = false>
; __device__ __forceinline__ void gemm_phase(PG8_LAS unsigned char* lds, const Gemm g, const Sched& S, const Epi& E) {
;     ...
;         const bool has_next = S.next(ui + 1, nxt);
;         if constexpr (Epi::LDS_PF) { if (has_next) E.prefetch(nxt, lds + STAGE_BYTES + ((ui + 1) % 3) * 4096, wid, lane); }
;         const char* nA = has_next ? (const char*)g.A + (size_t)nxt.pm * tstepA : cA; const char* nB = has_next ? (const char*)g.Bt + (size_t)nxt.pn * tstepB : cB;
;         for (int t = 0; t < nt; t += 2) {
;             const bool last = (t == nt - 2);
;             const char* a1 = cA + (size_t)(t + 1) * kstep;
;             const char* a2 = last ? nA : cA + (size_t)(t + 2) * kstep; const char* b2 = last ? nB : cB + (size_t)(t + 2) * kstep;
;             const char* a3 = a2 + kstep; const char* b3 = b2 + kstep;
;             if (last && has_next) S.a_ready(nxt);
;             if constexpr (SP2) {
;             PG8_LDB(B0, 0, 0); PG8_LDB(B1, 0, 1); PG8_SCHED; PG8_LDA(At, 0, 0); PG8_STAGE(PG8_SA(1, 1), a1 + hstepA, voffA);
;             PG8_WAIT_V(8); PG8_WAIT_L(0); PG8_BAR; PG8_MMA(0, 0, At, B0); PG8_MMA(0, 1, At, B1); PG8_BAR; PG8_SCHED;
;     ...
; #pragma unroll
;         for (int a = 0; a < 2; ++a)
; #pragma unroll
;             for (int b = 0; b < 2; ++b)
; #pragma unroll
;                 for (int m = 0; m < 4; ++m)
; #pragma unroll
;                     for (int n = 0; n < 2; ++n) acc[a][b][m][n] = (f32x4){0.f, 0.f, 0.f, 0.f};
;         cur = nxt; cA = nA; cB = nB; ++ui;
;         if constexpr (ALIGN_EPI) { if (wr == 1) PG8_BAR; }
.LBB0_1682:
	s_ashr_i32 s49, s48, 31
	s_lshl_b64 s[0:1], s[48:49], 19
	s_add_u32 s66, s26, s0
	s_addc_u32 s67, s27, s1
	s_and_b64 s[0:1], s[12:13], exec
	s_cselect_b32 s4, s67, s73
	s_cselect_b32 s5, s66, s72
	s_add_u32 s12, s70, 0x40080
	s_addc_u32 s13, s71, 0
	s_add_u32 s7, s72, 0x100
	v_mov_b32_e32 v2, 0
	s_addc_u32 s14, s73, 0
	s_mov_b32 s15, -2
	v_mov_b32_e32 v3, v2
	v_mov_b32_e32 v4, v2
	v_mov_b32_e32 v5, v2
	v_mov_b32_e32 v6, v2
	v_mov_b32_e32 v7, v2
	v_mov_b32_e32 v8, v2
	v_mov_b32_e32 v9, v2
	v_mov_b32_e32 v18, v2
	v_mov_b32_e32 v19, v2
	v_mov_b32_e32 v20, v2
	v_mov_b32_e32 v21, v2
	v_mov_b32_e32 v22, v2
	v_mov_b32_e32 v23, v2
	v_mov_b32_e32 v24, v2
	v_mov_b32_e32 v25, v2
	s_waitcnt vmcnt(0)
	v_mov_b32_e32 v34, v2
	v_mov_b32_e32 v35, v2
	v_mov_b32_e32 v36, v2
	v_mov_b32_e32 v37, v2
	v_mov_b32_e32 v38, v2
	v_mov_b32_e32 v39, v2
	v_mov_b32_e32 v40, v2
	v_mov_b32_e32 v41, v2
	v_mov_b32_e32 v50, v2
	v_mov_b32_e32 v51, v2
	v_mov_b32_e32 v52, v2
	v_mov_b32_e32 v53, v2
	v_mov_b32_e32 v54, v2
	v_mov_b32_e32 v55, v2
	v_mov_b32_e32 v56, v2
	v_mov_b32_e32 v57, v2
	v_mov_b32_e32 v10, v2
	v_mov_b32_e32 v11, v2
	v_mov_b32_e32 v12, v2
	v_mov_b32_e32 v13, v2
	v_mov_b32_e32 v14, v2
	v_mov_b32_e32 v15, v2
	v_mov_b32_e32 v16, v2
	v_mov_b32_e32 v17, v2
	v_mov_b32_e32 v26, v2
	v_mov_b32_e32 v27, v2
	v_mov_b32_e32 v28, v2
	v_mov_b32_e32 v29, v2
	v_mov_b32_e32 v30, v2
	v_mov_b32_e32 v31, v2
	v_mov_b32_e32 v32, v2
	v_mov_b32_e32 v33, v2
	v_mov_b32_e32 v42, v2
	v_mov_b32_e32 v43, v2
	v_mov_b32_e32 v44, v2
	v_mov_b32_e32 v45, v2
	v_mov_b32_e32 v46, v2
	v_mov_b32_e32 v47, v2
	v_mov_b32_e32 v48, v2
	v_mov_b32_e32 v49, v2
	v_mov_b32_e32 v58, v2
	v_mov_b32_e32 v59, v2
	v_mov_b32_e32 v60, v2
	v_mov_b32_e32 v61, v2
	v_mov_b32_e32 v62, v2
	v_mov_b32_e32 v63, v2
	v_mov_b32_e32 v64, v2
	v_mov_b32_e32 v65, v2
	v_mov_b32_e32 v66, v2
	v_mov_b32_e32 v67, v2
	v_mov_b32_e32 v68, v2
	v_mov_b32_e32 v69, v2
	v_mov_b32_e32 v70, v2
	v_mov_b32_e32 v71, v2
	v_mov_b32_e32 v72, v2
	v_mov_b32_e32 v73, v2
	v_mov_b32_e32 v82, v2
	v_mov_b32_e32 v83, v2
	v_mov_b32_e32 v84, v2
	v_mov_b32_e32 v85, v2
	v_mov_b32_e32 v86, v2
	v_mov_b32_e32 v87, v2
	v_mov_b32_e32 v88, v2
	v_mov_b32_e32 v89, v2
	v_mov_b32_e32 v98, v2
	v_mov_b32_e32 v99, v2
	v_mov_b32_e32 v100, v2
	v_mov_b32_e32 v101, v2
	v_mov_b32_e32 v102, v2
	v_mov_b32_e32 v103, v2
	v_mov_b32_e32 v104, v2
	v_mov_b32_e32 v105, v2
	v_mov_b32_e32 v114, v2
	v_mov_b32_e32 v115, v2
	v_mov_b32_e32 v116, v2
	v_mov_b32_e32 v117, v2
	v_mov_b32_e32 v118, v2
	v_mov_b32_e32 v119, v2
	v_mov_b32_e32 v120, v2
	v_mov_b32_e32 v121, v2
	v_mov_b32_e32 v74, v2
	v_mov_b32_e32 v75, v2
	v_mov_b32_e32 v76, v2
	v_mov_b32_e32 v77, v2
	v_mov_b32_e32 v78, v2
	v_mov_b32_e32 v79, v2
	v_mov_b32_e32 v80, v2
	v_mov_b32_e32 v81, v2
	v_mov_b32_e32 v90, v2
	v_mov_b32_e32 v91, v2
	v_mov_b32_e32 v92, v2
	v_mov_b32_e32 v93, v2
	v_mov_b32_e32 v94, v2
	v_mov_b32_e32 v95, v2
	v_mov_b32_e32 v96, v2
	v_mov_b32_e32 v97, v2
	v_mov_b32_e32 v106, v2
	v_mov_b32_e32 v107, v2
	v_mov_b32_e32 v108, v2
	v_mov_b32_e32 v109, v2
	v_mov_b32_e32 v110, v2
	v_mov_b32_e32 v111, v2
	v_mov_b32_e32 v112, v2
	v_mov_b32_e32 v113, v2
	v_mov_b32_e32 v122, v2
	v_mov_b32_e32 v123, v2
	v_mov_b32_e32 v124, v2
	v_mov_b32_e32 v125, v2
	v_mov_b32_e32 v126, v2
	v_mov_b32_e32 v127, v2
	v_mov_b32_e32 v128, v2
	v_mov_b32_e32 v129, v2
	s_cmp_eq_u32 s98, 1
	s_cbranch_scc0 .Ldefer_5
	s_barrier
	s_mov_b32 s98, 0
.Ldefer_5:
.LBB0_1683:
	ds_read_b128 v[130:133], v189
	ds_read_b128 v[134:137], v189 offset:1024
	ds_read_b128 v[138:141], v189 offset:2048
	ds_read_b128 v[142:145], v189 offset:3072
	ds_read_b128 v[168:171], v190
	ds_read_b128 v[194:197], v190 offset:1024
	ds_read_b128 v[198:201], v190 offset:2048
	ds_read_b128 v[202:205], v190 offset:3072
	s_add_u32 s0, s12, 0xfffc0080
	s_addc_u32 s1, s13, -1
	s_cmp_eq_u32 s15, 12
	s_cselect_b32 s73, s63, s1
	s_cselect_b32 s72, s62, s0
	s_cselect_b32 s71, s4, s14
	s_cselect_b32 s70, s5, s7
	v_lshl_add_u64 v[238:239], s[12:13], 0, v[160:161]
	s_add_i32 m0, s74, 0xc000
	ds_read_b128 v[206:209], v191
	ds_read_b128 v[210:213], v191 offset:1024
	ds_read_b128 v[214:217], v191 offset:2048
	ds_read_b128 v[218:221], v191 offset:3072
	ds_read_b128 v[222:225], v191 offset:4096
	ds_read_b128 v[226:229], v191 offset:5120
	ds_read_b128 v[230:233], v191 offset:6144
	ds_read_b128 v[234:237], v191 offset:7168
	global_load_lds_dwordx4 v[238:239], off
	v_lshl_add_u64 v[238:239], s[12:13], 0, v[162:163]
	s_add_i32 m0, s74, 0xe000
	s_nop 0
	global_load_lds_dwordx4 v[238:239], off
	s_waitcnt vmcnt(8)
	s_waitcnt lgkmcnt(0)
	s_setprio 1
	s_barrier
; #define PG8_STAGE(bufoff, gbase, voff) do { _Pragma("unroll") for (int _i = 0; _i < 2; ++_i) \
;         __builtin_amdgcn_global_load_lds((const unsigned*)((const char*)(gbase) + (voff)[_i]), (PG8_LAS unsigned*)(lds + (bufoff) + ldsw + _i * 8192), 16, 0, 0); } while (0)
; #define PG8_LDA(dst, b, h) do { _Pragma("unroll") for (int m = 0; m < 4; ++m) _Pragma("unroll") for (int k = 0; k < 2; ++k) dst[m][k] = *(const PG8_LAS bf16x8*)(lds + PG8_SA(b, h) + aoff + m * 2048 + k * 1024); } while (0)
; #define PG8_LDB(dst, b, h) do { _Pragma("unroll") for (int n = 0; n < 2; ++n) _Pragma("unroll") for (int k = 0; k < 2; ++k) dst[n][k] = *(const PG8_LAS bf16x8*)(lds + PG8_SB(b, h) + boff + n * 2048 + k * 1024); } while (0)
; #define PG8_MMA(ai, bj, At, Bt) do { __builtin_amdgcn_s_setprio(1); _Pragma("unroll") for (int m = 0; m < 4; ++m) _Pragma("unroll") for (int n = 0; n < 2; ++n) _Pragma("unroll") for (int k = 0; k < 2; ++k) \
;         acc[ai][bj][m][n] = __builtin_amdgcn_mfma_f32_16x16x32_bf16(Bt[n][k], At[m][k], acc[ai][bj][m][n], 0, 0, 0); __builtin_amdgcn_s_setprio(0); } while (0)
; #define PG8_WAIT_V(n) asm volatile("s_waitcnt vmcnt(" #n ")" ::: "memory")
; #define PG8_WAIT_L(n) asm volatile("s_waitcnt lgkmcnt(" #n ")" ::: "memory")
; #define PG8_BAR __builtin_amdgcn_s_barrier()
; #define PG8_SCHED __builtin_amdgcn_sched_barrier(0)
; template <class Epi, class Sched, bool ALIGN_EPI = false, bool SP2 = false>
; __device__ __forceinline__ void gemm_phase(PG8_LAS unsigned char* lds, const Gemm g, const Sched& S, const Epi& E) {
;     ...
;             PG8_LDB(B0, 0, 0); PG8_LDB(B1, 0, 1); PG8_SCHED; PG8_LDA(At, 0, 0); PG8_STAGE(PG8_SA(1, 1), a1 + hstepA, voffA);
;             PG8_WAIT_V(8); PG8_WAIT_L(0); PG8_BAR; PG8_MMA(0, 0, At, B0); PG8_MMA(0, 1, At, B1); PG8_BAR; PG8_SCHED;
;             PG8_LDA(At, 0, 1); PG8_STAGE(PG8_SB(0, 0), b2, voffB); PG8_STAGE(PG8_SB(0, 1), b2 + hstepB, voffB); PG8_STAGE(PG8_SA(0, 0), a2, voffA);
;             PG8_WAIT_V(8); PG8_WAIT_L(0); PG8_BAR; PG8_MMA(1, 0, At, B0); PG8_MMA(1, 1, At, B1); PG8_BAR; PG8_SCHED;
	v_mfma_f32_16x16x32_bf16 v[126:129], v[130:133], v[206:209], v[126:129]
	v_mfma_f32_16x16x32_bf16 v[122:125], v[138:141], v[206:209], v[122:125]
	v_mfma_f32_16x16x32_bf16 v[110:113], v[130:133], v[214:217], v[110:113]
	v_mfma_f32_16x16x32_bf16 v[106:109], v[138:141], v[214:217], v[106:109]
	v_mfma_f32_16x16x32_bf16 v[94:97], v[130:133], v[222:225], v[94:97]
	v_mfma_f32_16x16x32_bf16 v[90:93], v[138:141], v[222:225], v[90:93]
	v_mfma_f32_16x16x32_bf16 v[78:81], v[130:133], v[230:233], v[78:81]
	v_mfma_f32_16x16x32_bf16 v[74:77], v[138:141], v[230:233], v[74:77]
	v_mfma_f32_16x16x32_bf16 v[126:129], v[134:137], v[210:213], v[126:129]
	v_mfma_f32_16x16x32_bf16 v[122:125], v[142:145], v[210:213], v[122:125]
	v_mfma_f32_16x16x32_bf16 v[110:113], v[134:137], v[218:221], v[110:113]
	v_mfma_f32_16x16x32_bf16 v[106:109], v[142:145], v[218:221], v[106:109]
	v_mfma_f32_16x16x32_bf16 v[94:97], v[134:137], v[226:229], v[94:97]
	v_mfma_f32_16x16x32_bf16 v[90:93], v[142:145], v[226:229], v[90:93]
	v_mfma_f32_16x16x32_bf16 v[78:81], v[134:137], v[234:237], v[78:81]
	v_mfma_f32_16x16x32_bf16 v[74:77], v[142:145], v[234:237], v[74:77]
	s_setprio 0
	s_setprio 1
	v_mfma_f32_16x16x32_bf16 v[118:121], v[168:171], v[206:209], v[118:121]
	v_mfma_f32_16x16x32_bf16 v[114:117], v[198:201], v[206:209], v[114:117]
	v_mfma_f32_16x16x32_bf16 v[102:105], v[168:171], v[214:217], v[102:105]
	v_mfma_f32_16x16x32_bf16 v[98:101], v[198:201], v[214:217], v[98:101]
	v_mfma_f32_16x16x32_bf16 v[86:89], v[168:171], v[222:225], v[86:89]
	v_mfma_f32_16x16x32_bf16 v[82:85], v[198:201], v[222:225], v[82:85]
	v_mfma_f32_16x16x32_bf16 v[70:73], v[168:171], v[230:233], v[70:73]
	v_mfma_f32_16x16x32_bf16 v[66:69], v[198:201], v[230:233], v[66:69]
	v_mfma_f32_16x16x32_bf16 v[118:121], v[194:197], v[210:213], v[118:121]
	v_mfma_f32_16x16x32_bf16 v[114:117], v[202:205], v[210:213], v[114:117]
	v_mfma_f32_16x16x32_bf16 v[102:105], v[194:197], v[218:221], v[102:105]
	v_mfma_f32_16x16x32_bf16 v[98:101], v[202:205], v[218:221], v[98:101]
	v_mfma_f32_16x16x32_bf16 v[86:89], v[194:197], v[226:229], v[86:89]
	v_mfma_f32_16x16x32_bf16 v[82:85], v[202:205], v[226:229], v[82:85]
	v_mfma_f32_16x16x32_bf16 v[70:73], v[194:197], v[234:237], v[70:73]
	v_mfma_f32_16x16x32_bf16 v[66:69], v[202:205], v[234:237], v[66:69]
	s_setprio 0
	s_barrier
	s_add_i32 s0, s80, s69
	v_lshl_add_u64 v[238:239], s[70:71], 0, v[146:147]
	s_mov_b32 m0, s0
	ds_read_b128 v[206:209], v191 offset:16384
	ds_read_b128 v[210:213], v191 offset:17408
	ds_read_b128 v[214:217], v191 offset:18432
	ds_read_b128 v[218:221], v191 offset:19456
	ds_read_b128 v[222:225], v191 offset:20480
	ds_read_b128 v[226:229], v191 offset:21504
	ds_read_b128 v[230:233], v191 offset:22528
	ds_read_b128 v[234:237], v191 offset:23552
	global_load_lds_dwordx4 v[238:239], off
	s_add_i32 m0, s0, 0x2000
	s_add_u32 s0, s70, 0x40000
	v_lshl_add_u64 v[240:241], s[70:71], 0, v[152:153]
	s_addc_u32 s1, s71, 0
	s_add_i32 s2, s81, s69
	global_load_lds_dwordx4 v[240:241], off
	v_lshl_add_u64 v[242:243], s[0:1], 0, v[146:147]
	s_mov_b32 m0, s2
	v_lshl_add_u64 v[244:245], s[72:73], 0, v[150:151]
	global_load_lds_dwordx4 v[242:243], off
	v_lshl_add_u64 v[242:243], s[0:1], 0, v[152:153]
	s_add_i32 m0, s2, 0x2000
	s_nop 0
	global_load_lds_dwordx4 v[242:243], off
	v_lshl_add_u64 v[242:243], s[72:73], 0, v[148:149]
	s_mov_b32 m0, s74
	s_nop 0
	global_load_lds_dwordx4 v[242:243], off
	s_mov_b32 m0, s75
	s_nop 0
	global_load_lds_dwordx4 v[244:245], off
	s_waitcnt vmcnt(8)
	s_waitcnt lgkmcnt(0)
	s_setprio 1
	s_barrier
	v_mfma_f32_16x16x32_bf16 v[62:65], v[130:133], v[206:209], v[62:65]
	v_mfma_f32_16x16x32_bf16 v[58:61], v[138:141], v[206:209], v[58:61]
	v_mfma_f32_16x16x32_bf16 v[46:49], v[130:133], v[214:217], v[46:49]
	v_mfma_f32_16x16x32_bf16 v[42:45], v[138:141], v[214:217], v[42:45]
	v_mfma_f32_16x16x32_bf16 v[30:33], v[130:133], v[222:225], v[30:33]
	v_mfma_f32_16x16x32_bf16 v[26:29], v[138:141], v[222:225], v[26:29]
	v_mfma_f32_16x16x32_bf16 v[14:17], v[130:133], v[230:233], v[14:17]
	v_mfma_f32_16x16x32_bf16 v[10:13], v[138:141], v[230:233], v[10:13]
	v_mfma_f32_16x16x32_bf16 v[62:65], v[134:137], v[210:213], v[62:65]
	v_mfma_f32_16x16x32_bf16 v[58:61], v[142:145], v[210:213], v[58:61]
	v_mfma_f32_16x16x32_bf16 v[46:49], v[134:137], v[218:221], v[46:49]
	v_mfma_f32_16x16x32_bf16 v[42:45], v[142:145], v[218:221], v[42:45]
	v_mfma_f32_16x16x32_bf16 v[30:33], v[134:137], v[226:229], v[30:33]
	v_mfma_f32_16x16x32_bf16 v[26:29], v[142:145], v[226:229], v[26:29]
	v_mfma_f32_16x16x32_bf16 v[14:17], v[134:137], v[234:237], v[14:17]
	v_mfma_f32_16x16x32_bf16 v[10:13], v[142:145], v[234:237], v[10:13]
	s_setprio 0
	s_setprio 1
	v_mfma_f32_16x16x32_bf16 v[54:57], v[168:171], v[206:209], v[54:57]
	v_mfma_f32_16x16x32_bf16 v[50:53], v[198:201], v[206:209], v[50:53]
	v_mfma_f32_16x16x32_bf16 v[38:41], v[168:171], v[214:217], v[38:41]
	v_mfma_f32_16x16x32_bf16 v[34:37], v[198:201], v[214:217], v[34:37]
	v_mfma_f32_16x16x32_bf16 v[22:25], v[168:171], v[222:225], v[22:25]
	v_mfma_f32_16x16x32_bf16 v[18:21], v[198:201], v[222:225], v[18:21]
	v_mfma_f32_16x16x32_bf16 v[6:9], v[168:171], v[230:233], v[6:9]
	v_mfma_f32_16x16x32_bf16 v[2:5], v[198:201], v[230:233], v[2:5]
	v_mfma_f32_16x16x32_bf16 v[54:57], v[194:197], v[210:213], v[54:57]
	v_mfma_f32_16x16x32_bf16 v[50:53], v[202:205], v[210:213], v[50:53]
	v_mfma_f32_16x16x32_bf16 v[38:41], v[194:197], v[218:221], v[38:41]
	v_mfma_f32_16x16x32_bf16 v[34:37], v[202:205], v[218:221], v[34:37]
	v_mfma_f32_16x16x32_bf16 v[22:25], v[194:197], v[226:229], v[22:25]
	v_mfma_f32_16x16x32_bf16 v[18:21], v[202:205], v[226:229], v[18:21]
	v_mfma_f32_16x16x32_bf16 v[6:9], v[194:197], v[234:237], v[6:9]
	v_mfma_f32_16x16x32_bf16 v[2:5], v[202:205], v[234:237], v[2:5]
	s_setprio 0
	s_barrier
; #define PG8_STAGE(bufoff, gbase, voff) do { _Pragma("unroll") for (int _i = 0; _i < 2; ++_i) \
;         __builtin_amdgcn_global_load_lds((const unsigned*)((const char*)(gbase) + (voff)[_i]), (PG8_LAS unsigned*)(lds + (bufoff) + ldsw + _i * 8192), 16, 0, 0); } while (0)
; #define PG8_LDA(dst, b, h) do { _Pragma("unroll") for (int m = 0; m < 4; ++m) _Pragma("unroll") for (int k = 0; k < 2; ++k) dst[m][k] = *(const PG8_LAS bf16x8*)(lds + PG8_SA(b, h) + aoff + m * 2048 + k * 1024); } while (0)
; #define PG8_LDB(dst, b, h) do { _Pragma("unroll") for (int n = 0; n < 2; ++n) _Pragma("unroll") for (int k = 0; k < 2; ++k) dst[n][k] = *(const PG8_LAS bf16x8*)(lds + PG8_SB(b, h) + boff + n * 2048 + k * 1024); } while (0)
; #define PG8_MMA(ai, bj, At, Bt) do { __builtin_amdgcn_s_setprio(1); _Pragma("unroll") for (int m = 0; m < 4; ++m) _Pragma("unroll") for (int n = 0; n < 2; ++n) _Pragma("unroll") for (int k = 0; k < 2; ++k) \
;         acc[ai][bj][m][n] = __builtin_amdgcn_mfma_f32_16x16x32_bf16(Bt[n][k], At[m][k], acc[ai][bj][m][n], 0, 0, 0); __builtin_amdgcn_s_setprio(0); } while (0)
; #define PG8_WAIT_V(n) asm volatile("s_waitcnt vmcnt(" #n ")" ::: "memory")
; #define PG8_WAIT_L(n) asm volatile("s_waitcnt lgkmcnt(" #n ")" ::: "memory")
; #define PG8_BAR __builtin_amdgcn_s_barrier()
; #define PG8_SCHED __builtin_amdgcn_sched_barrier(0)
; template <class Epi, class Sched, bool ALIGN_EPI = false, bool SP2 = false>
; __device__ __forceinline__ void gemm_phase(PG8_LAS unsigned char* lds, const Gemm g, const Sched& S, const Epi& E) {
;     ...
;             PG8_LDB(B0, 1, 0); PG8_LDB(B1, 1, 1); PG8_SCHED; PG8_LDA(At, 1, 0); PG8_STAGE(PG8_SA(0, 1), a2 + hstepA, voffA);
;             PG8_WAIT_V(8); PG8_WAIT_L(0); PG8_BAR; PG8_MMA(0, 0, At, B0); PG8_MMA(0, 1, At, B1); PG8_BAR; PG8_SCHED;
;             PG8_LDA(At, 1, 1); PG8_STAGE(PG8_SB(1, 0), b3, voffB); PG8_STAGE(PG8_SB(1, 1), b3 + hstepB, voffB); PG8_STAGE(PG8_SA(1, 0), a3, voffA);
;             PG8_WAIT_V(8); PG8_WAIT_L(0); PG8_BAR; PG8_MMA(1, 0, At, B0); PG8_MMA(1, 1, At, B1); PG8_BAR; PG8_SCHED;
	ds_read_b128 v[130:133], v192
	ds_read_b128 v[134:137], v192 offset:1024
	ds_read_b128 v[138:141], v192 offset:2048
	ds_read_b128 v[142:145], v192 offset:3072
	ds_read_b128 v[168:171], v193
	ds_read_b128 v[194:197], v193 offset:1024
	ds_read_b128 v[198:201], v193 offset:2048
	ds_read_b128 v[202:205], v193 offset:3072
	s_add_u32 s0, s72, 0x40000
	s_addc_u32 s1, s73, 0
	s_mov_b32 m0, s76
	v_lshl_add_u64 v[246:247], s[0:1], 0, v[148:149]
	ds_read_b128 v[206:209], v191 offset:32768
	ds_read_b128 v[210:213], v191 offset:33792
	ds_read_b128 v[214:217], v191 offset:34816
	ds_read_b128 v[218:221], v191 offset:35840
	ds_read_b128 v[222:225], v191 offset:36864
	ds_read_b128 v[226:229], v191 offset:37888
	ds_read_b128 v[230:233], v191 offset:38912
	ds_read_b128 v[234:237], v191 offset:39936
	global_load_lds_dwordx4 v[246:247], off
	v_lshl_add_u64 v[246:247], s[0:1], 0, v[150:151]
	s_mov_b32 m0, s77
	s_nop 0
	global_load_lds_dwordx4 v[246:247], off
	s_waitcnt vmcnt(8)
	s_waitcnt lgkmcnt(0)
	s_setprio 1
	s_barrier
	v_mfma_f32_16x16x32_bf16 v[126:129], v[130:133], v[206:209], v[126:129]
	v_mfma_f32_16x16x32_bf16 v[122:125], v[138:141], v[206:209], v[122:125]
	v_mfma_f32_16x16x32_bf16 v[110:113], v[130:133], v[214:217], v[110:113]
	v_mfma_f32_16x16x32_bf16 v[106:109], v[138:141], v[214:217], v[106:109]
	v_mfma_f32_16x16x32_bf16 v[94:97], v[130:133], v[222:225], v[94:97]
	v_mfma_f32_16x16x32_bf16 v[90:93], v[138:141], v[222:225], v[90:93]
	v_mfma_f32_16x16x32_bf16 v[78:81], v[130:133], v[230:233], v[78:81]
	v_mfma_f32_16x16x32_bf16 v[74:77], v[138:141], v[230:233], v[74:77]
	v_mfma_f32_16x16x32_bf16 v[126:129], v[134:137], v[210:213], v[126:129]
	v_mfma_f32_16x16x32_bf16 v[122:125], v[142:145], v[210:213], v[122:125]
	v_mfma_f32_16x16x32_bf16 v[110:113], v[134:137], v[218:221], v[110:113]
	v_mfma_f32_16x16x32_bf16 v[106:109], v[142:145], v[218:221], v[106:109]
	v_mfma_f32_16x16x32_bf16 v[94:97], v[134:137], v[226:229], v[94:97]
	v_mfma_f32_16x16x32_bf16 v[90:93], v[142:145], v[226:229], v[90:93]
	v_mfma_f32_16x16x32_bf16 v[78:81], v[134:137], v[234:237], v[78:81]
	v_mfma_f32_16x16x32_bf16 v[74:77], v[142:145], v[234:237], v[74:77]
	s_setprio 0
	s_setprio 1
	v_mfma_f32_16x16x32_bf16 v[118:121], v[168:171], v[206:209], v[118:121]
	v_mfma_f32_16x16x32_bf16 v[114:117], v[198:201], v[206:209], v[114:117]
	v_mfma_f32_16x16x32_bf16 v[102:105], v[168:171], v[214:217], v[102:105]
	v_mfma_f32_16x16x32_bf16 v[98:101], v[198:201], v[214:217], v[98:101]
	v_mfma_f32_16x16x32_bf16 v[86:89], v[168:171], v[222:225], v[86:89]
	v_mfma_f32_16x16x32_bf16 v[82:85], v[198:201], v[222:225], v[82:85]
	v_mfma_f32_16x16x32_bf16 v[70:73], v[168:171], v[230:233], v[70:73]
	v_mfma_f32_16x16x32_bf16 v[66:69], v[198:201], v[230:233], v[66:69]
	v_mfma_f32_16x16x32_bf16 v[118:121], v[194:197], v[210:213], v[118:121]
	v_mfma_f32_16x16x32_bf16 v[114:117], v[202:205], v[210:213], v[114:117]
	v_mfma_f32_16x16x32_bf16 v[102:105], v[194:197], v[218:221], v[102:105]
	v_mfma_f32_16x16x32_bf16 v[98:101], v[202:205], v[218:221], v[98:101]
	v_mfma_f32_16x16x32_bf16 v[86:89], v[194:197], v[226:229], v[86:89]
	v_mfma_f32_16x16x32_bf16 v[82:85], v[202:205], v[226:229], v[82:85]
	v_mfma_f32_16x16x32_bf16 v[70:73], v[194:197], v[234:237], v[70:73]
	v_mfma_f32_16x16x32_bf16 v[66:69], v[202:205], v[234:237], v[66:69]
	s_setprio 0
	s_barrier
	s_add_i32 s0, s82, s69
	v_lshl_add_u64 v[238:239], v[238:239], 0, s[28:29]
	s_mov_b32 m0, s0
	ds_read_b128 v[206:209], v191 offset:49152
	ds_read_b128 v[210:213], v191 offset:50176
	ds_read_b128 v[214:217], v191 offset:51200
	ds_read_b128 v[218:221], v191 offset:52224
	ds_read_b128 v[222:225], v191 offset:53248
	ds_read_b128 v[226:229], v191 offset:54272
	ds_read_b128 v[230:233], v191 offset:55296
	ds_read_b128 v[234:237], v191 offset:56320
	global_load_lds_dwordx4 v[238:239], off
	s_add_i32 m0, s0, 0x2000
	s_add_u32 s0, s70, 0x40080
	v_lshl_add_u64 v[238:239], v[240:241], 0, s[28:29]
	s_addc_u32 s1, s71, 0
	s_add_i32 s2, s83, s69
	global_load_lds_dwordx4 v[238:239], off
	v_lshl_add_u64 v[238:239], s[0:1], 0, v[146:147]
	s_mov_b32 m0, s2
	s_nop 0
	global_load_lds_dwordx4 v[238:239], off
	v_lshl_add_u64 v[238:239], s[0:1], 0, v[152:153]
	s_add_i32 m0, s2, 0x2000
	s_nop 0
	global_load_lds_dwordx4 v[238:239], off
	v_lshl_add_u64 v[238:239], v[242:243], 0, s[28:29]
	s_mov_b32 m0, s78
	s_nop 0
	global_load_lds_dwordx4 v[238:239], off
	v_lshl_add_u64 v[238:239], v[244:245], 0, s[28:29]
	s_mov_b32 m0, s79
	s_nop 0
	global_load_lds_dwordx4 v[238:239], off
	s_waitcnt vmcnt(8)
	s_waitcnt lgkmcnt(0)
	s_setprio 1
	s_barrier
;     __device__ __forceinline__ void run(const f32x4 (&acc)[2][2][4][2], const Unit& u, int wr, int wc, int fr, int fq, const PG8_LAS unsigned char* sp) const {
;         typedef float f32x2r __attribute__((ext_vector_type(2)));
;         const int rl0 = wr * 64 + fr, cl0 = wc * 32 + 8 * fq;
;         const int row0 = u.pm * BM + rl0, col0 = u.pn * BM + cl0;
;         u32x4 pwa[4][2], pwb[4][2];
;     ...
;         RL_LOAD(pwa, 0);
;         RL_ROW(pwa, 0, 0); RL_ROW(pwa, 0, 1);
; template <class Epi, class Sched, bool ALIGN_EPI = false, bool SP2 = false>
; __device__ __forceinline__ void gemm_phase(PG8_LAS unsigned char* lds, const Gemm g, const Sched& S, const Epi& E) {
;     ...
;             PG8_WAIT_V(8); PG8_WAIT_L(0); PG8_BAR; PG8_MMA(0, 0, At, B0); PG8_MMA(0, 1, At, B1); PG8_BAR; PG8_SCHED;
;             PG8_LDA(At, 1, 1); PG8_STAGE(PG8_SB(1, 0), b3, voffB); PG8_STAGE(PG8_SB(1, 1), b3 + hstepB, voffB); PG8_STAGE(PG8_SA(1, 0), a3, voffA);
;             PG8_WAIT_V(8); PG8_WAIT_L(0); PG8_BAR; PG8_MMA(1, 0, At, B0); PG8_MMA(1, 1, At, B1); PG8_BAR; PG8_SCHED;
;             } else {
;             PG8_LDB(B0, 0, 0); PG8_SCHED; PG8_LDA(At, 0, 0); PG8_STAGE(PG8_SA(1, 1), a1 + hstepA, voffA);
;             PG8_WAIT_L(8); PG8_BAR; PG8_WAIT_L(0); PG8_MMA(0, 0, At, B0); PG8_BAR; PG8_SCHED;
;             PG8_LDB(B1, 0, 1); PG8_STAGE(PG8_SB(0, 0), b2, voffB);
;             PG8_BAR; PG8_WAIT_L(0); PG8_MMA(0, 1, At, B1); PG8_BAR;
;             PG8_LDA(At, 0, 1); PG8_STAGE(PG8_SA(0, 0), a2, voffA);
;             PG8_BAR; PG8_WAIT_L(0); PG8_MMA(1, 0, At, B0); PG8_BAR; PG8_SCHED;
;             PG8_STAGE(PG8_SB(0, 1), b2 + hstepB, voffB);
;             PG8_WAIT_V(6); PG8_BAR; PG8_MMA(1, 1, At, B1); PG8_BAR;
;             PG8_LDB(B0, 1, 0); PG8_SCHED; PG8_LDA(At, 1, 0); PG8_STAGE(PG8_SA(0, 1), a2 + hstepA, voffA);
;             PG8_WAIT_L(8); PG8_BAR; PG8_WAIT_L(0); PG8_MMA(0, 0, At, B0); PG8_BAR; PG8_SCHED;
;             PG8_LDB(B1, 1, 1); PG8_STAGE(PG8_SB(1, 0), b3, voffB);
;             PG8_BAR; PG8_WAIT_L(0); PG8_MMA(0, 1, At, B1); PG8_BAR;
;             PG8_LDA(At, 1, 1); PG8_STAGE(PG8_SA(1, 0), a3, voffA);
;             PG8_BAR; PG8_WAIT_L(0); PG8_MMA(1, 0, At, B0); PG8_BAR; PG8_SCHED;
;             PG8_STAGE(PG8_SB(1, 1), b3 + hstepB, voffB);
;             PG8_WAIT_V(6); PG8_BAR; PG8_MMA(1, 1, At, B1); PG8_BAR;
;             }
;         }
	v_mfma_f32_16x16x32_bf16 v[62:65], v[130:133], v[206:209], v[62:65]
	v_mfma_f32_16x16x32_bf16 v[58:61], v[138:141], v[206:209], v[58:61]
	v_mfma_f32_16x16x32_bf16 v[46:49], v[130:133], v[214:217], v[46:49]
	v_mfma_f32_16x16x32_bf16 v[42:45], v[138:141], v[214:217], v[42:45]
	v_mfma_f32_16x16x32_bf16 v[30:33], v[130:133], v[222:225], v[30:33]
	v_mfma_f32_16x16x32_bf16 v[26:29], v[138:141], v[222:225], v[26:29]
	v_mfma_f32_16x16x32_bf16 v[14:17], v[130:133], v[230:233], v[14:17]
	v_mfma_f32_16x16x32_bf16 v[10:13], v[138:141], v[230:233], v[10:13]
	v_mfma_f32_16x16x32_bf16 v[62:65], v[134:137], v[210:213], v[62:65]
	v_mfma_f32_16x16x32_bf16 v[58:61], v[142:145], v[210:213], v[58:61]
	v_mfma_f32_16x16x32_bf16 v[46:49], v[134:137], v[218:221], v[46:49]
	v_mfma_f32_16x16x32_bf16 v[42:45], v[142:145], v[218:221], v[42:45]
	v_mfma_f32_16x16x32_bf16 v[30:33], v[134:137], v[226:229], v[30:33]
	v_mfma_f32_16x16x32_bf16 v[26:29], v[142:145], v[226:229], v[26:29]
	v_mfma_f32_16x16x32_bf16 v[14:17], v[134:137], v[234:237], v[14:17]
	v_mfma_f32_16x16x32_bf16 v[10:13], v[142:145], v[234:237], v[10:13]
	s_setprio 0
	s_setprio 1
	v_mfma_f32_16x16x32_bf16 v[54:57], v[168:171], v[206:209], v[54:57]
	v_mfma_f32_16x16x32_bf16 v[50:53], v[198:201], v[206:209], v[50:53]
	v_mfma_f32_16x16x32_bf16 v[38:41], v[168:171], v[214:217], v[38:41]
	v_mfma_f32_16x16x32_bf16 v[34:37], v[198:201], v[214:217], v[34:37]
	v_mfma_f32_16x16x32_bf16 v[22:25], v[168:171], v[222:225], v[22:25]
	v_mfma_f32_16x16x32_bf16 v[18:21], v[198:201], v[222:225], v[18:21]
	v_mfma_f32_16x16x32_bf16 v[6:9], v[168:171], v[230:233], v[6:9]
	v_mfma_f32_16x16x32_bf16 v[2:5], v[198:201], v[230:233], v[2:5]
	v_mfma_f32_16x16x32_bf16 v[54:57], v[194:197], v[210:213], v[54:57]
	v_mfma_f32_16x16x32_bf16 v[50:53], v[202:205], v[210:213], v[50:53]
	v_mfma_f32_16x16x32_bf16 v[38:41], v[194:197], v[218:221], v[38:41]
	v_mfma_f32_16x16x32_bf16 v[34:37], v[202:205], v[218:221], v[34:37]
	v_mfma_f32_16x16x32_bf16 v[22:25], v[194:197], v[226:229], v[22:25]
	v_mfma_f32_16x16x32_bf16 v[18:21], v[202:205], v[226:229], v[18:21]
	v_mfma_f32_16x16x32_bf16 v[6:9], v[194:197], v[234:237], v[6:9]
	v_mfma_f32_16x16x32_bf16 v[2:5], v[202:205], v[234:237], v[2:5]
	s_setprio 0
	s_barrier
	s_add_i32 s15, s15, 2
	s_add_u32 s12, s12, 0x100
	s_addc_u32 s13, s13, 0
	s_add_u32 s7, s7, 0x100
	s_addc_u32 s14, s14, 0
	s_cmp_gt_u32 s15, 13
	s_cbranch_scc0 .LBB0_1683
	s_and_b64 vcc, exec, s[36:37]
	s_cbranch_vccz .LBB0_1686
	s_barrier
.LBB0_1686:
	s_lshl_b32 s4, s68, 8
	v_lshl_or_b32 v132, s6, 8, v172
	v_add_u32_e32 v130, s4, v1
	v_ashrrev_i32_e32 v133, 31, v132
	v_readlane_b32 s2, v253, 21
	v_lshlrev_b64 v[168:169], 1, v[132:133]
	v_readlane_b32 s3, v253, 22
	v_ashrrev_i32_e32 v131, 31, v130
	v_lshlrev_b64 v[134:135], 11, v[130:131]
	v_lshl_add_u64 v[132:133], s[2:3], 0, v[168:169]
	v_lshl_add_u64 v[170:171], v[132:133], 0, v[134:135]
	global_load_dwordx4 v[196:199], v[170:171], off
	global_load_dwordx4 v[200:203], v[170:171], off offset:256
	v_or_b32_e32 v136, 16, v130
	v_or_b32_e32 v138, 32, v130
	v_or_b32_e32 v130, 48, v130
	v_ashrrev_i32_e32 v137, 31, v136
	v_ashrrev_i32_e32 v139, 31, v138
	v_ashrrev_i32_e32 v131, 31, v130
	v_lshlrev_b64 v[136:137], 11, v[136:137]
	v_lshlrev_b64 v[138:139], 11, v[138:139]
	v_lshlrev_b64 v[130:131], 11, v[130:131]
	v_lshl_add_u64 v[134:135], s[2:3], 0, v[134:135]
	v_lshl_add_u64 v[136:137], v[132:133], 0, v[136:137]
	v_lshl_add_u64 v[138:139], v[132:133], 0, v[138:139]
	v_lshl_add_u64 v[130:131], v[132:133], 0, v[130:131]
	v_lshl_add_u64 v[228:229], v[134:135], 0, v[168:169]
	global_load_dwordx4 v[204:207], v[136:137], off
	global_load_dwordx4 v[208:211], v[136:137], off offset:256
	global_load_dwordx4 v[142:145], v[138:139], off
	s_nop 0
	global_load_dwordx4 v[138:141], v[138:139], off offset:256
	s_nop 0
	global_load_dwordx4 v[134:137], v[130:131], off
	s_nop 0
	global_load_dwordx4 v[130:133], v[130:131], off offset:256
	s_mul_hi_u32 s0, s41, 0xaaaaaaab
	s_lshr_b32 s0, s0, 1
	s_mul_i32 s0, s0, 3
	s_sub_i32 s0, s41, s0
	s_lshl_b32 s0, s0, 12
	s_add_i32 s5, s0, 0
	s_add_i32 s5, s5, 0x20000
	v_add_u32_e32 v195, s5, v173
	v_add_u32_e32 v194, s5, v174
	ds_read_b64 v[230:231], v195
	ds_read_b128 v[212:215], v194 offset:2048
	ds_read_b128 v[216:219], v194 offset:2064
	ds_read_b128 v[220:223], v194 offset:3072
	ds_read_b128 v[224:227], v194 offset:3088
	s_waitcnt vmcnt(0)
	v_lshlrev_b32_e32 v195, 16, v196
	v_and_b32_e32 v196, 0xffff0000, v196
	v_lshlrev_b32_e32 v232, 16, v197
	v_and_b32_e32 v233, 0xffff0000, v197
	v_lshlrev_b32_e32 v234, 16, v198
	v_and_b32_e32 v235, 0xffff0000, v198
	v_lshlrev_b32_e32 v236, 16, v199
	v_and_b32_e32 v237, 0xffff0000, v199
	v_lshlrev_b32_e32 v238, 16, v200
	v_and_b32_e32 v239, 0xffff0000, v200
	v_lshlrev_b32_e32 v240, 16, v201
	v_and_b32_e32 v241, 0xffff0000, v201
	v_lshlrev_b32_e32 v242, 16, v202
	v_and_b32_e32 v243, 0xffff0000, v202
	v_lshlrev_b32_e32 v244, 16, v203
	v_and_b32_e32 v245, 0xffff0000, v203
	s_waitcnt lgkmcnt(4)
	v_sub_f32_e32 v197, v196, v230
	v_sub_f32_e32 v196, v195, v230
	v_sub_f32_e32 v199, v233, v230
	v_sub_f32_e32 v198, v232, v230
	v_sub_f32_e32 v201, v235, v230
	v_sub_f32_e32 v200, v234, v230
	v_sub_f32_e32 v203, v237, v230
	v_sub_f32_e32 v202, v236, v230
	v_pk_mul_f32 v[198:199], v[230:231], v[198:199] op_sel:[1,0]
	v_pk_mul_f32 v[196:197], v[230:231], v[196:197] op_sel:[1,0]
	v_pk_mul_f32 v[202:203], v[230:231], v[202:203] op_sel:[1,0]
	v_pk_mul_f32 v[200:201], v[230:231], v[200:201] op_sel:[1,0]
	s_waitcnt lgkmcnt(1)
	v_pk_fma_f32 v[196:197], v[212:213], v[196:197], v[220:221]
	v_pk_fma_f32 v[198:199], v[214:215], v[198:199], v[222:223]
	s_waitcnt lgkmcnt(0)
; #define RL_LOAD(PW, AI) do { _Pragma("unroll") for (int m = 0; m < 4; ++m) _Pragma("unroll") for (int bj = 0; bj < 2; ++bj) (PW)[m][bj] = *(const u32x4*)(hin + (size_t)(row0 + (AI) * HALF + m * 16) * 1024 + col0 + bj * HALF); } while (0)
;     __device__ __forceinline__ void run(const f32x4 (&acc)[2][2][4][2], const Unit& u, int wr, int wc, int fr, int fq, const PG8_LAS unsigned char* sp) const {
;     ...
;         RL_LOAD(pwa, 0);
;         RL_ROW(pwa, 0, 0); RL_ROW(pwa, 0, 1);
	v_pk_fma_f32 v[200:201], v[216:217], v[200:201], v[224:225]
	v_pk_fma_f32 v[202:203], v[218:219], v[202:203], v[226:227]
	v_pk_fma_f32 v[128:129], v[198:199], s[40:41], v[128:129] op_sel_hi:[1,0,1]
	v_pk_fma_f32 v[126:127], v[196:197], s[40:41], v[126:127] op_sel_hi:[1,0,1]
	v_pk_fma_f32 v[196:197], v[202:203], s[40:41], v[124:125] op_sel_hi:[1,0,1]
	v_pk_fma_f32 v[124:125], v[200:201], s[40:41], v[122:123] op_sel_hi:[1,0,1]
	v_cvt_pk_bf16_f32 v122, v126, v127
	v_cvt_pk_bf16_f32 v123, v128, v129
	v_sub_f32_e32 v233, v239, v230
	v_cvt_pk_bf16_f32 v124, v124, v125
	v_cvt_pk_bf16_f32 v125, v196, v197
	ds_read_b128 v[126:129], v194 offset:2560
	ds_read_b128 v[196:199], v194 offset:2576
	ds_read_b128 v[200:203], v194 offset:3584
	ds_read_b128 v[212:215], v194 offset:3600
	v_sub_f32_e32 v232, v238, v230
	global_store_dwordx4 v[228:229], v[122:125], off
	v_lshlrev_b32_e32 v195, 16, v204
	v_lshlrev_b32_e32 v216, 16, v144
	v_sub_f32_e32 v123, v241, v230
	v_sub_f32_e32 v122, v240, v230
	v_pk_mul_f32 v[122:123], v[230:231], v[122:123] op_sel:[1,0]
	v_pk_mul_f32 v[124:125], v[230:231], v[232:233] op_sel:[1,0]
	s_waitcnt lgkmcnt(1)
	v_pk_fma_f32 v[122:123], v[122:123], v[128:129], v[202:203]
	v_pk_fma_f32 v[124:125], v[124:125], v[126:127], v[200:201]
	v_pk_fma_f32 v[120:121], v[122:123], s[40:41], v[120:121] op_sel_hi:[1,0,1]
	v_pk_fma_f32 v[118:119], v[124:125], s[40:41], v[118:119] op_sel_hi:[1,0,1]
	v_sub_f32_e32 v123, v243, v230
	v_sub_f32_e32 v122, v242, v230
	v_sub_f32_e32 v125, v245, v230
	v_sub_f32_e32 v124, v244, v230
	v_pk_mul_f32 v[124:125], v[230:231], v[124:125] op_sel:[1,0]
	v_pk_mul_f32 v[122:123], v[230:231], v[122:123] op_sel:[1,0]
	s_waitcnt lgkmcnt(0)
	v_pk_fma_f32 v[124:125], v[124:125], v[198:199], v[214:215]
	v_pk_fma_f32 v[122:123], v[122:123], v[196:197], v[212:213]
	v_pk_fma_f32 v[124:125], v[124:125], s[40:41], v[116:117] op_sel_hi:[1,0,1]
	v_pk_fma_f32 v[116:117], v[122:123], s[40:41], v[114:115] op_sel_hi:[1,0,1]
	v_cvt_pk_bf16_f32 v114, v118, v119
	v_cvt_pk_bf16_f32 v115, v120, v121
	v_and_b32_e32 v200, 0xffff0000, v204
	v_cvt_pk_bf16_f32 v116, v116, v117
	v_cvt_pk_bf16_f32 v117, v124, v125
	global_store_dwordx4 v[228:229], v[114:117], off offset:256
	v_lshlrev_b32_e32 v202, 16, v205
	v_and_b32_e32 v203, 0xffff0000, v205
	v_add_u32_e32 v116, s5, v176
	ds_read_b64 v[196:197], v116
	v_add_u32_e32 v114, s4, v175
	v_ashrrev_i32_e32 v115, 31, v114
	v_lshlrev_b64 v[198:199], 11, v[114:115]
	ds_read_b128 v[114:117], v194 offset:2048
	ds_read_b128 v[118:121], v194 offset:2064
	ds_read_b128 v[122:125], v194 offset:3072
	ds_read_b128 v[126:129], v194 offset:3088
	s_waitcnt lgkmcnt(4)
	v_sub_f32_e32 v201, v200, v196
	v_sub_f32_e32 v200, v195, v196
	v_sub_f32_e32 v203, v203, v196
	v_sub_f32_e32 v202, v202, v196
	v_pk_mul_f32 v[202:203], v[196:197], v[202:203] op_sel:[1,0]
	v_pk_mul_f32 v[200:201], v[196:197], v[200:201] op_sel:[1,0]
	v_lshlrev_b32_e32 v204, 16, v206
	v_and_b32_e32 v205, 0xffff0000, v206
	v_lshlrev_b32_e32 v206, 16, v207
	v_and_b32_e32 v207, 0xffff0000, v207
	s_waitcnt lgkmcnt(1)
	v_pk_fma_f32 v[114:115], v[114:115], v[200:201], v[122:123]
	v_pk_fma_f32 v[116:117], v[116:117], v[202:203], v[124:125]
	v_pk_fma_f32 v[110:111], v[114:115], s[40:41], v[110:111] op_sel_hi:[1,0,1]
	v_pk_fma_f32 v[112:113], v[116:117], s[40:41], v[112:113] op_sel_hi:[1,0,1]
	v_sub_f32_e32 v115, v205, v196
	v_sub_f32_e32 v114, v204, v196
	v_sub_f32_e32 v117, v207, v196
	v_sub_f32_e32 v116, v206, v196
	v_pk_mul_f32 v[116:117], v[196:197], v[116:117] op_sel:[1,0]
	v_pk_mul_f32 v[114:115], v[196:197], v[114:115] op_sel:[1,0]
	s_waitcnt lgkmcnt(0)
	v_pk_fma_f32 v[116:117], v[120:121], v[116:117], v[128:129]
	v_pk_fma_f32 v[114:115], v[118:119], v[114:115], v[126:127]
	v_pk_fma_f32 v[116:117], v[116:117], s[40:41], v[108:109] op_sel_hi:[1,0,1]
	v_pk_fma_f32 v[108:109], v[114:115], s[40:41], v[106:107] op_sel_hi:[1,0,1]
	v_cvt_pk_bf16_f32 v106, v110, v111
	v_lshl_add_u64 v[110:111], s[2:3], 0, v[198:199]
	v_lshl_add_u64 v[122:123], v[110:111], 0, v[168:169]
	v_cvt_pk_bf16_f32 v107, v112, v113
	v_cvt_pk_bf16_f32 v108, v108, v109
	v_cvt_pk_bf16_f32 v109, v116, v117
	global_store_dwordx4 v[122:123], v[106:109], off
	ds_read_b128 v[106:109], v194 offset:2560
	ds_read_b128 v[110:113], v194 offset:2576
	ds_read_b128 v[114:117], v194 offset:3584
	ds_read_b128 v[118:121], v194 offset:3600
	v_lshlrev_b32_e32 v124, 16, v208
	v_and_b32_e32 v125, 0xffff0000, v208
	v_lshlrev_b32_e32 v126, 16, v209
	v_and_b32_e32 v127, 0xffff0000, v209
	v_sub_f32_e32 v125, v125, v196
	v_sub_f32_e32 v124, v124, v196
	v_sub_f32_e32 v127, v127, v196
	v_sub_f32_e32 v126, v126, v196
	v_pk_mul_f32 v[126:127], v[196:197], v[126:127] op_sel:[1,0]
	v_pk_mul_f32 v[124:125], v[196:197], v[124:125] op_sel:[1,0]
	v_lshlrev_b32_e32 v128, 16, v210
	v_and_b32_e32 v129, 0xffff0000, v210
	v_lshlrev_b32_e32 v195, 16, v211
	v_and_b32_e32 v198, 0xffff0000, v211
	s_waitcnt lgkmcnt(1)
	v_pk_fma_f32 v[106:107], v[124:125], v[106:107], v[114:115]
	v_pk_fma_f32 v[108:109], v[126:127], v[108:109], v[116:117]
	v_pk_fma_f32 v[102:103], v[106:107], s[40:41], v[102:103] op_sel_hi:[1,0,1]
	v_pk_fma_f32 v[104:105], v[108:109], s[40:41], v[104:105] op_sel_hi:[1,0,1]
	v_sub_f32_e32 v107, v129, v196
	v_sub_f32_e32 v106, v128, v196
	v_sub_f32_e32 v109, v198, v196
	v_sub_f32_e32 v108, v195, v196
	v_pk_mul_f32 v[108:109], v[196:197], v[108:109] op_sel:[1,0]
	v_pk_mul_f32 v[106:107], v[196:197], v[106:107] op_sel:[1,0]
	s_waitcnt lgkmcnt(0)
; #define RL_LOAD(PW, AI) do { _Pragma("unroll") for (int m = 0; m < 4; ++m) _Pragma("unroll") for (int bj = 0; bj < 2; ++bj) (PW)[m][bj] = *(const u32x4*)(hin + (size_t)(row0 + (AI) * HALF + m * 16) * 1024 + col0 + bj * HALF); } while (0)
;     __device__ __forceinline__ void run(const f32x4 (&acc)[2][2][4][2], const Unit& u, int wr, int wc, int fr, int fq, const PG8_LAS unsigned char* sp) const {
;     ...
;         RL_LOAD(pwa, 0);
;         RL_ROW(pwa, 0, 0); RL_ROW(pwa, 0, 1);
;         RL_LOAD(pwb, 1);
;         RL_ROW(pwa, 0, 2); RL_ROW(pwa, 0, 3);
;         RL_ROW(pwb, 1, 0); RL_ROW(pwb, 1, 1); RL_ROW(pwb, 1, 2); RL_ROW(pwb, 1, 3);
	v_pk_fma_f32 v[108:109], v[108:109], v[112:113], v[120:121]
	v_pk_fma_f32 v[106:107], v[106:107], v[110:111], v[118:119]
	v_pk_fma_f32 v[108:109], v[108:109], s[40:41], v[100:101] op_sel_hi:[1,0,1]
	v_pk_fma_f32 v[100:101], v[106:107], s[40:41], v[98:99] op_sel_hi:[1,0,1]
	v_cvt_pk_bf16_f32 v98, v102, v103
	v_cvt_pk_bf16_f32 v99, v104, v105
	v_add_u32_e32 v195, s5, v178
	v_cvt_pk_bf16_f32 v100, v100, v101
	v_cvt_pk_bf16_f32 v101, v108, v109
	global_store_dwordx4 v[122:123], v[98:101], off offset:256
	v_lshlrev_b32_e32 v214, 16, v143
	v_and_b32_e32 v215, 0xffff0000, v143
	v_add_co_u32_e32 v100, vcc, s84, v170
	v_lshl_add_u64 v[98:99], v[170:171], 0, s[34:35]
	s_nop 0
	v_addc_co_u32_e32 v101, vcc, 0, v171, vcc
	global_load_dwordx4 v[126:129], v[100:101], off
	global_load_dwordx4 v[122:125], v[98:99], off offset:256
	v_add_co_u32_e32 v100, vcc, s85, v170
	v_lshl_add_u64 v[98:99], v[170:171], 0, s[42:43]
	s_nop 0
	v_addc_co_u32_e32 v101, vcc, 0, v171, vcc
	global_load_dwordx4 v[118:121], v[100:101], off
	global_load_dwordx4 v[114:117], v[98:99], off offset:256
	v_add_co_u32_e32 v100, vcc, s86, v170
	v_lshl_add_u64 v[98:99], v[170:171], 0, s[44:45]
	s_nop 0
	v_addc_co_u32_e32 v101, vcc, 0, v171, vcc
	global_load_dwordx4 v[110:113], v[100:101], off
	global_load_dwordx4 v[106:109], v[98:99], off offset:256
	v_add_co_u32_e32 v100, vcc, s87, v170
	v_lshl_add_u64 v[98:99], v[170:171], 0, s[46:47]
	s_nop 0
	v_addc_co_u32_e32 v101, vcc, 0, v171, vcc
	global_load_dwordx4 v[102:105], v[100:101], off
	s_nop 0
	global_load_dwordx4 v[98:101], v[98:99], off offset:256
	ds_read_b64 v[212:213], v195
	ds_read_b128 v[196:199], v194 offset:2048
	ds_read_b128 v[200:203], v194 offset:2064
	ds_read_b128 v[204:207], v194 offset:3072
	ds_read_b128 v[208:211], v194 offset:3088
	v_lshlrev_b32_e32 v195, 16, v142
	v_and_b32_e32 v142, 0xffff0000, v142
	v_and_b32_e32 v217, 0xffff0000, v144
	v_lshlrev_b32_e32 v218, 16, v145
	v_and_b32_e32 v219, 0xffff0000, v145
	s_waitcnt lgkmcnt(4)
	v_sub_f32_e32 v143, v142, v212
	v_sub_f32_e32 v142, v195, v212
	v_sub_f32_e32 v145, v215, v212
	v_sub_f32_e32 v144, v214, v212
	v_pk_mul_f32 v[144:145], v[212:213], v[144:145] op_sel:[1,0]
	v_pk_mul_f32 v[142:143], v[212:213], v[142:143] op_sel:[1,0]
	s_waitcnt lgkmcnt(1)
	v_pk_fma_f32 v[144:145], v[198:199], v[144:145], v[206:207]
	v_pk_fma_f32 v[142:143], v[196:197], v[142:143], v[204:205]
	v_add_u32_e32 v170, s4, v177
	v_pk_fma_f32 v[96:97], v[144:145], s[40:41], v[96:97] op_sel_hi:[1,0,1]
	v_pk_fma_f32 v[94:95], v[142:143], s[40:41], v[94:95] op_sel_hi:[1,0,1]
	v_sub_f32_e32 v143, v217, v212
	v_sub_f32_e32 v142, v216, v212
	v_sub_f32_e32 v145, v219, v212
	v_sub_f32_e32 v144, v218, v212
	v_ashrrev_i32_e32 v171, 31, v170
	v_pk_mul_f32 v[144:145], v[212:213], v[144:145] op_sel:[1,0]
	v_pk_mul_f32 v[142:143], v[212:213], v[142:143] op_sel:[1,0]
	v_lshlrev_b64 v[170:171], 11, v[170:171]
	s_waitcnt lgkmcnt(0)
	v_pk_fma_f32 v[142:143], v[200:201], v[142:143], v[208:209]
	v_pk_fma_f32 v[144:145], v[202:203], v[144:145], v[210:211]
	v_lshlrev_b32_e32 v195, 16, v138
	v_pk_fma_f32 v[144:145], v[144:145], s[40:41], v[92:93] op_sel_hi:[1,0,1]
	v_pk_fma_f32 v[92:93], v[142:143], s[40:41], v[90:91] op_sel_hi:[1,0,1]
	v_cvt_pk_bf16_f32 v90, v94, v95
	v_lshl_add_u64 v[94:95], s[2:3], 0, v[170:171]
	v_lshl_add_u64 v[170:171], v[94:95], 0, v[168:169]
	v_cvt_pk_bf16_f32 v91, v96, v97
	v_cvt_pk_bf16_f32 v92, v92, v93
	v_cvt_pk_bf16_f32 v93, v144, v145
	global_store_dwordx4 v[170:171], v[90:93], off
	ds_read_b128 v[90:93], v194 offset:2560
	ds_read_b128 v[94:97], v194 offset:2576
	ds_read_b128 v[142:145], v194 offset:3584
	ds_read_b128 v[196:199], v194 offset:3600
	v_and_b32_e32 v138, 0xffff0000, v138
	v_lshlrev_b32_e32 v200, 16, v139
	v_and_b32_e32 v201, 0xffff0000, v139
	v_lshlrev_b32_e32 v202, 16, v140
	v_and_b32_e32 v203, 0xffff0000, v140
	v_lshlrev_b32_e32 v204, 16, v141
	v_and_b32_e32 v205, 0xffff0000, v141
	v_sub_f32_e32 v139, v138, v212
	v_sub_f32_e32 v138, v195, v212
	v_sub_f32_e32 v141, v201, v212
	v_sub_f32_e32 v140, v200, v212
	v_pk_mul_f32 v[140:141], v[212:213], v[140:141] op_sel:[1,0]
	v_pk_mul_f32 v[138:139], v[212:213], v[138:139] op_sel:[1,0]
	s_waitcnt lgkmcnt(1)
	v_pk_fma_f32 v[92:93], v[140:141], v[92:93], v[144:145]
	v_pk_fma_f32 v[90:91], v[138:139], v[90:91], v[142:143]
	v_pk_fma_f32 v[88:89], v[92:93], s[40:41], v[88:89] op_sel_hi:[1,0,1]
	v_pk_fma_f32 v[86:87], v[90:91], s[40:41], v[86:87] op_sel_hi:[1,0,1]
	v_sub_f32_e32 v91, v203, v212
	v_sub_f32_e32 v90, v202, v212
	v_sub_f32_e32 v93, v205, v212
	v_sub_f32_e32 v92, v204, v212
	v_pk_mul_f32 v[92:93], v[212:213], v[92:93] op_sel:[1,0]
	v_pk_mul_f32 v[90:91], v[212:213], v[90:91] op_sel:[1,0]
	s_waitcnt lgkmcnt(0)
	v_pk_fma_f32 v[92:93], v[92:93], v[96:97], v[198:199]
	v_pk_fma_f32 v[90:91], v[90:91], v[94:95], v[196:197]
	v_pk_fma_f32 v[92:93], v[92:93], s[40:41], v[84:85] op_sel_hi:[1,0,1]
	v_pk_fma_f32 v[84:85], v[90:91], s[40:41], v[82:83] op_sel_hi:[1,0,1]
	v_cvt_pk_bf16_f32 v82, v86, v87
	v_cvt_pk_bf16_f32 v83, v88, v89
	v_lshlrev_b32_e32 v142, 16, v134
	v_cvt_pk_bf16_f32 v84, v84, v85
	v_cvt_pk_bf16_f32 v85, v92, v93
	global_store_dwordx4 v[170:171], v[82:85], off offset:256
	v_and_b32_e32 v134, 0xffff0000, v134
	v_lshlrev_b32_e32 v143, 16, v135
	v_add_u32_e32 v84, s5, v180
	ds_read_b64 v[138:139], v84
	v_add_u32_e32 v82, s4, v179
	v_ashrrev_i32_e32 v83, 31, v82
	v_lshlrev_b64 v[140:141], 11, v[82:83]
	ds_read_b128 v[82:85], v194 offset:2048
	ds_read_b128 v[86:89], v194 offset:2064
	ds_read_b128 v[90:93], v194 offset:3072
	ds_read_b128 v[94:97], v194 offset:3088
	v_and_b32_e32 v144, 0xffff0000, v135
	v_lshlrev_b32_e32 v145, 16, v136
	v_and_b32_e32 v170, 0xffff0000, v136
	v_lshlrev_b32_e32 v171, 16, v137
	v_and_b32_e32 v195, 0xffff0000, v137
	s_waitcnt lgkmcnt(4)
; #define RL_LOAD(PW, AI) do { _Pragma("unroll") for (int m = 0; m < 4; ++m) _Pragma("unroll") for (int bj = 0; bj < 2; ++bj) (PW)[m][bj] = *(const u32x4*)(hin + (size_t)(row0 + (AI) * HALF + m * 16) * 1024 + col0 + bj * HALF); } while (0)
;     __device__ __forceinline__ void run(const f32x4 (&acc)[2][2][4][2], const Unit& u, int wr, int wc, int fr, int fq, const PG8_LAS unsigned char* sp) const {
;     ...
;         RL_LOAD(pwa, 0);
;         RL_ROW(pwa, 0, 0); RL_ROW(pwa, 0, 1);
;         RL_LOAD(pwb, 1);
;         RL_ROW(pwa, 0, 2); RL_ROW(pwa, 0, 3);
;         RL_ROW(pwb, 1, 0); RL_ROW(pwb, 1, 1); RL_ROW(pwb, 1, 2); RL_ROW(pwb, 1, 3);
	v_sub_f32_e32 v135, v134, v138
	v_sub_f32_e32 v134, v142, v138
	v_sub_f32_e32 v137, v144, v138
	v_sub_f32_e32 v136, v143, v138
	v_pk_mul_f32 v[136:137], v[138:139], v[136:137] op_sel:[1,0]
	v_pk_mul_f32 v[134:135], v[138:139], v[134:135] op_sel:[1,0]
	s_waitcnt lgkmcnt(1)
	v_pk_fma_f32 v[84:85], v[84:85], v[136:137], v[92:93]
	v_pk_fma_f32 v[82:83], v[82:83], v[134:135], v[90:91]
	v_pk_fma_f32 v[80:81], v[84:85], s[40:41], v[80:81] op_sel_hi:[1,0,1]
	v_pk_fma_f32 v[78:79], v[82:83], s[40:41], v[78:79] op_sel_hi:[1,0,1]
	v_sub_f32_e32 v83, v170, v138
	v_sub_f32_e32 v82, v145, v138
	v_sub_f32_e32 v85, v195, v138
	v_sub_f32_e32 v84, v171, v138
	v_pk_mul_f32 v[84:85], v[138:139], v[84:85] op_sel:[1,0]
	v_pk_mul_f32 v[82:83], v[138:139], v[82:83] op_sel:[1,0]
	s_waitcnt lgkmcnt(0)
	v_pk_fma_f32 v[84:85], v[88:89], v[84:85], v[96:97]
	v_pk_fma_f32 v[82:83], v[86:87], v[82:83], v[94:95]
	v_pk_fma_f32 v[84:85], v[84:85], s[40:41], v[76:77] op_sel_hi:[1,0,1]
	v_pk_fma_f32 v[76:77], v[82:83], s[40:41], v[74:75] op_sel_hi:[1,0,1]
	v_cvt_pk_bf16_f32 v74, v78, v79
	v_lshl_add_u64 v[78:79], s[2:3], 0, v[140:141]
	v_lshl_add_u64 v[90:91], v[78:79], 0, v[168:169]
	v_cvt_pk_bf16_f32 v75, v80, v81
	v_cvt_pk_bf16_f32 v76, v76, v77
	v_cvt_pk_bf16_f32 v77, v84, v85
	global_store_dwordx4 v[90:91], v[74:77], off
	ds_read_b128 v[74:77], v194 offset:2560
	ds_read_b128 v[78:81], v194 offset:2576
	ds_read_b128 v[82:85], v194 offset:3584
	ds_read_b128 v[86:89], v194 offset:3600
	v_lshlrev_b32_e32 v92, 16, v130
	v_and_b32_e32 v93, 0xffff0000, v130
	v_lshlrev_b32_e32 v94, 16, v131
	v_and_b32_e32 v95, 0xffff0000, v131
	v_sub_f32_e32 v93, v93, v138
	v_sub_f32_e32 v92, v92, v138
	v_sub_f32_e32 v95, v95, v138
	v_sub_f32_e32 v94, v94, v138
	v_pk_mul_f32 v[94:95], v[138:139], v[94:95] op_sel:[1,0]
	v_pk_mul_f32 v[92:93], v[138:139], v[92:93] op_sel:[1,0]
	v_lshlrev_b32_e32 v96, 16, v132
	v_and_b32_e32 v97, 0xffff0000, v132
	v_lshlrev_b32_e32 v130, 16, v133
	v_and_b32_e32 v131, 0xffff0000, v133
	s_waitcnt lgkmcnt(1)
	v_pk_fma_f32 v[74:75], v[92:93], v[74:75], v[82:83]
	v_pk_fma_f32 v[76:77], v[94:95], v[76:77], v[84:85]
	v_pk_fma_f32 v[70:71], v[74:75], s[40:41], v[70:71] op_sel_hi:[1,0,1]
	v_pk_fma_f32 v[72:73], v[76:77], s[40:41], v[72:73] op_sel_hi:[1,0,1]
	v_sub_f32_e32 v75, v97, v138
	v_sub_f32_e32 v74, v96, v138
	v_sub_f32_e32 v77, v131, v138
	v_sub_f32_e32 v76, v130, v138
	v_pk_mul_f32 v[76:77], v[138:139], v[76:77] op_sel:[1,0]
	v_pk_mul_f32 v[74:75], v[138:139], v[74:75] op_sel:[1,0]
	s_waitcnt lgkmcnt(0)
	v_pk_fma_f32 v[76:77], v[76:77], v[80:81], v[88:89]
	v_pk_fma_f32 v[74:75], v[74:75], v[78:79], v[86:87]
	v_pk_fma_f32 v[76:77], v[76:77], s[40:41], v[68:69] op_sel_hi:[1,0,1]
	v_pk_fma_f32 v[68:69], v[74:75], s[40:41], v[66:67] op_sel_hi:[1,0,1]
	v_cvt_pk_bf16_f32 v66, v70, v71
	v_cvt_pk_bf16_f32 v67, v72, v73
	s_waitcnt vmcnt(10)
	v_lshlrev_b32_e32 v86, 16, v126
	v_cvt_pk_bf16_f32 v68, v68, v69
	v_cvt_pk_bf16_f32 v69, v76, v77
	global_store_dwordx4 v[90:91], v[66:69], off offset:256
	v_and_b32_e32 v87, 0xffff0000, v126
	v_lshlrev_b32_e32 v88, 16, v127
	v_add_u32_e32 v68, s5, v182
	ds_read_b64 v[82:83], v68
	v_add_u32_e32 v66, s4, v181
	v_ashrrev_i32_e32 v67, 31, v66
	v_lshlrev_b64 v[84:85], 11, v[66:67]
	ds_read_b128 v[66:69], v194 offset:2048
	ds_read_b128 v[70:73], v194 offset:2064
	ds_read_b128 v[74:77], v194 offset:3072
	ds_read_b128 v[78:81], v194 offset:3088
	v_and_b32_e32 v89, 0xffff0000, v127
	s_waitcnt lgkmcnt(4)
	v_sub_f32_e32 v87, v87, v82
	v_sub_f32_e32 v86, v86, v82
	v_sub_f32_e32 v89, v89, v82
	v_sub_f32_e32 v88, v88, v82
	v_pk_mul_f32 v[88:89], v[82:83], v[88:89] op_sel:[1,0]
	v_pk_mul_f32 v[86:87], v[82:83], v[86:87] op_sel:[1,0]
	v_lshlrev_b32_e32 v90, 16, v128
	v_and_b32_e32 v91, 0xffff0000, v128
	v_lshlrev_b32_e32 v92, 16, v129
	v_and_b32_e32 v93, 0xffff0000, v129
	s_waitcnt lgkmcnt(1)
	v_pk_fma_f32 v[66:67], v[66:67], v[86:87], v[74:75]
	v_pk_fma_f32 v[68:69], v[68:69], v[88:89], v[76:77]
	v_pk_fma_f32 v[62:63], v[66:67], s[40:41], v[62:63] op_sel_hi:[1,0,1]
	v_pk_fma_f32 v[64:65], v[68:69], s[40:41], v[64:65] op_sel_hi:[1,0,1]
	v_sub_f32_e32 v67, v91, v82
	v_sub_f32_e32 v66, v90, v82
	v_sub_f32_e32 v69, v93, v82
	v_sub_f32_e32 v68, v92, v82
	v_pk_mul_f32 v[68:69], v[82:83], v[68:69] op_sel:[1,0]
	v_pk_mul_f32 v[66:67], v[82:83], v[66:67] op_sel:[1,0]
	s_waitcnt lgkmcnt(0)
	v_pk_fma_f32 v[68:69], v[72:73], v[68:69], v[80:81]
	v_pk_fma_f32 v[66:67], v[70:71], v[66:67], v[78:79]
	v_pk_fma_f32 v[68:69], v[68:69], s[40:41], v[60:61] op_sel_hi:[1,0,1]
	v_pk_fma_f32 v[60:61], v[66:67], s[40:41], v[58:59] op_sel_hi:[1,0,1]
	v_cvt_pk_bf16_f32 v58, v62, v63
	v_lshl_add_u64 v[62:63], s[2:3], 0, v[84:85]
	v_lshl_add_u64 v[74:75], v[62:63], 0, v[168:169]
	v_cvt_pk_bf16_f32 v59, v64, v65
	v_cvt_pk_bf16_f32 v60, v60, v61
	v_cvt_pk_bf16_f32 v61, v68, v69
	global_store_dwordx4 v[74:75], v[58:61], off
	ds_read_b128 v[58:61], v194 offset:2560
	ds_read_b128 v[62:65], v194 offset:2576
	ds_read_b128 v[66:69], v194 offset:3584
	ds_read_b128 v[70:73], v194 offset:3600
	s_waitcnt vmcnt(11)
	v_lshlrev_b32_e32 v76, 16, v122
	v_and_b32_e32 v77, 0xffff0000, v122
	v_lshlrev_b32_e32 v78, 16, v123
	v_and_b32_e32 v79, 0xffff0000, v123
	v_sub_f32_e32 v77, v77, v82
	v_sub_f32_e32 v76, v76, v82
	v_sub_f32_e32 v79, v79, v82
	v_sub_f32_e32 v78, v78, v82
	v_pk_mul_f32 v[78:79], v[82:83], v[78:79] op_sel:[1,0]
	v_pk_mul_f32 v[76:77], v[82:83], v[76:77] op_sel:[1,0]
	v_lshlrev_b32_e32 v80, 16, v124
	v_and_b32_e32 v81, 0xffff0000, v124
	v_lshlrev_b32_e32 v84, 16, v125
	v_and_b32_e32 v85, 0xffff0000, v125
	s_waitcnt lgkmcnt(1)
; #define RL_LOAD(PW, AI) do { _Pragma("unroll") for (int m = 0; m < 4; ++m) _Pragma("unroll") for (int bj = 0; bj < 2; ++bj) (PW)[m][bj] = *(const u32x4*)(hin + (size_t)(row0 + (AI) * HALF + m * 16) * 1024 + col0 + bj * HALF); } while (0)
;     __device__ __forceinline__ void run(const f32x4 (&acc)[2][2][4][2], const Unit& u, int wr, int wc, int fr, int fq, const PG8_LAS unsigned char* sp) const {
;     ...
;         RL_LOAD(pwa, 0);
;         RL_ROW(pwa, 0, 0); RL_ROW(pwa, 0, 1);
;         RL_LOAD(pwb, 1);
;         RL_ROW(pwa, 0, 2); RL_ROW(pwa, 0, 3);
;         RL_ROW(pwb, 1, 0); RL_ROW(pwb, 1, 1); RL_ROW(pwb, 1, 2); RL_ROW(pwb, 1, 3);
	v_pk_fma_f32 v[58:59], v[76:77], v[58:59], v[66:67]
	v_pk_fma_f32 v[60:61], v[78:79], v[60:61], v[68:69]
	v_pk_fma_f32 v[54:55], v[58:59], s[40:41], v[54:55] op_sel_hi:[1,0,1]
	v_pk_fma_f32 v[56:57], v[60:61], s[40:41], v[56:57] op_sel_hi:[1,0,1]
	v_sub_f32_e32 v59, v81, v82
	v_sub_f32_e32 v58, v80, v82
	v_sub_f32_e32 v61, v85, v82
	v_sub_f32_e32 v60, v84, v82
	v_pk_mul_f32 v[60:61], v[82:83], v[60:61] op_sel:[1,0]
	v_pk_mul_f32 v[58:59], v[82:83], v[58:59] op_sel:[1,0]
	s_waitcnt lgkmcnt(0)
	v_pk_fma_f32 v[60:61], v[60:61], v[64:65], v[72:73]
	v_pk_fma_f32 v[58:59], v[58:59], v[62:63], v[70:71]
	v_pk_fma_f32 v[60:61], v[60:61], s[40:41], v[52:53] op_sel_hi:[1,0,1]
	v_pk_fma_f32 v[52:53], v[58:59], s[40:41], v[50:51] op_sel_hi:[1,0,1]
	v_cvt_pk_bf16_f32 v50, v54, v55
	v_cvt_pk_bf16_f32 v51, v56, v57
	s_waitcnt vmcnt(10)
	v_lshlrev_b32_e32 v70, 16, v118
	v_cvt_pk_bf16_f32 v52, v52, v53
	v_cvt_pk_bf16_f32 v53, v60, v61
	global_store_dwordx4 v[74:75], v[50:53], off offset:256
	v_and_b32_e32 v71, 0xffff0000, v118
	v_lshlrev_b32_e32 v72, 16, v119
	v_add_u32_e32 v52, s5, v184
	ds_read_b64 v[66:67], v52
	v_add_u32_e32 v50, s4, v183
	v_ashrrev_i32_e32 v51, 31, v50
	v_lshlrev_b64 v[68:69], 11, v[50:51]
	ds_read_b128 v[50:53], v194 offset:2048
	ds_read_b128 v[54:57], v194 offset:2064
	ds_read_b128 v[58:61], v194 offset:3072
	ds_read_b128 v[62:65], v194 offset:3088
	v_and_b32_e32 v73, 0xffff0000, v119
	s_waitcnt lgkmcnt(4)
	v_sub_f32_e32 v71, v71, v66
	v_sub_f32_e32 v70, v70, v66
	v_sub_f32_e32 v73, v73, v66
	v_sub_f32_e32 v72, v72, v66
	v_pk_mul_f32 v[72:73], v[66:67], v[72:73] op_sel:[1,0]
	v_pk_mul_f32 v[70:71], v[66:67], v[70:71] op_sel:[1,0]
	v_lshlrev_b32_e32 v74, 16, v120
	v_and_b32_e32 v75, 0xffff0000, v120
	v_lshlrev_b32_e32 v76, 16, v121
	v_and_b32_e32 v77, 0xffff0000, v121
	s_waitcnt lgkmcnt(1)
	v_pk_fma_f32 v[50:51], v[50:51], v[70:71], v[58:59]
	v_pk_fma_f32 v[52:53], v[52:53], v[72:73], v[60:61]
	v_pk_fma_f32 v[46:47], v[50:51], s[40:41], v[46:47] op_sel_hi:[1,0,1]
	v_pk_fma_f32 v[48:49], v[52:53], s[40:41], v[48:49] op_sel_hi:[1,0,1]
	v_sub_f32_e32 v51, v75, v66
	v_sub_f32_e32 v50, v74, v66
	v_sub_f32_e32 v53, v77, v66
	v_sub_f32_e32 v52, v76, v66
	v_pk_mul_f32 v[52:53], v[66:67], v[52:53] op_sel:[1,0]
	v_pk_mul_f32 v[50:51], v[66:67], v[50:51] op_sel:[1,0]
	s_waitcnt lgkmcnt(0)
	v_pk_fma_f32 v[52:53], v[56:57], v[52:53], v[64:65]
	v_pk_fma_f32 v[50:51], v[54:55], v[50:51], v[62:63]
	v_pk_fma_f32 v[52:53], v[52:53], s[40:41], v[44:45] op_sel_hi:[1,0,1]
	v_pk_fma_f32 v[44:45], v[50:51], s[40:41], v[42:43] op_sel_hi:[1,0,1]
	v_cvt_pk_bf16_f32 v42, v46, v47
	v_lshl_add_u64 v[46:47], s[2:3], 0, v[68:69]
	v_lshl_add_u64 v[58:59], v[46:47], 0, v[168:169]
	v_cvt_pk_bf16_f32 v43, v48, v49
	v_cvt_pk_bf16_f32 v44, v44, v45
	v_cvt_pk_bf16_f32 v45, v52, v53
	global_store_dwordx4 v[58:59], v[42:45], off
	ds_read_b128 v[42:45], v194 offset:2560
	ds_read_b128 v[46:49], v194 offset:2576
	ds_read_b128 v[50:53], v194 offset:3584
	ds_read_b128 v[54:57], v194 offset:3600
	s_waitcnt vmcnt(11)
	v_lshlrev_b32_e32 v60, 16, v114
	v_and_b32_e32 v61, 0xffff0000, v114
	v_lshlrev_b32_e32 v62, 16, v115
	v_and_b32_e32 v63, 0xffff0000, v115
	v_sub_f32_e32 v61, v61, v66
	v_sub_f32_e32 v60, v60, v66
	v_sub_f32_e32 v63, v63, v66
	v_sub_f32_e32 v62, v62, v66
	v_pk_mul_f32 v[62:63], v[66:67], v[62:63] op_sel:[1,0]
	v_pk_mul_f32 v[60:61], v[66:67], v[60:61] op_sel:[1,0]
	v_lshlrev_b32_e32 v64, 16, v116
	v_and_b32_e32 v65, 0xffff0000, v116
	v_lshlrev_b32_e32 v68, 16, v117
	v_and_b32_e32 v69, 0xffff0000, v117
	s_waitcnt lgkmcnt(1)
	v_pk_fma_f32 v[42:43], v[60:61], v[42:43], v[50:51]
	v_pk_fma_f32 v[44:45], v[62:63], v[44:45], v[52:53]
	v_pk_fma_f32 v[38:39], v[42:43], s[40:41], v[38:39] op_sel_hi:[1,0,1]
	v_pk_fma_f32 v[40:41], v[44:45], s[40:41], v[40:41] op_sel_hi:[1,0,1]
	v_sub_f32_e32 v43, v65, v66
	v_sub_f32_e32 v42, v64, v66
	v_sub_f32_e32 v45, v69, v66
	v_sub_f32_e32 v44, v68, v66
	v_pk_mul_f32 v[44:45], v[66:67], v[44:45] op_sel:[1,0]
	v_pk_mul_f32 v[42:43], v[66:67], v[42:43] op_sel:[1,0]
	s_waitcnt lgkmcnt(0)
	v_pk_fma_f32 v[44:45], v[44:45], v[48:49], v[56:57]
	v_pk_fma_f32 v[42:43], v[42:43], v[46:47], v[54:55]
	v_pk_fma_f32 v[44:45], v[44:45], s[40:41], v[36:37] op_sel_hi:[1,0,1]
	v_pk_fma_f32 v[36:37], v[42:43], s[40:41], v[34:35] op_sel_hi:[1,0,1]
	v_cvt_pk_bf16_f32 v34, v38, v39
	v_cvt_pk_bf16_f32 v35, v40, v41
	s_waitcnt vmcnt(10)
	v_lshlrev_b32_e32 v54, 16, v110
	v_cvt_pk_bf16_f32 v36, v36, v37
	v_cvt_pk_bf16_f32 v37, v44, v45
	global_store_dwordx4 v[58:59], v[34:37], off offset:256
	v_and_b32_e32 v55, 0xffff0000, v110
	v_lshlrev_b32_e32 v56, 16, v111
	v_add_u32_e32 v36, s5, v186
	ds_read_b64 v[50:51], v36
	v_add_u32_e32 v34, s4, v185
	v_ashrrev_i32_e32 v35, 31, v34
	v_lshlrev_b64 v[52:53], 11, v[34:35]
	ds_read_b128 v[34:37], v194 offset:2048
	ds_read_b128 v[38:41], v194 offset:2064
	ds_read_b128 v[42:45], v194 offset:3072
	ds_read_b128 v[46:49], v194 offset:3088
	v_and_b32_e32 v57, 0xffff0000, v111
	s_waitcnt lgkmcnt(4)
	v_sub_f32_e32 v55, v55, v50
	v_sub_f32_e32 v54, v54, v50
	v_sub_f32_e32 v57, v57, v50
	v_sub_f32_e32 v56, v56, v50
	v_pk_mul_f32 v[56:57], v[50:51], v[56:57] op_sel:[1,0]
	v_pk_mul_f32 v[54:55], v[50:51], v[54:55] op_sel:[1,0]
	v_lshlrev_b32_e32 v58, 16, v112
	v_and_b32_e32 v59, 0xffff0000, v112
	v_lshlrev_b32_e32 v60, 16, v113
	v_and_b32_e32 v61, 0xffff0000, v113
	s_waitcnt lgkmcnt(1)
	v_pk_fma_f32 v[34:35], v[34:35], v[54:55], v[42:43]
	v_pk_fma_f32 v[36:37], v[36:37], v[56:57], v[44:45]
	v_pk_fma_f32 v[30:31], v[34:35], s[40:41], v[30:31] op_sel_hi:[1,0,1]
	v_pk_fma_f32 v[32:33], v[36:37], s[40:41], v[32:33] op_sel_hi:[1,0,1]
	v_sub_f32_e32 v35, v59, v50
	v_sub_f32_e32 v34, v58, v50
	v_sub_f32_e32 v37, v61, v50
	v_sub_f32_e32 v36, v60, v50
	v_pk_mul_f32 v[36:37], v[50:51], v[36:37] op_sel:[1,0]
	v_pk_mul_f32 v[34:35], v[50:51], v[34:35] op_sel:[1,0]
	s_waitcnt lgkmcnt(0)
; #define RL_LOAD(PW, AI) do { _Pragma("unroll") for (int m = 0; m < 4; ++m) _Pragma("unroll") for (int bj = 0; bj < 2; ++bj) (PW)[m][bj] = *(const u32x4*)(hin + (size_t)(row0 + (AI) * HALF + m * 16) * 1024 + col0 + bj * HALF); } while (0)
; #define PG8_BAR __builtin_amdgcn_s_barrier()
;     __device__ __forceinline__ void run(const f32x4 (&acc)[2][2][4][2], const Unit& u, int wr, int wc, int fr, int fq, const PG8_LAS unsigned char* sp) const {
;     ...
;         RL_LOAD(pwa, 0);
;         RL_ROW(pwa, 0, 0); RL_ROW(pwa, 0, 1);
;         RL_LOAD(pwb, 1);
;         RL_ROW(pwa, 0, 2); RL_ROW(pwa, 0, 3);
;         RL_ROW(pwb, 1, 0); RL_ROW(pwb, 1, 1); RL_ROW(pwb, 1, 2); RL_ROW(pwb, 1, 3);
; template <class Epi, class Sched, bool ALIGN_EPI = false, bool SP2 = false>
; __device__ __forceinline__ void gemm_phase(PG8_LAS unsigned char* lds, const Gemm g, const Sched& S, const Epi& E) {
;     ...
;         if (!has_next) break;
; #pragma unroll
;         for (int a = 0; a < 2; ++a)
; #pragma unroll
;             for (int b = 0; b < 2; ++b)
; #pragma unroll
;                 for (int m = 0; m < 4; ++m)
; #pragma unroll
;                     for (int n = 0; n < 2; ++n) acc[a][b][m][n] = (f32x4){0.f, 0.f, 0.f, 0.f};
;         cur = nxt; cA = nA; cB = nB; ++ui;
;         if constexpr (ALIGN_EPI) { if (wr == 1) PG8_BAR; }
	v_pk_fma_f32 v[36:37], v[40:41], v[36:37], v[48:49]
	v_pk_fma_f32 v[34:35], v[38:39], v[34:35], v[46:47]
	v_pk_fma_f32 v[36:37], v[36:37], s[40:41], v[28:29] op_sel_hi:[1,0,1]
	v_pk_fma_f32 v[28:29], v[34:35], s[40:41], v[26:27] op_sel_hi:[1,0,1]
	v_cvt_pk_bf16_f32 v26, v30, v31
	v_lshl_add_u64 v[30:31], s[2:3], 0, v[52:53]
	v_lshl_add_u64 v[42:43], v[30:31], 0, v[168:169]
	v_cvt_pk_bf16_f32 v27, v32, v33
	v_cvt_pk_bf16_f32 v28, v28, v29
	v_cvt_pk_bf16_f32 v29, v36, v37
	global_store_dwordx4 v[42:43], v[26:29], off
	ds_read_b128 v[26:29], v194 offset:2560
	ds_read_b128 v[30:33], v194 offset:2576
	ds_read_b128 v[34:37], v194 offset:3584
	ds_read_b128 v[38:41], v194 offset:3600
	s_waitcnt vmcnt(11)
	v_lshlrev_b32_e32 v44, 16, v106
	v_and_b32_e32 v45, 0xffff0000, v106
	v_lshlrev_b32_e32 v46, 16, v107
	v_and_b32_e32 v47, 0xffff0000, v107
	v_sub_f32_e32 v45, v45, v50
	v_sub_f32_e32 v44, v44, v50
	v_sub_f32_e32 v47, v47, v50
	v_sub_f32_e32 v46, v46, v50
	v_pk_mul_f32 v[46:47], v[50:51], v[46:47] op_sel:[1,0]
	v_pk_mul_f32 v[44:45], v[50:51], v[44:45] op_sel:[1,0]
	v_lshlrev_b32_e32 v48, 16, v108
	v_and_b32_e32 v49, 0xffff0000, v108
	v_lshlrev_b32_e32 v52, 16, v109
	v_and_b32_e32 v53, 0xffff0000, v109
	s_waitcnt lgkmcnt(1)
	v_pk_fma_f32 v[26:27], v[44:45], v[26:27], v[34:35]
	v_pk_fma_f32 v[28:29], v[46:47], v[28:29], v[36:37]
	v_pk_fma_f32 v[22:23], v[26:27], s[40:41], v[22:23] op_sel_hi:[1,0,1]
	v_pk_fma_f32 v[24:25], v[28:29], s[40:41], v[24:25] op_sel_hi:[1,0,1]
	v_sub_f32_e32 v27, v49, v50
	v_sub_f32_e32 v26, v48, v50
	v_sub_f32_e32 v29, v53, v50
	v_sub_f32_e32 v28, v52, v50
	v_pk_mul_f32 v[28:29], v[50:51], v[28:29] op_sel:[1,0]
	v_pk_mul_f32 v[26:27], v[50:51], v[26:27] op_sel:[1,0]
	s_waitcnt lgkmcnt(0)
	v_pk_fma_f32 v[28:29], v[28:29], v[32:33], v[40:41]
	v_pk_fma_f32 v[26:27], v[26:27], v[30:31], v[38:39]
	v_pk_fma_f32 v[28:29], v[28:29], s[40:41], v[20:21] op_sel_hi:[1,0,1]
	v_pk_fma_f32 v[20:21], v[26:27], s[40:41], v[18:19] op_sel_hi:[1,0,1]
	v_cvt_pk_bf16_f32 v18, v22, v23
	v_cvt_pk_bf16_f32 v19, v24, v25
	s_waitcnt vmcnt(10)
	v_lshlrev_b32_e32 v38, 16, v102
	v_cvt_pk_bf16_f32 v20, v20, v21
	v_cvt_pk_bf16_f32 v21, v28, v29
	global_store_dwordx4 v[42:43], v[18:21], off offset:256
	v_and_b32_e32 v39, 0xffff0000, v102
	v_lshlrev_b32_e32 v40, 16, v103
	v_add_u32_e32 v20, s5, v188
	ds_read_b64 v[34:35], v20
	v_add_u32_e32 v18, s4, v187
	v_ashrrev_i32_e32 v19, 31, v18
	v_lshlrev_b64 v[36:37], 11, v[18:19]
	ds_read_b128 v[18:21], v194 offset:2048
	ds_read_b128 v[22:25], v194 offset:2064
	ds_read_b128 v[26:29], v194 offset:3072
	ds_read_b128 v[30:33], v194 offset:3088
	v_and_b32_e32 v41, 0xffff0000, v103
	s_waitcnt lgkmcnt(4)
	v_sub_f32_e32 v39, v39, v34
	v_sub_f32_e32 v38, v38, v34
	v_sub_f32_e32 v41, v41, v34
	v_sub_f32_e32 v40, v40, v34
	v_pk_mul_f32 v[40:41], v[34:35], v[40:41] op_sel:[1,0]
	v_pk_mul_f32 v[38:39], v[34:35], v[38:39] op_sel:[1,0]
	v_lshlrev_b32_e32 v42, 16, v104
	v_and_b32_e32 v43, 0xffff0000, v104
	v_lshlrev_b32_e32 v44, 16, v105
	v_and_b32_e32 v45, 0xffff0000, v105
	s_waitcnt lgkmcnt(1)
	v_pk_fma_f32 v[18:19], v[18:19], v[38:39], v[26:27]
	v_pk_fma_f32 v[20:21], v[20:21], v[40:41], v[28:29]
	v_pk_fma_f32 v[14:15], v[18:19], s[40:41], v[14:15] op_sel_hi:[1,0,1]
	v_pk_fma_f32 v[16:17], v[20:21], s[40:41], v[16:17] op_sel_hi:[1,0,1]
	v_sub_f32_e32 v19, v43, v34
	v_sub_f32_e32 v18, v42, v34
	v_sub_f32_e32 v21, v45, v34
	v_sub_f32_e32 v20, v44, v34
	v_pk_mul_f32 v[20:21], v[34:35], v[20:21] op_sel:[1,0]
	v_pk_mul_f32 v[18:19], v[34:35], v[18:19] op_sel:[1,0]
	s_waitcnt lgkmcnt(0)
	v_pk_fma_f32 v[20:21], v[24:25], v[20:21], v[32:33]
	v_pk_fma_f32 v[18:19], v[22:23], v[18:19], v[30:31]
	v_pk_fma_f32 v[20:21], v[20:21], s[40:41], v[12:13] op_sel_hi:[1,0,1]
	v_pk_fma_f32 v[12:13], v[18:19], s[40:41], v[10:11] op_sel_hi:[1,0,1]
	v_cvt_pk_bf16_f32 v10, v14, v15
	v_lshl_add_u64 v[14:15], s[2:3], 0, v[36:37]
	v_lshl_add_u64 v[26:27], v[14:15], 0, v[168:169]
	v_cvt_pk_bf16_f32 v11, v16, v17
	v_cvt_pk_bf16_f32 v12, v12, v13
	v_cvt_pk_bf16_f32 v13, v20, v21
	global_store_dwordx4 v[26:27], v[10:13], off
	ds_read_b128 v[10:13], v194 offset:2560
	ds_read_b128 v[14:17], v194 offset:2576
	ds_read_b128 v[18:21], v194 offset:3584
	ds_read_b128 v[22:25], v194 offset:3600
	s_waitcnt vmcnt(11)
	v_lshlrev_b32_e32 v28, 16, v98
	v_and_b32_e32 v29, 0xffff0000, v98
	v_lshlrev_b32_e32 v30, 16, v99
	v_and_b32_e32 v31, 0xffff0000, v99
	v_sub_f32_e32 v29, v29, v34
	v_sub_f32_e32 v28, v28, v34
	v_sub_f32_e32 v31, v31, v34
	v_sub_f32_e32 v30, v30, v34
	v_pk_mul_f32 v[30:31], v[34:35], v[30:31] op_sel:[1,0]
	v_pk_mul_f32 v[28:29], v[34:35], v[28:29] op_sel:[1,0]
	v_lshlrev_b32_e32 v32, 16, v100
	v_and_b32_e32 v33, 0xffff0000, v100
	v_lshlrev_b32_e32 v36, 16, v101
	v_and_b32_e32 v37, 0xffff0000, v101
	s_waitcnt lgkmcnt(1)
	v_pk_fma_f32 v[10:11], v[28:29], v[10:11], v[18:19]
	v_pk_fma_f32 v[12:13], v[30:31], v[12:13], v[20:21]
	v_pk_fma_f32 v[6:7], v[10:11], s[40:41], v[6:7] op_sel_hi:[1,0,1]
	v_pk_fma_f32 v[8:9], v[12:13], s[40:41], v[8:9] op_sel_hi:[1,0,1]
	v_sub_f32_e32 v11, v33, v34
	v_sub_f32_e32 v10, v32, v34
	v_sub_f32_e32 v13, v37, v34
	v_sub_f32_e32 v12, v36, v34
	v_pk_mul_f32 v[12:13], v[34:35], v[12:13] op_sel:[1,0]
	v_pk_mul_f32 v[10:11], v[34:35], v[10:11] op_sel:[1,0]
	s_waitcnt lgkmcnt(0)
	v_pk_fma_f32 v[12:13], v[12:13], v[16:17], v[24:25]
	v_pk_fma_f32 v[10:11], v[10:11], v[14:15], v[22:23]
	v_pk_fma_f32 v[12:13], v[12:13], s[40:41], v[4:5] op_sel_hi:[1,0,1]
	v_pk_fma_f32 v[4:5], v[10:11], s[40:41], v[2:3] op_sel_hi:[1,0,1]
	s_and_b64 vcc, exec, s[10:11]
	s_mov_b64 s[10:11], -1
	v_cvt_pk_bf16_f32 v2, v6, v7
	v_cvt_pk_bf16_f32 v3, v8, v9
	v_cvt_pk_bf16_f32 v4, v4, v5
	v_cvt_pk_bf16_f32 v5, v12, v13
	global_store_dwordx4 v[26:27], v[2:5], off offset:256
	s_cbranch_vccnz .LBB0_1669
	s_andn2_b64 vcc, exec, s[30:31]
	s_cbranch_vccnz .LBB0_1668
	s_mov_b32 s98, 1
	s_branch .LBB0_1668

; #define PG8_STAGE(bufoff, gbase, voff) do { _Pragma("unroll") for (int _i = 0; _i < 2; ++_i) \
;         __builtin_amdgcn_global_load_lds((const unsigned*)((const char*)(gbase) + (voff)[_i]), (PG8_LAS unsigned*)(lds + (bufoff) + ldsw + _i * 8192), 16, 0, 0); } while (0)
; #define PG8_LDA(dst, b, h) do { _Pragma("unroll") for (int m = 0; m < 4; ++m) _Pragma("unroll") for (int k = 0; k < 2; ++k) dst[m][k] = *(const PG8_LAS bf16x8*)(lds + PG8_SA(b, h) + aoff + m * 2048 + k * 1024); } while (0)
; #define PG8_LDB(dst, b, h) do { _Pragma("unroll") for (int n = 0; n < 2; ++n) _Pragma("unroll") for (int k = 0; k < 2; ++k) dst[n][k] = *(const PG8_LAS bf16x8*)(lds + PG8_SB(b, h) + boff + n * 2048 + k * 1024); } while (0)
; #define PG8_MMA(ai, bj, At, Bt) do { __builtin_amdgcn_s_setprio(1); _Pragma("unroll") for (int m = 0; m < 4; ++m) _Pragma("unroll") for (int n = 0; n < 2; ++n) _Pragma("unroll") for (int k = 0; k < 2; ++k) \
;         acc[ai][bj][m][n] = __builtin_amdgcn_mfma_f32_16x16x32_bf16(Bt[n][k], At[m][k], acc[ai][bj][m][n], 0, 0, 0); __builtin_amdgcn_s_setprio(0); } while (0)
; template <class Epi, class Sched, bool ALIGN_EPI = false, bool SP2 = false>
; __device__ __forceinline__ void gemm_phase(PG8_LAS unsigned char* lds, const Gemm g, const Sched& S, const Epi& E) {
;     ...
;         for (int t = 0; t < nt; t += 2) {
;             const bool last = (t == nt - 2);
;             const char* a1 = cA + (size_t)(t + 1) * kstep;
;             const char* a2 = last ? nA : cA + (size_t)(t + 2) * kstep; const char* b2 = last ? nB : cB + (size_t)(t + 2) * kstep;
;             const char* a3 = a2 + kstep; const char* b3 = b2 + kstep;
;             if (last && has_next) S.a_ready(nxt);
;             if constexpr (SP2) {
;             PG8_LDB(B0, 0, 0); PG8_LDB(B1, 0, 1); PG8_SCHED; PG8_LDA(At, 0, 0); PG8_STAGE(PG8_SA(1, 1), a1 + hstepA, voffA);
;             PG8_WAIT_V(8); PG8_WAIT_L(0); PG8_BAR; PG8_MMA(0, 0, At, B0); PG8_MMA(0, 1, At, B1); PG8_BAR; PG8_SCHED;
;     ...
; #pragma unroll
;         for (int a = 0; a < 2; ++a)
; #pragma unroll
;             for (int b = 0; b < 2; ++b)
; #pragma unroll
;                 for (int m = 0; m < 4; ++m)
; #pragma unroll
;                     for (int n = 0; n < 2; ++n) acc[a][b][m][n] = (f32x4){0.f, 0.f, 0.f, 0.f};
;         cur = nxt; cA = nA; cB = nB; ++ui;
;         if constexpr (ALIGN_EPI) { if (wr == 1) PG8_BAR; }
.LBB0_1845:
	s_ashr_i32 s35, s34, 31
	s_lshl_b64 s[0:1], s[34:35], 19
	s_add_u32 s40, s24, s0
	s_addc_u32 s41, s25, s1
	s_and_b64 s[0:1], s[14:15], exec
	s_cselect_b32 s5, s41, s47
	s_cselect_b32 s7, s40, s46
	s_add_u32 s18, s46, 0x100
	v_mov_b32_e32 v2, 0
	s_addc_u32 s19, s47, 0
	s_mov_b32 s35, -2
	v_mov_b32_e32 v3, v2
	v_mov_b32_e32 v4, v2
	v_mov_b32_e32 v5, v2
	v_mov_b32_e32 v6, v2
	v_mov_b32_e32 v7, v2
	v_mov_b32_e32 v8, v2
	v_mov_b32_e32 v9, v2
	v_mov_b32_e32 v22, v2
	v_mov_b32_e32 v23, v2
	v_mov_b32_e32 v24, v2
	v_mov_b32_e32 v25, v2
	v_mov_b32_e32 v38, v2
	v_mov_b32_e32 v39, v2
	v_mov_b32_e32 v40, v2
	v_mov_b32_e32 v41, v2
	v_mov_b32_e32 v46, v2
	v_mov_b32_e32 v47, v2
	v_mov_b32_e32 v48, v2
	v_mov_b32_e32 v49, v2
	v_mov_b32_e32 v54, v2
	v_mov_b32_e32 v55, v2
	v_mov_b32_e32 v56, v2
	v_mov_b32_e32 v57, v2
	v_mov_b32_e32 v58, v2
	v_mov_b32_e32 v59, v2
	v_mov_b32_e32 v60, v2
	v_mov_b32_e32 v61, v2
	v_mov_b32_e32 v62, v2
	v_mov_b32_e32 v63, v2
	v_mov_b32_e32 v64, v2
	v_mov_b32_e32 v65, v2
	v_mov_b32_e32 v10, v2
	v_mov_b32_e32 v11, v2
	v_mov_b32_e32 v12, v2
	v_mov_b32_e32 v13, v2
	v_mov_b32_e32 v26, v2
	v_mov_b32_e32 v27, v2
	v_mov_b32_e32 v28, v2
	v_mov_b32_e32 v29, v2
	v_mov_b32_e32 v14, v2
	v_mov_b32_e32 v15, v2
	v_mov_b32_e32 v16, v2
	v_mov_b32_e32 v17, v2
	v_mov_b32_e32 v30, v2
	v_mov_b32_e32 v31, v2
	v_mov_b32_e32 v32, v2
	v_mov_b32_e32 v33, v2
	v_mov_b32_e32 v18, v2
	v_mov_b32_e32 v19, v2
	v_mov_b32_e32 v20, v2
	v_mov_b32_e32 v21, v2
	v_mov_b32_e32 v34, v2
	v_mov_b32_e32 v35, v2
	v_mov_b32_e32 v36, v2
	v_mov_b32_e32 v37, v2
	v_mov_b32_e32 v42, v2
	v_mov_b32_e32 v43, v2
	v_mov_b32_e32 v44, v2
	v_mov_b32_e32 v45, v2
	v_mov_b32_e32 v50, v2
	v_mov_b32_e32 v51, v2
	v_mov_b32_e32 v52, v2
	v_mov_b32_e32 v53, v2
	v_mov_b32_e32 v66, v2
	v_mov_b32_e32 v67, v2
	v_mov_b32_e32 v68, v2
	v_mov_b32_e32 v69, v2
	v_mov_b32_e32 v70, v2
	v_mov_b32_e32 v71, v2
	v_mov_b32_e32 v72, v2
	v_mov_b32_e32 v73, v2
	v_mov_b32_e32 v86, v2
	v_mov_b32_e32 v87, v2
	v_mov_b32_e32 v88, v2
	v_mov_b32_e32 v89, v2
	v_mov_b32_e32 v102, v2
	v_mov_b32_e32 v103, v2
	v_mov_b32_e32 v104, v2
	v_mov_b32_e32 v105, v2
	v_mov_b32_e32 v110, v2
	v_mov_b32_e32 v111, v2
	v_mov_b32_e32 v112, v2
	v_mov_b32_e32 v113, v2
	v_mov_b32_e32 v118, v2
	v_mov_b32_e32 v119, v2
	v_mov_b32_e32 v120, v2
	v_mov_b32_e32 v121, v2
	v_mov_b32_e32 v122, v2
	v_mov_b32_e32 v123, v2
	v_mov_b32_e32 v124, v2
	v_mov_b32_e32 v125, v2
	v_mov_b32_e32 v158, v2
	v_mov_b32_e32 v159, v2
	v_mov_b32_e32 v160, v2
	v_mov_b32_e32 v161, v2
	v_mov_b32_e32 v74, v2
	v_mov_b32_e32 v75, v2
	v_mov_b32_e32 v76, v2
	v_mov_b32_e32 v77, v2
	v_mov_b32_e32 v90, v2
	v_mov_b32_e32 v91, v2
	v_mov_b32_e32 v92, v2
	v_mov_b32_e32 v93, v2
	v_mov_b32_e32 v78, v2
	v_mov_b32_e32 v79, v2
	v_mov_b32_e32 v80, v2
	v_mov_b32_e32 v81, v2
	v_mov_b32_e32 v94, v2
	v_mov_b32_e32 v95, v2
	v_mov_b32_e32 v96, v2
	v_mov_b32_e32 v97, v2
	v_mov_b32_e32 v82, v2
	v_mov_b32_e32 v83, v2
	v_mov_b32_e32 v84, v2
	v_mov_b32_e32 v85, v2
	v_mov_b32_e32 v98, v2
	v_mov_b32_e32 v99, v2
	v_mov_b32_e32 v100, v2
	v_mov_b32_e32 v101, v2
	v_mov_b32_e32 v106, v2
	v_mov_b32_e32 v107, v2
	v_mov_b32_e32 v108, v2
	v_mov_b32_e32 v109, v2
	v_mov_b32_e32 v114, v2
	v_mov_b32_e32 v115, v2
	v_mov_b32_e32 v116, v2
	v_mov_b32_e32 v117, v2
	s_cmp_eq_u32 s98, 1
	s_cbranch_scc0 .Ldefer_6
	s_barrier
	s_mov_b32 s98, 0
.Ldefer_6:
.LBB0_1846:
	ds_read_b128 v[126:129], v205
	ds_read_b128 v[130:133], v205 offset:1024
	ds_read_b128 v[134:137], v205 offset:2048
	ds_read_b128 v[138:141], v205 offset:3072
	ds_read_b128 v[142:145], v206
	ds_read_b128 v[146:149], v206 offset:1024
	ds_read_b128 v[150:153], v206 offset:2048
	ds_read_b128 v[154:157], v206 offset:3072
	s_add_u32 s14, s44, 0x100
	s_addc_u32 s15, s45, 0
	s_cmp_eq_u32 s35, 12
	s_cselect_b32 s49, s39, s15
	s_cselect_b32 s48, s38, s14
	s_cselect_b32 s47, s5, s19
	s_cselect_b32 s46, s7, s18
	v_lshl_add_u64 v[226:227], s[44:45], 0, v[192:193]
	s_add_i32 m0, s50, 0xc000
	ds_read_b128 v[162:165], v207
	ds_read_b128 v[166:169], v207 offset:1024
	ds_read_b128 v[170:173], v207 offset:2048
	ds_read_b128 v[174:177], v207 offset:3072
	ds_read_b128 v[210:213], v207 offset:4096
	ds_read_b128 v[214:217], v207 offset:5120
	ds_read_b128 v[218:221], v207 offset:6144
	ds_read_b128 v[222:225], v207 offset:7168
	global_load_lds_dwordx4 v[226:227], off
	v_lshl_add_u64 v[226:227], s[44:45], 0, v[194:195]
	s_add_i32 m0, s50, 0xe000
	s_nop 0
	global_load_lds_dwordx4 v[226:227], off
	s_waitcnt vmcnt(8)
	s_waitcnt lgkmcnt(0)
	s_setprio 1
	s_barrier
; #define PG8_STAGE(bufoff, gbase, voff) do { _Pragma("unroll") for (int _i = 0; _i < 2; ++_i) \
;         __builtin_amdgcn_global_load_lds((const unsigned*)((const char*)(gbase) + (voff)[_i]), (PG8_LAS unsigned*)(lds + (bufoff) + ldsw + _i * 8192), 16, 0, 0); } while (0)
; #define PG8_LDA(dst, b, h) do { _Pragma("unroll") for (int m = 0; m < 4; ++m) _Pragma("unroll") for (int k = 0; k < 2; ++k) dst[m][k] = *(const PG8_LAS bf16x8*)(lds + PG8_SA(b, h) + aoff + m * 2048 + k * 1024); } while (0)
; #define PG8_LDB(dst, b, h) do { _Pragma("unroll") for (int n = 0; n < 2; ++n) _Pragma("unroll") for (int k = 0; k < 2; ++k) dst[n][k] = *(const PG8_LAS bf16x8*)(lds + PG8_SB(b, h) + boff + n * 2048 + k * 1024); } while (0)
; #define PG8_MMA(ai, bj, At, Bt) do { __builtin_amdgcn_s_setprio(1); _Pragma("unroll") for (int m = 0; m < 4; ++m) _Pragma("unroll") for (int n = 0; n < 2; ++n) _Pragma("unroll") for (int k = 0; k < 2; ++k) \
;         acc[ai][bj][m][n] = __builtin_amdgcn_mfma_f32_16x16x32_bf16(Bt[n][k], At[m][k], acc[ai][bj][m][n], 0, 0, 0); __builtin_amdgcn_s_setprio(0); } while (0)
; #define PG8_WAIT_V(n) asm volatile("s_waitcnt vmcnt(" #n ")" ::: "memory")
; #define PG8_WAIT_L(n) asm volatile("s_waitcnt lgkmcnt(" #n ")" ::: "memory")
; #define PG8_BAR __builtin_amdgcn_s_barrier()
; #define PG8_SCHED __builtin_amdgcn_sched_barrier(0)
; template <class Epi, class Sched, bool ALIGN_EPI = false, bool SP2 = false>
; __device__ __forceinline__ void gemm_phase(PG8_LAS unsigned char* lds, const Gemm g, const Sched& S, const Epi& E) {
;     ...
;             PG8_WAIT_V(8); PG8_WAIT_L(0); PG8_BAR; PG8_MMA(0, 0, At, B0); PG8_MMA(0, 1, At, B1); PG8_BAR; PG8_SCHED;
;             PG8_LDA(At, 0, 1); PG8_STAGE(PG8_SB(0, 0), b2, voffB); PG8_STAGE(PG8_SB(0, 1), b2 + hstepB, voffB); PG8_STAGE(PG8_SA(0, 0), a2, voffA);
;             PG8_WAIT_V(8); PG8_WAIT_L(0); PG8_BAR; PG8_MMA(1, 0, At, B0); PG8_MMA(1, 1, At, B1); PG8_BAR; PG8_SCHED;
;             PG8_LDB(B0, 1, 0); PG8_LDB(B1, 1, 1); PG8_SCHED; PG8_LDA(At, 1, 0); PG8_STAGE(PG8_SA(0, 1), a2 + hstepA, voffA);
;             PG8_WAIT_V(8); PG8_WAIT_L(0); PG8_BAR; PG8_MMA(0, 0, At, B0); PG8_MMA(0, 1, At, B1); PG8_BAR; PG8_SCHED;
	v_mfma_f32_16x16x32_bf16 v[114:117], v[126:129], v[162:165], v[114:117]
	v_mfma_f32_16x16x32_bf16 v[106:109], v[134:137], v[162:165], v[106:109]
	v_mfma_f32_16x16x32_bf16 v[98:101], v[126:129], v[170:173], v[98:101]
	v_mfma_f32_16x16x32_bf16 v[82:85], v[134:137], v[170:173], v[82:85]
	v_mfma_f32_16x16x32_bf16 v[94:97], v[126:129], v[210:213], v[94:97]
	v_mfma_f32_16x16x32_bf16 v[78:81], v[134:137], v[210:213], v[78:81]
	v_mfma_f32_16x16x32_bf16 v[90:93], v[126:129], v[218:221], v[90:93]
	v_mfma_f32_16x16x32_bf16 v[74:77], v[134:137], v[218:221], v[74:77]
	v_mfma_f32_16x16x32_bf16 v[114:117], v[130:133], v[166:169], v[114:117]
	v_mfma_f32_16x16x32_bf16 v[106:109], v[138:141], v[166:169], v[106:109]
	v_mfma_f32_16x16x32_bf16 v[98:101], v[130:133], v[174:177], v[98:101]
	v_mfma_f32_16x16x32_bf16 v[82:85], v[138:141], v[174:177], v[82:85]
	v_mfma_f32_16x16x32_bf16 v[94:97], v[130:133], v[214:217], v[94:97]
	v_mfma_f32_16x16x32_bf16 v[78:81], v[138:141], v[214:217], v[78:81]
	v_mfma_f32_16x16x32_bf16 v[90:93], v[130:133], v[222:225], v[90:93]
	v_mfma_f32_16x16x32_bf16 v[74:77], v[138:141], v[222:225], v[74:77]
	s_setprio 0
	s_setprio 1
	v_mfma_f32_16x16x32_bf16 v[158:161], v[142:145], v[162:165], v[158:161]
	v_mfma_f32_16x16x32_bf16 v[122:125], v[150:153], v[162:165], v[122:125]
	v_mfma_f32_16x16x32_bf16 v[118:121], v[142:145], v[170:173], v[118:121]
	v_mfma_f32_16x16x32_bf16 v[110:113], v[150:153], v[170:173], v[110:113]
	v_mfma_f32_16x16x32_bf16 v[102:105], v[142:145], v[210:213], v[102:105]
	v_mfma_f32_16x16x32_bf16 v[86:89], v[150:153], v[210:213], v[86:89]
	v_mfma_f32_16x16x32_bf16 v[70:73], v[142:145], v[218:221], v[70:73]
	v_mfma_f32_16x16x32_bf16 v[66:69], v[150:153], v[218:221], v[66:69]
	v_mfma_f32_16x16x32_bf16 v[158:161], v[146:149], v[166:169], v[158:161]
	v_mfma_f32_16x16x32_bf16 v[122:125], v[154:157], v[166:169], v[122:125]
	v_mfma_f32_16x16x32_bf16 v[118:121], v[146:149], v[174:177], v[118:121]
	v_mfma_f32_16x16x32_bf16 v[110:113], v[154:157], v[174:177], v[110:113]
	v_mfma_f32_16x16x32_bf16 v[102:105], v[146:149], v[214:217], v[102:105]
	v_mfma_f32_16x16x32_bf16 v[86:89], v[154:157], v[214:217], v[86:89]
	v_mfma_f32_16x16x32_bf16 v[70:73], v[146:149], v[222:225], v[70:73]
	v_mfma_f32_16x16x32_bf16 v[66:69], v[154:157], v[222:225], v[66:69]
	s_setprio 0
	s_barrier
	s_add_i32 s0, s70, s43
	v_lshl_add_u64 v[226:227], s[46:47], 0, v[180:181]
	s_mov_b32 m0, s0
	ds_read_b128 v[162:165], v207 offset:16384
	ds_read_b128 v[166:169], v207 offset:17408
	ds_read_b128 v[170:173], v207 offset:18432
	ds_read_b128 v[174:177], v207 offset:19456
	ds_read_b128 v[210:213], v207 offset:20480
	ds_read_b128 v[214:217], v207 offset:21504
	ds_read_b128 v[218:221], v207 offset:22528
	ds_read_b128 v[222:225], v207 offset:23552
	global_load_lds_dwordx4 v[226:227], off
	s_add_i32 m0, s0, 0x2000
	s_add_u32 s0, s46, 0x40000
	v_lshl_add_u64 v[228:229], s[46:47], 0, v[184:185]
	s_addc_u32 s1, s47, 0
	s_add_i32 s2, s71, s43
	global_load_lds_dwordx4 v[228:229], off
	v_lshl_add_u64 v[230:231], s[0:1], 0, v[180:181]
	s_mov_b32 m0, s2
	v_lshl_add_u64 v[232:233], s[48:49], 0, v[182:183]
	global_load_lds_dwordx4 v[230:231], off
	v_lshl_add_u64 v[230:231], s[0:1], 0, v[184:185]
	s_add_i32 m0, s2, 0x2000
	s_nop 0
	global_load_lds_dwordx4 v[230:231], off
	v_lshl_add_u64 v[230:231], s[48:49], 0, v[178:179]
	s_mov_b32 m0, s50
	s_nop 0
	global_load_lds_dwordx4 v[230:231], off
	s_mov_b32 m0, s51
	s_nop 0
	global_load_lds_dwordx4 v[232:233], off
	s_waitcnt vmcnt(8)
	s_waitcnt lgkmcnt(0)
	s_setprio 1
	s_barrier
	v_mfma_f32_16x16x32_bf16 v[50:53], v[126:129], v[162:165], v[50:53]
	v_mfma_f32_16x16x32_bf16 v[42:45], v[134:137], v[162:165], v[42:45]
	v_mfma_f32_16x16x32_bf16 v[34:37], v[126:129], v[170:173], v[34:37]
	v_mfma_f32_16x16x32_bf16 v[18:21], v[134:137], v[170:173], v[18:21]
	v_mfma_f32_16x16x32_bf16 v[30:33], v[126:129], v[210:213], v[30:33]
	v_mfma_f32_16x16x32_bf16 v[14:17], v[134:137], v[210:213], v[14:17]
	v_mfma_f32_16x16x32_bf16 v[26:29], v[126:129], v[218:221], v[26:29]
	v_mfma_f32_16x16x32_bf16 v[10:13], v[134:137], v[218:221], v[10:13]
	v_mfma_f32_16x16x32_bf16 v[50:53], v[130:133], v[166:169], v[50:53]
	v_mfma_f32_16x16x32_bf16 v[42:45], v[138:141], v[166:169], v[42:45]
	v_mfma_f32_16x16x32_bf16 v[34:37], v[130:133], v[174:177], v[34:37]
	v_mfma_f32_16x16x32_bf16 v[18:21], v[138:141], v[174:177], v[18:21]
	v_mfma_f32_16x16x32_bf16 v[30:33], v[130:133], v[214:217], v[30:33]
	v_mfma_f32_16x16x32_bf16 v[14:17], v[138:141], v[214:217], v[14:17]
	v_mfma_f32_16x16x32_bf16 v[26:29], v[130:133], v[222:225], v[26:29]
	v_mfma_f32_16x16x32_bf16 v[10:13], v[138:141], v[222:225], v[10:13]
	s_setprio 0
	s_setprio 1
	v_mfma_f32_16x16x32_bf16 v[62:65], v[142:145], v[162:165], v[62:65]
	v_mfma_f32_16x16x32_bf16 v[58:61], v[150:153], v[162:165], v[58:61]
	v_mfma_f32_16x16x32_bf16 v[54:57], v[142:145], v[170:173], v[54:57]
	v_mfma_f32_16x16x32_bf16 v[46:49], v[150:153], v[170:173], v[46:49]
	v_mfma_f32_16x16x32_bf16 v[38:41], v[142:145], v[210:213], v[38:41]
	v_mfma_f32_16x16x32_bf16 v[22:25], v[150:153], v[210:213], v[22:25]
	v_mfma_f32_16x16x32_bf16 v[6:9], v[142:145], v[218:221], v[6:9]
	v_mfma_f32_16x16x32_bf16 v[2:5], v[150:153], v[218:221], v[2:5]
	v_mfma_f32_16x16x32_bf16 v[62:65], v[146:149], v[166:169], v[62:65]
	v_mfma_f32_16x16x32_bf16 v[58:61], v[154:157], v[166:169], v[58:61]
	v_mfma_f32_16x16x32_bf16 v[54:57], v[146:149], v[174:177], v[54:57]
	v_mfma_f32_16x16x32_bf16 v[46:49], v[154:157], v[174:177], v[46:49]
	v_mfma_f32_16x16x32_bf16 v[38:41], v[146:149], v[214:217], v[38:41]
	v_mfma_f32_16x16x32_bf16 v[22:25], v[154:157], v[214:217], v[22:25]
	v_mfma_f32_16x16x32_bf16 v[6:9], v[146:149], v[222:225], v[6:9]
	v_mfma_f32_16x16x32_bf16 v[2:5], v[154:157], v[222:225], v[2:5]
	s_setprio 0
	s_barrier
; #define PG8_STAGE(bufoff, gbase, voff) do { _Pragma("unroll") for (int _i = 0; _i < 2; ++_i) \
;         __builtin_amdgcn_global_load_lds((const unsigned*)((const char*)(gbase) + (voff)[_i]), (PG8_LAS unsigned*)(lds + (bufoff) + ldsw + _i * 8192), 16, 0, 0); } while (0)
; #define PG8_BAR __builtin_amdgcn_s_barrier()
; template <class Epi, class Sched, bool ALIGN_EPI = false, bool SP2 = false>
; __device__ __forceinline__ void gemm_phase(PG8_LAS unsigned char* lds, const Gemm g, const Sched& S, const Epi& E) {
;     ...
;             PG8_LDB(B0, 1, 0); PG8_LDB(B1, 1, 1); PG8_SCHED; PG8_LDA(At, 1, 0); PG8_STAGE(PG8_SA(0, 1), a2 + hstepA, voffA);
;             PG8_WAIT_V(8); PG8_WAIT_L(0); PG8_BAR; PG8_MMA(0, 0, At, B0); PG8_MMA(0, 1, At, B1); PG8_BAR; PG8_SCHED;
;             PG8_LDA(At, 1, 1); PG8_STAGE(PG8_SB(1, 0), b3, voffB); PG8_STAGE(PG8_SB(1, 1), b3 + hstepB, voffB); PG8_STAGE(PG8_SA(1, 0), a3, voffA);
;             PG8_WAIT_V(8); PG8_WAIT_L(0); PG8_BAR; PG8_MMA(1, 0, At, B0); PG8_MMA(1, 1, At, B1); PG8_BAR; PG8_SCHED;
;             } else {
;             PG8_LDB(B0, 0, 0); PG8_SCHED; PG8_LDA(At, 0, 0); PG8_STAGE(PG8_SA(1, 1), a1 + hstepA, voffA);
;             PG8_WAIT_L(8); PG8_BAR; PG8_WAIT_L(0); PG8_MMA(0, 0, At, B0); PG8_BAR; PG8_SCHED;
;             PG8_LDB(B1, 0, 1); PG8_STAGE(PG8_SB(0, 0), b2, voffB);
;             PG8_BAR; PG8_WAIT_L(0); PG8_MMA(0, 1, At, B1); PG8_BAR;
;             PG8_LDA(At, 0, 1); PG8_STAGE(PG8_SA(0, 0), a2, voffA);
;             PG8_BAR; PG8_WAIT_L(0); PG8_MMA(1, 0, At, B0); PG8_BAR; PG8_SCHED;
;             PG8_STAGE(PG8_SB(0, 1), b2 + hstepB, voffB);
;             PG8_WAIT_V(6); PG8_BAR; PG8_MMA(1, 1, At, B1); PG8_BAR;
;             PG8_LDB(B0, 1, 0); PG8_SCHED; PG8_LDA(At, 1, 0); PG8_STAGE(PG8_SA(0, 1), a2 + hstepA, voffA);
;             PG8_WAIT_L(8); PG8_BAR; PG8_WAIT_L(0); PG8_MMA(0, 0, At, B0); PG8_BAR; PG8_SCHED;
;             PG8_LDB(B1, 1, 1); PG8_STAGE(PG8_SB(1, 0), b3, voffB);
;             PG8_BAR; PG8_WAIT_L(0); PG8_MMA(0, 1, At, B1); PG8_BAR;
;             PG8_LDA(At, 1, 1); PG8_STAGE(PG8_SA(1, 0), a3, voffA);
;             PG8_BAR; PG8_WAIT_L(0); PG8_MMA(1, 0, At, B0); PG8_BAR; PG8_SCHED;
;             PG8_STAGE(PG8_SB(1, 1), b3 + hstepB, voffB);
;             PG8_WAIT_V(6); PG8_BAR; PG8_MMA(1, 1, At, B1); PG8_BAR;
;             }
;         }
;         if constexpr (ALIGN_EPI) { if (wr == 0) PG8_BAR; }
	ds_read_b128 v[126:129], v208
	ds_read_b128 v[130:133], v208 offset:1024
	ds_read_b128 v[134:137], v208 offset:2048
	ds_read_b128 v[138:141], v208 offset:3072
	ds_read_b128 v[142:145], v209
	ds_read_b128 v[146:149], v209 offset:1024
	ds_read_b128 v[150:153], v209 offset:2048
	ds_read_b128 v[154:157], v209 offset:3072
	s_add_u32 s0, s48, 0x40000
	s_addc_u32 s1, s49, 0
	s_mov_b32 m0, s62
	v_lshl_add_u64 v[234:235], s[0:1], 0, v[178:179]
	ds_read_b128 v[162:165], v207 offset:32768
	ds_read_b128 v[166:169], v207 offset:33792
	ds_read_b128 v[170:173], v207 offset:34816
	ds_read_b128 v[174:177], v207 offset:35840
	ds_read_b128 v[210:213], v207 offset:36864
	ds_read_b128 v[214:217], v207 offset:37888
	ds_read_b128 v[218:221], v207 offset:38912
	ds_read_b128 v[222:225], v207 offset:39936
	global_load_lds_dwordx4 v[234:235], off
	v_lshl_add_u64 v[234:235], s[0:1], 0, v[182:183]
	s_mov_b32 m0, s63
	s_nop 0
	global_load_lds_dwordx4 v[234:235], off
	s_waitcnt vmcnt(8)
	s_waitcnt lgkmcnt(0)
	s_setprio 1
	s_barrier
	v_mfma_f32_16x16x32_bf16 v[114:117], v[126:129], v[162:165], v[114:117]
	v_mfma_f32_16x16x32_bf16 v[106:109], v[134:137], v[162:165], v[106:109]
	v_mfma_f32_16x16x32_bf16 v[98:101], v[126:129], v[170:173], v[98:101]
	v_mfma_f32_16x16x32_bf16 v[82:85], v[134:137], v[170:173], v[82:85]
	v_mfma_f32_16x16x32_bf16 v[94:97], v[126:129], v[210:213], v[94:97]
	v_mfma_f32_16x16x32_bf16 v[78:81], v[134:137], v[210:213], v[78:81]
	v_mfma_f32_16x16x32_bf16 v[90:93], v[126:129], v[218:221], v[90:93]
	v_mfma_f32_16x16x32_bf16 v[74:77], v[134:137], v[218:221], v[74:77]
	v_mfma_f32_16x16x32_bf16 v[114:117], v[130:133], v[166:169], v[114:117]
	v_mfma_f32_16x16x32_bf16 v[106:109], v[138:141], v[166:169], v[106:109]
	v_mfma_f32_16x16x32_bf16 v[98:101], v[130:133], v[174:177], v[98:101]
	v_mfma_f32_16x16x32_bf16 v[82:85], v[138:141], v[174:177], v[82:85]
	v_mfma_f32_16x16x32_bf16 v[94:97], v[130:133], v[214:217], v[94:97]
	v_mfma_f32_16x16x32_bf16 v[78:81], v[138:141], v[214:217], v[78:81]
	v_mfma_f32_16x16x32_bf16 v[90:93], v[130:133], v[222:225], v[90:93]
	v_mfma_f32_16x16x32_bf16 v[74:77], v[138:141], v[222:225], v[74:77]
	s_setprio 0
	s_setprio 1
	v_mfma_f32_16x16x32_bf16 v[158:161], v[142:145], v[162:165], v[158:161]
	v_mfma_f32_16x16x32_bf16 v[122:125], v[150:153], v[162:165], v[122:125]
	v_mfma_f32_16x16x32_bf16 v[118:121], v[142:145], v[170:173], v[118:121]
	v_mfma_f32_16x16x32_bf16 v[110:113], v[150:153], v[170:173], v[110:113]
	v_mfma_f32_16x16x32_bf16 v[102:105], v[142:145], v[210:213], v[102:105]
	v_mfma_f32_16x16x32_bf16 v[86:89], v[150:153], v[210:213], v[86:89]
	v_mfma_f32_16x16x32_bf16 v[70:73], v[142:145], v[218:221], v[70:73]
	v_mfma_f32_16x16x32_bf16 v[66:69], v[150:153], v[218:221], v[66:69]
	v_mfma_f32_16x16x32_bf16 v[158:161], v[146:149], v[166:169], v[158:161]
	v_mfma_f32_16x16x32_bf16 v[122:125], v[154:157], v[166:169], v[122:125]
	v_mfma_f32_16x16x32_bf16 v[118:121], v[146:149], v[174:177], v[118:121]
	v_mfma_f32_16x16x32_bf16 v[110:113], v[154:157], v[174:177], v[110:113]
	v_mfma_f32_16x16x32_bf16 v[102:105], v[146:149], v[214:217], v[102:105]
	v_mfma_f32_16x16x32_bf16 v[86:89], v[154:157], v[214:217], v[86:89]
	v_mfma_f32_16x16x32_bf16 v[70:73], v[146:149], v[222:225], v[70:73]
	v_mfma_f32_16x16x32_bf16 v[66:69], v[154:157], v[222:225], v[66:69]
	s_setprio 0
	s_barrier
	s_add_i32 s0, s72, s43
	v_lshl_add_u64 v[226:227], v[226:227], 0, s[20:21]
	s_mov_b32 m0, s0
	ds_read_b128 v[162:165], v207 offset:49152
	ds_read_b128 v[166:169], v207 offset:50176
	ds_read_b128 v[170:173], v207 offset:51200
	ds_read_b128 v[174:177], v207 offset:52224
	ds_read_b128 v[210:213], v207 offset:53248
	ds_read_b128 v[214:217], v207 offset:54272
	ds_read_b128 v[218:221], v207 offset:55296
	ds_read_b128 v[222:225], v207 offset:56320
	global_load_lds_dwordx4 v[226:227], off
	s_add_i32 m0, s0, 0x2000
	s_add_u32 s0, s46, 0x40080
	v_lshl_add_u64 v[226:227], v[228:229], 0, s[20:21]
	s_addc_u32 s1, s47, 0
	s_add_i32 s2, s73, s43
	global_load_lds_dwordx4 v[226:227], off
	v_lshl_add_u64 v[226:227], s[0:1], 0, v[180:181]
	s_mov_b32 m0, s2
	s_nop 0
	global_load_lds_dwordx4 v[226:227], off
	v_lshl_add_u64 v[226:227], s[0:1], 0, v[184:185]
	s_add_i32 m0, s2, 0x2000
	s_nop 0
	global_load_lds_dwordx4 v[226:227], off
	v_lshl_add_u64 v[226:227], v[230:231], 0, s[20:21]
	s_mov_b32 m0, s66
	s_nop 0
	global_load_lds_dwordx4 v[226:227], off
	v_lshl_add_u64 v[226:227], v[232:233], 0, s[20:21]
	s_mov_b32 m0, s67
	s_nop 0
	global_load_lds_dwordx4 v[226:227], off
	s_waitcnt vmcnt(8)
	s_waitcnt lgkmcnt(0)
	s_setprio 1
	s_barrier
	v_mfma_f32_16x16x32_bf16 v[50:53], v[126:129], v[162:165], v[50:53]
	v_mfma_f32_16x16x32_bf16 v[42:45], v[134:137], v[162:165], v[42:45]
	v_mfma_f32_16x16x32_bf16 v[34:37], v[126:129], v[170:173], v[34:37]
	v_mfma_f32_16x16x32_bf16 v[18:21], v[134:137], v[170:173], v[18:21]
	v_mfma_f32_16x16x32_bf16 v[30:33], v[126:129], v[210:213], v[30:33]
	v_mfma_f32_16x16x32_bf16 v[14:17], v[134:137], v[210:213], v[14:17]
	v_mfma_f32_16x16x32_bf16 v[26:29], v[126:129], v[218:221], v[26:29]
	v_mfma_f32_16x16x32_bf16 v[10:13], v[134:137], v[218:221], v[10:13]
	v_mfma_f32_16x16x32_bf16 v[50:53], v[130:133], v[166:169], v[50:53]
	v_mfma_f32_16x16x32_bf16 v[42:45], v[138:141], v[166:169], v[42:45]
	v_mfma_f32_16x16x32_bf16 v[34:37], v[130:133], v[174:177], v[34:37]
	v_mfma_f32_16x16x32_bf16 v[18:21], v[138:141], v[174:177], v[18:21]
	v_mfma_f32_16x16x32_bf16 v[30:33], v[130:133], v[214:217], v[30:33]
	v_mfma_f32_16x16x32_bf16 v[14:17], v[138:141], v[214:217], v[14:17]
	v_mfma_f32_16x16x32_bf16 v[26:29], v[130:133], v[222:225], v[26:29]
	v_mfma_f32_16x16x32_bf16 v[10:13], v[138:141], v[222:225], v[10:13]
	s_setprio 0
	s_setprio 1
	v_mfma_f32_16x16x32_bf16 v[62:65], v[142:145], v[162:165], v[62:65]
	v_mfma_f32_16x16x32_bf16 v[58:61], v[150:153], v[162:165], v[58:61]
	v_mfma_f32_16x16x32_bf16 v[54:57], v[142:145], v[170:173], v[54:57]
	v_mfma_f32_16x16x32_bf16 v[46:49], v[150:153], v[170:173], v[46:49]
	v_mfma_f32_16x16x32_bf16 v[38:41], v[142:145], v[210:213], v[38:41]
	v_mfma_f32_16x16x32_bf16 v[22:25], v[150:153], v[210:213], v[22:25]
	v_mfma_f32_16x16x32_bf16 v[6:9], v[142:145], v[218:221], v[6:9]
	v_mfma_f32_16x16x32_bf16 v[2:5], v[150:153], v[218:221], v[2:5]
	v_mfma_f32_16x16x32_bf16 v[62:65], v[146:149], v[166:169], v[62:65]
	v_mfma_f32_16x16x32_bf16 v[58:61], v[154:157], v[166:169], v[58:61]
	v_mfma_f32_16x16x32_bf16 v[54:57], v[146:149], v[174:177], v[54:57]
	v_mfma_f32_16x16x32_bf16 v[46:49], v[154:157], v[174:177], v[46:49]
	v_mfma_f32_16x16x32_bf16 v[38:41], v[146:149], v[214:217], v[38:41]
	v_mfma_f32_16x16x32_bf16 v[22:25], v[154:157], v[214:217], v[22:25]
	v_mfma_f32_16x16x32_bf16 v[6:9], v[146:149], v[222:225], v[6:9]
	v_mfma_f32_16x16x32_bf16 v[2:5], v[154:157], v[222:225], v[2:5]
	s_setprio 0
	s_barrier
	s_add_i32 s35, s35, 2
	s_add_u32 s18, s18, 0x100
	s_addc_u32 s19, s19, 0
	s_cmp_gt_u32 s35, 13
	s_mov_b64 s[44:45], s[14:15]
	s_cbranch_scc0 .LBB0_1846
	s_and_b64 vcc, exec, s[28:29]
	s_cbranch_vccz .LBB0_1849
	s_barrier

;     __device__ __forceinline__ void run(const f32x4 (&acc)[2][2][4][2], const Unit& u, int wr, int wc, int fr, int fq, const PG8_LAS unsigned char* sp) const {
;     ...
;         for (int ai = 0; ai < 2; ++ai) {
;             const int rb64 = u.pm * BM + ai * HALF + wr * 64;
;             f32x4 H2[2], H3[2];
;             { const unsigned a2[4] = {hr2[ai].x, hr2[ai].y, hr2[ai].z, hr2[ai].w}, a3[4] = {hr3[ai].x, hr3[ai].y, hr3[ai].z, hr3[ai].w};
; #pragma unroll
;               for (int q = 0; q < 4; ++q) { H2[q >> 1][2 * (q & 1)] = __builtin_bit_cast(float, a2[q] << 16); H2[q >> 1][2 * (q & 1) + 1] = __builtin_bit_cast(float, a2[q] & 0xffff0000u);
;                                             H3[q >> 1][2 * (q & 1)] = __builtin_bit_cast(float, a3[q] << 16); H3[q >> 1][2 * (q & 1) + 1] = __builtin_bit_cast(float, a3[q] & 0xffff0000u); } }
;             f32x4 S2[2], S3[2];
; #pragma unroll
;             for (int n = 0; n < 2; ++n)
; #pragma unroll
;                 for (int e = 0; e < 4; ++e) { S2[n][e] = dpp_old<0x111>(H2[n][e], acc[ai][0][2][n][e]); S3[n][e] = dpp_old<0x111>(H3[n][e], acc[ai][0][3][n][e]); }
; #pragma unroll
;             for (int m = 0; m < 4; ++m) {
;                 u32x4 w;
; #pragma unroll
;                 for (int n = 0; n < 2; ++n) {
;                     const f32x4 G0 = acc[ai][0][0][n], G1 = acc[ai][0][1][n], G2 = acc[ai][0][2][n];
;                     const f32x4 Gv = acc[ai][0][m][n], Uv = acc[ai][1][m][n];
;                     const f32x4 g1 = (m == 0) ? S3[n] : (m == 1) ? G0 : (m == 2) ? G1 : G2, g2 = (m == 0) ? S2[n] : (m == 1) ? S3[n] : (m == 2) ? G0 : G1;
;                     f32x2e oh[2];
; #pragma unroll
;                     for (int hq = 0; hq < 2; ++hq) {
;                         const f32x2e g2p = hq ? g2.hi : g2.lo, g1p = hq ? g1.hi : g1.lo, Gp = hq ? Gv.hi : Gv.lo, Up = hq ? Uv.hi : Uv.lo;
;                         const f32x2e w0p = hq ? w0[n].hi : w0[n].lo, w1p = hq ? w1[n].hi : w1[n].lo, w2p = hq ? w2[n].hi : w2[n].lo, bp = hq ? bb[n].hi : bb[n].lo;
;                         const f32x2e y = __builtin_elementwise_fma(w0p, g2p, __builtin_elementwise_fma(w1p, g1p, __builtin_elementwise_fma(w2p, Gp, bp)));
;                         const f32x2e t = y * -1.4426950408889634f;
;                         f32x2e den; den.x = __builtin_amdgcn_exp2f(t.x); den.y = __builtin_amdgcn_exp2f(t.y); den = den + 1.f;
.LBB0_1853:
	s_or_b64 exec, exec, s[14:15]
	s_waitcnt lgkmcnt(0)
	v_lshlrev_b32_e32 v216, 16, v174
	v_and_b32_e32 v217, 0xffff0000, v174
	v_lshlrev_b32_e32 v214, 16, v170
	v_and_b32_e32 v215, 0xffff0000, v170
	v_lshlrev_b32_e32 v174, 16, v175
	v_and_b32_e32 v175, 0xffff0000, v175
	v_mov_b32_dpp v216, v90 row_shr:1 row_mask:0xf bank_mask:0xf
	v_mov_b32_dpp v217, v91 row_shr:1 row_mask:0xf bank_mask:0xf
	v_pk_fma_f32 v[224:225], v[150:151], v[114:115], v[154:155]
	v_lshlrev_b32_e32 v170, 16, v171
	v_and_b32_e32 v171, 0xffff0000, v171
	v_mov_b32_dpp v214, v94 row_shr:1 row_mask:0xf bank_mask:0xf
	v_mov_b32_dpp v215, v95 row_shr:1 row_mask:0xf bank_mask:0xf
	v_mov_b32_dpp v174, v92 row_shr:1 row_mask:0xf bank_mask:0xf
	v_mov_b32_dpp v175, v93 row_shr:1 row_mask:0xf bank_mask:0xf
	v_pk_fma_f32 v[222:223], v[152:153], v[116:117], v[156:157]
	v_pk_fma_f32 v[224:225], v[146:147], v[216:217], v[224:225]
	v_mov_b32_dpp v170, v96 row_shr:1 row_mask:0xf bank_mask:0xf
	v_mov_b32_dpp v171, v97 row_shr:1 row_mask:0xf bank_mask:0xf
	v_pk_fma_f32 v[214:215], v[142:143], v[214:215], v[224:225]
	v_pk_fma_f32 v[222:223], v[148:149], v[174:175], v[222:223]
	v_pk_mul_f32 v[224:225], v[214:215], s[30:31] op_sel_hi:[1,0]
	v_pk_fma_f32 v[170:171], v[144:145], v[170:171], v[222:223]
	v_exp_f32_e32 v224, v224
	v_exp_f32_e32 v225, v225
	v_pk_mul_f32 v[222:223], v[170:171], s[30:31] op_sel_hi:[1,0]
	v_lshlrev_b32_e32 v220, 16, v176
	v_exp_f32_e32 v222, v222
	v_exp_f32_e32 v223, v223
	v_pk_add_f32 v[224:225], v[224:225], 1.0 op_sel_hi:[1,0]
	v_and_b32_e32 v221, 0xffff0000, v176
	v_rcp_f32_e32 v224, v224
	v_rcp_f32_e32 v225, v225
	v_pk_add_f32 v[222:223], v[222:223], 1.0 op_sel_hi:[1,0]
	v_lshlrev_b32_e32 v218, 16, v172
	v_rcp_f32_e32 v222, v222
	v_rcp_f32_e32 v223, v223
	v_pk_mul_f32 v[214:215], v[214:215], v[224:225]
	v_and_b32_e32 v219, 0xffff0000, v172
	v_lshlrev_b32_e32 v176, 16, v177
	v_and_b32_e32 v177, 0xffff0000, v177
	v_mov_b32_dpp v220, v74 row_shr:1 row_mask:0xf bank_mask:0xf
	v_mov_b32_dpp v221, v75 row_shr:1 row_mask:0xf bank_mask:0xf
	v_pk_mul_f32 v[158:159], v[158:159], v[214:215]
	v_pk_mul_f32 v[170:171], v[170:171], v[222:223]
	v_pk_fma_f32 v[214:215], v[134:135], v[106:107], v[138:139]
	v_lshlrev_b32_e32 v172, 16, v173
	v_and_b32_e32 v173, 0xffff0000, v173
	v_mov_b32_dpp v218, v78 row_shr:1 row_mask:0xf bank_mask:0xf
	v_mov_b32_dpp v219, v79 row_shr:1 row_mask:0xf bank_mask:0xf
	v_mov_b32_dpp v176, v76 row_shr:1 row_mask:0xf bank_mask:0xf
	v_mov_b32_dpp v177, v77 row_shr:1 row_mask:0xf bank_mask:0xf
	v_pk_mul_f32 v[160:161], v[160:161], v[170:171]
	v_pk_fma_f32 v[170:171], v[136:137], v[108:109], v[140:141]
	v_pk_fma_f32 v[214:215], v[130:131], v[220:221], v[214:215]
	v_mov_b32_dpp v172, v80 row_shr:1 row_mask:0xf bank_mask:0xf
	v_mov_b32_dpp v173, v81 row_shr:1 row_mask:0xf bank_mask:0xf
	v_pk_fma_f32 v[214:215], v[126:127], v[218:219], v[214:215]
	v_pk_fma_f32 v[170:171], v[132:133], v[176:177], v[170:171]
	v_pk_mul_f32 v[218:219], v[214:215], s[30:31] op_sel_hi:[1,0]
	v_pk_fma_f32 v[170:171], v[128:129], v[172:173], v[170:171]
	v_exp_f32_e32 v218, v218
	v_exp_f32_e32 v219, v219
	v_pk_mul_f32 v[172:173], v[170:171], s[30:31] op_sel_hi:[1,0]
	v_cvt_pk_bf16_f32 v158, v158, v159
	v_cvt_pk_bf16_f32 v159, v160, v161
	v_pk_add_f32 v[218:219], v[218:219], 1.0 op_sel_hi:[1,0]
	v_exp_f32_e32 v172, v172
	v_exp_f32_e32 v173, v173
	v_rcp_f32_e32 v218, v218
	v_rcp_f32_e32 v219, v219
	v_lshl_or_b32 v212, s6, 7, v202
	v_pk_add_f32 v[172:173], v[172:173], 1.0 op_sel_hi:[1,0]
	v_ashrrev_i32_e32 v213, 31, v212
	v_rcp_f32_e32 v172, v172
	v_rcp_f32_e32 v173, v173
	v_pk_mul_f32 v[160:161], v[214:215], v[218:219]
	v_or_b32_e32 v210, s0, v201
	v_pk_mul_f32 v[122:123], v[122:123], v[160:161]
	v_pk_mul_f32 v[160:161], v[170:171], v[172:173]
	v_pk_fma_f32 v[172:173], v[152:153], v[100:101], v[156:157]
	v_pk_mul_f32 v[124:125], v[124:125], v[160:161]
	v_cvt_pk_bf16_f32 v160, v122, v123
	v_pk_fma_f32 v[172:173], v[148:149], v[116:117], v[172:173]
	v_cvt_pk_bf16_f32 v161, v124, v125
	v_lshlrev_b64 v[124:125], 1, v[212:213]
	v_pk_fma_f32 v[212:213], v[150:151], v[98:99], v[154:155]
	v_pk_fma_f32 v[172:173], v[144:145], v[174:175], v[172:173]
	v_pk_fma_f32 v[212:213], v[146:147], v[114:115], v[212:213]
	v_pk_mul_f32 v[174:175], v[172:173], s[30:31] op_sel_hi:[1,0]
	v_pk_fma_f32 v[212:213], v[142:143], v[216:217], v[212:213]
	v_exp_f32_e32 v174, v174
	v_pk_mul_f32 v[214:215], v[212:213], s[30:31] op_sel_hi:[1,0]
	v_exp_f32_e32 v175, v175
	v_exp_f32_e32 v214, v214
	v_exp_f32_e32 v215, v215
	v_readlane_b32 s0, v253, 29
	v_readlane_b32 s1, v253, 30
	v_pk_add_f32 v[174:175], v[174:175], 1.0 op_sel_hi:[1,0]
	v_pk_add_f32 v[214:215], v[214:215], 1.0 op_sel_hi:[1,0]
	v_mov_b64_e32 v[122:123], s[0:1]
	v_rcp_f32_e32 v214, v214
	v_rcp_f32_e32 v215, v215
	v_rcp_f32_e32 v174, v174
	v_rcp_f32_e32 v175, v175
	v_mad_i64_i32 v[170:171], s[0:1], v210, s69, v[122:123]
	v_lshl_add_u64 v[170:171], v[170:171], 0, v[124:125]
	global_store_dwordx4 v[170:171], v[158:161], off
	v_pk_fma_f32 v[90:91], v[150:151], v[90:91], v[154:155]
	v_pk_fma_f32 v[74:75], v[134:135], v[74:75], v[138:139]
	v_pk_mul_f32 v[158:159], v[212:213], v[214:215]
	v_pk_fma_f32 v[160:161], v[134:135], v[82:83], v[138:139]
	v_pk_mul_f32 v[118:119], v[118:119], v[158:159]
	v_pk_mul_f32 v[158:159], v[172:173], v[174:175]
	v_pk_fma_f32 v[160:161], v[130:131], v[106:107], v[160:161]
	v_pk_mul_f32 v[120:121], v[120:121], v[158:159]
	v_pk_fma_f32 v[158:159], v[136:137], v[84:85], v[140:141]
	v_pk_fma_f32 v[160:161], v[126:127], v[220:221], v[160:161]
	v_pk_fma_f32 v[158:159], v[132:133], v[108:109], v[158:159]
; __device__ __forceinline__ unsigned cvt_pk_bf16(float lo, float hi) { unsigned r; asm volatile("v_cvt_pk_bf16_f32 %0, %1, %2" : "=v"(r) : "v"(lo), "v"(hi)); return r; }
;     __device__ __forceinline__ void run(const f32x4 (&acc)[2][2][4][2], const Unit& u, int wr, int wc, int fr, int fq, const PG8_LAS unsigned char* sp) const {
;     ...
; #pragma unroll
;             for (int m = 0; m < 4; ++m) {
;                 u32x4 w;
; #pragma unroll
;                 for (int n = 0; n < 2; ++n) {
;                     const f32x4 G0 = acc[ai][0][0][n], G1 = acc[ai][0][1][n], G2 = acc[ai][0][2][n];
;                     const f32x4 Gv = acc[ai][0][m][n], Uv = acc[ai][1][m][n];
;                     const f32x4 g1 = (m == 0) ? S3[n] : (m == 1) ? G0 : (m == 2) ? G1 : G2, g2 = (m == 0) ? S2[n] : (m == 1) ? S3[n] : (m == 2) ? G0 : G1;
;                     f32x2e oh[2];
; #pragma unroll
;                     for (int hq = 0; hq < 2; ++hq) {
;                         const f32x2e g2p = hq ? g2.hi : g2.lo, g1p = hq ? g1.hi : g1.lo, Gp = hq ? Gv.hi : Gv.lo, Up = hq ? Uv.hi : Uv.lo;
;                         const f32x2e w0p = hq ? w0[n].hi : w0[n].lo, w1p = hq ? w1[n].hi : w1[n].lo, w2p = hq ? w2[n].hi : w2[n].lo, bp = hq ? bb[n].hi : bb[n].lo;
;                         const f32x2e y = __builtin_elementwise_fma(w0p, g2p, __builtin_elementwise_fma(w1p, g1p, __builtin_elementwise_fma(w2p, Gp, bp)));
;                         const f32x2e t = y * -1.4426950408889634f;
;                         f32x2e den; den.x = __builtin_amdgcn_exp2f(t.x); den.y = __builtin_amdgcn_exp2f(t.y); den = den + 1.f;
;                         f32x2e r; r.x = __builtin_amdgcn_rcpf(den.x); r.y = __builtin_amdgcn_rcpf(den.y);
;                         oh[hq] = y * r * Up;
;                     }
;                     if (n == 0) { w.x = cvt_pk_bf16(oh[0].x, oh[0].y); w.y = cvt_pk_bf16(oh[1].x, oh[1].y); } else { w.z = cvt_pk_bf16(oh[0].x, oh[0].y); w.w = cvt_pk_bf16(oh[1].x, oh[1].y); }
;                 }
;                 *(u32x4*)(act + (size_t)(rb64 + 4 * fr + m) * dff + ch0) = w;
;             }
	v_pk_mul_f32 v[170:171], v[160:161], s[30:31] op_sel_hi:[1,0]
	v_pk_fma_f32 v[158:159], v[128:129], v[176:177], v[158:159]
	v_exp_f32_e32 v170, v170
	v_exp_f32_e32 v171, v171
	v_pk_mul_f32 v[172:173], v[158:159], s[30:31] op_sel_hi:[1,0]
	v_cvt_pk_bf16_f32 v118, v118, v119
	v_cvt_pk_bf16_f32 v119, v120, v121
	v_pk_add_f32 v[170:171], v[170:171], 1.0 op_sel_hi:[1,0]
	v_exp_f32_e32 v172, v172
	v_exp_f32_e32 v173, v173
	v_rcp_f32_e32 v170, v170
	v_rcp_f32_e32 v171, v171
	v_pk_fma_f32 v[90:91], v[146:147], v[94:95], v[90:91]
	v_pk_add_f32 v[172:173], v[172:173], 1.0 op_sel_hi:[1,0]
	v_pk_fma_f32 v[90:91], v[142:143], v[98:99], v[90:91]
	v_rcp_f32_e32 v172, v172
	v_rcp_f32_e32 v173, v173
	v_pk_mul_f32 v[120:121], v[160:161], v[170:171]
	v_pk_fma_f32 v[76:77], v[136:137], v[76:77], v[140:141]
	v_pk_mul_f32 v[110:111], v[110:111], v[120:121]
	v_pk_mul_f32 v[120:121], v[158:159], v[172:173]
	v_pk_fma_f32 v[158:159], v[150:151], v[94:95], v[154:155]
	v_pk_mul_f32 v[112:113], v[112:113], v[120:121]
	v_cvt_pk_bf16_f32 v120, v110, v111
	v_pk_fma_f32 v[158:159], v[146:147], v[98:99], v[158:159]
	v_cvt_pk_bf16_f32 v121, v112, v113
	v_pk_fma_f32 v[112:113], v[152:153], v[96:97], v[156:157]
	v_pk_fma_f32 v[114:115], v[142:143], v[114:115], v[158:159]
	v_pk_fma_f32 v[112:113], v[148:149], v[100:101], v[112:113]
	v_or_b32_e32 v110, 1, v210
	v_pk_fma_f32 v[112:113], v[144:145], v[116:117], v[112:113]
	v_pk_mul_f32 v[116:117], v[114:115], s[30:31] op_sel_hi:[1,0]
	v_pk_mul_f32 v[158:159], v[112:113], s[30:31] op_sel_hi:[1,0]
	v_exp_f32_e32 v116, v116
	v_exp_f32_e32 v117, v117
	v_exp_f32_e32 v158, v158
	v_exp_f32_e32 v159, v159
	v_mad_i64_i32 v[110:111], s[0:1], v110, s69, v[122:123]
	v_pk_add_f32 v[116:117], v[116:117], 1.0 op_sel_hi:[1,0]
	v_pk_add_f32 v[158:159], v[158:159], 1.0 op_sel_hi:[1,0]
	v_rcp_f32_e32 v116, v116
	v_rcp_f32_e32 v117, v117
	v_rcp_f32_e32 v158, v158
	v_rcp_f32_e32 v159, v159
	v_lshl_add_u64 v[110:111], v[110:111], 0, v[124:125]
	global_store_dwordx4 v[110:111], v[118:121], off
	v_pk_mul_f32 v[110:111], v[114:115], v[116:117]
	v_pk_fma_f32 v[74:75], v[130:131], v[78:79], v[74:75]
	v_pk_mul_f32 v[102:103], v[102:103], v[110:111]
	v_pk_mul_f32 v[110:111], v[112:113], v[158:159]
	v_pk_fma_f32 v[112:113], v[134:135], v[78:79], v[138:139]
	v_pk_mul_f32 v[104:105], v[104:105], v[110:111]
	v_pk_fma_f32 v[110:111], v[136:137], v[80:81], v[140:141]
	v_pk_fma_f32 v[112:113], v[130:131], v[82:83], v[112:113]
	v_pk_fma_f32 v[110:111], v[132:133], v[84:85], v[110:111]
	v_pk_fma_f32 v[106:107], v[126:127], v[106:107], v[112:113]
	v_pk_fma_f32 v[108:109], v[128:129], v[108:109], v[110:111]
	v_pk_mul_f32 v[110:111], v[106:107], s[30:31] op_sel_hi:[1,0]
	v_pk_mul_f32 v[112:113], v[108:109], s[30:31] op_sel_hi:[1,0]
	v_exp_f32_e32 v110, v110
	v_exp_f32_e32 v111, v111
	v_exp_f32_e32 v112, v112
	v_exp_f32_e32 v113, v113
	v_cvt_pk_bf16_f32 v102, v102, v103
	v_pk_add_f32 v[110:111], v[110:111], 1.0 op_sel_hi:[1,0]
	v_cvt_pk_bf16_f32 v103, v104, v105
	v_pk_add_f32 v[112:113], v[112:113], 1.0 op_sel_hi:[1,0]
	v_rcp_f32_e32 v110, v110
	v_rcp_f32_e32 v111, v111
	v_rcp_f32_e32 v112, v112
	v_rcp_f32_e32 v113, v113
	v_pk_fma_f32 v[76:77], v[132:133], v[80:81], v[76:77]
	v_pk_mul_f32 v[104:105], v[106:107], v[110:111]
	v_pk_fma_f32 v[74:75], v[126:127], v[82:83], v[74:75]
	v_pk_mul_f32 v[86:87], v[86:87], v[104:105]
	v_pk_mul_f32 v[104:105], v[108:109], v[112:113]
	v_pk_fma_f32 v[76:77], v[128:129], v[84:85], v[76:77]
	v_pk_mul_f32 v[88:89], v[88:89], v[104:105]
	v_cvt_pk_bf16_f32 v104, v86, v87
	v_pk_mul_f32 v[78:79], v[74:75], s[30:31] op_sel_hi:[1,0]
	v_cvt_pk_bf16_f32 v105, v88, v89
	v_pk_fma_f32 v[88:89], v[152:153], v[92:93], v[156:157]
	v_pk_mul_f32 v[92:93], v[90:91], s[30:31] op_sel_hi:[1,0]
	v_pk_fma_f32 v[88:89], v[148:149], v[96:97], v[88:89]
	v_exp_f32_e32 v92, v92
	v_pk_fma_f32 v[88:89], v[144:145], v[100:101], v[88:89]
	v_exp_f32_e32 v93, v93
	v_pk_mul_f32 v[94:95], v[88:89], s[30:31] op_sel_hi:[1,0]
	v_exp_f32_e32 v78, v78
	v_exp_f32_e32 v94, v94
	v_exp_f32_e32 v95, v95
	v_exp_f32_e32 v79, v79
	v_pk_mul_f32 v[80:81], v[76:77], s[30:31] op_sel_hi:[1,0]
	v_pk_add_f32 v[92:93], v[92:93], 1.0 op_sel_hi:[1,0]
	v_exp_f32_e32 v80, v80
	v_exp_f32_e32 v81, v81
	v_rcp_f32_e32 v92, v92
	v_rcp_f32_e32 v93, v93
	v_pk_add_f32 v[94:95], v[94:95], 1.0 op_sel_hi:[1,0]
	v_or_b32_e32 v86, 2, v210
	v_rcp_f32_e32 v94, v94
	v_rcp_f32_e32 v95, v95
	v_mad_i64_i32 v[86:87], s[0:1], v86, s69, v[122:123]
	v_pk_add_f32 v[78:79], v[78:79], 1.0 op_sel_hi:[1,0]
	v_lshl_add_u64 v[86:87], v[86:87], 0, v[124:125]
	v_rcp_f32_e32 v78, v78
	v_rcp_f32_e32 v79, v79
	v_pk_add_f32 v[80:81], v[80:81], 1.0 op_sel_hi:[1,0]
	global_store_dwordx4 v[86:87], v[102:105], off
	v_pk_mul_f32 v[86:87], v[90:91], v[92:93]
	v_rcp_f32_e32 v80, v80
	v_rcp_f32_e32 v81, v81
	v_pk_mul_f32 v[70:71], v[70:71], v[86:87]
	v_pk_mul_f32 v[86:87], v[88:89], v[94:95]
	v_cvt_pk_bf16_f32 v70, v70, v71
	v_pk_fma_f32 v[84:85], v[150:151], v[50:51], v[154:155]
	v_pk_mul_f32 v[72:73], v[72:73], v[86:87]
	v_pk_fma_f32 v[82:83], v[152:153], v[52:53], v[156:157]
	v_cvt_pk_bf16_f32 v71, v72, v73
	v_pk_mul_f32 v[72:73], v[74:75], v[78:79]
	v_lshlrev_b32_e32 v74, 16, v164
	v_pk_mul_f32 v[66:67], v[66:67], v[72:73]
	v_pk_mul_f32 v[72:73], v[76:77], v[80:81]
	v_lshlrev_b32_e32 v76, 16, v168
	v_pk_mul_f32 v[68:69], v[68:69], v[72:73]
	v_cvt_pk_bf16_f32 v72, v66, v67
	v_or_b32_e32 v66, 3, v210
	v_mad_i64_i32 v[66:67], s[0:1], v66, s69, v[122:123]
	v_cvt_pk_bf16_f32 v73, v68, v69
	v_lshl_add_u64 v[66:67], v[66:67], 0, v[124:125]
	v_lshlrev_b32_e32 v68, 16, v166
	v_and_b32_e32 v69, 0xffff0000, v166
	global_store_dwordx4 v[66:67], v[70:73], off
;     __device__ __forceinline__ void run(const f32x4 (&acc)[2][2][4][2], const Unit& u, int wr, int wc, int fr, int fq, const PG8_LAS unsigned char* sp) const {
;     ...
;         for (int ai = 0; ai < 2; ++ai) {
;             const int rb64 = u.pm * BM + ai * HALF + wr * 64;
;             f32x4 H2[2], H3[2];
;             { const unsigned a2[4] = {hr2[ai].x, hr2[ai].y, hr2[ai].z, hr2[ai].w}, a3[4] = {hr3[ai].x, hr3[ai].y, hr3[ai].z, hr3[ai].w};
; #pragma unroll
;               for (int q = 0; q < 4; ++q) { H2[q >> 1][2 * (q & 1)] = __builtin_bit_cast(float, a2[q] << 16); H2[q >> 1][2 * (q & 1) + 1] = __builtin_bit_cast(float, a2[q] & 0xffff0000u);
;                                             H3[q >> 1][2 * (q & 1)] = __builtin_bit_cast(float, a3[q] << 16); H3[q >> 1][2 * (q & 1) + 1] = __builtin_bit_cast(float, a3[q] & 0xffff0000u); } }
;             f32x4 S2[2], S3[2];
; #pragma unroll
;             for (int n = 0; n < 2; ++n)
; #pragma unroll
;                 for (int e = 0; e < 4; ++e) { S2[n][e] = dpp_old<0x111>(H2[n][e], acc[ai][0][2][n][e]); S3[n][e] = dpp_old<0x111>(H3[n][e], acc[ai][0][3][n][e]); }
; #pragma unroll
;             for (int m = 0; m < 4; ++m) {
;                 u32x4 w;
; #pragma unroll
;                 for (int n = 0; n < 2; ++n) {
;                     const f32x4 G0 = acc[ai][0][0][n], G1 = acc[ai][0][1][n], G2 = acc[ai][0][2][n];
;                     const f32x4 Gv = acc[ai][0][m][n], Uv = acc[ai][1][m][n];
;                     const f32x4 g1 = (m == 0) ? S3[n] : (m == 1) ? G0 : (m == 2) ? G1 : G2, g2 = (m == 0) ? S2[n] : (m == 1) ? S3[n] : (m == 2) ? G0 : G1;
;                     f32x2e oh[2];
; #pragma unroll
;                     for (int hq = 0; hq < 2; ++hq) {
;                         const f32x2e g2p = hq ? g2.hi : g2.lo, g1p = hq ? g1.hi : g1.lo, Gp = hq ? Gv.hi : Gv.lo, Up = hq ? Uv.hi : Uv.lo;
;                         const f32x2e w0p = hq ? w0[n].hi : w0[n].lo, w1p = hq ? w1[n].hi : w1[n].lo, w2p = hq ? w2[n].hi : w2[n].lo, bp = hq ? bb[n].hi : bb[n].lo;
;                         const f32x2e y = __builtin_elementwise_fma(w0p, g2p, __builtin_elementwise_fma(w1p, g1p, __builtin_elementwise_fma(w2p, Gp, bp)));
;                         const f32x2e t = y * -1.4426950408889634f;
;                         f32x2e den; den.x = __builtin_amdgcn_exp2f(t.x); den.y = __builtin_amdgcn_exp2f(t.y); den = den + 1.f;
	v_lshlrev_b32_e32 v66, 16, v162
	v_and_b32_e32 v67, 0xffff0000, v162
	v_lshlrev_b32_e32 v72, 16, v167
	v_and_b32_e32 v73, 0xffff0000, v167
	v_mov_b32_dpp v68, v26 row_shr:1 row_mask:0xf bank_mask:0xf
	v_mov_b32_dpp v69, v27 row_shr:1 row_mask:0xf bank_mask:0xf
	v_lshlrev_b32_e32 v70, 16, v163
	v_and_b32_e32 v71, 0xffff0000, v163
	v_mov_b32_dpp v66, v30 row_shr:1 row_mask:0xf bank_mask:0xf
	v_mov_b32_dpp v67, v31 row_shr:1 row_mask:0xf bank_mask:0xf
	v_mov_b32_dpp v72, v28 row_shr:1 row_mask:0xf bank_mask:0xf
	v_mov_b32_dpp v73, v29 row_shr:1 row_mask:0xf bank_mask:0xf
	v_pk_fma_f32 v[84:85], v[146:147], v[68:69], v[84:85]
	v_mov_b32_dpp v70, v32 row_shr:1 row_mask:0xf bank_mask:0xf
	v_mov_b32_dpp v71, v33 row_shr:1 row_mask:0xf bank_mask:0xf
	v_pk_fma_f32 v[66:67], v[142:143], v[66:67], v[84:85]
	v_pk_fma_f32 v[82:83], v[148:149], v[72:73], v[82:83]
	v_pk_mul_f32 v[84:85], v[66:67], s[30:31] op_sel_hi:[1,0]
	v_pk_fma_f32 v[70:71], v[144:145], v[70:71], v[82:83]
	v_exp_f32_e32 v84, v84
	v_exp_f32_e32 v85, v85
	v_pk_mul_f32 v[82:83], v[70:71], s[30:31] op_sel_hi:[1,0]
	v_and_b32_e32 v77, 0xffff0000, v168
	v_exp_f32_e32 v82, v82
	v_exp_f32_e32 v83, v83
	v_pk_add_f32 v[84:85], v[84:85], 1.0 op_sel_hi:[1,0]
	v_and_b32_e32 v75, 0xffff0000, v164
	v_rcp_f32_e32 v84, v84
	v_rcp_f32_e32 v85, v85
	v_pk_add_f32 v[82:83], v[82:83], 1.0 op_sel_hi:[1,0]
	v_lshlrev_b32_e32 v80, 16, v169
	v_rcp_f32_e32 v82, v82
	v_rcp_f32_e32 v83, v83
	v_pk_mul_f32 v[66:67], v[66:67], v[84:85]
	v_and_b32_e32 v81, 0xffff0000, v169
	v_mov_b32_dpp v76, v10 row_shr:1 row_mask:0xf bank_mask:0xf
	v_mov_b32_dpp v77, v11 row_shr:1 row_mask:0xf bank_mask:0xf
	v_pk_mul_f32 v[62:63], v[62:63], v[66:67]
	v_pk_mul_f32 v[66:67], v[70:71], v[82:83]
	v_pk_fma_f32 v[70:71], v[134:135], v[42:43], v[138:139]
	v_lshlrev_b32_e32 v78, 16, v165
	v_and_b32_e32 v79, 0xffff0000, v165
	v_mov_b32_dpp v74, v14 row_shr:1 row_mask:0xf bank_mask:0xf
	v_mov_b32_dpp v75, v15 row_shr:1 row_mask:0xf bank_mask:0xf
	v_mov_b32_dpp v80, v12 row_shr:1 row_mask:0xf bank_mask:0xf
	v_mov_b32_dpp v81, v13 row_shr:1 row_mask:0xf bank_mask:0xf
	v_pk_mul_f32 v[64:65], v[64:65], v[66:67]
	v_pk_fma_f32 v[66:67], v[136:137], v[44:45], v[140:141]
	v_pk_fma_f32 v[70:71], v[130:131], v[76:77], v[70:71]
	v_mov_b32_dpp v78, v16 row_shr:1 row_mask:0xf bank_mask:0xf
	v_mov_b32_dpp v79, v17 row_shr:1 row_mask:0xf bank_mask:0xf
	v_pk_fma_f32 v[70:71], v[126:127], v[74:75], v[70:71]
	v_pk_fma_f32 v[66:67], v[132:133], v[80:81], v[66:67]
	v_pk_mul_f32 v[74:75], v[70:71], s[30:31] op_sel_hi:[1,0]
	v_pk_fma_f32 v[66:67], v[128:129], v[78:79], v[66:67]
	v_exp_f32_e32 v74, v74
	v_exp_f32_e32 v75, v75
	v_pk_mul_f32 v[78:79], v[66:67], s[30:31] op_sel_hi:[1,0]
	v_cvt_pk_bf16_f32 v62, v62, v63
	v_cvt_pk_bf16_f32 v63, v64, v65
	v_pk_add_f32 v[74:75], v[74:75], 1.0 op_sel_hi:[1,0]
	v_exp_f32_e32 v78, v78
	v_exp_f32_e32 v79, v79
	v_rcp_f32_e32 v74, v74
	v_rcp_f32_e32 v75, v75
	v_add_u32_e32 v86, 0x80, v210
	v_pk_add_f32 v[78:79], v[78:79], 1.0 op_sel_hi:[1,0]
	v_pk_fma_f32 v[26:27], v[150:151], v[26:27], v[154:155]
	v_rcp_f32_e32 v78, v78
	v_rcp_f32_e32 v79, v79
	v_pk_mul_f32 v[64:65], v[70:71], v[74:75]
	v_pk_fma_f32 v[26:27], v[146:147], v[30:31], v[26:27]
	v_pk_mul_f32 v[58:59], v[58:59], v[64:65]
	v_pk_mul_f32 v[64:65], v[66:67], v[78:79]
	v_pk_fma_f32 v[66:67], v[150:151], v[34:35], v[154:155]
	v_pk_mul_f32 v[60:61], v[60:61], v[64:65]
	v_cvt_pk_bf16_f32 v64, v58, v59
	v_pk_fma_f32 v[66:67], v[146:147], v[50:51], v[66:67]
	v_cvt_pk_bf16_f32 v65, v60, v61
	v_pk_fma_f32 v[60:61], v[152:153], v[36:37], v[156:157]
	v_pk_fma_f32 v[66:67], v[142:143], v[68:69], v[66:67]
	v_pk_fma_f32 v[60:61], v[148:149], v[52:53], v[60:61]
	v_pk_mul_f32 v[68:69], v[66:67], s[30:31] op_sel_hi:[1,0]
	v_pk_fma_f32 v[60:61], v[144:145], v[72:73], v[60:61]
	v_exp_f32_e32 v68, v68
	v_exp_f32_e32 v69, v69
	v_pk_mul_f32 v[70:71], v[60:61], s[30:31] op_sel_hi:[1,0]
	v_mad_i64_i32 v[58:59], s[0:1], v86, s69, v[122:123]
	v_exp_f32_e32 v70, v70
	v_exp_f32_e32 v71, v71
	v_pk_add_f32 v[68:69], v[68:69], 1.0 op_sel_hi:[1,0]
	v_lshl_add_u64 v[58:59], v[58:59], 0, v[124:125]
	v_rcp_f32_e32 v68, v68
	v_rcp_f32_e32 v69, v69
	v_pk_add_f32 v[70:71], v[70:71], 1.0 op_sel_hi:[1,0]
	global_store_dwordx4 v[58:59], v[62:65], off
	v_rcp_f32_e32 v70, v70
	v_rcp_f32_e32 v71, v71
	v_pk_mul_f32 v[58:59], v[66:67], v[68:69]
	v_pk_fma_f32 v[26:27], v[142:143], v[34:35], v[26:27]
	v_pk_mul_f32 v[54:55], v[54:55], v[58:59]
	v_pk_mul_f32 v[58:59], v[60:61], v[70:71]
	v_pk_fma_f32 v[60:61], v[134:135], v[18:19], v[138:139]
	v_pk_mul_f32 v[56:57], v[56:57], v[58:59]
	v_pk_fma_f32 v[58:59], v[136:137], v[20:21], v[140:141]
	v_pk_fma_f32 v[60:61], v[130:131], v[42:43], v[60:61]
	v_pk_fma_f32 v[58:59], v[132:133], v[44:45], v[58:59]
	v_pk_fma_f32 v[60:61], v[126:127], v[76:77], v[60:61]
	v_pk_fma_f32 v[58:59], v[128:129], v[80:81], v[58:59]
	v_pk_mul_f32 v[62:63], v[60:61], s[30:31] op_sel_hi:[1,0]
	v_pk_mul_f32 v[64:65], v[58:59], s[30:31] op_sel_hi:[1,0]
	v_exp_f32_e32 v62, v62
	v_exp_f32_e32 v63, v63
;     __device__ __forceinline__ void run(const f32x4 (&acc)[2][2][4][2], const Unit& u, int wr, int wc, int fr, int fq, const PG8_LAS unsigned char* sp) const {
;     ...
; #pragma unroll
;             for (int m = 0; m < 4; ++m) {
;                 u32x4 w;
; #pragma unroll
;                 for (int n = 0; n < 2; ++n) {
;                     const f32x4 G0 = acc[ai][0][0][n], G1 = acc[ai][0][1][n], G2 = acc[ai][0][2][n];
;                     const f32x4 Gv = acc[ai][0][m][n], Uv = acc[ai][1][m][n];
;                     const f32x4 g1 = (m == 0) ? S3[n] : (m == 1) ? G0 : (m == 2) ? G1 : G2, g2 = (m == 0) ? S2[n] : (m == 1) ? S3[n] : (m == 2) ? G0 : G1;
;                     f32x2e oh[2];
; #pragma unroll
;                     for (int hq = 0; hq < 2; ++hq) {
;                         const f32x2e g2p = hq ? g2.hi : g2.lo, g1p = hq ? g1.hi : g1.lo, Gp = hq ? Gv.hi : Gv.lo, Up = hq ? Uv.hi : Uv.lo;
;                         const f32x2e w0p = hq ? w0[n].hi : w0[n].lo, w1p = hq ? w1[n].hi : w1[n].lo, w2p = hq ? w2[n].hi : w2[n].lo, bp = hq ? bb[n].hi : bb[n].lo;
;                         const f32x2e y = __builtin_elementwise_fma(w0p, g2p, __builtin_elementwise_fma(w1p, g1p, __builtin_elementwise_fma(w2p, Gp, bp)));
;                         const f32x2e t = y * -1.4426950408889634f;
;                         f32x2e den; den.x = __builtin_amdgcn_exp2f(t.x); den.y = __builtin_amdgcn_exp2f(t.y); den = den + 1.f;
;                         f32x2e r; r.x = __builtin_amdgcn_rcpf(den.x); r.y = __builtin_amdgcn_rcpf(den.y);
;                         oh[hq] = y * r * Up;
;                     }
;                     if (n == 0) { w.x = cvt_pk_bf16(oh[0].x, oh[0].y); w.y = cvt_pk_bf16(oh[1].x, oh[1].y); } else { w.z = cvt_pk_bf16(oh[0].x, oh[0].y); w.w = cvt_pk_bf16(oh[1].x, oh[1].y); }
;                 }
;                 *(u32x4*)(act + (size_t)(rb64 + 4 * fr + m) * dff + ch0) = w;
;             }
; template <class Epi, class Sched, bool ALIGN_EPI = false, bool SP2 = false>
; __device__ __forceinline__ void gemm_phase(PG8_LAS unsigned char* lds, const Gemm g, const Sched& S, const Epi& E) {
;     ...
;         if (!has_next) break;
; #pragma unroll
;         for (int a = 0; a < 2; ++a)
; #pragma unroll
;             for (int b = 0; b < 2; ++b)
; #pragma unroll
;                 for (int m = 0; m < 4; ++m)
; #pragma unroll
	v_exp_f32_e32 v64, v64
	v_exp_f32_e32 v65, v65
	v_cvt_pk_bf16_f32 v54, v54, v55
	v_pk_add_f32 v[62:63], v[62:63], 1.0 op_sel_hi:[1,0]
	v_cvt_pk_bf16_f32 v55, v56, v57
	v_pk_add_f32 v[64:65], v[64:65], 1.0 op_sel_hi:[1,0]
	v_rcp_f32_e32 v62, v62
	v_rcp_f32_e32 v63, v63
	v_rcp_f32_e32 v64, v64
	v_rcp_f32_e32 v65, v65
	v_pk_fma_f32 v[10:11], v[134:135], v[10:11], v[138:139]
	v_pk_mul_f32 v[56:57], v[60:61], v[62:63]
	v_pk_fma_f32 v[12:13], v[136:137], v[12:13], v[140:141]
	v_pk_mul_f32 v[46:47], v[46:47], v[56:57]
	v_pk_mul_f32 v[56:57], v[58:59], v[64:65]
	v_pk_fma_f32 v[58:59], v[150:151], v[30:31], v[154:155]
	v_pk_mul_f32 v[48:49], v[48:49], v[56:57]
	v_cvt_pk_bf16_f32 v56, v46, v47
	v_pk_fma_f32 v[58:59], v[146:147], v[34:35], v[58:59]
	v_cvt_pk_bf16_f32 v57, v48, v49
	v_pk_fma_f32 v[48:49], v[152:153], v[32:33], v[156:157]
	v_pk_fma_f32 v[50:51], v[142:143], v[50:51], v[58:59]
	v_pk_fma_f32 v[48:49], v[148:149], v[36:37], v[48:49]
	v_add_u32_e32 v46, 0x81, v210
	v_pk_fma_f32 v[48:49], v[144:145], v[52:53], v[48:49]
	v_pk_mul_f32 v[52:53], v[50:51], s[30:31] op_sel_hi:[1,0]
	v_pk_mul_f32 v[58:59], v[48:49], s[30:31] op_sel_hi:[1,0]
	v_exp_f32_e32 v52, v52
	v_exp_f32_e32 v53, v53
	v_exp_f32_e32 v58, v58
	v_exp_f32_e32 v59, v59
	v_mad_i64_i32 v[46:47], s[0:1], v46, s69, v[122:123]
	v_pk_add_f32 v[52:53], v[52:53], 1.0 op_sel_hi:[1,0]
	v_pk_add_f32 v[58:59], v[58:59], 1.0 op_sel_hi:[1,0]
	v_rcp_f32_e32 v52, v52
	v_rcp_f32_e32 v53, v53
	v_rcp_f32_e32 v58, v58
	v_rcp_f32_e32 v59, v59
	v_lshl_add_u64 v[46:47], v[46:47], 0, v[124:125]
	global_store_dwordx4 v[46:47], v[54:57], off
	v_pk_mul_f32 v[46:47], v[50:51], v[52:53]
	v_pk_fma_f32 v[10:11], v[130:131], v[14:15], v[10:11]
	v_pk_mul_f32 v[38:39], v[38:39], v[46:47]
	v_pk_mul_f32 v[46:47], v[48:49], v[58:59]
	v_pk_fma_f32 v[48:49], v[134:135], v[14:15], v[138:139]
	v_pk_mul_f32 v[40:41], v[40:41], v[46:47]
	v_pk_fma_f32 v[46:47], v[136:137], v[16:17], v[140:141]
	v_pk_fma_f32 v[48:49], v[130:131], v[18:19], v[48:49]
	v_pk_fma_f32 v[46:47], v[132:133], v[20:21], v[46:47]
	v_pk_fma_f32 v[42:43], v[126:127], v[42:43], v[48:49]
	v_pk_fma_f32 v[44:45], v[128:129], v[44:45], v[46:47]
	v_pk_mul_f32 v[46:47], v[42:43], s[30:31] op_sel_hi:[1,0]
	v_pk_mul_f32 v[48:49], v[44:45], s[30:31] op_sel_hi:[1,0]
	v_exp_f32_e32 v46, v46
	v_exp_f32_e32 v47, v47
	v_exp_f32_e32 v48, v48
	v_exp_f32_e32 v49, v49
	v_cvt_pk_bf16_f32 v38, v38, v39
	v_pk_add_f32 v[46:47], v[46:47], 1.0 op_sel_hi:[1,0]
	v_cvt_pk_bf16_f32 v39, v40, v41
	v_pk_add_f32 v[48:49], v[48:49], 1.0 op_sel_hi:[1,0]
	v_rcp_f32_e32 v46, v46
	v_rcp_f32_e32 v47, v47
	v_rcp_f32_e32 v48, v48
	v_rcp_f32_e32 v49, v49
	v_pk_fma_f32 v[12:13], v[132:133], v[16:17], v[12:13]
	v_pk_mul_f32 v[40:41], v[42:43], v[46:47]
	v_pk_fma_f32 v[10:11], v[126:127], v[18:19], v[10:11]
	v_pk_mul_f32 v[22:23], v[22:23], v[40:41]
	v_pk_mul_f32 v[40:41], v[44:45], v[48:49]
	v_pk_fma_f32 v[12:13], v[128:129], v[20:21], v[12:13]
	v_pk_mul_f32 v[24:25], v[24:25], v[40:41]
	v_cvt_pk_bf16_f32 v40, v22, v23
	v_pk_mul_f32 v[14:15], v[10:11], s[30:31] op_sel_hi:[1,0]
	v_cvt_pk_bf16_f32 v41, v24, v25
	v_pk_fma_f32 v[24:25], v[152:153], v[28:29], v[156:157]
	v_pk_mul_f32 v[28:29], v[26:27], s[30:31] op_sel_hi:[1,0]
	v_pk_fma_f32 v[24:25], v[148:149], v[32:33], v[24:25]
	v_exp_f32_e32 v28, v28
	v_pk_fma_f32 v[24:25], v[144:145], v[36:37], v[24:25]
	v_exp_f32_e32 v29, v29
	v_pk_mul_f32 v[30:31], v[24:25], s[30:31] op_sel_hi:[1,0]
	v_exp_f32_e32 v14, v14
	v_exp_f32_e32 v30, v30
	v_exp_f32_e32 v31, v31
	v_exp_f32_e32 v15, v15
	v_pk_mul_f32 v[16:17], v[12:13], s[30:31] op_sel_hi:[1,0]
	v_pk_add_f32 v[28:29], v[28:29], 1.0 op_sel_hi:[1,0]
	v_exp_f32_e32 v16, v16
	v_exp_f32_e32 v17, v17
	v_rcp_f32_e32 v28, v28
	v_rcp_f32_e32 v29, v29
	v_pk_add_f32 v[30:31], v[30:31], 1.0 op_sel_hi:[1,0]
	v_add_u32_e32 v22, 0x82, v210
	v_rcp_f32_e32 v30, v30
	v_rcp_f32_e32 v31, v31
	v_mad_i64_i32 v[22:23], s[0:1], v22, s69, v[122:123]
	v_pk_add_f32 v[14:15], v[14:15], 1.0 op_sel_hi:[1,0]
	v_lshl_add_u64 v[22:23], v[22:23], 0, v[124:125]
	v_rcp_f32_e32 v14, v14
	v_rcp_f32_e32 v15, v15
	v_pk_add_f32 v[16:17], v[16:17], 1.0 op_sel_hi:[1,0]
	global_store_dwordx4 v[22:23], v[38:41], off
	v_pk_mul_f32 v[22:23], v[26:27], v[28:29]
	v_rcp_f32_e32 v16, v16
	v_rcp_f32_e32 v17, v17
	v_pk_mul_f32 v[6:7], v[6:7], v[22:23]
	v_pk_mul_f32 v[22:23], v[24:25], v[30:31]
	v_cvt_pk_bf16_f32 v6, v6, v7
	s_and_b64 vcc, exec, s[12:13]
	v_pk_mul_f32 v[8:9], v[8:9], v[22:23]
	s_mov_b64 s[12:13], -1
	v_cvt_pk_bf16_f32 v7, v8, v9
	v_pk_mul_f32 v[8:9], v[10:11], v[14:15]
	s_nop 0
	v_pk_mul_f32 v[2:3], v[2:3], v[8:9]
	v_pk_mul_f32 v[8:9], v[12:13], v[16:17]
	s_nop 0
	v_pk_mul_f32 v[4:5], v[4:5], v[8:9]
	v_cvt_pk_bf16_f32 v8, v2, v3
	v_add_u32_e32 v2, 0x83, v210
	v_mad_i64_i32 v[2:3], s[0:1], v2, s69, v[122:123]
	v_lshl_add_u64 v[2:3], v[2:3], 0, v[124:125]
	v_cvt_pk_bf16_f32 v9, v4, v5
	global_store_dwordx4 v[2:3], v[6:9], off
	s_cbranch_vccnz .LBB0_1838
	s_andn2_b64 vcc, exec, s[26:27]
	s_cbranch_vccnz .LBB0_1837
	s_mov_b32 s98, 1
	s_branch .LBB0_1837

; #define PG8_STAGE(bufoff, gbase, voff) do { _Pragma("unroll") for (int _i = 0; _i < 2; ++_i) \
;         __builtin_amdgcn_global_load_lds((const unsigned*)((const char*)(gbase) + (voff)[_i]), (PG8_LAS unsigned*)(lds + (bufoff) + ldsw + _i * 8192), 16, 0, 0); } while (0)
; #define PG8_LDA(dst, b, h) do { _Pragma("unroll") for (int m = 0; m < 4; ++m) _Pragma("unroll") for (int k = 0; k < 2; ++k) dst[m][k] = *(const PG8_LAS bf16x8*)(lds + PG8_SA(b, h) + aoff + m * 2048 + k * 1024); } while (0)
; #define PG8_LDB(dst, b, h) do { _Pragma("unroll") for (int n = 0; n < 2; ++n) _Pragma("unroll") for (int k = 0; k < 2; ++k) dst[n][k] = *(const PG8_LAS bf16x8*)(lds + PG8_SB(b, h) + boff + n * 2048 + k * 1024); } while (0)
; #define PG8_MMA(ai, bj, At, Bt) do { __builtin_amdgcn_s_setprio(1); _Pragma("unroll") for (int m = 0; m < 4; ++m) _Pragma("unroll") for (int n = 0; n < 2; ++n) _Pragma("unroll") for (int k = 0; k < 2; ++k) \
;         acc[ai][bj][m][n] = __builtin_amdgcn_mfma_f32_16x16x32_bf16(Bt[n][k], At[m][k], acc[ai][bj][m][n], 0, 0, 0); __builtin_amdgcn_s_setprio(0); } while (0)
; template <class Epi, class Sched, bool ALIGN_EPI = false, bool SP2 = false>
; __device__ __forceinline__ void gemm_phase(PG8_LAS unsigned char* lds, const Gemm g, const Sched& S, const Epi& E) {
;     ...
;         for (int t = 0; t < nt; t += 2) {
;             const bool last = (t == nt - 2);
;             const char* a1 = cA + (size_t)(t + 1) * kstep;
;             const char* a2 = last ? nA : cA + (size_t)(t + 2) * kstep; const char* b2 = last ? nB : cB + (size_t)(t + 2) * kstep;
;             const char* a3 = a2 + kstep; const char* b3 = b2 + kstep;
;             if (last && has_next) S.a_ready(nxt);
;             if constexpr (SP2) {
;             PG8_LDB(B0, 0, 0); PG8_LDB(B1, 0, 1); PG8_SCHED; PG8_LDA(At, 0, 0); PG8_STAGE(PG8_SA(1, 1), a1 + hstepA, voffA);
;             PG8_WAIT_V(8); PG8_WAIT_L(0); PG8_BAR; PG8_MMA(0, 0, At, B0); PG8_MMA(0, 1, At, B1); PG8_BAR; PG8_SCHED;
;     ...
; #pragma unroll
;         for (int a = 0; a < 2; ++a)
; #pragma unroll
;             for (int b = 0; b < 2; ++b)
; #pragma unroll
;                 for (int m = 0; m < 4; ++m)
; #pragma unroll
;                     for (int n = 0; n < 2; ++n) acc[a][b][m][n] = (f32x4){0.f, 0.f, 0.f, 0.f};
;         cur = nxt; cA = nA; cB = nB; ++ui;
;         if constexpr (ALIGN_EPI) { if (wr == 1) PG8_BAR; }
.LBB0_1936:
	s_add_u32 s4, s42, 0x100
	v_mov_b32_e32 v2, 0
	s_addc_u32 s5, s43, 0
	s_mov_b32 s35, -2
	v_mov_b32_e32 v3, v2
	v_mov_b32_e32 v4, v2
	v_mov_b32_e32 v5, v2
	v_mov_b32_e32 v6, v2
	v_mov_b32_e32 v7, v2
	v_mov_b32_e32 v8, v2
	v_mov_b32_e32 v9, v2
	v_mov_b32_e32 v18, v2
	v_mov_b32_e32 v19, v2
	v_mov_b32_e32 v20, v2
	v_mov_b32_e32 v21, v2
	v_mov_b32_e32 v22, v2
	v_mov_b32_e32 v23, v2
	v_mov_b32_e32 v24, v2
	v_mov_b32_e32 v25, v2
	v_mov_b32_e32 v34, v2
	v_mov_b32_e32 v35, v2
	v_mov_b32_e32 v36, v2
	v_mov_b32_e32 v37, v2
	v_mov_b32_e32 v38, v2
	v_mov_b32_e32 v39, v2
	v_mov_b32_e32 v40, v2
	v_mov_b32_e32 v41, v2
	v_mov_b32_e32 v50, v2
	v_mov_b32_e32 v51, v2
	v_mov_b32_e32 v52, v2
	v_mov_b32_e32 v53, v2
	v_mov_b32_e32 v54, v2
	v_mov_b32_e32 v55, v2
	v_mov_b32_e32 v56, v2
	v_mov_b32_e32 v57, v2
	v_mov_b32_e32 v10, v2
	v_mov_b32_e32 v11, v2
	v_mov_b32_e32 v12, v2
	v_mov_b32_e32 v13, v2
	v_mov_b32_e32 v14, v2
	v_mov_b32_e32 v15, v2
	v_mov_b32_e32 v16, v2
	v_mov_b32_e32 v17, v2
	v_mov_b32_e32 v26, v2
	v_mov_b32_e32 v27, v2
	v_mov_b32_e32 v28, v2
	v_mov_b32_e32 v29, v2
	v_mov_b32_e32 v30, v2
	v_mov_b32_e32 v31, v2
	v_mov_b32_e32 v32, v2
	v_mov_b32_e32 v33, v2
	v_mov_b32_e32 v42, v2
	v_mov_b32_e32 v43, v2
	v_mov_b32_e32 v44, v2
	v_mov_b32_e32 v45, v2
	v_mov_b32_e32 v46, v2
	v_mov_b32_e32 v47, v2
	v_mov_b32_e32 v48, v2
	v_mov_b32_e32 v49, v2
	v_mov_b32_e32 v58, v2
	v_mov_b32_e32 v59, v2
	v_mov_b32_e32 v60, v2
	v_mov_b32_e32 v61, v2
	v_mov_b32_e32 v62, v2
	v_mov_b32_e32 v63, v2
	v_mov_b32_e32 v64, v2
	v_mov_b32_e32 v65, v2
	v_mov_b32_e32 v66, v2
	v_mov_b32_e32 v67, v2
	v_mov_b32_e32 v68, v2
	v_mov_b32_e32 v69, v2
	v_mov_b32_e32 v70, v2
	v_mov_b32_e32 v71, v2
	v_mov_b32_e32 v72, v2
	v_mov_b32_e32 v73, v2
	v_mov_b32_e32 v82, v2
	v_mov_b32_e32 v83, v2
	v_mov_b32_e32 v84, v2
	v_mov_b32_e32 v85, v2
	v_mov_b32_e32 v86, v2
	v_mov_b32_e32 v87, v2
	v_mov_b32_e32 v88, v2
	v_mov_b32_e32 v89, v2
	v_mov_b32_e32 v98, v2
	v_mov_b32_e32 v99, v2
	v_mov_b32_e32 v100, v2
	v_mov_b32_e32 v101, v2
	v_mov_b32_e32 v102, v2
	v_mov_b32_e32 v103, v2
	v_mov_b32_e32 v104, v2
	v_mov_b32_e32 v105, v2
	v_mov_b32_e32 v114, v2
	v_mov_b32_e32 v115, v2
	v_mov_b32_e32 v116, v2
	v_mov_b32_e32 v117, v2
	v_mov_b32_e32 v118, v2
	v_mov_b32_e32 v119, v2
	v_mov_b32_e32 v120, v2
	v_mov_b32_e32 v121, v2
	v_mov_b32_e32 v74, v2
	v_mov_b32_e32 v75, v2
	v_mov_b32_e32 v76, v2
	v_mov_b32_e32 v77, v2
	v_mov_b32_e32 v78, v2
	v_mov_b32_e32 v79, v2
	v_mov_b32_e32 v80, v2
	v_mov_b32_e32 v81, v2
	v_mov_b32_e32 v90, v2
	v_mov_b32_e32 v91, v2
	v_mov_b32_e32 v92, v2
	v_mov_b32_e32 v93, v2
	v_mov_b32_e32 v94, v2
	v_mov_b32_e32 v95, v2
	v_mov_b32_e32 v96, v2
	v_mov_b32_e32 v97, v2
	v_mov_b32_e32 v106, v2
	v_mov_b32_e32 v107, v2
	v_mov_b32_e32 v108, v2
	v_mov_b32_e32 v109, v2
	v_mov_b32_e32 v110, v2
	v_mov_b32_e32 v111, v2
	v_mov_b32_e32 v112, v2
	v_mov_b32_e32 v113, v2
	v_mov_b32_e32 v122, v2
	v_mov_b32_e32 v123, v2
	v_mov_b32_e32 v124, v2
	v_mov_b32_e32 v125, v2
	v_mov_b32_e32 v126, v2
	v_mov_b32_e32 v127, v2
	v_mov_b32_e32 v128, v2
	v_mov_b32_e32 v129, v2
	s_cmp_eq_u32 s98, 1
	s_cbranch_scc0 .Ldefer_7
	s_barrier
	s_mov_b32 s98, 0
.Ldefer_7:
.LBB0_1937:
	ds_read_b128 v[130:133], v189
	ds_read_b128 v[134:137], v189 offset:1024
	ds_read_b128 v[138:141], v189 offset:2048
	ds_read_b128 v[142:145], v189 offset:3072
	ds_read_b128 v[168:171], v190
	ds_read_b128 v[194:197], v190 offset:1024
	ds_read_b128 v[198:201], v190 offset:2048
	ds_read_b128 v[202:205], v190 offset:3072
	s_add_u32 s42, s40, 0x100
	s_addc_u32 s43, s41, 0
	s_cmp_eq_u32 s35, 40
	s_cselect_b32 s47, s11, s43
	s_cselect_b32 s46, s10, s42
	s_cselect_b32 s45, s37, s5
	s_cselect_b32 s44, s36, s4
	v_lshl_add_u64 v[238:239], s[40:41], 0, v[160:161]
	s_add_i32 m0, s48, 0xc000
	ds_read_b128 v[206:209], v191
	ds_read_b128 v[210:213], v191 offset:1024
	ds_read_b128 v[214:217], v191 offset:2048
	ds_read_b128 v[218:221], v191 offset:3072
	ds_read_b128 v[222:225], v191 offset:4096
	ds_read_b128 v[226:229], v191 offset:5120
	ds_read_b128 v[230:233], v191 offset:6144
	ds_read_b128 v[234:237], v191 offset:7168
	global_load_lds_dwordx4 v[238:239], off
	v_lshl_add_u64 v[238:239], s[40:41], 0, v[162:163]
	s_add_i32 m0, s48, 0xe000
	s_nop 0
	global_load_lds_dwordx4 v[238:239], off
	s_waitcnt vmcnt(8)
	s_waitcnt lgkmcnt(0)
	s_setprio 1
	s_barrier
	v_mfma_f32_16x16x32_bf16 v[126:129], v[130:133], v[206:209], v[126:129]
	v_mfma_f32_16x16x32_bf16 v[122:125], v[138:141], v[206:209], v[122:125]
	v_mfma_f32_16x16x32_bf16 v[110:113], v[130:133], v[214:217], v[110:113]
	v_mfma_f32_16x16x32_bf16 v[106:109], v[138:141], v[214:217], v[106:109]
	v_mfma_f32_16x16x32_bf16 v[94:97], v[130:133], v[222:225], v[94:97]
	v_mfma_f32_16x16x32_bf16 v[90:93], v[138:141], v[222:225], v[90:93]
	v_mfma_f32_16x16x32_bf16 v[78:81], v[130:133], v[230:233], v[78:81]
	v_mfma_f32_16x16x32_bf16 v[74:77], v[138:141], v[230:233], v[74:77]
	v_mfma_f32_16x16x32_bf16 v[126:129], v[134:137], v[210:213], v[126:129]
	v_mfma_f32_16x16x32_bf16 v[122:125], v[142:145], v[210:213], v[122:125]
	v_mfma_f32_16x16x32_bf16 v[110:113], v[134:137], v[218:221], v[110:113]
	v_mfma_f32_16x16x32_bf16 v[106:109], v[142:145], v[218:221], v[106:109]
	v_mfma_f32_16x16x32_bf16 v[94:97], v[134:137], v[226:229], v[94:97]
	v_mfma_f32_16x16x32_bf16 v[90:93], v[142:145], v[226:229], v[90:93]
	v_mfma_f32_16x16x32_bf16 v[78:81], v[134:137], v[234:237], v[78:81]
	v_mfma_f32_16x16x32_bf16 v[74:77], v[142:145], v[234:237], v[74:77]
	s_setprio 0
	s_setprio 1
	v_mfma_f32_16x16x32_bf16 v[118:121], v[168:171], v[206:209], v[118:121]
	v_mfma_f32_16x16x32_bf16 v[114:117], v[198:201], v[206:209], v[114:117]
	v_mfma_f32_16x16x32_bf16 v[102:105], v[168:171], v[214:217], v[102:105]
	v_mfma_f32_16x16x32_bf16 v[98:101], v[198:201], v[214:217], v[98:101]
	v_mfma_f32_16x16x32_bf16 v[86:89], v[168:171], v[222:225], v[86:89]
	v_mfma_f32_16x16x32_bf16 v[82:85], v[198:201], v[222:225], v[82:85]
	v_mfma_f32_16x16x32_bf16 v[70:73], v[168:171], v[230:233], v[70:73]
	v_mfma_f32_16x16x32_bf16 v[66:69], v[198:201], v[230:233], v[66:69]
	v_mfma_f32_16x16x32_bf16 v[118:121], v[194:197], v[210:213], v[118:121]
	v_mfma_f32_16x16x32_bf16 v[114:117], v[202:205], v[210:213], v[114:117]
	v_mfma_f32_16x16x32_bf16 v[102:105], v[194:197], v[218:221], v[102:105]
	v_mfma_f32_16x16x32_bf16 v[98:101], v[202:205], v[218:221], v[98:101]
	v_mfma_f32_16x16x32_bf16 v[86:89], v[194:197], v[226:229], v[86:89]
	v_mfma_f32_16x16x32_bf16 v[82:85], v[202:205], v[226:229], v[82:85]
	v_mfma_f32_16x16x32_bf16 v[70:73], v[194:197], v[234:237], v[70:73]
	v_mfma_f32_16x16x32_bf16 v[66:69], v[202:205], v[234:237], v[66:69]
	s_setprio 0
	s_barrier
; #define PG8_STAGE(bufoff, gbase, voff) do { _Pragma("unroll") for (int _i = 0; _i < 2; ++_i) \
;         __builtin_amdgcn_global_load_lds((const unsigned*)((const char*)(gbase) + (voff)[_i]), (PG8_LAS unsigned*)(lds + (bufoff) + ldsw + _i * 8192), 16, 0, 0); } while (0)
; #define PG8_LDA(dst, b, h) do { _Pragma("unroll") for (int m = 0; m < 4; ++m) _Pragma("unroll") for (int k = 0; k < 2; ++k) dst[m][k] = *(const PG8_LAS bf16x8*)(lds + PG8_SA(b, h) + aoff + m * 2048 + k * 1024); } while (0)
; #define PG8_LDB(dst, b, h) do { _Pragma("unroll") for (int n = 0; n < 2; ++n) _Pragma("unroll") for (int k = 0; k < 2; ++k) dst[n][k] = *(const PG8_LAS bf16x8*)(lds + PG8_SB(b, h) + boff + n * 2048 + k * 1024); } while (0)
; #define PG8_MMA(ai, bj, At, Bt) do { __builtin_amdgcn_s_setprio(1); _Pragma("unroll") for (int m = 0; m < 4; ++m) _Pragma("unroll") for (int n = 0; n < 2; ++n) _Pragma("unroll") for (int k = 0; k < 2; ++k) \
;         acc[ai][bj][m][n] = __builtin_amdgcn_mfma_f32_16x16x32_bf16(Bt[n][k], At[m][k], acc[ai][bj][m][n], 0, 0, 0); __builtin_amdgcn_s_setprio(0); } while (0)
; #define PG8_WAIT_V(n) asm volatile("s_waitcnt vmcnt(" #n ")" ::: "memory")
; #define PG8_WAIT_L(n) asm volatile("s_waitcnt lgkmcnt(" #n ")" ::: "memory")
; #define PG8_BAR __builtin_amdgcn_s_barrier()
; #define PG8_SCHED __builtin_amdgcn_sched_barrier(0)
; template <class Epi, class Sched, bool ALIGN_EPI = false, bool SP2 = false>
; __device__ __forceinline__ void gemm_phase(PG8_LAS unsigned char* lds, const Gemm g, const Sched& S, const Epi& E) {
;     ...
;             PG8_LDA(At, 0, 1); PG8_STAGE(PG8_SB(0, 0), b2, voffB); PG8_STAGE(PG8_SB(0, 1), b2 + hstepB, voffB); PG8_STAGE(PG8_SA(0, 0), a2, voffA);
;             PG8_WAIT_V(8); PG8_WAIT_L(0); PG8_BAR; PG8_MMA(1, 0, At, B0); PG8_MMA(1, 1, At, B1); PG8_BAR; PG8_SCHED;
;             PG8_LDB(B0, 1, 0); PG8_LDB(B1, 1, 1); PG8_SCHED; PG8_LDA(At, 1, 0); PG8_STAGE(PG8_SA(0, 1), a2 + hstepA, voffA);
;             PG8_WAIT_V(8); PG8_WAIT_L(0); PG8_BAR; PG8_MMA(0, 0, At, B0); PG8_MMA(0, 1, At, B1); PG8_BAR; PG8_SCHED;
	s_add_i32 s0, s66, s39
	v_lshl_add_u64 v[238:239], s[44:45], 0, v[146:147]
	s_mov_b32 m0, s0
	ds_read_b128 v[206:209], v191 offset:16384
	ds_read_b128 v[210:213], v191 offset:17408
	ds_read_b128 v[214:217], v191 offset:18432
	ds_read_b128 v[218:221], v191 offset:19456
	ds_read_b128 v[222:225], v191 offset:20480
	ds_read_b128 v[226:229], v191 offset:21504
	ds_read_b128 v[230:233], v191 offset:22528
	ds_read_b128 v[234:237], v191 offset:23552
	global_load_lds_dwordx4 v[238:239], off
	s_add_i32 m0, s0, 0x2000
	s_add_u32 s0, s44, 0xb0000
	v_lshl_add_u64 v[240:241], s[44:45], 0, v[152:153]
	s_addc_u32 s1, s45, 0
	s_add_i32 s2, s67, s39
	global_load_lds_dwordx4 v[240:241], off
	v_lshl_add_u64 v[242:243], s[0:1], 0, v[146:147]
	s_mov_b32 m0, s2
	v_lshl_add_u64 v[244:245], s[46:47], 0, v[150:151]
	global_load_lds_dwordx4 v[242:243], off
	v_lshl_add_u64 v[242:243], s[0:1], 0, v[152:153]
	s_add_i32 m0, s2, 0x2000
	s_nop 0
	global_load_lds_dwordx4 v[242:243], off
	v_lshl_add_u64 v[242:243], s[46:47], 0, v[148:149]
	s_mov_b32 m0, s48
	s_nop 0
	global_load_lds_dwordx4 v[242:243], off
	s_mov_b32 m0, s49
	s_nop 0
	global_load_lds_dwordx4 v[244:245], off
	s_waitcnt vmcnt(8)
	s_waitcnt lgkmcnt(0)
	s_setprio 1
	s_barrier
	v_mfma_f32_16x16x32_bf16 v[62:65], v[130:133], v[206:209], v[62:65]
	v_mfma_f32_16x16x32_bf16 v[58:61], v[138:141], v[206:209], v[58:61]
	v_mfma_f32_16x16x32_bf16 v[46:49], v[130:133], v[214:217], v[46:49]
	v_mfma_f32_16x16x32_bf16 v[42:45], v[138:141], v[214:217], v[42:45]
	v_mfma_f32_16x16x32_bf16 v[30:33], v[130:133], v[222:225], v[30:33]
	v_mfma_f32_16x16x32_bf16 v[26:29], v[138:141], v[222:225], v[26:29]
	v_mfma_f32_16x16x32_bf16 v[14:17], v[130:133], v[230:233], v[14:17]
	v_mfma_f32_16x16x32_bf16 v[10:13], v[138:141], v[230:233], v[10:13]
	v_mfma_f32_16x16x32_bf16 v[62:65], v[134:137], v[210:213], v[62:65]
	v_mfma_f32_16x16x32_bf16 v[58:61], v[142:145], v[210:213], v[58:61]
	v_mfma_f32_16x16x32_bf16 v[46:49], v[134:137], v[218:221], v[46:49]
	v_mfma_f32_16x16x32_bf16 v[42:45], v[142:145], v[218:221], v[42:45]
	v_mfma_f32_16x16x32_bf16 v[30:33], v[134:137], v[226:229], v[30:33]
	v_mfma_f32_16x16x32_bf16 v[26:29], v[142:145], v[226:229], v[26:29]
	v_mfma_f32_16x16x32_bf16 v[14:17], v[134:137], v[234:237], v[14:17]
	v_mfma_f32_16x16x32_bf16 v[10:13], v[142:145], v[234:237], v[10:13]
	s_setprio 0
	s_setprio 1
	v_mfma_f32_16x16x32_bf16 v[54:57], v[168:171], v[206:209], v[54:57]
	v_mfma_f32_16x16x32_bf16 v[50:53], v[198:201], v[206:209], v[50:53]
	v_mfma_f32_16x16x32_bf16 v[38:41], v[168:171], v[214:217], v[38:41]
	v_mfma_f32_16x16x32_bf16 v[34:37], v[198:201], v[214:217], v[34:37]
	v_mfma_f32_16x16x32_bf16 v[22:25], v[168:171], v[222:225], v[22:25]
	v_mfma_f32_16x16x32_bf16 v[18:21], v[198:201], v[222:225], v[18:21]
	v_mfma_f32_16x16x32_bf16 v[6:9], v[168:171], v[230:233], v[6:9]
	v_mfma_f32_16x16x32_bf16 v[2:5], v[198:201], v[230:233], v[2:5]
	v_mfma_f32_16x16x32_bf16 v[54:57], v[194:197], v[210:213], v[54:57]
	v_mfma_f32_16x16x32_bf16 v[50:53], v[202:205], v[210:213], v[50:53]
	v_mfma_f32_16x16x32_bf16 v[38:41], v[194:197], v[218:221], v[38:41]
	v_mfma_f32_16x16x32_bf16 v[34:37], v[202:205], v[218:221], v[34:37]
	v_mfma_f32_16x16x32_bf16 v[22:25], v[194:197], v[226:229], v[22:25]
	v_mfma_f32_16x16x32_bf16 v[18:21], v[202:205], v[226:229], v[18:21]
	v_mfma_f32_16x16x32_bf16 v[6:9], v[194:197], v[234:237], v[6:9]
	v_mfma_f32_16x16x32_bf16 v[2:5], v[202:205], v[234:237], v[2:5]
	s_setprio 0
	s_barrier
	ds_read_b128 v[130:133], v192
	ds_read_b128 v[134:137], v192 offset:1024
	ds_read_b128 v[138:141], v192 offset:2048
	ds_read_b128 v[142:145], v192 offset:3072
	ds_read_b128 v[168:171], v193
	ds_read_b128 v[194:197], v193 offset:1024
	ds_read_b128 v[198:201], v193 offset:2048
	ds_read_b128 v[202:205], v193 offset:3072
	s_add_u32 s0, s46, 0xb0000
	s_addc_u32 s1, s47, 0
	s_mov_b32 m0, s50
	v_lshl_add_u64 v[246:247], s[0:1], 0, v[148:149]
	ds_read_b128 v[206:209], v191 offset:32768
	ds_read_b128 v[210:213], v191 offset:33792
	ds_read_b128 v[214:217], v191 offset:34816
	ds_read_b128 v[218:221], v191 offset:35840
	ds_read_b128 v[222:225], v191 offset:36864
	ds_read_b128 v[226:229], v191 offset:37888
	ds_read_b128 v[230:233], v191 offset:38912
	ds_read_b128 v[234:237], v191 offset:39936
	global_load_lds_dwordx4 v[246:247], off
	v_lshl_add_u64 v[246:247], s[0:1], 0, v[150:151]
	s_mov_b32 m0, s51
	s_nop 0
	global_load_lds_dwordx4 v[246:247], off
	s_waitcnt vmcnt(8)
	s_waitcnt lgkmcnt(0)
	s_setprio 1
	s_barrier
; #define PG8_STAGE(bufoff, gbase, voff) do { _Pragma("unroll") for (int _i = 0; _i < 2; ++_i) \
;         __builtin_amdgcn_global_load_lds((const unsigned*)((const char*)(gbase) + (voff)[_i]), (PG8_LAS unsigned*)(lds + (bufoff) + ldsw + _i * 8192), 16, 0, 0); } while (0)
; #define PG8_WAIT_V(n) asm volatile("s_waitcnt vmcnt(" #n ")" ::: "memory")
; #define PG8_WAIT_L(n) asm volatile("s_waitcnt lgkmcnt(" #n ")" ::: "memory")
; template <class Epi, class Sched, bool ALIGN_EPI = false, bool SP2 = false>
; __device__ __forceinline__ void gemm_phase(PG8_LAS unsigned char* lds, const Gemm g, const Sched& S, const Epi& E) {
;     ...
;             PG8_WAIT_V(8); PG8_WAIT_L(0); PG8_BAR; PG8_MMA(0, 0, At, B0); PG8_MMA(0, 1, At, B1); PG8_BAR; PG8_SCHED;
;             PG8_LDA(At, 1, 1); PG8_STAGE(PG8_SB(1, 0), b3, voffB); PG8_STAGE(PG8_SB(1, 1), b3 + hstepB, voffB); PG8_STAGE(PG8_SA(1, 0), a3, voffA);
;             PG8_WAIT_V(8); PG8_WAIT_L(0); PG8_BAR; PG8_MMA(1, 0, At, B0); PG8_MMA(1, 1, At, B1); PG8_BAR; PG8_SCHED;
;             } else {
;             PG8_LDB(B0, 0, 0); PG8_SCHED; PG8_LDA(At, 0, 0); PG8_STAGE(PG8_SA(1, 1), a1 + hstepA, voffA);
;             PG8_WAIT_L(8); PG8_BAR; PG8_WAIT_L(0); PG8_MMA(0, 0, At, B0); PG8_BAR; PG8_SCHED;
;             PG8_LDB(B1, 0, 1); PG8_STAGE(PG8_SB(0, 0), b2, voffB);
;             PG8_BAR; PG8_WAIT_L(0); PG8_MMA(0, 1, At, B1); PG8_BAR;
;             PG8_LDA(At, 0, 1); PG8_STAGE(PG8_SA(0, 0), a2, voffA);
;             PG8_BAR; PG8_WAIT_L(0); PG8_MMA(1, 0, At, B0); PG8_BAR; PG8_SCHED;
;             PG8_STAGE(PG8_SB(0, 1), b2 + hstepB, voffB);
;             PG8_WAIT_V(6); PG8_BAR; PG8_MMA(1, 1, At, B1); PG8_BAR;
;             PG8_LDB(B0, 1, 0); PG8_SCHED; PG8_LDA(At, 1, 0); PG8_STAGE(PG8_SA(0, 1), a2 + hstepA, voffA);
;             PG8_WAIT_L(8); PG8_BAR; PG8_WAIT_L(0); PG8_MMA(0, 0, At, B0); PG8_BAR; PG8_SCHED;
;             PG8_LDB(B1, 1, 1); PG8_STAGE(PG8_SB(1, 0), b3, voffB);
;             PG8_BAR; PG8_WAIT_L(0); PG8_MMA(0, 1, At, B1); PG8_BAR;
;             PG8_LDA(At, 1, 1); PG8_STAGE(PG8_SA(1, 0), a3, voffA);
;             PG8_BAR; PG8_WAIT_L(0); PG8_MMA(1, 0, At, B0); PG8_BAR; PG8_SCHED;
;             PG8_STAGE(PG8_SB(1, 1), b3 + hstepB, voffB);
;             PG8_WAIT_V(6); PG8_BAR; PG8_MMA(1, 1, At, B1); PG8_BAR;
;             }
;         }
;         if constexpr (ALIGN_EPI) { if (wr == 0) PG8_BAR; }
	v_mfma_f32_16x16x32_bf16 v[126:129], v[130:133], v[206:209], v[126:129]
	v_mfma_f32_16x16x32_bf16 v[122:125], v[138:141], v[206:209], v[122:125]
	v_mfma_f32_16x16x32_bf16 v[110:113], v[130:133], v[214:217], v[110:113]
	v_mfma_f32_16x16x32_bf16 v[106:109], v[138:141], v[214:217], v[106:109]
	v_mfma_f32_16x16x32_bf16 v[94:97], v[130:133], v[222:225], v[94:97]
	v_mfma_f32_16x16x32_bf16 v[90:93], v[138:141], v[222:225], v[90:93]
	v_mfma_f32_16x16x32_bf16 v[78:81], v[130:133], v[230:233], v[78:81]
	v_mfma_f32_16x16x32_bf16 v[74:77], v[138:141], v[230:233], v[74:77]
	v_mfma_f32_16x16x32_bf16 v[126:129], v[134:137], v[210:213], v[126:129]
	v_mfma_f32_16x16x32_bf16 v[122:125], v[142:145], v[210:213], v[122:125]
	v_mfma_f32_16x16x32_bf16 v[110:113], v[134:137], v[218:221], v[110:113]
	v_mfma_f32_16x16x32_bf16 v[106:109], v[142:145], v[218:221], v[106:109]
	v_mfma_f32_16x16x32_bf16 v[94:97], v[134:137], v[226:229], v[94:97]
	v_mfma_f32_16x16x32_bf16 v[90:93], v[142:145], v[226:229], v[90:93]
	v_mfma_f32_16x16x32_bf16 v[78:81], v[134:137], v[234:237], v[78:81]
	v_mfma_f32_16x16x32_bf16 v[74:77], v[142:145], v[234:237], v[74:77]
	s_setprio 0
	s_setprio 1
	v_mfma_f32_16x16x32_bf16 v[118:121], v[168:171], v[206:209], v[118:121]
	v_mfma_f32_16x16x32_bf16 v[114:117], v[198:201], v[206:209], v[114:117]
	v_mfma_f32_16x16x32_bf16 v[102:105], v[168:171], v[214:217], v[102:105]
	v_mfma_f32_16x16x32_bf16 v[98:101], v[198:201], v[214:217], v[98:101]
	v_mfma_f32_16x16x32_bf16 v[86:89], v[168:171], v[222:225], v[86:89]
	v_mfma_f32_16x16x32_bf16 v[82:85], v[198:201], v[222:225], v[82:85]
	v_mfma_f32_16x16x32_bf16 v[70:73], v[168:171], v[230:233], v[70:73]
	v_mfma_f32_16x16x32_bf16 v[66:69], v[198:201], v[230:233], v[66:69]
	v_mfma_f32_16x16x32_bf16 v[118:121], v[194:197], v[210:213], v[118:121]
	v_mfma_f32_16x16x32_bf16 v[114:117], v[202:205], v[210:213], v[114:117]
	v_mfma_f32_16x16x32_bf16 v[102:105], v[194:197], v[218:221], v[102:105]
	v_mfma_f32_16x16x32_bf16 v[98:101], v[202:205], v[218:221], v[98:101]
	v_mfma_f32_16x16x32_bf16 v[86:89], v[194:197], v[226:229], v[86:89]
	v_mfma_f32_16x16x32_bf16 v[82:85], v[202:205], v[226:229], v[82:85]
	v_mfma_f32_16x16x32_bf16 v[70:73], v[194:197], v[234:237], v[70:73]
	v_mfma_f32_16x16x32_bf16 v[66:69], v[202:205], v[234:237], v[66:69]
	s_setprio 0
	s_barrier
	s_add_i32 s0, s68, s39
	v_lshl_add_u64 v[238:239], v[238:239], 0, s[12:13]
	s_mov_b32 m0, s0
	ds_read_b128 v[206:209], v191 offset:49152
	ds_read_b128 v[210:213], v191 offset:50176
	ds_read_b128 v[214:217], v191 offset:51200
	ds_read_b128 v[218:221], v191 offset:52224
	ds_read_b128 v[222:225], v191 offset:53248
	ds_read_b128 v[226:229], v191 offset:54272
	ds_read_b128 v[230:233], v191 offset:55296
	ds_read_b128 v[234:237], v191 offset:56320
	global_load_lds_dwordx4 v[238:239], off
	s_add_i32 m0, s0, 0x2000
	s_add_u32 s0, s44, 0xb0080
	v_lshl_add_u64 v[238:239], v[240:241], 0, s[12:13]
	s_addc_u32 s1, s45, 0
	s_add_i32 s2, s69, s39
	global_load_lds_dwordx4 v[238:239], off
	v_lshl_add_u64 v[238:239], s[0:1], 0, v[146:147]
	s_mov_b32 m0, s2
	s_nop 0
	global_load_lds_dwordx4 v[238:239], off
	v_lshl_add_u64 v[238:239], s[0:1], 0, v[152:153]
	s_add_i32 m0, s2, 0x2000
	s_nop 0
	global_load_lds_dwordx4 v[238:239], off
	v_lshl_add_u64 v[238:239], v[242:243], 0, s[12:13]
	s_mov_b32 m0, s62
	s_nop 0
	global_load_lds_dwordx4 v[238:239], off
	v_lshl_add_u64 v[238:239], v[244:245], 0, s[12:13]
	s_mov_b32 m0, s63
	s_nop 0
	global_load_lds_dwordx4 v[238:239], off
	s_waitcnt vmcnt(8)
	s_waitcnt lgkmcnt(0)
	s_setprio 1
	s_barrier
	v_mfma_f32_16x16x32_bf16 v[62:65], v[130:133], v[206:209], v[62:65]
	v_mfma_f32_16x16x32_bf16 v[58:61], v[138:141], v[206:209], v[58:61]
	v_mfma_f32_16x16x32_bf16 v[46:49], v[130:133], v[214:217], v[46:49]
	v_mfma_f32_16x16x32_bf16 v[42:45], v[138:141], v[214:217], v[42:45]
	v_mfma_f32_16x16x32_bf16 v[30:33], v[130:133], v[222:225], v[30:33]
	v_mfma_f32_16x16x32_bf16 v[26:29], v[138:141], v[222:225], v[26:29]
	v_mfma_f32_16x16x32_bf16 v[14:17], v[130:133], v[230:233], v[14:17]
	v_mfma_f32_16x16x32_bf16 v[10:13], v[138:141], v[230:233], v[10:13]
	v_mfma_f32_16x16x32_bf16 v[62:65], v[134:137], v[210:213], v[62:65]
	v_mfma_f32_16x16x32_bf16 v[58:61], v[142:145], v[210:213], v[58:61]
	v_mfma_f32_16x16x32_bf16 v[46:49], v[134:137], v[218:221], v[46:49]
	v_mfma_f32_16x16x32_bf16 v[42:45], v[142:145], v[218:221], v[42:45]
	v_mfma_f32_16x16x32_bf16 v[30:33], v[134:137], v[226:229], v[30:33]
	v_mfma_f32_16x16x32_bf16 v[26:29], v[142:145], v[226:229], v[26:29]
	v_mfma_f32_16x16x32_bf16 v[14:17], v[134:137], v[234:237], v[14:17]
	v_mfma_f32_16x16x32_bf16 v[10:13], v[142:145], v[234:237], v[10:13]
	s_setprio 0
	s_setprio 1
	v_mfma_f32_16x16x32_bf16 v[54:57], v[168:171], v[206:209], v[54:57]
	v_mfma_f32_16x16x32_bf16 v[50:53], v[198:201], v[206:209], v[50:53]
	v_mfma_f32_16x16x32_bf16 v[38:41], v[168:171], v[214:217], v[38:41]
	v_mfma_f32_16x16x32_bf16 v[34:37], v[198:201], v[214:217], v[34:37]
	v_mfma_f32_16x16x32_bf16 v[22:25], v[168:171], v[222:225], v[22:25]
	v_mfma_f32_16x16x32_bf16 v[18:21], v[198:201], v[222:225], v[18:21]
	v_mfma_f32_16x16x32_bf16 v[6:9], v[168:171], v[230:233], v[6:9]
	v_mfma_f32_16x16x32_bf16 v[2:5], v[198:201], v[230:233], v[2:5]
	v_mfma_f32_16x16x32_bf16 v[54:57], v[194:197], v[210:213], v[54:57]
	v_mfma_f32_16x16x32_bf16 v[50:53], v[202:205], v[210:213], v[50:53]
	v_mfma_f32_16x16x32_bf16 v[38:41], v[194:197], v[218:221], v[38:41]
	v_mfma_f32_16x16x32_bf16 v[34:37], v[202:205], v[218:221], v[34:37]
	v_mfma_f32_16x16x32_bf16 v[22:25], v[194:197], v[226:229], v[22:25]
	v_mfma_f32_16x16x32_bf16 v[18:21], v[202:205], v[226:229], v[18:21]
	v_mfma_f32_16x16x32_bf16 v[6:9], v[194:197], v[234:237], v[6:9]
	v_mfma_f32_16x16x32_bf16 v[2:5], v[202:205], v[234:237], v[2:5]
	s_setprio 0
	s_barrier
	s_add_i32 s35, s35, 2
	s_add_u32 s4, s4, 0x100
	s_addc_u32 s5, s5, 0
	s_cmp_gt_u32 s35, 41
	s_mov_b64 s[40:41], s[42:43]
	s_cbranch_scc0 .LBB0_1937
	s_and_b64 vcc, exec, s[18:19]
	s_cbranch_vccz .LBB0_1940
	s_barrier
; #define PG8_LAS __attribute__((address_space(3)))
; #define RL_LOAD(PW, AI) do { _Pragma("unroll") for (int m = 0; m < 4; ++m) _Pragma("unroll") for (int bj = 0; bj < 2; ++bj) (PW)[m][bj] = *(const u32x4*)(hin + (size_t)(row0 + (AI) * HALF + m * 16) * 1024 + col0 + bj * HALF); } while (0)
; #define PG8_BAR __builtin_amdgcn_s_barrier()
;     __device__ __forceinline__ void run(const f32x4 (&acc)[2][2][4][2], const Unit& u, int wr, int wc, int fr, int fq, const PG8_LAS unsigned char* sp) const {
;         typedef float f32x2r __attribute__((ext_vector_type(2)));
;         const int rl0 = wr * 64 + fr, cl0 = wc * 32 + 8 * fq;
;         const int row0 = u.pm * BM + rl0, col0 = u.pn * BM + cl0;
;         u32x4 pwa[4][2], pwb[4][2];
;     ...
;         RL_LOAD(pwa, 0);
;         RL_ROW(pwa, 0, 0); RL_ROW(pwa, 0, 1);
; template <class Epi, class Sched, bool ALIGN_EPI = false, bool SP2 = false>
; __device__ __forceinline__ void gemm_phase(PG8_LAS unsigned char* lds, const Gemm g, const Sched& S, const Epi& E) {
;     ...
;         if constexpr (ALIGN_EPI) { if (wr == 0) PG8_BAR; }
;         if constexpr (Epi::LDS_PF) { E.run(acc, cur, wr, wc, fr, fq, lds + STAGE_BYTES + (ui % 3) * 4096); S.done(cur); }
.LBB0_1940:
	s_lshl_b32 s4, s38, 8
	v_lshl_or_b32 v132, s76, 8, v172
	v_add_u32_e32 v130, s4, v1
	v_ashrrev_i32_e32 v133, 31, v132
	v_readlane_b32 s0, v253, 21
	v_lshlrev_b64 v[168:169], 1, v[132:133]
	v_readlane_b32 s1, v253, 22
	v_ashrrev_i32_e32 v131, 31, v130
	v_lshlrev_b64 v[134:135], 11, v[130:131]
	v_lshl_add_u64 v[132:133], s[0:1], 0, v[168:169]
	v_lshl_add_u64 v[170:171], v[132:133], 0, v[134:135]
	global_load_dwordx4 v[196:199], v[170:171], off
	global_load_dwordx4 v[200:203], v[170:171], off offset:256
	v_or_b32_e32 v136, 16, v130
	v_or_b32_e32 v138, 32, v130
	v_or_b32_e32 v130, 48, v130
	v_ashrrev_i32_e32 v137, 31, v136
	v_ashrrev_i32_e32 v139, 31, v138
	v_ashrrev_i32_e32 v131, 31, v130
	v_readlane_b32 s2, v253, 23
	v_lshlrev_b64 v[136:137], 11, v[136:137]
	v_lshlrev_b64 v[138:139], 11, v[138:139]
	v_lshlrev_b64 v[130:131], 11, v[130:131]
	v_readlane_b32 s3, v253, 24
	v_lshl_add_u64 v[136:137], v[132:133], 0, v[136:137]
	v_lshl_add_u64 v[138:139], v[132:133], 0, v[138:139]
	v_lshl_add_u64 v[134:135], s[2:3], 0, v[134:135]
	v_lshl_add_u64 v[130:131], v[132:133], 0, v[130:131]
	v_lshl_add_u64 v[228:229], v[134:135], 0, v[168:169]
	global_load_dwordx4 v[204:207], v[136:137], off
	global_load_dwordx4 v[208:211], v[136:137], off offset:256
	global_load_dwordx4 v[142:145], v[138:139], off
	s_nop 0
	global_load_dwordx4 v[138:141], v[138:139], off offset:256
	s_nop 0
	global_load_dwordx4 v[134:137], v[130:131], off
	s_nop 0
	global_load_dwordx4 v[130:133], v[130:131], off offset:256
	s_mul_hi_u32 s0, s21, 0xaaaaaaab
	s_lshr_b32 s0, s0, 1
	s_mul_i32 s0, s0, 3
	s_sub_i32 s0, s21, s0
	s_lshl_b32 s0, s0, 12
	s_add_i32 s5, s0, 0
	s_add_i32 s5, s5, 0x20000
	v_add_u32_e32 v195, s5, v173
	v_add_u32_e32 v194, s5, v174
	ds_read_b64 v[230:231], v195
	ds_read_b128 v[212:215], v194 offset:2048
	ds_read_b128 v[216:219], v194 offset:2064
	ds_read_b128 v[220:223], v194 offset:3072
	ds_read_b128 v[224:227], v194 offset:3088
	s_waitcnt vmcnt(0)
	v_lshlrev_b32_e32 v195, 16, v196
	v_and_b32_e32 v196, 0xffff0000, v196
	v_lshlrev_b32_e32 v232, 16, v197
	v_and_b32_e32 v233, 0xffff0000, v197
	v_lshlrev_b32_e32 v234, 16, v198
	v_and_b32_e32 v235, 0xffff0000, v198
	v_lshlrev_b32_e32 v236, 16, v199
	v_and_b32_e32 v237, 0xffff0000, v199
	v_lshlrev_b32_e32 v238, 16, v200
	v_and_b32_e32 v239, 0xffff0000, v200
	v_lshlrev_b32_e32 v240, 16, v201
	v_and_b32_e32 v241, 0xffff0000, v201
	v_lshlrev_b32_e32 v242, 16, v202
	v_and_b32_e32 v243, 0xffff0000, v202
	v_lshlrev_b32_e32 v244, 16, v203
	v_and_b32_e32 v245, 0xffff0000, v203
	s_waitcnt lgkmcnt(4)
	v_sub_f32_e32 v197, v196, v230
	v_sub_f32_e32 v196, v195, v230
	v_sub_f32_e32 v199, v233, v230
	v_sub_f32_e32 v198, v232, v230
	v_sub_f32_e32 v201, v235, v230
	v_sub_f32_e32 v200, v234, v230
	v_sub_f32_e32 v203, v237, v230
	v_sub_f32_e32 v202, v236, v230
	v_pk_mul_f32 v[198:199], v[230:231], v[198:199] op_sel:[1,0]
	v_pk_mul_f32 v[196:197], v[230:231], v[196:197] op_sel:[1,0]
	v_pk_mul_f32 v[202:203], v[230:231], v[202:203] op_sel:[1,0]
	v_pk_mul_f32 v[200:201], v[230:231], v[200:201] op_sel:[1,0]
	s_waitcnt lgkmcnt(1)
	v_pk_fma_f32 v[196:197], v[212:213], v[196:197], v[220:221]
	v_pk_fma_f32 v[198:199], v[214:215], v[198:199], v[222:223]
	s_waitcnt lgkmcnt(0)
	v_pk_fma_f32 v[200:201], v[216:217], v[200:201], v[224:225]
	v_pk_fma_f32 v[202:203], v[218:219], v[202:203], v[226:227]
	v_pk_fma_f32 v[128:129], v[198:199], s[20:21], v[128:129] op_sel_hi:[1,0,1]
	v_pk_fma_f32 v[126:127], v[196:197], s[20:21], v[126:127] op_sel_hi:[1,0,1]
	v_pk_fma_f32 v[196:197], v[202:203], s[20:21], v[124:125] op_sel_hi:[1,0,1]
	v_pk_fma_f32 v[124:125], v[200:201], s[20:21], v[122:123] op_sel_hi:[1,0,1]
	v_cvt_pk_bf16_f32 v122, v126, v127
	v_cvt_pk_bf16_f32 v123, v128, v129
	v_sub_f32_e32 v233, v239, v230
	v_cvt_pk_bf16_f32 v124, v124, v125
	v_cvt_pk_bf16_f32 v125, v196, v197
	ds_read_b128 v[126:129], v194 offset:2560
	ds_read_b128 v[196:199], v194 offset:2576
	ds_read_b128 v[200:203], v194 offset:3584
	ds_read_b128 v[212:215], v194 offset:3600
	v_sub_f32_e32 v232, v238, v230
	global_store_dwordx4 v[228:229], v[122:125], off
	v_lshlrev_b32_e32 v195, 16, v204
	v_lshlrev_b32_e32 v216, 16, v144
	v_sub_f32_e32 v123, v241, v230
	v_sub_f32_e32 v122, v240, v230
	v_pk_mul_f32 v[122:123], v[230:231], v[122:123] op_sel:[1,0]
	v_pk_mul_f32 v[124:125], v[230:231], v[232:233] op_sel:[1,0]
	s_waitcnt lgkmcnt(1)
	v_pk_fma_f32 v[122:123], v[122:123], v[128:129], v[202:203]
	v_pk_fma_f32 v[124:125], v[124:125], v[126:127], v[200:201]
	v_pk_fma_f32 v[120:121], v[122:123], s[20:21], v[120:121] op_sel_hi:[1,0,1]
	v_pk_fma_f32 v[118:119], v[124:125], s[20:21], v[118:119] op_sel_hi:[1,0,1]
	v_sub_f32_e32 v123, v243, v230
	v_sub_f32_e32 v122, v242, v230
	v_sub_f32_e32 v125, v245, v230
	v_sub_f32_e32 v124, v244, v230
	v_pk_mul_f32 v[124:125], v[230:231], v[124:125] op_sel:[1,0]
	v_pk_mul_f32 v[122:123], v[230:231], v[122:123] op_sel:[1,0]
	s_waitcnt lgkmcnt(0)
	v_pk_fma_f32 v[124:125], v[124:125], v[198:199], v[214:215]
	v_pk_fma_f32 v[122:123], v[122:123], v[196:197], v[212:213]
	v_pk_fma_f32 v[124:125], v[124:125], s[20:21], v[116:117] op_sel_hi:[1,0,1]
	v_pk_fma_f32 v[116:117], v[122:123], s[20:21], v[114:115] op_sel_hi:[1,0,1]
	v_cvt_pk_bf16_f32 v114, v118, v119
	v_cvt_pk_bf16_f32 v115, v120, v121
	v_and_b32_e32 v200, 0xffff0000, v204
	v_cvt_pk_bf16_f32 v116, v116, v117
	v_cvt_pk_bf16_f32 v117, v124, v125
	global_store_dwordx4 v[228:229], v[114:117], off offset:256
	v_lshlrev_b32_e32 v202, 16, v205
	v_and_b32_e32 v203, 0xffff0000, v205
	v_add_u32_e32 v116, s5, v176
	ds_read_b64 v[196:197], v116
	v_add_u32_e32 v114, s4, v175
	v_ashrrev_i32_e32 v115, 31, v114
	v_lshlrev_b64 v[198:199], 11, v[114:115]
	ds_read_b128 v[114:117], v194 offset:2048
	ds_read_b128 v[118:121], v194 offset:2064
	ds_read_b128 v[122:125], v194 offset:3072
	ds_read_b128 v[126:129], v194 offset:3088
	s_waitcnt lgkmcnt(4)
; #define RL_LOAD(PW, AI) do { _Pragma("unroll") for (int m = 0; m < 4; ++m) _Pragma("unroll") for (int bj = 0; bj < 2; ++bj) (PW)[m][bj] = *(const u32x4*)(hin + (size_t)(row0 + (AI) * HALF + m * 16) * 1024 + col0 + bj * HALF); } while (0)
;     __device__ __forceinline__ void run(const f32x4 (&acc)[2][2][4][2], const Unit& u, int wr, int wc, int fr, int fq, const PG8_LAS unsigned char* sp) const {
;     ...
;         RL_LOAD(pwa, 0);
;         RL_ROW(pwa, 0, 0); RL_ROW(pwa, 0, 1);
;         RL_LOAD(pwb, 1);
;         RL_ROW(pwa, 0, 2); RL_ROW(pwa, 0, 3);
;         RL_ROW(pwb, 1, 0); RL_ROW(pwb, 1, 1); RL_ROW(pwb, 1, 2); RL_ROW(pwb, 1, 3);
	v_sub_f32_e32 v201, v200, v196
	v_sub_f32_e32 v200, v195, v196
	v_sub_f32_e32 v203, v203, v196
	v_sub_f32_e32 v202, v202, v196
	v_pk_mul_f32 v[202:203], v[196:197], v[202:203] op_sel:[1,0]
	v_pk_mul_f32 v[200:201], v[196:197], v[200:201] op_sel:[1,0]
	v_lshlrev_b32_e32 v204, 16, v206
	v_and_b32_e32 v205, 0xffff0000, v206
	v_lshlrev_b32_e32 v206, 16, v207
	v_and_b32_e32 v207, 0xffff0000, v207
	s_waitcnt lgkmcnt(1)
	v_pk_fma_f32 v[114:115], v[114:115], v[200:201], v[122:123]
	v_pk_fma_f32 v[116:117], v[116:117], v[202:203], v[124:125]
	v_pk_fma_f32 v[110:111], v[114:115], s[20:21], v[110:111] op_sel_hi:[1,0,1]
	v_pk_fma_f32 v[112:113], v[116:117], s[20:21], v[112:113] op_sel_hi:[1,0,1]
	v_sub_f32_e32 v115, v205, v196
	v_sub_f32_e32 v114, v204, v196
	v_sub_f32_e32 v117, v207, v196
	v_sub_f32_e32 v116, v206, v196
	v_pk_mul_f32 v[116:117], v[196:197], v[116:117] op_sel:[1,0]
	v_pk_mul_f32 v[114:115], v[196:197], v[114:115] op_sel:[1,0]
	s_waitcnt lgkmcnt(0)
	v_pk_fma_f32 v[116:117], v[120:121], v[116:117], v[128:129]
	v_pk_fma_f32 v[114:115], v[118:119], v[114:115], v[126:127]
	v_pk_fma_f32 v[116:117], v[116:117], s[20:21], v[108:109] op_sel_hi:[1,0,1]
	v_pk_fma_f32 v[108:109], v[114:115], s[20:21], v[106:107] op_sel_hi:[1,0,1]
	v_cvt_pk_bf16_f32 v106, v110, v111
	v_lshl_add_u64 v[110:111], s[2:3], 0, v[198:199]
	v_lshl_add_u64 v[122:123], v[110:111], 0, v[168:169]
	v_cvt_pk_bf16_f32 v107, v112, v113
	v_cvt_pk_bf16_f32 v108, v108, v109
	v_cvt_pk_bf16_f32 v109, v116, v117
	global_store_dwordx4 v[122:123], v[106:109], off
	ds_read_b128 v[106:109], v194 offset:2560
	ds_read_b128 v[110:113], v194 offset:2576
	ds_read_b128 v[114:117], v194 offset:3584
	ds_read_b128 v[118:121], v194 offset:3600
	v_lshlrev_b32_e32 v124, 16, v208
	v_and_b32_e32 v125, 0xffff0000, v208
	v_lshlrev_b32_e32 v126, 16, v209
	v_and_b32_e32 v127, 0xffff0000, v209
	v_sub_f32_e32 v125, v125, v196
	v_sub_f32_e32 v124, v124, v196
	v_sub_f32_e32 v127, v127, v196
	v_sub_f32_e32 v126, v126, v196
	v_pk_mul_f32 v[126:127], v[196:197], v[126:127] op_sel:[1,0]
	v_pk_mul_f32 v[124:125], v[196:197], v[124:125] op_sel:[1,0]
	v_lshlrev_b32_e32 v128, 16, v210
	v_and_b32_e32 v129, 0xffff0000, v210
	v_lshlrev_b32_e32 v195, 16, v211
	v_and_b32_e32 v198, 0xffff0000, v211
	s_waitcnt lgkmcnt(1)
	v_pk_fma_f32 v[106:107], v[124:125], v[106:107], v[114:115]
	v_pk_fma_f32 v[108:109], v[126:127], v[108:109], v[116:117]
	v_pk_fma_f32 v[102:103], v[106:107], s[20:21], v[102:103] op_sel_hi:[1,0,1]
	v_pk_fma_f32 v[104:105], v[108:109], s[20:21], v[104:105] op_sel_hi:[1,0,1]
	v_sub_f32_e32 v107, v129, v196
	v_sub_f32_e32 v106, v128, v196
	v_sub_f32_e32 v109, v198, v196
	v_sub_f32_e32 v108, v195, v196
	v_pk_mul_f32 v[108:109], v[196:197], v[108:109] op_sel:[1,0]
	v_pk_mul_f32 v[106:107], v[196:197], v[106:107] op_sel:[1,0]
	s_waitcnt lgkmcnt(0)
	v_pk_fma_f32 v[108:109], v[108:109], v[112:113], v[120:121]
	v_pk_fma_f32 v[106:107], v[106:107], v[110:111], v[118:119]
	v_pk_fma_f32 v[108:109], v[108:109], s[20:21], v[100:101] op_sel_hi:[1,0,1]
	v_pk_fma_f32 v[100:101], v[106:107], s[20:21], v[98:99] op_sel_hi:[1,0,1]
	v_cvt_pk_bf16_f32 v98, v102, v103
	v_cvt_pk_bf16_f32 v99, v104, v105
	v_add_u32_e32 v195, s5, v178
	v_cvt_pk_bf16_f32 v100, v100, v101
	v_cvt_pk_bf16_f32 v101, v108, v109
	global_store_dwordx4 v[122:123], v[98:101], off offset:256
	v_lshlrev_b32_e32 v214, 16, v143
	v_and_b32_e32 v215, 0xffff0000, v143
	v_add_co_u32_e32 v100, vcc, s70, v170
	v_lshl_add_u64 v[98:99], v[170:171], 0, s[24:25]
	s_nop 0
	v_addc_co_u32_e32 v101, vcc, 0, v171, vcc
	global_load_dwordx4 v[126:129], v[100:101], off
	global_load_dwordx4 v[122:125], v[98:99], off offset:256
	v_add_co_u32_e32 v100, vcc, s71, v170
	v_lshl_add_u64 v[98:99], v[170:171], 0, s[26:27]
	s_nop 0
	v_addc_co_u32_e32 v101, vcc, 0, v171, vcc
	global_load_dwordx4 v[118:121], v[100:101], off
	global_load_dwordx4 v[114:117], v[98:99], off offset:256
	v_add_co_u32_e32 v100, vcc, s72, v170
	v_lshl_add_u64 v[98:99], v[170:171], 0, s[28:29]
	s_nop 0
	v_addc_co_u32_e32 v101, vcc, 0, v171, vcc
	global_load_dwordx4 v[110:113], v[100:101], off
	global_load_dwordx4 v[106:109], v[98:99], off offset:256
	v_add_co_u32_e32 v100, vcc, s73, v170
	v_lshl_add_u64 v[98:99], v[170:171], 0, s[30:31]
	s_nop 0
	v_addc_co_u32_e32 v101, vcc, 0, v171, vcc
	global_load_dwordx4 v[102:105], v[100:101], off
	s_nop 0
	global_load_dwordx4 v[98:101], v[98:99], off offset:256
	ds_read_b64 v[212:213], v195
	ds_read_b128 v[196:199], v194 offset:2048
	ds_read_b128 v[200:203], v194 offset:2064
	ds_read_b128 v[204:207], v194 offset:3072
	ds_read_b128 v[208:211], v194 offset:3088
	v_lshlrev_b32_e32 v195, 16, v142
	v_and_b32_e32 v142, 0xffff0000, v142
	v_and_b32_e32 v217, 0xffff0000, v144
	v_lshlrev_b32_e32 v218, 16, v145
	v_and_b32_e32 v219, 0xffff0000, v145
	s_waitcnt lgkmcnt(4)
	v_sub_f32_e32 v143, v142, v212
	v_sub_f32_e32 v142, v195, v212
	v_sub_f32_e32 v145, v215, v212
	v_sub_f32_e32 v144, v214, v212
	v_pk_mul_f32 v[144:145], v[212:213], v[144:145] op_sel:[1,0]
	v_pk_mul_f32 v[142:143], v[212:213], v[142:143] op_sel:[1,0]
	s_waitcnt lgkmcnt(1)
	v_pk_fma_f32 v[144:145], v[198:199], v[144:145], v[206:207]
	v_pk_fma_f32 v[142:143], v[196:197], v[142:143], v[204:205]
	v_add_u32_e32 v170, s4, v177
	v_pk_fma_f32 v[96:97], v[144:145], s[20:21], v[96:97] op_sel_hi:[1,0,1]
	v_pk_fma_f32 v[94:95], v[142:143], s[20:21], v[94:95] op_sel_hi:[1,0,1]
	v_sub_f32_e32 v143, v217, v212
	v_sub_f32_e32 v142, v216, v212
	v_sub_f32_e32 v145, v219, v212
	v_sub_f32_e32 v144, v218, v212
	v_ashrrev_i32_e32 v171, 31, v170
	v_pk_mul_f32 v[144:145], v[212:213], v[144:145] op_sel:[1,0]
	v_pk_mul_f32 v[142:143], v[212:213], v[142:143] op_sel:[1,0]
	v_lshlrev_b64 v[170:171], 11, v[170:171]
	s_waitcnt lgkmcnt(0)
; #define RL_LOAD(PW, AI) do { _Pragma("unroll") for (int m = 0; m < 4; ++m) _Pragma("unroll") for (int bj = 0; bj < 2; ++bj) (PW)[m][bj] = *(const u32x4*)(hin + (size_t)(row0 + (AI) * HALF + m * 16) * 1024 + col0 + bj * HALF); } while (0)
;     __device__ __forceinline__ void run(const f32x4 (&acc)[2][2][4][2], const Unit& u, int wr, int wc, int fr, int fq, const PG8_LAS unsigned char* sp) const {
;     ...
;         RL_LOAD(pwa, 0);
;         RL_ROW(pwa, 0, 0); RL_ROW(pwa, 0, 1);
;         RL_LOAD(pwb, 1);
;         RL_ROW(pwa, 0, 2); RL_ROW(pwa, 0, 3);
;         RL_ROW(pwb, 1, 0); RL_ROW(pwb, 1, 1); RL_ROW(pwb, 1, 2); RL_ROW(pwb, 1, 3);
	v_pk_fma_f32 v[142:143], v[200:201], v[142:143], v[208:209]
	v_pk_fma_f32 v[144:145], v[202:203], v[144:145], v[210:211]
	v_lshlrev_b32_e32 v195, 16, v138
	v_pk_fma_f32 v[144:145], v[144:145], s[20:21], v[92:93] op_sel_hi:[1,0,1]
	v_pk_fma_f32 v[92:93], v[142:143], s[20:21], v[90:91] op_sel_hi:[1,0,1]
	v_cvt_pk_bf16_f32 v90, v94, v95
	v_lshl_add_u64 v[94:95], s[2:3], 0, v[170:171]
	v_lshl_add_u64 v[170:171], v[94:95], 0, v[168:169]
	v_cvt_pk_bf16_f32 v91, v96, v97
	v_cvt_pk_bf16_f32 v92, v92, v93
	v_cvt_pk_bf16_f32 v93, v144, v145
	global_store_dwordx4 v[170:171], v[90:93], off
	ds_read_b128 v[90:93], v194 offset:2560
	ds_read_b128 v[94:97], v194 offset:2576
	ds_read_b128 v[142:145], v194 offset:3584
	ds_read_b128 v[196:199], v194 offset:3600
	v_and_b32_e32 v138, 0xffff0000, v138
	v_lshlrev_b32_e32 v200, 16, v139
	v_and_b32_e32 v201, 0xffff0000, v139
	v_lshlrev_b32_e32 v202, 16, v140
	v_and_b32_e32 v203, 0xffff0000, v140
	v_lshlrev_b32_e32 v204, 16, v141
	v_and_b32_e32 v205, 0xffff0000, v141
	v_sub_f32_e32 v139, v138, v212
	v_sub_f32_e32 v138, v195, v212
	v_sub_f32_e32 v141, v201, v212
	v_sub_f32_e32 v140, v200, v212
	v_pk_mul_f32 v[140:141], v[212:213], v[140:141] op_sel:[1,0]
	v_pk_mul_f32 v[138:139], v[212:213], v[138:139] op_sel:[1,0]
	s_waitcnt lgkmcnt(1)
	v_pk_fma_f32 v[92:93], v[140:141], v[92:93], v[144:145]
	v_pk_fma_f32 v[90:91], v[138:139], v[90:91], v[142:143]
	v_pk_fma_f32 v[88:89], v[92:93], s[20:21], v[88:89] op_sel_hi:[1,0,1]
	v_pk_fma_f32 v[86:87], v[90:91], s[20:21], v[86:87] op_sel_hi:[1,0,1]
	v_sub_f32_e32 v91, v203, v212
	v_sub_f32_e32 v90, v202, v212
	v_sub_f32_e32 v93, v205, v212
	v_sub_f32_e32 v92, v204, v212
	v_pk_mul_f32 v[92:93], v[212:213], v[92:93] op_sel:[1,0]
	v_pk_mul_f32 v[90:91], v[212:213], v[90:91] op_sel:[1,0]
	s_waitcnt lgkmcnt(0)
	v_pk_fma_f32 v[92:93], v[92:93], v[96:97], v[198:199]
	v_pk_fma_f32 v[90:91], v[90:91], v[94:95], v[196:197]
	v_pk_fma_f32 v[92:93], v[92:93], s[20:21], v[84:85] op_sel_hi:[1,0,1]
	v_pk_fma_f32 v[84:85], v[90:91], s[20:21], v[82:83] op_sel_hi:[1,0,1]
	v_cvt_pk_bf16_f32 v82, v86, v87
	v_cvt_pk_bf16_f32 v83, v88, v89
	v_lshlrev_b32_e32 v142, 16, v134
	v_cvt_pk_bf16_f32 v84, v84, v85
	v_cvt_pk_bf16_f32 v85, v92, v93
	global_store_dwordx4 v[170:171], v[82:85], off offset:256
	v_and_b32_e32 v134, 0xffff0000, v134
	v_lshlrev_b32_e32 v143, 16, v135
	v_add_u32_e32 v84, s5, v180
	ds_read_b64 v[138:139], v84
	v_add_u32_e32 v82, s4, v179
	v_ashrrev_i32_e32 v83, 31, v82
	v_lshlrev_b64 v[140:141], 11, v[82:83]
	ds_read_b128 v[82:85], v194 offset:2048
	ds_read_b128 v[86:89], v194 offset:2064
	ds_read_b128 v[90:93], v194 offset:3072
	ds_read_b128 v[94:97], v194 offset:3088
	v_and_b32_e32 v144, 0xffff0000, v135
	v_lshlrev_b32_e32 v145, 16, v136
	v_and_b32_e32 v170, 0xffff0000, v136
	v_lshlrev_b32_e32 v171, 16, v137
	v_and_b32_e32 v195, 0xffff0000, v137
	s_waitcnt lgkmcnt(4)
	v_sub_f32_e32 v135, v134, v138
	v_sub_f32_e32 v134, v142, v138
	v_sub_f32_e32 v137, v144, v138
	v_sub_f32_e32 v136, v143, v138
	v_pk_mul_f32 v[136:137], v[138:139], v[136:137] op_sel:[1,0]
	v_pk_mul_f32 v[134:135], v[138:139], v[134:135] op_sel:[1,0]
	s_waitcnt lgkmcnt(1)
	v_pk_fma_f32 v[84:85], v[84:85], v[136:137], v[92:93]
	v_pk_fma_f32 v[82:83], v[82:83], v[134:135], v[90:91]
	v_pk_fma_f32 v[80:81], v[84:85], s[20:21], v[80:81] op_sel_hi:[1,0,1]
	v_pk_fma_f32 v[78:79], v[82:83], s[20:21], v[78:79] op_sel_hi:[1,0,1]
	v_sub_f32_e32 v83, v170, v138
	v_sub_f32_e32 v82, v145, v138
	v_sub_f32_e32 v85, v195, v138
	v_sub_f32_e32 v84, v171, v138
	v_pk_mul_f32 v[84:85], v[138:139], v[84:85] op_sel:[1,0]
	v_pk_mul_f32 v[82:83], v[138:139], v[82:83] op_sel:[1,0]
	s_waitcnt lgkmcnt(0)
	v_pk_fma_f32 v[84:85], v[88:89], v[84:85], v[96:97]
	v_pk_fma_f32 v[82:83], v[86:87], v[82:83], v[94:95]
	v_pk_fma_f32 v[84:85], v[84:85], s[20:21], v[76:77] op_sel_hi:[1,0,1]
	v_pk_fma_f32 v[76:77], v[82:83], s[20:21], v[74:75] op_sel_hi:[1,0,1]
	v_cvt_pk_bf16_f32 v74, v78, v79
	v_lshl_add_u64 v[78:79], s[2:3], 0, v[140:141]
	v_lshl_add_u64 v[90:91], v[78:79], 0, v[168:169]
	v_cvt_pk_bf16_f32 v75, v80, v81
	v_cvt_pk_bf16_f32 v76, v76, v77
	v_cvt_pk_bf16_f32 v77, v84, v85
	global_store_dwordx4 v[90:91], v[74:77], off
	ds_read_b128 v[74:77], v194 offset:2560
	ds_read_b128 v[78:81], v194 offset:2576
	ds_read_b128 v[82:85], v194 offset:3584
	ds_read_b128 v[86:89], v194 offset:3600
	v_lshlrev_b32_e32 v92, 16, v130
	v_and_b32_e32 v93, 0xffff0000, v130
	v_lshlrev_b32_e32 v94, 16, v131
	v_and_b32_e32 v95, 0xffff0000, v131
	v_sub_f32_e32 v93, v93, v138
	v_sub_f32_e32 v92, v92, v138
	v_sub_f32_e32 v95, v95, v138
	v_sub_f32_e32 v94, v94, v138
	v_pk_mul_f32 v[94:95], v[138:139], v[94:95] op_sel:[1,0]
	v_pk_mul_f32 v[92:93], v[138:139], v[92:93] op_sel:[1,0]
	v_lshlrev_b32_e32 v96, 16, v132
	v_and_b32_e32 v97, 0xffff0000, v132
	v_lshlrev_b32_e32 v130, 16, v133
	v_and_b32_e32 v131, 0xffff0000, v133
	s_waitcnt lgkmcnt(1)
	v_pk_fma_f32 v[74:75], v[92:93], v[74:75], v[82:83]
	v_pk_fma_f32 v[76:77], v[94:95], v[76:77], v[84:85]
	v_pk_fma_f32 v[70:71], v[74:75], s[20:21], v[70:71] op_sel_hi:[1,0,1]
	v_pk_fma_f32 v[72:73], v[76:77], s[20:21], v[72:73] op_sel_hi:[1,0,1]
	v_sub_f32_e32 v75, v97, v138
	v_sub_f32_e32 v74, v96, v138
	v_sub_f32_e32 v77, v131, v138
	v_sub_f32_e32 v76, v130, v138
	v_pk_mul_f32 v[76:77], v[138:139], v[76:77] op_sel:[1,0]
	v_pk_mul_f32 v[74:75], v[138:139], v[74:75] op_sel:[1,0]
	s_waitcnt lgkmcnt(0)
	v_pk_fma_f32 v[76:77], v[76:77], v[80:81], v[88:89]
	v_pk_fma_f32 v[74:75], v[74:75], v[78:79], v[86:87]
	v_pk_fma_f32 v[76:77], v[76:77], s[20:21], v[68:69] op_sel_hi:[1,0,1]
	v_pk_fma_f32 v[68:69], v[74:75], s[20:21], v[66:67] op_sel_hi:[1,0,1]
	v_cvt_pk_bf16_f32 v66, v70, v71
	v_cvt_pk_bf16_f32 v67, v72, v73
	s_waitcnt vmcnt(10)
	v_lshlrev_b32_e32 v86, 16, v126
	v_cvt_pk_bf16_f32 v68, v68, v69
	v_cvt_pk_bf16_f32 v69, v76, v77
	global_store_dwordx4 v[90:91], v[66:69], off offset:256
	v_and_b32_e32 v87, 0xffff0000, v126
	v_lshlrev_b32_e32 v88, 16, v127
	v_add_u32_e32 v68, s5, v182
	ds_read_b64 v[82:83], v68
	v_add_u32_e32 v66, s4, v181
	v_ashrrev_i32_e32 v67, 31, v66
	v_lshlrev_b64 v[84:85], 11, v[66:67]
	ds_read_b128 v[66:69], v194 offset:2048
	ds_read_b128 v[70:73], v194 offset:2064
	ds_read_b128 v[74:77], v194 offset:3072
	ds_read_b128 v[78:81], v194 offset:3088
	v_and_b32_e32 v89, 0xffff0000, v127
	s_waitcnt lgkmcnt(4)
	v_sub_f32_e32 v87, v87, v82
	v_sub_f32_e32 v86, v86, v82
	v_sub_f32_e32 v89, v89, v82
	v_sub_f32_e32 v88, v88, v82
	v_pk_mul_f32 v[88:89], v[82:83], v[88:89] op_sel:[1,0]
	v_pk_mul_f32 v[86:87], v[82:83], v[86:87] op_sel:[1,0]
	v_lshlrev_b32_e32 v90, 16, v128
	v_and_b32_e32 v91, 0xffff0000, v128
	v_lshlrev_b32_e32 v92, 16, v129
	v_and_b32_e32 v93, 0xffff0000, v129
	s_waitcnt lgkmcnt(1)
	v_pk_fma_f32 v[66:67], v[66:67], v[86:87], v[74:75]
	v_pk_fma_f32 v[68:69], v[68:69], v[88:89], v[76:77]
	v_pk_fma_f32 v[62:63], v[66:67], s[20:21], v[62:63] op_sel_hi:[1,0,1]
	v_pk_fma_f32 v[64:65], v[68:69], s[20:21], v[64:65] op_sel_hi:[1,0,1]
	v_sub_f32_e32 v67, v91, v82
	v_sub_f32_e32 v66, v90, v82
	v_sub_f32_e32 v69, v93, v82
	v_sub_f32_e32 v68, v92, v82
	v_pk_mul_f32 v[68:69], v[82:83], v[68:69] op_sel:[1,0]
	v_pk_mul_f32 v[66:67], v[82:83], v[66:67] op_sel:[1,0]
	s_waitcnt lgkmcnt(0)
	v_pk_fma_f32 v[68:69], v[72:73], v[68:69], v[80:81]
	v_pk_fma_f32 v[66:67], v[70:71], v[66:67], v[78:79]
	v_pk_fma_f32 v[68:69], v[68:69], s[20:21], v[60:61] op_sel_hi:[1,0,1]
	v_pk_fma_f32 v[60:61], v[66:67], s[20:21], v[58:59] op_sel_hi:[1,0,1]
	v_cvt_pk_bf16_f32 v58, v62, v63
	v_lshl_add_u64 v[62:63], s[2:3], 0, v[84:85]
	v_lshl_add_u64 v[74:75], v[62:63], 0, v[168:169]
	v_cvt_pk_bf16_f32 v59, v64, v65
	v_cvt_pk_bf16_f32 v60, v60, v61
	v_cvt_pk_bf16_f32 v61, v68, v69
	global_store_dwordx4 v[74:75], v[58:61], off
	ds_read_b128 v[58:61], v194 offset:2560
	ds_read_b128 v[62:65], v194 offset:2576
	ds_read_b128 v[66:69], v194 offset:3584
	ds_read_b128 v[70:73], v194 offset:3600
	s_waitcnt vmcnt(11)
	v_lshlrev_b32_e32 v76, 16, v122
	v_and_b32_e32 v77, 0xffff0000, v122
	v_lshlrev_b32_e32 v78, 16, v123
	v_and_b32_e32 v79, 0xffff0000, v123
	v_sub_f32_e32 v77, v77, v82
	v_sub_f32_e32 v76, v76, v82
	v_sub_f32_e32 v79, v79, v82
	v_sub_f32_e32 v78, v78, v82
	v_pk_mul_f32 v[78:79], v[82:83], v[78:79] op_sel:[1,0]
	v_pk_mul_f32 v[76:77], v[82:83], v[76:77] op_sel:[1,0]
	v_lshlrev_b32_e32 v80, 16, v124
	v_and_b32_e32 v81, 0xffff0000, v124
	v_lshlrev_b32_e32 v84, 16, v125
	v_and_b32_e32 v85, 0xffff0000, v125
	s_waitcnt lgkmcnt(1)
	v_pk_fma_f32 v[58:59], v[76:77], v[58:59], v[66:67]
	v_pk_fma_f32 v[60:61], v[78:79], v[60:61], v[68:69]
	v_pk_fma_f32 v[54:55], v[58:59], s[20:21], v[54:55] op_sel_hi:[1,0,1]
	v_pk_fma_f32 v[56:57], v[60:61], s[20:21], v[56:57] op_sel_hi:[1,0,1]
	v_sub_f32_e32 v59, v81, v82
	v_sub_f32_e32 v58, v80, v82
	v_sub_f32_e32 v61, v85, v82
	v_sub_f32_e32 v60, v84, v82
	v_pk_mul_f32 v[60:61], v[82:83], v[60:61] op_sel:[1,0]
	v_pk_mul_f32 v[58:59], v[82:83], v[58:59] op_sel:[1,0]
	s_waitcnt lgkmcnt(0)
	v_pk_fma_f32 v[60:61], v[60:61], v[64:65], v[72:73]
	v_pk_fma_f32 v[58:59], v[58:59], v[62:63], v[70:71]
	v_pk_fma_f32 v[60:61], v[60:61], s[20:21], v[52:53] op_sel_hi:[1,0,1]
	v_pk_fma_f32 v[52:53], v[58:59], s[20:21], v[50:51] op_sel_hi:[1,0,1]
	v_cvt_pk_bf16_f32 v50, v54, v55
	v_cvt_pk_bf16_f32 v51, v56, v57
	s_waitcnt vmcnt(10)
	v_lshlrev_b32_e32 v70, 16, v118
	v_cvt_pk_bf16_f32 v52, v52, v53
	v_cvt_pk_bf16_f32 v53, v60, v61
	global_store_dwordx4 v[74:75], v[50:53], off offset:256
	v_and_b32_e32 v71, 0xffff0000, v118
	v_lshlrev_b32_e32 v72, 16, v119
	v_add_u32_e32 v52, s5, v184
	ds_read_b64 v[66:67], v52
	v_add_u32_e32 v50, s4, v183
	v_ashrrev_i32_e32 v51, 31, v50
	v_lshlrev_b64 v[68:69], 11, v[50:51]
	ds_read_b128 v[50:53], v194 offset:2048
	ds_read_b128 v[54:57], v194 offset:2064
	ds_read_b128 v[58:61], v194 offset:3072
	ds_read_b128 v[62:65], v194 offset:3088
	v_and_b32_e32 v73, 0xffff0000, v119
	s_waitcnt lgkmcnt(4)
	v_sub_f32_e32 v71, v71, v66
	v_sub_f32_e32 v70, v70, v66
	v_sub_f32_e32 v73, v73, v66
	v_sub_f32_e32 v72, v72, v66
	v_pk_mul_f32 v[72:73], v[66:67], v[72:73] op_sel:[1,0]
	v_pk_mul_f32 v[70:71], v[66:67], v[70:71] op_sel:[1,0]
	v_lshlrev_b32_e32 v74, 16, v120
	v_and_b32_e32 v75, 0xffff0000, v120
	v_lshlrev_b32_e32 v76, 16, v121
	v_and_b32_e32 v77, 0xffff0000, v121
	s_waitcnt lgkmcnt(1)
	v_pk_fma_f32 v[50:51], v[50:51], v[70:71], v[58:59]
	v_pk_fma_f32 v[52:53], v[52:53], v[72:73], v[60:61]
	v_pk_fma_f32 v[46:47], v[50:51], s[20:21], v[46:47] op_sel_hi:[1,0,1]
	v_pk_fma_f32 v[48:49], v[52:53], s[20:21], v[48:49] op_sel_hi:[1,0,1]
	v_sub_f32_e32 v51, v75, v66
	v_sub_f32_e32 v50, v74, v66
	v_sub_f32_e32 v53, v77, v66
	v_sub_f32_e32 v52, v76, v66
	v_pk_mul_f32 v[52:53], v[66:67], v[52:53] op_sel:[1,0]
	v_pk_mul_f32 v[50:51], v[66:67], v[50:51] op_sel:[1,0]
	s_waitcnt lgkmcnt(0)
	v_pk_fma_f32 v[52:53], v[56:57], v[52:53], v[64:65]
	v_pk_fma_f32 v[50:51], v[54:55], v[50:51], v[62:63]
	v_pk_fma_f32 v[52:53], v[52:53], s[20:21], v[44:45] op_sel_hi:[1,0,1]
	v_pk_fma_f32 v[44:45], v[50:51], s[20:21], v[42:43] op_sel_hi:[1,0,1]
	v_cvt_pk_bf16_f32 v42, v46, v47
	v_lshl_add_u64 v[46:47], s[2:3], 0, v[68:69]
	v_lshl_add_u64 v[58:59], v[46:47], 0, v[168:169]
	v_cvt_pk_bf16_f32 v43, v48, v49
	v_cvt_pk_bf16_f32 v44, v44, v45
	v_cvt_pk_bf16_f32 v45, v52, v53
	global_store_dwordx4 v[58:59], v[42:45], off
	ds_read_b128 v[42:45], v194 offset:2560
	ds_read_b128 v[46:49], v194 offset:2576
	ds_read_b128 v[50:53], v194 offset:3584
	ds_read_b128 v[54:57], v194 offset:3600
	s_waitcnt vmcnt(11)
	v_lshlrev_b32_e32 v60, 16, v114
	v_and_b32_e32 v61, 0xffff0000, v114
	v_lshlrev_b32_e32 v62, 16, v115
	v_and_b32_e32 v63, 0xffff0000, v115
	v_sub_f32_e32 v61, v61, v66
	v_sub_f32_e32 v60, v60, v66
	v_sub_f32_e32 v63, v63, v66
	v_sub_f32_e32 v62, v62, v66
	v_pk_mul_f32 v[62:63], v[66:67], v[62:63] op_sel:[1,0]
	v_pk_mul_f32 v[60:61], v[66:67], v[60:61] op_sel:[1,0]
	v_lshlrev_b32_e32 v64, 16, v116
	v_and_b32_e32 v65, 0xffff0000, v116
	v_lshlrev_b32_e32 v68, 16, v117
	v_and_b32_e32 v69, 0xffff0000, v117
	s_waitcnt lgkmcnt(1)
	v_pk_fma_f32 v[42:43], v[60:61], v[42:43], v[50:51]
	v_pk_fma_f32 v[44:45], v[62:63], v[44:45], v[52:53]
	v_pk_fma_f32 v[38:39], v[42:43], s[20:21], v[38:39] op_sel_hi:[1,0,1]
	v_pk_fma_f32 v[40:41], v[44:45], s[20:21], v[40:41] op_sel_hi:[1,0,1]
	v_sub_f32_e32 v43, v65, v66
	v_sub_f32_e32 v42, v64, v66
	v_sub_f32_e32 v45, v69, v66
	v_sub_f32_e32 v44, v68, v66
	v_pk_mul_f32 v[44:45], v[66:67], v[44:45] op_sel:[1,0]
	v_pk_mul_f32 v[42:43], v[66:67], v[42:43] op_sel:[1,0]
	s_waitcnt lgkmcnt(0)
	v_pk_fma_f32 v[44:45], v[44:45], v[48:49], v[56:57]
	v_pk_fma_f32 v[42:43], v[42:43], v[46:47], v[54:55]
	v_pk_fma_f32 v[44:45], v[44:45], s[20:21], v[36:37] op_sel_hi:[1,0,1]
	v_pk_fma_f32 v[36:37], v[42:43], s[20:21], v[34:35] op_sel_hi:[1,0,1]
	v_cvt_pk_bf16_f32 v34, v38, v39
	v_cvt_pk_bf16_f32 v35, v40, v41
	s_waitcnt vmcnt(10)
	v_lshlrev_b32_e32 v54, 16, v110
	v_cvt_pk_bf16_f32 v36, v36, v37
	v_cvt_pk_bf16_f32 v37, v44, v45
	global_store_dwordx4 v[58:59], v[34:37], off offset:256
	v_and_b32_e32 v55, 0xffff0000, v110
	v_lshlrev_b32_e32 v56, 16, v111
	v_add_u32_e32 v36, s5, v186
	ds_read_b64 v[50:51], v36
	v_add_u32_e32 v34, s4, v185
	v_ashrrev_i32_e32 v35, 31, v34
	v_lshlrev_b64 v[52:53], 11, v[34:35]
	ds_read_b128 v[34:37], v194 offset:2048
	ds_read_b128 v[38:41], v194 offset:2064
	ds_read_b128 v[42:45], v194 offset:3072
	ds_read_b128 v[46:49], v194 offset:3088
	v_and_b32_e32 v57, 0xffff0000, v111
	s_waitcnt lgkmcnt(4)
	v_sub_f32_e32 v55, v55, v50
	v_sub_f32_e32 v54, v54, v50
	v_sub_f32_e32 v57, v57, v50
	v_sub_f32_e32 v56, v56, v50
	v_pk_mul_f32 v[56:57], v[50:51], v[56:57] op_sel:[1,0]
	v_pk_mul_f32 v[54:55], v[50:51], v[54:55] op_sel:[1,0]
	v_lshlrev_b32_e32 v58, 16, v112
	v_and_b32_e32 v59, 0xffff0000, v112
	v_lshlrev_b32_e32 v60, 16, v113
	v_and_b32_e32 v61, 0xffff0000, v113
	s_waitcnt lgkmcnt(1)
	v_pk_fma_f32 v[34:35], v[34:35], v[54:55], v[42:43]
	v_pk_fma_f32 v[36:37], v[36:37], v[56:57], v[44:45]
	v_pk_fma_f32 v[30:31], v[34:35], s[20:21], v[30:31] op_sel_hi:[1,0,1]
	v_pk_fma_f32 v[32:33], v[36:37], s[20:21], v[32:33] op_sel_hi:[1,0,1]
	v_sub_f32_e32 v35, v59, v50
	v_sub_f32_e32 v34, v58, v50
	v_sub_f32_e32 v37, v61, v50
	v_sub_f32_e32 v36, v60, v50
	v_pk_mul_f32 v[36:37], v[50:51], v[36:37] op_sel:[1,0]
	v_pk_mul_f32 v[34:35], v[50:51], v[34:35] op_sel:[1,0]
	s_waitcnt lgkmcnt(0)
	v_pk_fma_f32 v[36:37], v[40:41], v[36:37], v[48:49]
	v_pk_fma_f32 v[34:35], v[38:39], v[34:35], v[46:47]
	v_pk_fma_f32 v[36:37], v[36:37], s[20:21], v[28:29] op_sel_hi:[1,0,1]
	v_pk_fma_f32 v[28:29], v[34:35], s[20:21], v[26:27] op_sel_hi:[1,0,1]
	v_cvt_pk_bf16_f32 v26, v30, v31
	v_lshl_add_u64 v[30:31], s[2:3], 0, v[52:53]
	v_lshl_add_u64 v[42:43], v[30:31], 0, v[168:169]
	v_cvt_pk_bf16_f32 v27, v32, v33
	v_cvt_pk_bf16_f32 v28, v28, v29
	v_cvt_pk_bf16_f32 v29, v36, v37
	global_store_dwordx4 v[42:43], v[26:29], off
	ds_read_b128 v[26:29], v194 offset:2560
	ds_read_b128 v[30:33], v194 offset:2576
	ds_read_b128 v[34:37], v194 offset:3584
	ds_read_b128 v[38:41], v194 offset:3600
	s_waitcnt vmcnt(11)
	v_lshlrev_b32_e32 v44, 16, v106
	v_and_b32_e32 v45, 0xffff0000, v106
	v_lshlrev_b32_e32 v46, 16, v107
	v_and_b32_e32 v47, 0xffff0000, v107
	v_sub_f32_e32 v45, v45, v50
	v_sub_f32_e32 v44, v44, v50
	v_sub_f32_e32 v47, v47, v50
	v_sub_f32_e32 v46, v46, v50
	v_pk_mul_f32 v[46:47], v[50:51], v[46:47] op_sel:[1,0]
	v_pk_mul_f32 v[44:45], v[50:51], v[44:45] op_sel:[1,0]
	v_lshlrev_b32_e32 v48, 16, v108
	v_and_b32_e32 v49, 0xffff0000, v108
	v_lshlrev_b32_e32 v52, 16, v109
	v_and_b32_e32 v53, 0xffff0000, v109
	s_waitcnt lgkmcnt(1)
	v_pk_fma_f32 v[26:27], v[44:45], v[26:27], v[34:35]
	v_pk_fma_f32 v[28:29], v[46:47], v[28:29], v[36:37]
	v_pk_fma_f32 v[22:23], v[26:27], s[20:21], v[22:23] op_sel_hi:[1,0,1]
	v_pk_fma_f32 v[24:25], v[28:29], s[20:21], v[24:25] op_sel_hi:[1,0,1]
	v_sub_f32_e32 v27, v49, v50
	v_sub_f32_e32 v26, v48, v50
	v_sub_f32_e32 v29, v53, v50
	v_sub_f32_e32 v28, v52, v50
	v_pk_mul_f32 v[28:29], v[50:51], v[28:29] op_sel:[1,0]
	v_pk_mul_f32 v[26:27], v[50:51], v[26:27] op_sel:[1,0]
	s_waitcnt lgkmcnt(0)
; #define PG8_BAR __builtin_amdgcn_s_barrier()
; template <class Epi, class Sched, bool ALIGN_EPI = false, bool SP2 = false>
; __device__ __forceinline__ void gemm_phase(PG8_LAS unsigned char* lds, const Gemm g, const Sched& S, const Epi& E) {
;     ...
;         if constexpr (ALIGN_EPI) { if (wr == 1) PG8_BAR; }
	v_pk_fma_f32 v[28:29], v[28:29], v[32:33], v[40:41]
	v_pk_fma_f32 v[26:27], v[26:27], v[30:31], v[38:39]
	v_pk_fma_f32 v[28:29], v[28:29], s[20:21], v[20:21] op_sel_hi:[1,0,1]
	v_pk_fma_f32 v[20:21], v[26:27], s[20:21], v[18:19] op_sel_hi:[1,0,1]
	v_cvt_pk_bf16_f32 v18, v22, v23
	v_cvt_pk_bf16_f32 v19, v24, v25
	s_waitcnt vmcnt(10)
	v_lshlrev_b32_e32 v38, 16, v102
	v_cvt_pk_bf16_f32 v20, v20, v21
	v_cvt_pk_bf16_f32 v21, v28, v29
	global_store_dwordx4 v[42:43], v[18:21], off offset:256
	v_and_b32_e32 v39, 0xffff0000, v102
	v_lshlrev_b32_e32 v40, 16, v103
	v_add_u32_e32 v20, s5, v188
	ds_read_b64 v[34:35], v20
	v_add_u32_e32 v18, s4, v187
	v_ashrrev_i32_e32 v19, 31, v18
	v_lshlrev_b64 v[36:37], 11, v[18:19]
	ds_read_b128 v[18:21], v194 offset:2048
	ds_read_b128 v[22:25], v194 offset:2064
	ds_read_b128 v[26:29], v194 offset:3072
	ds_read_b128 v[30:33], v194 offset:3088
	v_and_b32_e32 v41, 0xffff0000, v103
	s_waitcnt lgkmcnt(4)
	v_sub_f32_e32 v39, v39, v34
	v_sub_f32_e32 v38, v38, v34
	v_sub_f32_e32 v41, v41, v34
	v_sub_f32_e32 v40, v40, v34
	v_pk_mul_f32 v[40:41], v[34:35], v[40:41] op_sel:[1,0]
	v_pk_mul_f32 v[38:39], v[34:35], v[38:39] op_sel:[1,0]
	v_lshlrev_b32_e32 v42, 16, v104
	v_and_b32_e32 v43, 0xffff0000, v104
	v_lshlrev_b32_e32 v44, 16, v105
	v_and_b32_e32 v45, 0xffff0000, v105
	s_waitcnt lgkmcnt(1)
	v_pk_fma_f32 v[18:19], v[18:19], v[38:39], v[26:27]
	v_pk_fma_f32 v[20:21], v[20:21], v[40:41], v[28:29]
	v_pk_fma_f32 v[14:15], v[18:19], s[20:21], v[14:15] op_sel_hi:[1,0,1]
	v_pk_fma_f32 v[16:17], v[20:21], s[20:21], v[16:17] op_sel_hi:[1,0,1]
	v_sub_f32_e32 v19, v43, v34
	v_sub_f32_e32 v18, v42, v34
	v_sub_f32_e32 v21, v45, v34
	v_sub_f32_e32 v20, v44, v34
	v_pk_mul_f32 v[20:21], v[34:35], v[20:21] op_sel:[1,0]
	v_pk_mul_f32 v[18:19], v[34:35], v[18:19] op_sel:[1,0]
	s_waitcnt lgkmcnt(0)
	v_pk_fma_f32 v[20:21], v[24:25], v[20:21], v[32:33]
	v_pk_fma_f32 v[18:19], v[22:23], v[18:19], v[30:31]
	v_pk_fma_f32 v[20:21], v[20:21], s[20:21], v[12:13] op_sel_hi:[1,0,1]
	v_pk_fma_f32 v[12:13], v[18:19], s[20:21], v[10:11] op_sel_hi:[1,0,1]
	v_cvt_pk_bf16_f32 v10, v14, v15
	v_lshl_add_u64 v[14:15], s[2:3], 0, v[36:37]
	v_lshl_add_u64 v[26:27], v[14:15], 0, v[168:169]
	v_cvt_pk_bf16_f32 v11, v16, v17
	v_cvt_pk_bf16_f32 v12, v12, v13
	v_cvt_pk_bf16_f32 v13, v20, v21
	global_store_dwordx4 v[26:27], v[10:13], off
	ds_read_b128 v[10:13], v194 offset:2560
	ds_read_b128 v[14:17], v194 offset:2576
	ds_read_b128 v[18:21], v194 offset:3584
	ds_read_b128 v[22:25], v194 offset:3600
	s_waitcnt vmcnt(11)
	v_lshlrev_b32_e32 v28, 16, v98
	v_and_b32_e32 v29, 0xffff0000, v98
	v_lshlrev_b32_e32 v30, 16, v99
	v_and_b32_e32 v31, 0xffff0000, v99
	v_sub_f32_e32 v29, v29, v34
	v_sub_f32_e32 v28, v28, v34
	v_sub_f32_e32 v31, v31, v34
	v_sub_f32_e32 v30, v30, v34
	v_pk_mul_f32 v[30:31], v[34:35], v[30:31] op_sel:[1,0]
	v_pk_mul_f32 v[28:29], v[34:35], v[28:29] op_sel:[1,0]
	v_lshlrev_b32_e32 v32, 16, v100
	v_and_b32_e32 v33, 0xffff0000, v100
	v_lshlrev_b32_e32 v36, 16, v101
	v_and_b32_e32 v37, 0xffff0000, v101
	s_waitcnt lgkmcnt(1)
	v_pk_fma_f32 v[10:11], v[28:29], v[10:11], v[18:19]
	v_pk_fma_f32 v[12:13], v[30:31], v[12:13], v[20:21]
	v_pk_fma_f32 v[6:7], v[10:11], s[20:21], v[6:7] op_sel_hi:[1,0,1]
	v_pk_fma_f32 v[8:9], v[12:13], s[20:21], v[8:9] op_sel_hi:[1,0,1]
	v_sub_f32_e32 v11, v33, v34
	v_sub_f32_e32 v10, v32, v34
	v_sub_f32_e32 v13, v37, v34
	v_sub_f32_e32 v12, v36, v34
	v_pk_mul_f32 v[12:13], v[34:35], v[12:13] op_sel:[1,0]
	v_pk_mul_f32 v[10:11], v[34:35], v[10:11] op_sel:[1,0]
	s_waitcnt lgkmcnt(0)
	v_pk_fma_f32 v[12:13], v[12:13], v[16:17], v[24:25]
	v_pk_fma_f32 v[10:11], v[10:11], v[14:15], v[22:23]
	v_pk_fma_f32 v[12:13], v[12:13], s[20:21], v[4:5] op_sel_hi:[1,0,1]
	v_pk_fma_f32 v[4:5], v[10:11], s[20:21], v[2:3] op_sel_hi:[1,0,1]
	s_and_b64 vcc, exec, s[8:9]
	s_mov_b64 s[8:9], -1
	v_cvt_pk_bf16_f32 v2, v6, v7
	v_cvt_pk_bf16_f32 v3, v8, v9
	v_cvt_pk_bf16_f32 v4, v4, v5
	v_cvt_pk_bf16_f32 v5, v12, v13
	global_store_dwordx4 v[26:27], v[2:5], off offset:256
	s_cbranch_vccnz .LBB0_1921
	s_andn2_b64 vcc, exec, s[14:15]
	s_cbranch_vccnz .LBB0_1920
	s_mov_b32 s98, 1
	s_branch .LBB0_1920
